# U sweep: per-group reduction batched over four experts with a transposed DPP reduction; one vmcnt wait per step
# speedup vs baseline: 1.0045x; 1.0045x over previous
; __device__ __forceinline__ float bflo(unsigned w) { return __uint_as_float(w << 16); }
; __device__ void ph_peer(const float* __restrict__ SC, const bf16_t* __restrict__ H  , const float* __restrict__ gffn, const unsigned char* __restrict__ U, const unsigned char* __restrict__ V, float* X, const float* __restrict__ fgain) {
;     const int wave = TID() >> 6, lane = TID() & 63, grp = lane >> 4, sub = lane & 15;
;     for (int tok = blockIdx.x * 8 + wave; tok < GT; tok += gridDim.x * 8) {
;         float rstd;
;         {   const u32x4* hp0 = (const u32x4*)(H + (size_t)tok * 1024); float ss = 0.f;
; #pragma unroll
;             for (int s4 = 0; s4 < 2; ++s4) { const u32x4 w = hp0[s4 * 64 + lane]; const unsigned ww[4] = {w.x, w.y, w.z, w.w};
; #pragma unroll
;                 for (int e4 = 0; e4 < 4; ++e4) { const float lo = bflo(ww[e4]), hi = bfhi(ww[e4]); ss += lo * lo + hi * hi; } }
;             ss = wave_sum(ss); rstd = rsqrtf(ss * (1.0f / 1024.0f) + 1e-6f); }
;         int idx_lo = 0, idx_hi = 0; float g_lo = 0.f, g_hi = 0.f;
; #pragma unroll 1
;         for (int h = 0; h < 8; h += 2) {
;             unsigned k00[2], k01[2], k10[2], k11[2], top0[2], top1[2];
; #pragma unroll
;             for (int u = 0; u < 2; ++u) { const float* sc = SC + (size_t)tok * 2048 + (h + u) * 256;
;                 const float2 a0 = ((const float2*)sc)[lane], a1 = ((const float2*)(sc + 128))[lane];
;                 k00[u] = (f2key(a0.x) & ~127u) | (unsigned)(127 - 2 * lane); k01[u] = (f2key(a0.y) & ~127u) | (unsigned)(126 - 2 * lane);
;                 k10[u] = (f2key(a1.x) & ~127u) | (unsigned)(127 - 2 * lane); k11[u] = (f2key(a1.y) & ~127u) | (unsigned)(126 - 2 * lane);
;                 top0[u] = 0u; top1[u] = 0u; }
; __device__ __forceinline__ void run_step(const Params& p, int step, unsigned char* smem) {
;     ...
;     const int s = step - N_PRO, l = s / (NGRP * N_SLOT), g = (s / N_SLOT) % NGRP, slot = s % N_SLOT;
;     float* X = p.out + (size_t)g * GT * 1024;
;     bf16_t* H = (bf16_t*)(ws + O_H); bf16_t* PROJ = (bf16_t*)(ws + O_PROJ); bf16_t* ZT = (bf16_t*)(ws + O_ZT); bf16_t* YT = (bf16_t*)(ws + O_YT);
;     bf16_t* GA = (bf16_t*)(ws + O_GA); bf16_t* Y = (bf16_t*)(ws + O_Y); float* MT = (float*)(ws + O_MT); bf16_t* MBb = (bf16_t*)(ws + O_MB);
;     int* IDX = (int*)(ws + O_IDX); float* GATE = (float*)(ws + O_GATE); float* SC = (float*)(ws + O_SC);
;     switch (slot) {
.LBB0_213:
	v_readlane_b32 s0, v254, 54
	s_add_i32 s0, s0, -3
	s_mul_hi_i32 s1, s0, 0xb60b60b7
	s_add_i32 s1, s1, s0
	s_lshr_b32 s2, s1, 31
	s_ashr_i32 s1, s1, 5
	s_add_i32 s86, s1, s2
	s_mul_hi_i32 s1, s0, 0x38e38e39
	s_lshr_b32 s2, s1, 31
	s_ashr_i32 s1, s1, 1
	s_add_i32 s1, s1, s2
	s_mul_hi_i32 s2, s1, 0x66666667
	s_lshr_b32 s6, s2, 31
	s_ashr_i32 s2, s2, 1
	s_add_i32 s2, s2, s6
	s_mul_i32 s2, s2, 5
	s_sub_i32 s90, s1, s2
	s_mul_i32 s1, s1, 9
	s_ashr_i32 s91, s90, 31
	s_sub_i32 s84, s0, s1
	s_lshl_b64 s[0:1], s[90:91], 26
	s_add_u32 s88, s20, s0
	s_addc_u32 s89, s21, s1
	s_mov_b64 s[0:1], -1
	s_mov_b64 s[78:79], 0
	s_cmp_lt_i32 s84, 4
	s_mov_b64 s[92:93], 0
	s_cbranch_scc1 .LBB0_335
	s_cmp_gt_i32 s84, 5
	s_cbranch_scc0 .LBB0_281
	s_cmp_gt_i32 s84, 6
	s_cbranch_scc0 .LBB0_258
	s_cmp_gt_i32 s84, 7
	s_mov_b64 s[6:7], -1
	s_cbranch_scc0 .LBB0_236
	s_cmp_eq_u32 s84, 8
	s_cbranch_scc0 .LBB0_235
	s_waitcnt vmcnt(3)
	v_mov_b32_e32 v0, v131
	v_readlane_b32 s0, v251, 28
	v_ashrrev_i32_e32 v1, 6, v0
	v_mov_b32_e32 v0, v131
	v_add_u32_e32 v72, s0, v1
	s_movk_i32 s0, 0x4000
	v_cmp_gt_i32_e32 vcc, s0, v72
	s_and_saveexec_b64 s[38:39], vcc
	s_cbranch_execz .LBB0_234
	v_readlane_b32 s0, v254, 54
	s_sub_i32 s0, s0, 48
	s_cmp_lt_u32 s0, 45
	s_mul_i32 s14, s86, 0xc00000
	v_readlane_b32 s6, v251, 16
	s_cselect_b32 s1, s19, 0
	s_cselect_b32 s0, s18, 0
	s_mul_hi_i32 s2, s86, 0xc00000
	v_readlane_b32 s7, v251, 17
	s_add_u32 s6, s6, s14
	s_addc_u32 s7, s7, s2
	v_readlane_b32 s16, v254, 48
	v_readlane_b32 s17, v254, 49
	s_add_u32 s24, s16, s14
	s_addc_u32 s25, s17, s2
	s_lshl_b32 s14, s86, 10
	s_ashr_i32 s15, s14, 31
	s_lshl_b64 s[14:15], s[14:15], 2
	s_add_u32 s26, s8, s14
	v_and_b32_e32 v1, 15, v0
	s_addc_u32 s27, s9, s15
	v_lshlrev_b32_e32 v128, 8, v1
	global_load_dwordx4 v[64:67], v128, s[26:27]
	global_load_dwordx4 v[68:71], v128, s[26:27] offset:16
	v_and_b32_e32 v74, 63, v0
	v_lshlrev_b32_e32 v2, 1, v74
	v_bfe_u32 v3, v0, 2, 4
	s_waitcnt vmcnt(2)
	v_and_b32_e32 v146, 64, v174
	v_and_b32_e32 v6, 31, v0
	v_mul_u32_u24_e32 v4, 48, v1
	v_mov_b32_e32 v5, v129
	v_xor_b32_e32 v76, 0x7f, v2
	v_xor_b32_e32 v75, 0x7e, v2
	v_or_b32_e32 v2, v146, v3
	v_lshl_add_u64 v[80:81], s[24:25], 0, v[4:5]
	v_mul_u32_u24_e32 v4, 24, v6
	v_bfe_u32 v91, v0, 4, 2
	v_lshlrev_b32_e32 v8, 2, v0
	v_lshlrev_b32_e32 v147, 2, v2
	v_or_b32_e32 v2, v146, v1
	v_lshl_add_u64 v[82:83], s[6:7], 0, v[4:5]
	v_lshlrev_b32_e32 v4, 7, v6
	v_lshlrev_b32_e32 v0, 1, v0
	v_lshlrev_b32_e32 v149, 2, v2
	v_lshlrev_b32_e32 v2, 6, v1
	v_lshl_add_u64 v[6:7], s[88:89], 0, v[4:5]
	v_and_b32_e32 v0, 64, v0
	v_mov_b32_e32 v1, v129
	v_lshl_add_u64 v[4:5], s[0:1], 0, v[4:5]
	v_lshl_add_u64 v[84:85], v[6:7], 0, v[0:1]
	v_lshl_add_u64 v[86:87], v[4:5], 0, v[0:1]
	v_lshlrev_b32_e32 v0, 4, v3
	v_and_b32_e32 v1, 12, v8
	v_xor_b32_e32 v0, 0xff, v0
	v_or_b32_e32 v3, v146, v1
	v_lshlrev_b32_e32 v150, 2, v3
	v_xad_u32 v88, v1, -1, v0
	v_sub_u32_e32 v77, v0, v1
	v_or_b32_e32 v3, 2, v1
	v_or_b32_e32 v1, 3, v1
	v_sub_u32_e32 v89, v0, v3
	v_sub_u32_e32 v90, v0, v1
	v_xor_b32_e32 v0, 32, v174
	v_add_u32_e32 v1, 64, v146
	v_cmp_lt_i32_e32 vcc, v0, v1
	v_lshl_add_u64 v[78:79], s[26:27], 0, v[128:129]
	s_cmp_lg_u64 s[0:1], 0
	v_cndmask_b32_e32 v0, v174, v0, vcc
	v_lshlrev_b32_e32 v128, 3, v74
	v_lshlrev_b32_e32 v148, 2, v146
	v_cmp_gt_u32_e64 s[42:43], 16, v74
	v_cmp_gt_u32_e64 s[44:45], 32, v74
	s_mov_b64 s[26:27], 0
	s_cselect_b64 s[92:93], -1, 0
	v_or_b32_e32 v151, 4, v150
	v_or_b32_e32 v152, 8, v150
	v_or_b32_e32 v153, 12, v150
	v_cmp_eq_u32_e64 s[46:47], 0, v74
	v_cmp_eq_u32_e64 s[48:49], 1, v74
	v_cmp_eq_u32_e64 s[50:51], 2, v74
	v_cmp_eq_u32_e64 s[52:53], 3, v74
	v_cmp_eq_u32_e64 s[54:55], 4, v74
	v_cmp_eq_u32_e64 s[56:57], 5, v74
	v_cmp_eq_u32_e64 s[58:59], 6, v74
	v_cmp_eq_u32_e64 s[60:61], 7, v74
	v_cmp_eq_u32_e64 s[62:63], 8, v74
	v_cmp_eq_u32_e64 s[64:65], 9, v74
	v_cmp_eq_u32_e64 s[66:67], 10, v74
	v_cmp_eq_u32_e64 s[68:69], 11, v74
	v_cmp_eq_u32_e64 s[70:71], 12, v74
	v_cmp_eq_u32_e64 s[72:73], 13, v74
	v_cmp_eq_u32_e64 s[74:75], 14, v74
	v_cmp_eq_u32_e64 s[76:77], 15, v74
	v_lshlrev_b32_e32 v154, 2, v0
	v_or_b32_e32 v155, v146, v91
	v_lshl_add_u64 v[92:93], s[82:83], 0, v[128:129]
	v_lshlrev_b32_e32 v128, 4, v74
	v_lshlrev_b32_e32 v94, 1, v2
	v_and_b32_e32 v216, 3, v74
	v_lshlrev_b32_e32 v155, 4, v216
	v_cmp_eq_u32_e64 s[50:51], 0, v216
	v_cmp_eq_u32_e64 s[52:53], 1, v216
	v_cmp_eq_u32_e64 s[54:55], 2, v216
	v_cmp_eq_u32_e64 s[56:57], 3, v216
	v_and_b32_e32 v217, 1, v74
	v_cmp_eq_u32_e64 s[58:59], 1, v217
	v_and_b32_e32 v217, 2, v74
	v_cmp_eq_u32_e64 s[60:61], 2, v217
	v_readfirstlane_b32 s46, v80
	v_readfirstlane_b32 s47, v81
	v_readfirstlane_b32 s48, v82
	v_readfirstlane_b32 s49, v83
	v_and_b32_e32 v92, 15, v74
	v_mul_u32_u24_e32 v92, 48, v92
	v_and_b32_e32 v93, 31, v74
	v_mul_u32_u24_e32 v93, 24, v93
	v_readfirstlane_b32 s0, v72
	s_mov_b32 s30, 0xffffff80
	s_mov_b32 s31, 0xffffff00
	s_mov_b32 s36, 0x1000000
	s_lshl_b32 s1, s0, 13
	s_add_u32 s28, s82, s1
	s_addc_u32 s29, s83, 0
	v_lshrrev_b32_e32 v216, 3, v74
	v_and_b32_e32 v217, 7, v74
	v_lshlrev_b32_e32 v216, 10, v216
	v_lshl_or_b32 v216, v217, 4, v216
	v_lshrrev_b32_e32 v144, 6, v131
	v_mul_u32_u24_e32 v145, 0x2400, v144
	v_lshrrev_b32_e32 v157, 3, v74
	v_mul_u32_u24_e32 v157, 0x90, v157
	v_lshl_add_u32 v157, v217, 4, v157
	v_add_u32_e32 v144, v145, v157
	v_mul_u32_u24_e32 v157, 0x90, v74
	v_add_u32_e32 v145, v145, v157
	v_lshrrev_b32_e32 v156, 6, v131
	v_mul_u32_u24_e32 v156, 0x1c00, v156
	v_mul_u32_u24_e32 v157, 0x70, v74
	v_add_u32_e32 v156, v156, v157
	v_add_u32_e32 v156, 0x12000, v156
	v_mov_b32_e32 v217, v216
	global_load_dwordx4 v[180:183], v217, s[28:29] offset:0
	v_add_u32_e32 v157, s36, v217
	global_load_dwordx4 v[184:187], v157, s[28:29] offset:0
	v_add_u32_e32 v217, s36, v157
	global_load_dwordx4 v[188:191], v217, s[28:29] offset:0
	v_add_u32_e32 v157, s36, v217
	global_load_dwordx4 v[192:195], v157, s[28:29] offset:0
	v_add_u32_e32 v217, s36, v157
	global_load_dwordx4 v[196:199], v217, s[28:29] offset:0
	v_add_u32_e32 v157, s36, v217
	global_load_dwordx4 v[200:203], v157, s[28:29] offset:0
	v_add_u32_e32 v217, s36, v157
	global_load_dwordx4 v[204:207], v217, s[28:29] offset:0
	v_add_u32_e32 v157, s36, v217
	global_load_dwordx4 v[208:211], v157, s[28:29] offset:0
	v_mov_b32_e32 v217, v216
	global_load_dwordx4 v[52:55], v217, s[28:29] offset:128
	v_add_u32_e32 v157, s36, v217
	global_load_dwordx4 v[56:59], v157, s[28:29] offset:128
	v_add_u32_e32 v217, s36, v157
	global_load_dwordx4 v[60:63], v217, s[28:29] offset:128
	v_add_u32_e32 v157, s36, v217
	global_load_dwordx4 v[112:115], v157, s[28:29] offset:128
	v_add_u32_e32 v217, s36, v157
	global_load_dwordx4 v[116:119], v217, s[28:29] offset:128
	v_add_u32_e32 v157, s36, v217
	global_load_dwordx4 v[120:123], v157, s[28:29] offset:128
	v_add_u32_e32 v217, s36, v157
	global_load_dwordx4 v[124:127], v217, s[28:29] offset:128
	v_add_u32_e32 v157, s36, v217
	global_load_dwordx4 v[158:161], v157, s[28:29] offset:128
	s_waitcnt vmcnt(8)
; __device__ __forceinline__ unsigned f2key(float f) { const unsigned u = __float_as_uint(f); return (u & 0x80000000u) ? ~u : (u | 0x80000000u); }
; __device__ void ph_peer(const float* __restrict__ SC, const bf16_t* __restrict__ H  , const float* __restrict__ gffn, const unsigned char* __restrict__ U, const unsigned char* __restrict__ V, float* X, const float* __restrict__ fgain) {
;     ...
;             unsigned k00[2], k01[2], k10[2], k11[2], top0[2], top1[2];
; #pragma unroll
;             for (int u = 0; u < 2; ++u) { const float* sc = SC + (size_t)tok * 2048 + (h + u) * 256;
;                 const float2 a0 = ((const float2*)sc)[lane], a1 = ((const float2*)(sc + 128))[lane];
;                 k00[u] = (f2key(a0.x) & ~127u) | (unsigned)(127 - 2 * lane); k01[u] = (f2key(a0.y) & ~127u) | (unsigned)(126 - 2 * lane);
;                 k10[u] = (f2key(a1.x) & ~127u) | (unsigned)(127 - 2 * lane); k11[u] = (f2key(a1.y) & ~127u) | (unsigned)(126 - 2 * lane);
;                 top0[u] = 0u; top1[u] = 0u; }
;             for (int it = 0; it < 16; ++it) {
; #pragma unroll
;                 for (int u = 0; u < 2; ++u) {
;                     const unsigned m0 = wave_max_u32(k00[u] > k01[u] ? k00[u] : k01[u]);
;                     const unsigned m1 = wave_max_u32(k10[u] > k11[u] ? k10[u] : k11[u]);
;                     if (lane == it) { top0[u] = m0; top1[u] = m1; }
;                     if (k00[u] == m0) k00[u] = 0u; if (k01[u] == m0) k01[u] = 0u;
;                     if (k10[u] == m1) k10[u] = 0u; if (k11[u] == m1) k11[u] = 0u; }
;             }
	ds_write_b128 v144, v[180:183] offset:0
	ds_write_b128 v144, v[184:187] offset:1152
	ds_write_b128 v144, v[188:191] offset:2304
	ds_write_b128 v144, v[192:195] offset:3456
	ds_write_b128 v144, v[196:199] offset:4608
	ds_write_b128 v144, v[200:203] offset:5760
	ds_write_b128 v144, v[204:207] offset:6912
	ds_write_b128 v144, v[208:211] offset:8064
	ds_read_b128 v[0:3], v145 offset:0
	ds_read_b128 v[4:7], v145 offset:16
	ds_read_b128 v[8:11], v145 offset:32
	ds_read_b128 v[12:15], v145 offset:48
	ds_read_b128 v[16:19], v145 offset:64
	ds_read_b128 v[20:23], v145 offset:80
	ds_read_b128 v[24:27], v145 offset:96
	ds_read_b128 v[28:31], v145 offset:112
	s_waitcnt lgkmcnt(0)
	v_ashrrev_i32_e32 v212, 31, v0
	v_or_b32_e32 v212, 0x80000000, v212
	v_xor_b32_e32 v0, v0, v212
	v_and_b32_e32 v0, s30, v0
	v_or_b32_e32 v0, 0x7f, v0
	v_ashrrev_i32_e32 v212, 31, v1
	v_or_b32_e32 v212, 0x80000000, v212
	v_xor_b32_e32 v1, v1, v212
	v_and_b32_e32 v1, s30, v1
	v_or_b32_e32 v1, 0x7e, v1
	v_ashrrev_i32_e32 v212, 31, v2
	v_or_b32_e32 v212, 0x80000000, v212
	v_xor_b32_e32 v2, v2, v212
	v_and_b32_e32 v2, s30, v2
	v_or_b32_e32 v2, 0x7d, v2
	v_ashrrev_i32_e32 v212, 31, v3
	v_or_b32_e32 v212, 0x80000000, v212
	v_xor_b32_e32 v3, v3, v212
	v_and_b32_e32 v3, s30, v3
	v_or_b32_e32 v3, 0x7c, v3
	v_ashrrev_i32_e32 v212, 31, v4
	v_or_b32_e32 v212, 0x80000000, v212
	v_xor_b32_e32 v4, v4, v212
	v_and_b32_e32 v4, s30, v4
	v_or_b32_e32 v4, 0x7b, v4
	v_ashrrev_i32_e32 v212, 31, v5
	v_or_b32_e32 v212, 0x80000000, v212
	v_xor_b32_e32 v5, v5, v212
	v_and_b32_e32 v5, s30, v5
	v_or_b32_e32 v5, 0x7a, v5
	v_ashrrev_i32_e32 v212, 31, v6
	v_or_b32_e32 v212, 0x80000000, v212
	v_xor_b32_e32 v6, v6, v212
	v_and_b32_e32 v6, s30, v6
	v_or_b32_e32 v6, 0x79, v6
	v_ashrrev_i32_e32 v212, 31, v7
	v_or_b32_e32 v212, 0x80000000, v212
	v_xor_b32_e32 v7, v7, v212
	v_and_b32_e32 v7, s30, v7
	v_or_b32_e32 v7, 0x78, v7
	v_ashrrev_i32_e32 v212, 31, v8
	v_or_b32_e32 v212, 0x80000000, v212
	v_xor_b32_e32 v8, v8, v212
	v_and_b32_e32 v8, s30, v8
	v_or_b32_e32 v8, 0x77, v8
	v_ashrrev_i32_e32 v212, 31, v9
	v_or_b32_e32 v212, 0x80000000, v212
	v_xor_b32_e32 v9, v9, v212
	v_and_b32_e32 v9, s30, v9
	v_or_b32_e32 v9, 0x76, v9
	v_ashrrev_i32_e32 v212, 31, v10
	v_or_b32_e32 v212, 0x80000000, v212
	v_xor_b32_e32 v10, v10, v212
	v_and_b32_e32 v10, s30, v10
	v_or_b32_e32 v10, 0x75, v10
	v_ashrrev_i32_e32 v212, 31, v11
	v_or_b32_e32 v212, 0x80000000, v212
	v_xor_b32_e32 v11, v11, v212
	v_and_b32_e32 v11, s30, v11
	v_or_b32_e32 v11, 0x74, v11
	v_ashrrev_i32_e32 v212, 31, v12
	v_or_b32_e32 v212, 0x80000000, v212
	v_xor_b32_e32 v12, v12, v212
	v_and_b32_e32 v12, s30, v12
	v_or_b32_e32 v12, 0x73, v12
	v_ashrrev_i32_e32 v212, 31, v13
	v_or_b32_e32 v212, 0x80000000, v212
	v_xor_b32_e32 v13, v13, v212
	v_and_b32_e32 v13, s30, v13
	v_or_b32_e32 v13, 0x72, v13
	v_ashrrev_i32_e32 v212, 31, v14
	v_or_b32_e32 v212, 0x80000000, v212
	v_xor_b32_e32 v14, v14, v212
	v_and_b32_e32 v14, s30, v14
	v_or_b32_e32 v14, 0x71, v14
	v_ashrrev_i32_e32 v212, 31, v15
	v_or_b32_e32 v212, 0x80000000, v212
	v_xor_b32_e32 v15, v15, v212
	v_and_b32_e32 v15, s30, v15
	v_or_b32_e32 v15, 0x70, v15
	v_ashrrev_i32_e32 v212, 31, v16
	v_or_b32_e32 v212, 0x80000000, v212
	v_xor_b32_e32 v16, v16, v212
	v_and_b32_e32 v16, s30, v16
	v_or_b32_e32 v16, 0x6f, v16
	v_ashrrev_i32_e32 v212, 31, v17
	v_or_b32_e32 v212, 0x80000000, v212
	v_xor_b32_e32 v17, v17, v212
	v_and_b32_e32 v17, s30, v17
	v_or_b32_e32 v17, 0x6e, v17
	v_ashrrev_i32_e32 v212, 31, v18
	v_or_b32_e32 v212, 0x80000000, v212
	v_xor_b32_e32 v18, v18, v212
	v_and_b32_e32 v18, s30, v18
	v_or_b32_e32 v18, 0x6d, v18
	v_ashrrev_i32_e32 v212, 31, v19
	v_or_b32_e32 v212, 0x80000000, v212
	v_xor_b32_e32 v19, v19, v212
	v_and_b32_e32 v19, s30, v19
	v_or_b32_e32 v19, 0x6c, v19
	v_ashrrev_i32_e32 v212, 31, v20
	v_or_b32_e32 v212, 0x80000000, v212
	v_xor_b32_e32 v20, v20, v212
	v_and_b32_e32 v20, s30, v20
	v_or_b32_e32 v20, 0x6b, v20
	v_ashrrev_i32_e32 v212, 31, v21
	v_or_b32_e32 v212, 0x80000000, v212
	v_xor_b32_e32 v21, v21, v212
	v_and_b32_e32 v21, s30, v21
	v_or_b32_e32 v21, 0x6a, v21
	v_ashrrev_i32_e32 v212, 31, v22
	v_or_b32_e32 v212, 0x80000000, v212
	v_xor_b32_e32 v22, v22, v212
	v_and_b32_e32 v22, s30, v22
	v_or_b32_e32 v22, 0x69, v22
	v_ashrrev_i32_e32 v212, 31, v23
	v_or_b32_e32 v212, 0x80000000, v212
	v_xor_b32_e32 v23, v23, v212
	v_and_b32_e32 v23, s30, v23
	v_or_b32_e32 v23, 0x68, v23
	v_ashrrev_i32_e32 v212, 31, v24
	v_or_b32_e32 v212, 0x80000000, v212
	v_xor_b32_e32 v24, v24, v212
	v_and_b32_e32 v24, s30, v24
	v_or_b32_e32 v24, 0x67, v24
	v_ashrrev_i32_e32 v212, 31, v25
	v_or_b32_e32 v212, 0x80000000, v212
	v_xor_b32_e32 v25, v25, v212
	v_and_b32_e32 v25, s30, v25
	v_or_b32_e32 v25, 0x66, v25
	v_ashrrev_i32_e32 v212, 31, v26
	v_or_b32_e32 v212, 0x80000000, v212
	v_xor_b32_e32 v26, v26, v212
	v_and_b32_e32 v26, s30, v26
	v_or_b32_e32 v26, 0x65, v26
	v_ashrrev_i32_e32 v212, 31, v27
	v_or_b32_e32 v212, 0x80000000, v212
	v_xor_b32_e32 v27, v27, v212
	v_and_b32_e32 v27, s30, v27
	v_or_b32_e32 v27, 0x64, v27
	v_ashrrev_i32_e32 v212, 31, v28
	v_or_b32_e32 v212, 0x80000000, v212
	v_xor_b32_e32 v28, v28, v212
	v_and_b32_e32 v28, s30, v28
	v_or_b32_e32 v28, 0x63, v28
	v_ashrrev_i32_e32 v212, 31, v29
	v_or_b32_e32 v212, 0x80000000, v212
	v_xor_b32_e32 v29, v29, v212
	v_and_b32_e32 v29, s30, v29
	v_or_b32_e32 v29, 0x62, v29
	v_ashrrev_i32_e32 v212, 31, v30
	v_or_b32_e32 v212, 0x80000000, v212
	v_xor_b32_e32 v30, v30, v212
	v_and_b32_e32 v30, s30, v30
	v_or_b32_e32 v30, 0x61, v30
	v_ashrrev_i32_e32 v212, 31, v31
	v_or_b32_e32 v212, 0x80000000, v212
	v_xor_b32_e32 v31, v31, v212
	v_and_b32_e32 v31, s30, v31
; __device__ __forceinline__ unsigned f2key(float f) { const unsigned u = __float_as_uint(f); return (u & 0x80000000u) ? ~u : (u | 0x80000000u); }
; __device__ void ph_peer(const float* __restrict__ SC, const bf16_t* __restrict__ H  , const float* __restrict__ gffn, const unsigned char* __restrict__ U, const unsigned char* __restrict__ V, float* X, const float* __restrict__ fgain) {
;     ...
;             unsigned k00[2], k01[2], k10[2], k11[2], top0[2], top1[2];
; #pragma unroll
;             for (int u = 0; u < 2; ++u) { const float* sc = SC + (size_t)tok * 2048 + (h + u) * 256;
;                 const float2 a0 = ((const float2*)sc)[lane], a1 = ((const float2*)(sc + 128))[lane];
;                 k00[u] = (f2key(a0.x) & ~127u) | (unsigned)(127 - 2 * lane); k01[u] = (f2key(a0.y) & ~127u) | (unsigned)(126 - 2 * lane);
;                 k10[u] = (f2key(a1.x) & ~127u) | (unsigned)(127 - 2 * lane); k11[u] = (f2key(a1.y) & ~127u) | (unsigned)(126 - 2 * lane);
;                 top0[u] = 0u; top1[u] = 0u; }
;             for (int it = 0; it < 16; ++it) {
; #pragma unroll
;                 for (int u = 0; u < 2; ++u) {
;                     const unsigned m0 = wave_max_u32(k00[u] > k01[u] ? k00[u] : k01[u]);
;                     const unsigned m1 = wave_max_u32(k10[u] > k11[u] ? k10[u] : k11[u]);
;                     if (lane == it) { top0[u] = m0; top1[u] = m1; }
;                     if (k00[u] == m0) k00[u] = 0u; if (k01[u] == m0) k01[u] = 0u;
;                     if (k10[u] == m1) k10[u] = 0u; if (k11[u] == m1) k11[u] = 0u; }
;             }
	v_or_b32_e32 v31, 0x60, v31
	v_max_u32_e32 v215, v0, v1
	v_min_u32_e32 v1, v0, v1
	v_max_u32_e32 v214, v16, v17
	v_min_u32_e32 v17, v16, v17
	v_max_u32_e32 v213, v2, v3
	v_min_u32_e32 v3, v2, v3
	v_max_u32_e32 v0, v18, v19
	v_min_u32_e32 v19, v18, v19
	v_max_u32_e32 v16, v4, v5
	v_min_u32_e32 v5, v4, v5
	v_max_u32_e32 v2, v20, v21
	v_min_u32_e32 v21, v20, v21
	v_max_u32_e32 v18, v6, v7
	v_min_u32_e32 v7, v6, v7
	v_max_u32_e32 v4, v22, v23
	v_min_u32_e32 v23, v22, v23
	v_max_u32_e32 v20, v8, v9
	v_min_u32_e32 v9, v8, v9
	v_max_u32_e32 v6, v24, v25
	v_min_u32_e32 v25, v24, v25
	v_max_u32_e32 v22, v10, v11
	v_min_u32_e32 v11, v10, v11
	v_max_u32_e32 v8, v26, v27
	v_min_u32_e32 v27, v26, v27
	v_max_u32_e32 v24, v12, v13
	v_min_u32_e32 v13, v12, v13
	v_max_u32_e32 v10, v28, v29
	v_min_u32_e32 v29, v28, v29
	v_max_u32_e32 v26, v14, v15
	v_min_u32_e32 v15, v14, v15
	v_max_u32_e32 v12, v30, v31
	v_min_u32_e32 v31, v30, v31
	v_max_u32_e32 v28, v215, v213
	v_min_u32_e32 v213, v215, v213
	v_max_u32_e32 v14, v214, v0
	v_min_u32_e32 v0, v214, v0
	v_max_u32_e32 v30, v1, v3
	v_min_u32_e32 v3, v1, v3
	v_max_u32_e32 v215, v17, v19
	v_min_u32_e32 v19, v17, v19
	v_max_u32_e32 v214, v16, v18
	v_min_u32_e32 v18, v16, v18
	v_max_u32_e32 v1, v2, v4
	v_min_u32_e32 v4, v2, v4
	v_max_u32_e32 v17, v5, v7
	v_min_u32_e32 v7, v5, v7
	v_max_u32_e32 v16, v21, v23
	v_min_u32_e32 v23, v21, v23
	v_max_u32_e32 v2, v20, v22
	v_min_u32_e32 v22, v20, v22
	v_max_u32_e32 v5, v6, v8
	v_min_u32_e32 v8, v6, v8
	v_max_u32_e32 v21, v9, v11
	v_min_u32_e32 v11, v9, v11
	v_max_u32_e32 v20, v25, v27
	v_min_u32_e32 v27, v25, v27
	v_max_u32_e32 v6, v24, v26
	v_min_u32_e32 v26, v24, v26
	v_max_u32_e32 v9, v10, v12
	v_min_u32_e32 v12, v10, v12
	v_max_u32_e32 v25, v13, v15
	v_min_u32_e32 v15, v13, v15
	v_max_u32_e32 v24, v29, v31
	v_min_u32_e32 v31, v29, v31
	v_max_u32_e32 v10, v30, v213
	v_min_u32_e32 v213, v30, v213
	v_max_u32_e32 v13, v215, v0
	v_min_u32_e32 v0, v215, v0
	v_max_u32_e32 v29, v17, v18
	v_min_u32_e32 v18, v17, v18
	v_max_u32_e32 v30, v16, v4
	v_min_u32_e32 v4, v16, v4
	v_max_u32_e32 v215, v21, v22
	v_min_u32_e32 v22, v21, v22
	v_max_u32_e32 v17, v20, v8
	v_min_u32_e32 v8, v20, v8
	v_max_u32_e32 v16, v25, v26
	v_min_u32_e32 v26, v25, v26
	v_max_u32_e32 v21, v24, v12
	v_min_u32_e32 v12, v24, v12
	v_max_u32_e32 v20, v28, v214
	v_min_u32_e32 v214, v28, v214
	v_max_u32_e32 v25, v14, v1
	v_min_u32_e32 v1, v14, v1
	v_max_u32_e32 v24, v10, v29
	v_min_u32_e32 v29, v10, v29
	v_max_u32_e32 v28, v13, v30
	v_min_u32_e32 v30, v13, v30
	v_max_u32_e32 v14, v213, v18
	v_min_u32_e32 v18, v213, v18
	v_max_u32_e32 v10, v0, v4
	v_min_u32_e32 v4, v0, v4
	v_max_u32_e32 v13, v3, v7
	v_min_u32_e32 v7, v3, v7
	v_max_u32_e32 v213, v19, v23
	v_min_u32_e32 v23, v19, v23
	v_max_u32_e32 v0, v2, v6
	v_min_u32_e32 v6, v2, v6
	v_max_u32_e32 v3, v5, v9
	v_min_u32_e32 v9, v5, v9
	v_max_u32_e32 v19, v215, v16
	v_min_u32_e32 v16, v215, v16
	v_max_u32_e32 v2, v17, v21
	v_min_u32_e32 v21, v17, v21
	v_max_u32_e32 v5, v22, v26
	v_min_u32_e32 v26, v22, v26
	v_max_u32_e32 v215, v8, v12
	v_min_u32_e32 v12, v8, v12
	v_max_u32_e32 v17, v11, v15
	v_min_u32_e32 v15, v11, v15
	v_max_u32_e32 v22, v27, v31
	v_min_u32_e32 v31, v27, v31
	v_max_u32_e32 v8, v14, v214
	v_min_u32_e32 v214, v14, v214
	v_max_u32_e32 v11, v10, v1
	v_min_u32_e32 v1, v10, v1
	v_max_u32_e32 v27, v13, v29
	v_min_u32_e32 v29, v13, v29
	v_max_u32_e32 v14, v213, v30
	v_min_u32_e32 v30, v213, v30
	v_max_u32_e32 v10, v5, v6
	v_min_u32_e32 v6, v5, v6
	v_max_u32_e32 v13, v215, v9
	v_min_u32_e32 v9, v215, v9
	v_max_u32_e32 v213, v17, v16
	v_min_u32_e32 v16, v17, v16
	v_max_u32_e32 v5, v22, v21
	v_min_u32_e32 v21, v22, v21
	v_max_u32_e32 v215, v24, v8
	v_min_u32_e32 v8, v24, v8
	v_max_u32_e32 v17, v28, v11
	v_min_u32_e32 v11, v28, v11
	v_max_u32_e32 v22, v27, v214
	v_min_u32_e32 v214, v27, v214
	v_max_u32_e32 v24, v14, v1
	v_min_u32_e32 v1, v14, v1
	v_max_u32_e32 v28, v29, v18
	v_min_u32_e32 v18, v29, v18
	v_max_u32_e32 v27, v30, v4
	v_min_u32_e32 v4, v30, v4
	v_max_u32_e32 v14, v19, v10
	v_min_u32_e32 v10, v19, v10
	v_max_u32_e32 v29, v2, v13
	v_min_u32_e32 v13, v2, v13
	v_max_u32_e32 v30, v213, v6
	v_min_u32_e32 v6, v213, v6
	v_max_u32_e32 v19, v5, v9
	v_min_u32_e32 v9, v5, v9
	v_max_u32_e32 v2, v16, v26
	v_min_u32_e32 v26, v16, v26
	v_max_u32_e32 v213, v21, v12
	v_min_u32_e32 v12, v21, v12
	v_max_u32_e32 v5, v20, v0
	v_min_u32_e32 v0, v20, v0
	v_max_u32_e32 v16, v25, v3
	v_min_u32_e32 v3, v25, v3
	v_max_u32_e32 v21, v215, v14
	v_min_u32_e32 v14, v215, v14
	v_max_u32_e32 v20, v17, v29
	v_min_u32_e32 v29, v17, v29
	v_max_u32_e32 v25, v8, v10
	v_min_u32_e32 v10, v8, v10
	v_max_u32_e32 v215, v11, v13
	v_min_u32_e32 v13, v11, v13
	v_max_u32_e32 v17, v22, v30
	v_min_u32_e32 v30, v22, v30
	v_max_u32_e32 v8, v24, v19
	v_min_u32_e32 v19, v24, v19
	v_max_u32_e32 v11, v214, v6
	v_min_u32_e32 v6, v214, v6
	v_max_u32_e32 v22, v1, v9
	v_min_u32_e32 v9, v1, v9
	v_max_u32_e32 v24, v28, v2
	v_min_u32_e32 v2, v28, v2
	v_max_u32_e32 v214, v27, v213
	v_min_u32_e32 v213, v27, v213
	v_max_u32_e32 v1, v18, v26
	v_min_u32_e32 v26, v18, v26
	v_max_u32_e32 v28, v4, v12
	v_min_u32_e32 v12, v4, v12
	v_max_u32_e32 v27, v7, v15
	v_min_u32_e32 v15, v7, v15
	v_max_u32_e32 v18, v23, v31
	v_min_u32_e32 v31, v23, v31
	v_max_u32_e32 v4, v11, v0
	v_min_u32_e32 v0, v11, v0
	v_max_u32_e32 v7, v22, v3
	v_min_u32_e32 v3, v22, v3
	v_max_u32_e32 v23, v24, v14
	v_min_u32_e32 v14, v24, v14
	v_max_u32_e32 v11, v214, v29
	v_min_u32_e32 v29, v214, v29
	v_max_u32_e32 v22, v1, v10
	v_min_u32_e32 v10, v1, v10
	v_max_u32_e32 v24, v28, v13
	v_min_u32_e32 v13, v28, v13
	v_max_u32_e32 v214, v27, v30
; __device__ __forceinline__ unsigned f2key(float f) { const unsigned u = __float_as_uint(f); return (u & 0x80000000u) ? ~u : (u | 0x80000000u); }
; __device__ void ph_peer(const float* __restrict__ SC, const bf16_t* __restrict__ H  , const float* __restrict__ gffn, const unsigned char* __restrict__ U, const unsigned char* __restrict__ V, float* X, const float* __restrict__ fgain) {
;     ...
;             unsigned k00[2], k01[2], k10[2], k11[2], top0[2], top1[2];
; #pragma unroll
;             for (int u = 0; u < 2; ++u) { const float* sc = SC + (size_t)tok * 2048 + (h + u) * 256;
;                 const float2 a0 = ((const float2*)sc)[lane], a1 = ((const float2*)(sc + 128))[lane];
;                 k00[u] = (f2key(a0.x) & ~127u) | (unsigned)(127 - 2 * lane); k01[u] = (f2key(a0.y) & ~127u) | (unsigned)(126 - 2 * lane);
;                 k10[u] = (f2key(a1.x) & ~127u) | (unsigned)(127 - 2 * lane); k11[u] = (f2key(a1.y) & ~127u) | (unsigned)(126 - 2 * lane);
;                 top0[u] = 0u; top1[u] = 0u; }
;             for (int it = 0; it < 16; ++it) {
; #pragma unroll
;                 for (int u = 0; u < 2; ++u) {
;                     const unsigned m0 = wave_max_u32(k00[u] > k01[u] ? k00[u] : k01[u]);
;                     const unsigned m1 = wave_max_u32(k10[u] > k11[u] ? k10[u] : k11[u]);
;                     if (lane == it) { top0[u] = m0; top1[u] = m1; }
;                     if (k00[u] == m0) k00[u] = 0u; if (k01[u] == m0) k01[u] = 0u;
;                     if (k10[u] == m1) k10[u] = 0u; if (k11[u] == m1) k11[u] = 0u; }
;             }
	v_min_u32_e32 v30, v27, v30
	v_max_u32_e32 v1, v18, v19
	v_min_u32_e32 v19, v18, v19
	v_max_u32_e32 v28, v25, v4
	v_min_u32_e32 v4, v25, v4
	v_max_u32_e32 v27, v215, v7
	v_min_u32_e32 v7, v215, v7
	v_max_u32_e32 v18, v17, v23
	v_min_u32_e32 v23, v17, v23
	v_max_u32_e32 v25, v8, v11
	v_min_u32_e32 v11, v8, v11
	v_max_u32_e32 v215, v22, v0
	v_min_u32_e32 v0, v22, v0
	v_max_u32_e32 v17, v24, v3
	v_min_u32_e32 v3, v24, v3
	v_max_u32_e32 v8, v214, v14
	v_min_u32_e32 v14, v214, v14
	v_max_u32_e32 v22, v1, v29
	v_min_u32_e32 v29, v1, v29
	v_max_u32_e32 v24, v10, v6
	v_min_u32_e32 v6, v10, v6
	v_max_u32_e32 v214, v13, v9
	v_min_u32_e32 v9, v13, v9
	v_max_u32_e32 v1, v30, v2
	v_min_u32_e32 v2, v30, v2
	v_max_u32_e32 v10, v19, v213
	v_min_u32_e32 v213, v19, v213
	v_max_u32_e32 v13, v21, v28
	v_min_u32_e32 v28, v21, v28
	v_max_u32_e32 v30, v20, v27
	v_min_u32_e32 v27, v20, v27
	v_max_u32_e32 v19, v18, v4
	v_min_u32_e32 v4, v18, v4
	v_max_u32_e32 v21, v25, v7
	v_min_u32_e32 v7, v25, v7
	v_max_u32_e32 v20, v23, v215
	v_min_u32_e32 v215, v23, v215
	v_max_u32_e32 v18, v11, v17
	v_min_u32_e32 v17, v11, v17
	v_max_u32_e32 v25, v8, v0
	v_min_u32_e32 v0, v8, v0
	v_max_u32_e32 v23, v22, v3
	v_min_u32_e32 v3, v22, v3
	v_max_u32_e32 v11, v14, v24
	v_min_u32_e32 v24, v14, v24
	v_max_u32_e32 v8, v29, v214
	v_min_u32_e32 v214, v29, v214
	v_max_u32_e32 v22, v1, v6
	v_min_u32_e32 v6, v1, v6
	v_max_u32_e32 v14, v10, v9
	v_min_u32_e32 v9, v10, v9
	v_max_u32_e32 v29, v2, v26
	v_min_u32_e32 v26, v2, v26
	v_max_u32_e32 v1, v213, v12
	v_min_u32_e32 v12, v213, v12
	v_mov_b32_e32 v51, v5
	v_mov_b32_e32 v50, v13
	v_mov_b32_e32 v49, v28
	v_mov_b32_e32 v48, v19
	v_mov_b32_e32 v47, v4
	v_mov_b32_e32 v46, v20
	v_mov_b32_e32 v45, v215
	v_mov_b32_e32 v44, v25
	v_mov_b32_e32 v43, v0
	v_mov_b32_e32 v42, v11
	v_mov_b32_e32 v41, v24
	v_mov_b32_e32 v40, v22
	v_mov_b32_e32 v39, v6
	v_mov_b32_e32 v38, v29
	v_mov_b32_e32 v37, v26
	v_mov_b32_e32 v36, v15
	v_max_u32_e32 v35, v51, v31
	v_max_u32_e32 v34, v50, v12
	v_max_u32_e32 v33, v49, v1
	v_max_u32_e32 v32, v48, v9
	v_max_u32_e32 v51, v47, v14
	v_max_u32_e32 v50, v46, v214
	v_max_u32_e32 v49, v45, v8
	v_max_u32_e32 v48, v44, v3
	v_max_u32_e32 v47, v43, v23
	v_max_u32_e32 v46, v42, v17
	v_max_u32_e32 v45, v41, v18
	v_max_u32_e32 v44, v40, v7
	v_max_u32_e32 v43, v39, v21
	v_max_u32_e32 v42, v38, v27
	v_max_u32_e32 v41, v37, v30
	v_max_u32_e32 v40, v36, v16
	v_max_u32_e32 v39, v35, v47
	v_min_u32_e32 v47, v35, v47
	v_max_u32_e32 v38, v34, v46
	v_min_u32_e32 v46, v34, v46
	v_max_u32_e32 v37, v33, v45
	v_min_u32_e32 v45, v33, v45
	v_max_u32_e32 v36, v32, v44
	v_min_u32_e32 v44, v32, v44
	v_max_u32_e32 v35, v51, v43
	v_min_u32_e32 v43, v51, v43
	v_max_u32_e32 v34, v50, v42
	v_min_u32_e32 v42, v50, v42
	v_max_u32_e32 v33, v49, v41
	v_min_u32_e32 v41, v49, v41
	v_max_u32_e32 v32, v48, v40
	v_min_u32_e32 v40, v48, v40
	v_max_u32_e32 v51, v39, v35
	v_min_u32_e32 v35, v39, v35
	v_max_u32_e32 v50, v38, v34
	v_min_u32_e32 v34, v38, v34
	v_max_u32_e32 v49, v37, v33
	v_min_u32_e32 v33, v37, v33
	v_max_u32_e32 v48, v36, v32
	v_min_u32_e32 v32, v36, v32
	v_max_u32_e32 v39, v47, v43
	v_min_u32_e32 v43, v47, v43
	v_max_u32_e32 v38, v46, v42
	v_min_u32_e32 v42, v46, v42
	v_max_u32_e32 v37, v45, v41
	v_min_u32_e32 v41, v45, v41
	v_max_u32_e32 v36, v44, v40
	v_min_u32_e32 v40, v44, v40
	v_max_u32_e32 v47, v51, v49
	v_min_u32_e32 v49, v51, v49
	v_max_u32_e32 v46, v50, v48
	v_min_u32_e32 v48, v50, v48
	v_max_u32_e32 v45, v35, v33
	v_min_u32_e32 v33, v35, v33
	v_max_u32_e32 v44, v34, v32
	v_min_u32_e32 v32, v34, v32
	v_max_u32_e32 v51, v39, v37
	v_min_u32_e32 v37, v39, v37
	v_max_u32_e32 v50, v38, v36
	v_min_u32_e32 v36, v38, v36
	v_max_u32_e32 v35, v43, v41
	v_min_u32_e32 v41, v43, v41
	v_max_u32_e32 v34, v42, v40
	v_min_u32_e32 v40, v42, v40
	v_max_u32_e32 v39, v47, v46
	v_min_u32_e32 v46, v47, v46
	v_max_u32_e32 v38, v49, v48
	v_min_u32_e32 v48, v49, v48
	v_max_u32_e32 v43, v45, v44
	v_min_u32_e32 v44, v45, v44
	v_max_u32_e32 v42, v33, v32
	v_min_u32_e32 v32, v33, v32
	v_max_u32_e32 v47, v51, v50
	v_min_u32_e32 v50, v51, v50
	v_max_u32_e32 v49, v37, v36
	v_min_u32_e32 v36, v37, v36
	v_max_u32_e32 v45, v35, v34
	v_min_u32_e32 v34, v35, v34
	v_max_u32_e32 v33, v41, v40
	v_min_u32_e32 v40, v41, v40
	v_mov_b32_e32 v217, v216
	global_load_dwordx4 v[180:183], v217, s[28:29] offset:256
	v_add_u32_e32 v157, s36, v217
	global_load_dwordx4 v[184:187], v157, s[28:29] offset:256
	v_add_u32_e32 v217, s36, v157
	global_load_dwordx4 v[188:191], v217, s[28:29] offset:256
	v_add_u32_e32 v157, s36, v217
	global_load_dwordx4 v[192:195], v157, s[28:29] offset:256
	v_add_u32_e32 v217, s36, v157
	global_load_dwordx4 v[196:199], v217, s[28:29] offset:256
	v_add_u32_e32 v157, s36, v217
	global_load_dwordx4 v[200:203], v157, s[28:29] offset:256
	v_add_u32_e32 v217, s36, v157
	global_load_dwordx4 v[204:207], v217, s[28:29] offset:256
	v_add_u32_e32 v157, s36, v217
	global_load_dwordx4 v[208:211], v157, s[28:29] offset:256
	s_waitcnt vmcnt(8)
	ds_write_b128 v144, v[52:55] offset:0
	ds_write_b128 v144, v[56:59] offset:1152
	ds_write_b128 v144, v[60:63] offset:2304
	ds_write_b128 v144, v[112:115] offset:3456
	ds_write_b128 v144, v[116:119] offset:4608
	ds_write_b128 v144, v[120:123] offset:5760
	ds_write_b128 v144, v[124:127] offset:6912
	ds_write_b128 v144, v[158:161] offset:8064
	ds_read_b128 v[0:3], v145 offset:0
	ds_read_b128 v[4:7], v145 offset:16
	ds_read_b128 v[8:11], v145 offset:32
	ds_read_b128 v[12:15], v145 offset:48
	ds_read_b128 v[16:19], v145 offset:64
	ds_read_b128 v[20:23], v145 offset:80
	ds_read_b128 v[24:27], v145 offset:96
	ds_read_b128 v[28:31], v145 offset:112
	s_waitcnt lgkmcnt(0)
; __device__ __forceinline__ unsigned f2key(float f) { const unsigned u = __float_as_uint(f); return (u & 0x80000000u) ? ~u : (u | 0x80000000u); }
; __device__ void ph_peer(const float* __restrict__ SC, const bf16_t* __restrict__ H  , const float* __restrict__ gffn, const unsigned char* __restrict__ U, const unsigned char* __restrict__ V, float* X, const float* __restrict__ fgain) {
;     ...
;             unsigned k00[2], k01[2], k10[2], k11[2], top0[2], top1[2];
; #pragma unroll
;             for (int u = 0; u < 2; ++u) { const float* sc = SC + (size_t)tok * 2048 + (h + u) * 256;
;                 const float2 a0 = ((const float2*)sc)[lane], a1 = ((const float2*)(sc + 128))[lane];
;                 k00[u] = (f2key(a0.x) & ~127u) | (unsigned)(127 - 2 * lane); k01[u] = (f2key(a0.y) & ~127u) | (unsigned)(126 - 2 * lane);
;                 k10[u] = (f2key(a1.x) & ~127u) | (unsigned)(127 - 2 * lane); k11[u] = (f2key(a1.y) & ~127u) | (unsigned)(126 - 2 * lane);
;                 top0[u] = 0u; top1[u] = 0u; }
;             for (int it = 0; it < 16; ++it) {
; #pragma unroll
;                 for (int u = 0; u < 2; ++u) {
;                     const unsigned m0 = wave_max_u32(k00[u] > k01[u] ? k00[u] : k01[u]);
;                     const unsigned m1 = wave_max_u32(k10[u] > k11[u] ? k10[u] : k11[u]);
;                     if (lane == it) { top0[u] = m0; top1[u] = m1; }
;                     if (k00[u] == m0) k00[u] = 0u; if (k01[u] == m0) k01[u] = 0u;
;                     if (k10[u] == m1) k10[u] = 0u; if (k11[u] == m1) k11[u] = 0u; }
;             }
	v_ashrrev_i32_e32 v212, 31, v0
	v_or_b32_e32 v212, 0x80000000, v212
	v_xor_b32_e32 v0, v0, v212
	v_and_b32_e32 v0, s30, v0
	v_or_b32_e32 v0, 0x5f, v0
	v_ashrrev_i32_e32 v212, 31, v1
	v_or_b32_e32 v212, 0x80000000, v212
	v_xor_b32_e32 v1, v1, v212
	v_and_b32_e32 v1, s30, v1
	v_or_b32_e32 v1, 0x5e, v1
	v_ashrrev_i32_e32 v212, 31, v2
	v_or_b32_e32 v212, 0x80000000, v212
	v_xor_b32_e32 v2, v2, v212
	v_and_b32_e32 v2, s30, v2
	v_or_b32_e32 v2, 0x5d, v2
	v_ashrrev_i32_e32 v212, 31, v3
	v_or_b32_e32 v212, 0x80000000, v212
	v_xor_b32_e32 v3, v3, v212
	v_and_b32_e32 v3, s30, v3
	v_or_b32_e32 v3, 0x5c, v3
	v_ashrrev_i32_e32 v212, 31, v4
	v_or_b32_e32 v212, 0x80000000, v212
	v_xor_b32_e32 v4, v4, v212
	v_and_b32_e32 v4, s30, v4
	v_or_b32_e32 v4, 0x5b, v4
	v_ashrrev_i32_e32 v212, 31, v5
	v_or_b32_e32 v212, 0x80000000, v212
	v_xor_b32_e32 v5, v5, v212
	v_and_b32_e32 v5, s30, v5
	v_or_b32_e32 v5, 0x5a, v5
	v_ashrrev_i32_e32 v212, 31, v6
	v_or_b32_e32 v212, 0x80000000, v212
	v_xor_b32_e32 v6, v6, v212
	v_and_b32_e32 v6, s30, v6
	v_or_b32_e32 v6, 0x59, v6
	v_ashrrev_i32_e32 v212, 31, v7
	v_or_b32_e32 v212, 0x80000000, v212
	v_xor_b32_e32 v7, v7, v212
	v_and_b32_e32 v7, s30, v7
	v_or_b32_e32 v7, 0x58, v7
	v_ashrrev_i32_e32 v212, 31, v8
	v_or_b32_e32 v212, 0x80000000, v212
	v_xor_b32_e32 v8, v8, v212
	v_and_b32_e32 v8, s30, v8
	v_or_b32_e32 v8, 0x57, v8
	v_ashrrev_i32_e32 v212, 31, v9
	v_or_b32_e32 v212, 0x80000000, v212
	v_xor_b32_e32 v9, v9, v212
	v_and_b32_e32 v9, s30, v9
	v_or_b32_e32 v9, 0x56, v9
	v_ashrrev_i32_e32 v212, 31, v10
	v_or_b32_e32 v212, 0x80000000, v212
	v_xor_b32_e32 v10, v10, v212
	v_and_b32_e32 v10, s30, v10
	v_or_b32_e32 v10, 0x55, v10
	v_ashrrev_i32_e32 v212, 31, v11
	v_or_b32_e32 v212, 0x80000000, v212
	v_xor_b32_e32 v11, v11, v212
	v_and_b32_e32 v11, s30, v11
	v_or_b32_e32 v11, 0x54, v11
	v_ashrrev_i32_e32 v212, 31, v12
	v_or_b32_e32 v212, 0x80000000, v212
	v_xor_b32_e32 v12, v12, v212
	v_and_b32_e32 v12, s30, v12
	v_or_b32_e32 v12, 0x53, v12
	v_ashrrev_i32_e32 v212, 31, v13
	v_or_b32_e32 v212, 0x80000000, v212
	v_xor_b32_e32 v13, v13, v212
	v_and_b32_e32 v13, s30, v13
	v_or_b32_e32 v13, 0x52, v13
	v_ashrrev_i32_e32 v212, 31, v14
	v_or_b32_e32 v212, 0x80000000, v212
	v_xor_b32_e32 v14, v14, v212
	v_and_b32_e32 v14, s30, v14
	v_or_b32_e32 v14, 0x51, v14
	v_ashrrev_i32_e32 v212, 31, v15
	v_or_b32_e32 v212, 0x80000000, v212
	v_xor_b32_e32 v15, v15, v212
	v_and_b32_e32 v15, s30, v15
	v_or_b32_e32 v15, 0x50, v15
	v_ashrrev_i32_e32 v212, 31, v16
	v_or_b32_e32 v212, 0x80000000, v212
	v_xor_b32_e32 v16, v16, v212
	v_and_b32_e32 v16, s30, v16
	v_or_b32_e32 v16, 0x4f, v16
	v_ashrrev_i32_e32 v212, 31, v17
	v_or_b32_e32 v212, 0x80000000, v212
	v_xor_b32_e32 v17, v17, v212
	v_and_b32_e32 v17, s30, v17
	v_or_b32_e32 v17, 0x4e, v17
	v_ashrrev_i32_e32 v212, 31, v18
	v_or_b32_e32 v212, 0x80000000, v212
	v_xor_b32_e32 v18, v18, v212
	v_and_b32_e32 v18, s30, v18
	v_or_b32_e32 v18, 0x4d, v18
	v_ashrrev_i32_e32 v212, 31, v19
	v_or_b32_e32 v212, 0x80000000, v212
	v_xor_b32_e32 v19, v19, v212
	v_and_b32_e32 v19, s30, v19
	v_or_b32_e32 v19, 0x4c, v19
	v_ashrrev_i32_e32 v212, 31, v20
	v_or_b32_e32 v212, 0x80000000, v212
	v_xor_b32_e32 v20, v20, v212
	v_and_b32_e32 v20, s30, v20
	v_or_b32_e32 v20, 0x4b, v20
	v_ashrrev_i32_e32 v212, 31, v21
	v_or_b32_e32 v212, 0x80000000, v212
	v_xor_b32_e32 v21, v21, v212
	v_and_b32_e32 v21, s30, v21
	v_or_b32_e32 v21, 0x4a, v21
	v_ashrrev_i32_e32 v212, 31, v22
	v_or_b32_e32 v212, 0x80000000, v212
	v_xor_b32_e32 v22, v22, v212
	v_and_b32_e32 v22, s30, v22
	v_or_b32_e32 v22, 0x49, v22
	v_ashrrev_i32_e32 v212, 31, v23
	v_or_b32_e32 v212, 0x80000000, v212
	v_xor_b32_e32 v23, v23, v212
	v_and_b32_e32 v23, s30, v23
	v_or_b32_e32 v23, 0x48, v23
	v_ashrrev_i32_e32 v212, 31, v24
	v_or_b32_e32 v212, 0x80000000, v212
	v_xor_b32_e32 v24, v24, v212
	v_and_b32_e32 v24, s30, v24
	v_or_b32_e32 v24, 0x47, v24
	v_ashrrev_i32_e32 v212, 31, v25
	v_or_b32_e32 v212, 0x80000000, v212
	v_xor_b32_e32 v25, v25, v212
	v_and_b32_e32 v25, s30, v25
	v_or_b32_e32 v25, 0x46, v25
	v_ashrrev_i32_e32 v212, 31, v26
	v_or_b32_e32 v212, 0x80000000, v212
	v_xor_b32_e32 v26, v26, v212
	v_and_b32_e32 v26, s30, v26
	v_or_b32_e32 v26, 0x45, v26
	v_ashrrev_i32_e32 v212, 31, v27
	v_or_b32_e32 v212, 0x80000000, v212
	v_xor_b32_e32 v27, v27, v212
	v_and_b32_e32 v27, s30, v27
	v_or_b32_e32 v27, 0x44, v27
	v_ashrrev_i32_e32 v212, 31, v28
	v_or_b32_e32 v212, 0x80000000, v212
	v_xor_b32_e32 v28, v28, v212
	v_and_b32_e32 v28, s30, v28
	v_or_b32_e32 v28, 0x43, v28
	v_ashrrev_i32_e32 v212, 31, v29
	v_or_b32_e32 v212, 0x80000000, v212
	v_xor_b32_e32 v29, v29, v212
	v_and_b32_e32 v29, s30, v29
	v_or_b32_e32 v29, 0x42, v29
	v_ashrrev_i32_e32 v212, 31, v30
	v_or_b32_e32 v212, 0x80000000, v212
	v_xor_b32_e32 v30, v30, v212
	v_and_b32_e32 v30, s30, v30
	v_or_b32_e32 v30, 0x41, v30
	v_ashrrev_i32_e32 v212, 31, v31
	v_or_b32_e32 v212, 0x80000000, v212
	v_xor_b32_e32 v31, v31, v212
	v_and_or_b32 v31, v31, s30, 64
	v_max_u32_e32 v215, v0, v1
	v_min_u32_e32 v1, v0, v1
	v_max_u32_e32 v214, v16, v17
	v_min_u32_e32 v17, v16, v17
	v_max_u32_e32 v213, v2, v3
	v_min_u32_e32 v3, v2, v3
	v_max_u32_e32 v0, v18, v19
	v_min_u32_e32 v19, v18, v19
	v_max_u32_e32 v16, v4, v5
	v_min_u32_e32 v5, v4, v5
	v_max_u32_e32 v2, v20, v21
	v_min_u32_e32 v21, v20, v21
	v_max_u32_e32 v18, v6, v7
	v_min_u32_e32 v7, v6, v7
	v_max_u32_e32 v4, v22, v23
	v_min_u32_e32 v23, v22, v23
	v_max_u32_e32 v20, v8, v9
	v_min_u32_e32 v9, v8, v9
	v_max_u32_e32 v6, v24, v25
	v_min_u32_e32 v25, v24, v25
	v_max_u32_e32 v22, v10, v11
	v_min_u32_e32 v11, v10, v11
	v_max_u32_e32 v8, v26, v27
	v_min_u32_e32 v27, v26, v27
; __device__ __forceinline__ unsigned f2key(float f) { const unsigned u = __float_as_uint(f); return (u & 0x80000000u) ? ~u : (u | 0x80000000u); }
; __device__ void ph_peer(const float* __restrict__ SC, const bf16_t* __restrict__ H  , const float* __restrict__ gffn, const unsigned char* __restrict__ U, const unsigned char* __restrict__ V, float* X, const float* __restrict__ fgain) {
;     ...
;             unsigned k00[2], k01[2], k10[2], k11[2], top0[2], top1[2];
; #pragma unroll
;             for (int u = 0; u < 2; ++u) { const float* sc = SC + (size_t)tok * 2048 + (h + u) * 256;
;                 const float2 a0 = ((const float2*)sc)[lane], a1 = ((const float2*)(sc + 128))[lane];
;                 k00[u] = (f2key(a0.x) & ~127u) | (unsigned)(127 - 2 * lane); k01[u] = (f2key(a0.y) & ~127u) | (unsigned)(126 - 2 * lane);
;                 k10[u] = (f2key(a1.x) & ~127u) | (unsigned)(127 - 2 * lane); k11[u] = (f2key(a1.y) & ~127u) | (unsigned)(126 - 2 * lane);
;                 top0[u] = 0u; top1[u] = 0u; }
;             for (int it = 0; it < 16; ++it) {
; #pragma unroll
;                 for (int u = 0; u < 2; ++u) {
;                     const unsigned m0 = wave_max_u32(k00[u] > k01[u] ? k00[u] : k01[u]);
;                     const unsigned m1 = wave_max_u32(k10[u] > k11[u] ? k10[u] : k11[u]);
;                     if (lane == it) { top0[u] = m0; top1[u] = m1; }
;                     if (k00[u] == m0) k00[u] = 0u; if (k01[u] == m0) k01[u] = 0u;
;                     if (k10[u] == m1) k10[u] = 0u; if (k11[u] == m1) k11[u] = 0u; }
;             }
	v_max_u32_e32 v24, v12, v13
	v_min_u32_e32 v13, v12, v13
	v_max_u32_e32 v10, v28, v29
	v_min_u32_e32 v29, v28, v29
	v_max_u32_e32 v26, v14, v15
	v_min_u32_e32 v15, v14, v15
	v_max_u32_e32 v12, v30, v31
	v_min_u32_e32 v31, v30, v31
	v_max_u32_e32 v28, v215, v213
	v_min_u32_e32 v213, v215, v213
	v_max_u32_e32 v14, v214, v0
	v_min_u32_e32 v0, v214, v0
	v_max_u32_e32 v30, v1, v3
	v_min_u32_e32 v3, v1, v3
	v_max_u32_e32 v215, v17, v19
	v_min_u32_e32 v19, v17, v19
	v_max_u32_e32 v214, v16, v18
	v_min_u32_e32 v18, v16, v18
	v_max_u32_e32 v1, v2, v4
	v_min_u32_e32 v4, v2, v4
	v_max_u32_e32 v17, v5, v7
	v_min_u32_e32 v7, v5, v7
	v_max_u32_e32 v16, v21, v23
	v_min_u32_e32 v23, v21, v23
	v_max_u32_e32 v2, v20, v22
	v_min_u32_e32 v22, v20, v22
	v_max_u32_e32 v5, v6, v8
	v_min_u32_e32 v8, v6, v8
	v_max_u32_e32 v21, v9, v11
	v_min_u32_e32 v11, v9, v11
	v_max_u32_e32 v20, v25, v27
	v_min_u32_e32 v27, v25, v27
	v_max_u32_e32 v6, v24, v26
	v_min_u32_e32 v26, v24, v26
	v_max_u32_e32 v9, v10, v12
	v_min_u32_e32 v12, v10, v12
	v_max_u32_e32 v25, v13, v15
	v_min_u32_e32 v15, v13, v15
	v_max_u32_e32 v24, v29, v31
	v_min_u32_e32 v31, v29, v31
	v_max_u32_e32 v10, v30, v213
	v_min_u32_e32 v213, v30, v213
	v_max_u32_e32 v13, v215, v0
	v_min_u32_e32 v0, v215, v0
	v_max_u32_e32 v29, v17, v18
	v_min_u32_e32 v18, v17, v18
	v_max_u32_e32 v30, v16, v4
	v_min_u32_e32 v4, v16, v4
	v_max_u32_e32 v215, v21, v22
	v_min_u32_e32 v22, v21, v22
	v_max_u32_e32 v17, v20, v8
	v_min_u32_e32 v8, v20, v8
	v_max_u32_e32 v16, v25, v26
	v_min_u32_e32 v26, v25, v26
	v_max_u32_e32 v21, v24, v12
	v_min_u32_e32 v12, v24, v12
	v_max_u32_e32 v20, v28, v214
	v_min_u32_e32 v214, v28, v214
	v_max_u32_e32 v25, v14, v1
	v_min_u32_e32 v1, v14, v1
	v_max_u32_e32 v24, v10, v29
	v_min_u32_e32 v29, v10, v29
	v_max_u32_e32 v28, v13, v30
	v_min_u32_e32 v30, v13, v30
	v_max_u32_e32 v14, v213, v18
	v_min_u32_e32 v18, v213, v18
	v_max_u32_e32 v10, v0, v4
	v_min_u32_e32 v4, v0, v4
	v_max_u32_e32 v13, v3, v7
	v_min_u32_e32 v7, v3, v7
	v_max_u32_e32 v213, v19, v23
	v_min_u32_e32 v23, v19, v23
	v_max_u32_e32 v0, v2, v6
	v_min_u32_e32 v6, v2, v6
	v_max_u32_e32 v3, v5, v9
	v_min_u32_e32 v9, v5, v9
	v_max_u32_e32 v19, v215, v16
	v_min_u32_e32 v16, v215, v16
	v_max_u32_e32 v2, v17, v21
	v_min_u32_e32 v21, v17, v21
	v_max_u32_e32 v5, v22, v26
	v_min_u32_e32 v26, v22, v26
	v_max_u32_e32 v215, v8, v12
	v_min_u32_e32 v12, v8, v12
	v_max_u32_e32 v17, v11, v15
	v_min_u32_e32 v15, v11, v15
	v_max_u32_e32 v22, v27, v31
	v_min_u32_e32 v31, v27, v31
	v_max_u32_e32 v8, v14, v214
	v_min_u32_e32 v214, v14, v214
	v_max_u32_e32 v11, v10, v1
	v_min_u32_e32 v1, v10, v1
	v_max_u32_e32 v27, v13, v29
	v_min_u32_e32 v29, v13, v29
	v_max_u32_e32 v14, v213, v30
	v_min_u32_e32 v30, v213, v30
	v_max_u32_e32 v10, v5, v6
	v_min_u32_e32 v6, v5, v6
	v_max_u32_e32 v13, v215, v9
	v_min_u32_e32 v9, v215, v9
	v_max_u32_e32 v213, v17, v16
	v_min_u32_e32 v16, v17, v16
	v_max_u32_e32 v5, v22, v21
	v_min_u32_e32 v21, v22, v21
	v_max_u32_e32 v215, v24, v8
	v_min_u32_e32 v8, v24, v8
	v_max_u32_e32 v17, v28, v11
	v_min_u32_e32 v11, v28, v11
	v_max_u32_e32 v22, v27, v214
	v_min_u32_e32 v214, v27, v214
	v_max_u32_e32 v24, v14, v1
	v_min_u32_e32 v1, v14, v1
	v_max_u32_e32 v28, v29, v18
	v_min_u32_e32 v18, v29, v18
	v_max_u32_e32 v27, v30, v4
	v_min_u32_e32 v4, v30, v4
	v_max_u32_e32 v14, v19, v10
	v_min_u32_e32 v10, v19, v10
	v_max_u32_e32 v29, v2, v13
	v_min_u32_e32 v13, v2, v13
	v_max_u32_e32 v30, v213, v6
	v_min_u32_e32 v6, v213, v6
	v_max_u32_e32 v19, v5, v9
	v_min_u32_e32 v9, v5, v9
	v_max_u32_e32 v2, v16, v26
	v_min_u32_e32 v26, v16, v26
	v_max_u32_e32 v213, v21, v12
	v_min_u32_e32 v12, v21, v12
	v_max_u32_e32 v5, v20, v0
	v_min_u32_e32 v0, v20, v0
	v_max_u32_e32 v16, v25, v3
	v_min_u32_e32 v3, v25, v3
	v_max_u32_e32 v21, v215, v14
	v_min_u32_e32 v14, v215, v14
	v_max_u32_e32 v20, v17, v29
	v_min_u32_e32 v29, v17, v29
	v_max_u32_e32 v25, v8, v10
	v_min_u32_e32 v10, v8, v10
	v_max_u32_e32 v215, v11, v13
	v_min_u32_e32 v13, v11, v13
	v_max_u32_e32 v17, v22, v30
	v_min_u32_e32 v30, v22, v30
	v_max_u32_e32 v8, v24, v19
	v_min_u32_e32 v19, v24, v19
	v_max_u32_e32 v11, v214, v6
	v_min_u32_e32 v6, v214, v6
	v_max_u32_e32 v22, v1, v9
	v_min_u32_e32 v9, v1, v9
	v_max_u32_e32 v24, v28, v2
	v_min_u32_e32 v2, v28, v2
	v_max_u32_e32 v214, v27, v213
	v_min_u32_e32 v213, v27, v213
	v_max_u32_e32 v1, v18, v26
	v_min_u32_e32 v26, v18, v26
	v_max_u32_e32 v28, v4, v12
	v_min_u32_e32 v12, v4, v12
	v_max_u32_e32 v27, v7, v15
	v_min_u32_e32 v15, v7, v15
	v_max_u32_e32 v18, v23, v31
	v_min_u32_e32 v31, v23, v31
	v_max_u32_e32 v4, v11, v0
	v_min_u32_e32 v0, v11, v0
	v_max_u32_e32 v7, v22, v3
	v_min_u32_e32 v3, v22, v3
	v_max_u32_e32 v23, v24, v14
	v_min_u32_e32 v14, v24, v14
	v_max_u32_e32 v11, v214, v29
	v_min_u32_e32 v29, v214, v29
	v_max_u32_e32 v22, v1, v10
	v_min_u32_e32 v10, v1, v10
	v_max_u32_e32 v24, v28, v13
	v_min_u32_e32 v13, v28, v13
	v_max_u32_e32 v214, v27, v30
	v_min_u32_e32 v30, v27, v30
	v_max_u32_e32 v1, v18, v19
	v_min_u32_e32 v19, v18, v19
	v_max_u32_e32 v28, v25, v4
	v_min_u32_e32 v4, v25, v4
	v_max_u32_e32 v27, v215, v7
	v_min_u32_e32 v7, v215, v7
	v_max_u32_e32 v18, v17, v23
	v_min_u32_e32 v23, v17, v23
	v_max_u32_e32 v25, v8, v11
	v_min_u32_e32 v11, v8, v11
	v_max_u32_e32 v215, v22, v0
	v_min_u32_e32 v0, v22, v0
	v_max_u32_e32 v17, v24, v3
	v_min_u32_e32 v3, v24, v3
	v_max_u32_e32 v8, v214, v14
	v_min_u32_e32 v14, v214, v14
	v_max_u32_e32 v22, v1, v29
	v_min_u32_e32 v29, v1, v29
	v_max_u32_e32 v24, v10, v6
	v_min_u32_e32 v6, v10, v6
	v_max_u32_e32 v214, v13, v9
	v_min_u32_e32 v9, v13, v9
	v_max_u32_e32 v1, v30, v2
	v_min_u32_e32 v2, v30, v2
; __device__ __forceinline__ unsigned f2key(float f) { const unsigned u = __float_as_uint(f); return (u & 0x80000000u) ? ~u : (u | 0x80000000u); }
; __device__ void ph_peer(const float* __restrict__ SC, const bf16_t* __restrict__ H  , const float* __restrict__ gffn, const unsigned char* __restrict__ U, const unsigned char* __restrict__ V, float* X, const float* __restrict__ fgain) {
;     ...
;             unsigned k00[2], k01[2], k10[2], k11[2], top0[2], top1[2];
; #pragma unroll
;             for (int u = 0; u < 2; ++u) { const float* sc = SC + (size_t)tok * 2048 + (h + u) * 256;
;                 const float2 a0 = ((const float2*)sc)[lane], a1 = ((const float2*)(sc + 128))[lane];
;                 k00[u] = (f2key(a0.x) & ~127u) | (unsigned)(127 - 2 * lane); k01[u] = (f2key(a0.y) & ~127u) | (unsigned)(126 - 2 * lane);
;                 k10[u] = (f2key(a1.x) & ~127u) | (unsigned)(127 - 2 * lane); k11[u] = (f2key(a1.y) & ~127u) | (unsigned)(126 - 2 * lane);
;                 top0[u] = 0u; top1[u] = 0u; }
;             for (int it = 0; it < 16; ++it) {
; #pragma unroll
;                 for (int u = 0; u < 2; ++u) {
;                     const unsigned m0 = wave_max_u32(k00[u] > k01[u] ? k00[u] : k01[u]);
;                     const unsigned m1 = wave_max_u32(k10[u] > k11[u] ? k10[u] : k11[u]);
;                     if (lane == it) { top0[u] = m0; top1[u] = m1; }
;                     if (k00[u] == m0) k00[u] = 0u; if (k01[u] == m0) k01[u] = 0u;
;                     if (k10[u] == m1) k10[u] = 0u; if (k11[u] == m1) k11[u] = 0u; }
;             }
	v_max_u32_e32 v10, v19, v213
	v_min_u32_e32 v213, v19, v213
	v_max_u32_e32 v13, v21, v28
	v_min_u32_e32 v28, v21, v28
	v_max_u32_e32 v30, v20, v27
	v_min_u32_e32 v27, v20, v27
	v_max_u32_e32 v19, v18, v4
	v_min_u32_e32 v4, v18, v4
	v_max_u32_e32 v21, v25, v7
	v_min_u32_e32 v7, v25, v7
	v_max_u32_e32 v20, v23, v215
	v_min_u32_e32 v215, v23, v215
	v_max_u32_e32 v18, v11, v17
	v_min_u32_e32 v17, v11, v17
	v_max_u32_e32 v25, v8, v0
	v_min_u32_e32 v0, v8, v0
	v_max_u32_e32 v23, v22, v3
	v_min_u32_e32 v3, v22, v3
	v_max_u32_e32 v11, v14, v24
	v_min_u32_e32 v24, v14, v24
	v_max_u32_e32 v8, v29, v214
	v_min_u32_e32 v214, v29, v214
	v_max_u32_e32 v22, v1, v6
	v_min_u32_e32 v6, v1, v6
	v_max_u32_e32 v14, v10, v9
	v_min_u32_e32 v9, v10, v9
	v_max_u32_e32 v29, v2, v26
	v_min_u32_e32 v26, v2, v26
	v_max_u32_e32 v1, v213, v12
	v_min_u32_e32 v12, v213, v12
	v_max_u32_e32 v51, v39, v15
	v_max_u32_e32 v37, v46, v26
	v_max_u32_e32 v35, v38, v29
	v_max_u32_e32 v41, v48, v6
	v_max_u32_e32 v39, v43, v22
	v_max_u32_e32 v46, v44, v24
	v_max_u32_e32 v38, v42, v11
	v_max_u32_e32 v48, v32, v0
	v_max_u32_e32 v43, v47, v25
	v_max_u32_e32 v44, v50, v215
	v_max_u32_e32 v42, v49, v20
	v_max_u32_e32 v32, v36, v4
	v_max_u32_e32 v47, v45, v19
	v_max_u32_e32 v50, v34, v28
	v_max_u32_e32 v49, v33, v13
	v_max_u32_e32 v36, v40, v5
	v_max_u32_e32 v45, v51, v43
	v_min_u32_e32 v43, v51, v43
	v_max_u32_e32 v34, v37, v44
	v_min_u32_e32 v44, v37, v44
	v_max_u32_e32 v33, v35, v42
	v_min_u32_e32 v42, v35, v42
	v_max_u32_e32 v40, v41, v32
	v_min_u32_e32 v32, v41, v32
	v_max_u32_e32 v51, v39, v47
	v_min_u32_e32 v47, v39, v47
	v_max_u32_e32 v37, v46, v50
	v_min_u32_e32 v50, v46, v50
	v_max_u32_e32 v35, v38, v49
	v_min_u32_e32 v49, v38, v49
	v_max_u32_e32 v41, v48, v36
	v_min_u32_e32 v36, v48, v36
	v_max_u32_e32 v39, v45, v51
	v_min_u32_e32 v51, v45, v51
	v_max_u32_e32 v46, v34, v37
	v_min_u32_e32 v37, v34, v37
	v_max_u32_e32 v38, v33, v35
	v_min_u32_e32 v35, v33, v35
	v_max_u32_e32 v48, v40, v41
	v_min_u32_e32 v41, v40, v41
	v_max_u32_e32 v45, v43, v47
	v_min_u32_e32 v47, v43, v47
	v_max_u32_e32 v34, v44, v50
	v_min_u32_e32 v50, v44, v50
	v_max_u32_e32 v33, v42, v49
	v_min_u32_e32 v49, v42, v49
	v_max_u32_e32 v40, v32, v36
	v_min_u32_e32 v36, v32, v36
	v_max_u32_e32 v43, v39, v38
	v_min_u32_e32 v38, v39, v38
	v_max_u32_e32 v44, v46, v48
	v_min_u32_e32 v48, v46, v48
	v_max_u32_e32 v42, v51, v35
	v_min_u32_e32 v35, v51, v35
	v_max_u32_e32 v32, v37, v41
	v_min_u32_e32 v41, v37, v41
	v_max_u32_e32 v39, v45, v33
	v_min_u32_e32 v33, v45, v33
	v_max_u32_e32 v46, v34, v40
	v_min_u32_e32 v40, v34, v40
	v_max_u32_e32 v51, v47, v49
	v_min_u32_e32 v49, v47, v49
	v_max_u32_e32 v37, v50, v36
	v_min_u32_e32 v36, v50, v36
	v_max_u32_e32 v45, v43, v44
	v_min_u32_e32 v44, v43, v44
	v_max_u32_e32 v34, v38, v48
	v_min_u32_e32 v48, v38, v48
	v_max_u32_e32 v47, v42, v32
	v_min_u32_e32 v32, v42, v32
	v_max_u32_e32 v50, v35, v41
	v_min_u32_e32 v41, v35, v41
	v_max_u32_e32 v43, v39, v46
	v_min_u32_e32 v46, v39, v46
	v_max_u32_e32 v38, v33, v40
	v_min_u32_e32 v40, v33, v40
	v_max_u32_e32 v42, v51, v37
	v_min_u32_e32 v37, v51, v37
	v_max_u32_e32 v35, v49, v36
	v_min_u32_e32 v36, v49, v36
	v_max_u32_e32 v39, v45, v31
	v_max_u32_e32 v33, v44, v12
	v_max_u32_e32 v51, v34, v1
	v_max_u32_e32 v49, v48, v9
	v_max_u32_e32 v45, v47, v14
	v_max_u32_e32 v44, v32, v214
	v_max_u32_e32 v34, v50, v8
	v_max_u32_e32 v48, v41, v3
	v_max_u32_e32 v47, v43, v23
	v_max_u32_e32 v32, v46, v17
	v_max_u32_e32 v50, v38, v18
	v_max_u32_e32 v41, v40, v7
	v_max_u32_e32 v43, v42, v21
	v_max_u32_e32 v46, v37, v27
	v_max_u32_e32 v38, v35, v30
	v_max_u32_e32 v40, v36, v16
	v_max_u32_e32 v42, v39, v47
	v_min_u32_e32 v47, v39, v47
	v_max_u32_e32 v37, v33, v32
	v_min_u32_e32 v32, v33, v32
	v_max_u32_e32 v35, v51, v50
	v_min_u32_e32 v50, v51, v50
	v_max_u32_e32 v36, v49, v41
	v_min_u32_e32 v41, v49, v41
	v_max_u32_e32 v39, v45, v43
	v_min_u32_e32 v43, v45, v43
	v_max_u32_e32 v33, v44, v46
	v_min_u32_e32 v46, v44, v46
	v_max_u32_e32 v51, v34, v38
	v_min_u32_e32 v38, v34, v38
	v_max_u32_e32 v49, v48, v40
	v_min_u32_e32 v40, v48, v40
	v_max_u32_e32 v45, v42, v39
	v_min_u32_e32 v39, v42, v39
	v_max_u32_e32 v44, v37, v33
	v_min_u32_e32 v33, v37, v33
	v_max_u32_e32 v34, v35, v51
	v_min_u32_e32 v51, v35, v51
	v_max_u32_e32 v48, v36, v49
	v_min_u32_e32 v49, v36, v49
	v_max_u32_e32 v42, v47, v43
	v_min_u32_e32 v43, v47, v43
	v_max_u32_e32 v37, v32, v46
	v_min_u32_e32 v46, v32, v46
	v_max_u32_e32 v35, v50, v38
	v_min_u32_e32 v38, v50, v38
	v_max_u32_e32 v36, v41, v40
	v_min_u32_e32 v40, v41, v40
	v_max_u32_e32 v47, v45, v34
	v_min_u32_e32 v34, v45, v34
	v_max_u32_e32 v32, v44, v48
	v_min_u32_e32 v48, v44, v48
	v_max_u32_e32 v50, v39, v51
	v_min_u32_e32 v51, v39, v51
	v_max_u32_e32 v41, v33, v49
	v_min_u32_e32 v49, v33, v49
	v_max_u32_e32 v45, v42, v35
	v_min_u32_e32 v35, v42, v35
	v_max_u32_e32 v44, v37, v36
	v_min_u32_e32 v36, v37, v36
	v_max_u32_e32 v39, v43, v38
	v_min_u32_e32 v38, v43, v38
	v_max_u32_e32 v33, v46, v40
	v_min_u32_e32 v40, v46, v40
	v_max_u32_e32 v42, v47, v32
	v_min_u32_e32 v32, v47, v32
	v_max_u32_e32 v37, v34, v48
	v_min_u32_e32 v48, v34, v48
	v_max_u32_e32 v43, v50, v41
	v_min_u32_e32 v41, v50, v41
	v_max_u32_e32 v46, v51, v49
	v_min_u32_e32 v49, v51, v49
	v_max_u32_e32 v47, v45, v44
	v_min_u32_e32 v44, v45, v44
	v_max_u32_e32 v34, v35, v36
	v_min_u32_e32 v36, v35, v36
	v_max_u32_e32 v50, v39, v33
	v_min_u32_e32 v33, v39, v33
	v_max_u32_e32 v51, v38, v40
	v_min_u32_e32 v40, v38, v40
	v_mov_b32_e32 v217, v216
	global_load_dwordx4 v[52:55], v217, s[28:29] offset:384
	v_add_u32_e32 v157, s36, v217
	global_load_dwordx4 v[56:59], v157, s[28:29] offset:384
	v_add_u32_e32 v217, s36, v157
	global_load_dwordx4 v[60:63], v217, s[28:29] offset:384
	v_add_u32_e32 v157, s36, v217
	global_load_dwordx4 v[112:115], v157, s[28:29] offset:384
	v_add_u32_e32 v217, s36, v157
	global_load_dwordx4 v[116:119], v217, s[28:29] offset:384
	v_add_u32_e32 v157, s36, v217
	global_load_dwordx4 v[120:123], v157, s[28:29] offset:384
	v_add_u32_e32 v217, s36, v157
	global_load_dwordx4 v[124:127], v217, s[28:29] offset:384
	v_add_u32_e32 v157, s36, v217
	global_load_dwordx4 v[158:161], v157, s[28:29] offset:384
	s_waitcnt vmcnt(8)
; __device__ __forceinline__ unsigned f2key(float f) { const unsigned u = __float_as_uint(f); return (u & 0x80000000u) ? ~u : (u | 0x80000000u); }
; __device__ void ph_peer(const float* __restrict__ SC, const bf16_t* __restrict__ H  , const float* __restrict__ gffn, const unsigned char* __restrict__ U, const unsigned char* __restrict__ V, float* X, const float* __restrict__ fgain) {
;     ...
;             unsigned k00[2], k01[2], k10[2], k11[2], top0[2], top1[2];
; #pragma unroll
;             for (int u = 0; u < 2; ++u) { const float* sc = SC + (size_t)tok * 2048 + (h + u) * 256;
;                 const float2 a0 = ((const float2*)sc)[lane], a1 = ((const float2*)(sc + 128))[lane];
;                 k00[u] = (f2key(a0.x) & ~127u) | (unsigned)(127 - 2 * lane); k01[u] = (f2key(a0.y) & ~127u) | (unsigned)(126 - 2 * lane);
;                 k10[u] = (f2key(a1.x) & ~127u) | (unsigned)(127 - 2 * lane); k11[u] = (f2key(a1.y) & ~127u) | (unsigned)(126 - 2 * lane);
;                 top0[u] = 0u; top1[u] = 0u; }
;             for (int it = 0; it < 16; ++it) {
; #pragma unroll
;                 for (int u = 0; u < 2; ++u) {
;                     const unsigned m0 = wave_max_u32(k00[u] > k01[u] ? k00[u] : k01[u]);
;                     const unsigned m1 = wave_max_u32(k10[u] > k11[u] ? k10[u] : k11[u]);
;                     if (lane == it) { top0[u] = m0; top1[u] = m1; }
;                     if (k00[u] == m0) k00[u] = 0u; if (k01[u] == m0) k01[u] = 0u;
;                     if (k10[u] == m1) k10[u] = 0u; if (k11[u] == m1) k11[u] = 0u; }
;             }
	ds_write_b128 v144, v[180:183] offset:0
	ds_write_b128 v144, v[184:187] offset:1152
	ds_write_b128 v144, v[188:191] offset:2304
	ds_write_b128 v144, v[192:195] offset:3456
	ds_write_b128 v144, v[196:199] offset:4608
	ds_write_b128 v144, v[200:203] offset:5760
	ds_write_b128 v144, v[204:207] offset:6912
	ds_write_b128 v144, v[208:211] offset:8064
	ds_read_b128 v[0:3], v145 offset:0
	ds_read_b128 v[4:7], v145 offset:16
	ds_read_b128 v[8:11], v145 offset:32
	ds_read_b128 v[12:15], v145 offset:48
	ds_read_b128 v[16:19], v145 offset:64
	ds_read_b128 v[20:23], v145 offset:80
	ds_read_b128 v[24:27], v145 offset:96
	ds_read_b128 v[28:31], v145 offset:112
	s_waitcnt lgkmcnt(0)
	v_ashrrev_i32_e32 v212, 31, v0
	v_or_b32_e32 v212, 0x80000000, v212
	v_xor_b32_e32 v0, v0, v212
	v_and_or_b32 v0, v0, s30, 63
	v_ashrrev_i32_e32 v212, 31, v1
	v_or_b32_e32 v212, 0x80000000, v212
	v_xor_b32_e32 v1, v1, v212
	v_and_or_b32 v1, v1, s30, 62
	v_ashrrev_i32_e32 v212, 31, v2
	v_or_b32_e32 v212, 0x80000000, v212
	v_xor_b32_e32 v2, v2, v212
	v_and_or_b32 v2, v2, s30, 61
	v_ashrrev_i32_e32 v212, 31, v3
	v_or_b32_e32 v212, 0x80000000, v212
	v_xor_b32_e32 v3, v3, v212
	v_and_or_b32 v3, v3, s30, 60
	v_ashrrev_i32_e32 v212, 31, v4
	v_or_b32_e32 v212, 0x80000000, v212
	v_xor_b32_e32 v4, v4, v212
	v_and_or_b32 v4, v4, s30, 59
	v_ashrrev_i32_e32 v212, 31, v5
	v_or_b32_e32 v212, 0x80000000, v212
	v_xor_b32_e32 v5, v5, v212
	v_and_or_b32 v5, v5, s30, 58
	v_ashrrev_i32_e32 v212, 31, v6
	v_or_b32_e32 v212, 0x80000000, v212
	v_xor_b32_e32 v6, v6, v212
	v_and_or_b32 v6, v6, s30, 57
	v_ashrrev_i32_e32 v212, 31, v7
	v_or_b32_e32 v212, 0x80000000, v212
	v_xor_b32_e32 v7, v7, v212
	v_and_or_b32 v7, v7, s30, 56
	v_ashrrev_i32_e32 v212, 31, v8
	v_or_b32_e32 v212, 0x80000000, v212
	v_xor_b32_e32 v8, v8, v212
	v_and_or_b32 v8, v8, s30, 55
	v_ashrrev_i32_e32 v212, 31, v9
	v_or_b32_e32 v212, 0x80000000, v212
	v_xor_b32_e32 v9, v9, v212
	v_and_or_b32 v9, v9, s30, 54
	v_ashrrev_i32_e32 v212, 31, v10
	v_or_b32_e32 v212, 0x80000000, v212
	v_xor_b32_e32 v10, v10, v212
	v_and_or_b32 v10, v10, s30, 53
	v_ashrrev_i32_e32 v212, 31, v11
	v_or_b32_e32 v212, 0x80000000, v212
	v_xor_b32_e32 v11, v11, v212
	v_and_or_b32 v11, v11, s30, 52
	v_ashrrev_i32_e32 v212, 31, v12
	v_or_b32_e32 v212, 0x80000000, v212
	v_xor_b32_e32 v12, v12, v212
	v_and_or_b32 v12, v12, s30, 51
	v_ashrrev_i32_e32 v212, 31, v13
	v_or_b32_e32 v212, 0x80000000, v212
	v_xor_b32_e32 v13, v13, v212
	v_and_or_b32 v13, v13, s30, 50
	v_ashrrev_i32_e32 v212, 31, v14
	v_or_b32_e32 v212, 0x80000000, v212
	v_xor_b32_e32 v14, v14, v212
	v_and_or_b32 v14, v14, s30, 49
	v_ashrrev_i32_e32 v212, 31, v15
	v_or_b32_e32 v212, 0x80000000, v212
	v_xor_b32_e32 v15, v15, v212
	v_and_or_b32 v15, v15, s30, 48
	v_ashrrev_i32_e32 v212, 31, v16
	v_or_b32_e32 v212, 0x80000000, v212
	v_xor_b32_e32 v16, v16, v212
	v_and_or_b32 v16, v16, s30, 47
	v_ashrrev_i32_e32 v212, 31, v17
	v_or_b32_e32 v212, 0x80000000, v212
	v_xor_b32_e32 v17, v17, v212
	v_and_or_b32 v17, v17, s30, 46
	v_ashrrev_i32_e32 v212, 31, v18
	v_or_b32_e32 v212, 0x80000000, v212
	v_xor_b32_e32 v18, v18, v212
	v_and_or_b32 v18, v18, s30, 45
	v_ashrrev_i32_e32 v212, 31, v19
	v_or_b32_e32 v212, 0x80000000, v212
	v_xor_b32_e32 v19, v19, v212
	v_and_or_b32 v19, v19, s30, 44
	v_ashrrev_i32_e32 v212, 31, v20
	v_or_b32_e32 v212, 0x80000000, v212
	v_xor_b32_e32 v20, v20, v212
	v_and_or_b32 v20, v20, s30, 43
	v_ashrrev_i32_e32 v212, 31, v21
	v_or_b32_e32 v212, 0x80000000, v212
	v_xor_b32_e32 v21, v21, v212
	v_and_or_b32 v21, v21, s30, 42
	v_ashrrev_i32_e32 v212, 31, v22
	v_or_b32_e32 v212, 0x80000000, v212
	v_xor_b32_e32 v22, v22, v212
	v_and_or_b32 v22, v22, s30, 41
	v_ashrrev_i32_e32 v212, 31, v23
	v_or_b32_e32 v212, 0x80000000, v212
	v_xor_b32_e32 v23, v23, v212
	v_and_or_b32 v23, v23, s30, 40
	v_ashrrev_i32_e32 v212, 31, v24
	v_or_b32_e32 v212, 0x80000000, v212
	v_xor_b32_e32 v24, v24, v212
	v_and_or_b32 v24, v24, s30, 39
	v_ashrrev_i32_e32 v212, 31, v25
	v_or_b32_e32 v212, 0x80000000, v212
	v_xor_b32_e32 v25, v25, v212
	v_and_or_b32 v25, v25, s30, 38
	v_ashrrev_i32_e32 v212, 31, v26
	v_or_b32_e32 v212, 0x80000000, v212
	v_xor_b32_e32 v26, v26, v212
	v_and_or_b32 v26, v26, s30, 37
	v_ashrrev_i32_e32 v212, 31, v27
	v_or_b32_e32 v212, 0x80000000, v212
	v_xor_b32_e32 v27, v27, v212
	v_and_or_b32 v27, v27, s30, 36
	v_ashrrev_i32_e32 v212, 31, v28
	v_or_b32_e32 v212, 0x80000000, v212
	v_xor_b32_e32 v28, v28, v212
	v_and_or_b32 v28, v28, s30, 35
	v_ashrrev_i32_e32 v212, 31, v29
	v_or_b32_e32 v212, 0x80000000, v212
	v_xor_b32_e32 v29, v29, v212
	v_and_or_b32 v29, v29, s30, 34
	v_ashrrev_i32_e32 v212, 31, v30
	v_or_b32_e32 v212, 0x80000000, v212
	v_xor_b32_e32 v30, v30, v212
	v_and_or_b32 v30, v30, s30, 33
	v_ashrrev_i32_e32 v212, 31, v31
	v_or_b32_e32 v212, 0x80000000, v212
	v_xor_b32_e32 v31, v31, v212
	v_and_or_b32 v31, v31, s30, 32
	v_max_u32_e32 v215, v0, v1
	v_min_u32_e32 v1, v0, v1
	v_max_u32_e32 v214, v16, v17
	v_min_u32_e32 v17, v16, v17
	v_max_u32_e32 v213, v2, v3
	v_min_u32_e32 v3, v2, v3
	v_max_u32_e32 v0, v18, v19
	v_min_u32_e32 v19, v18, v19
	v_max_u32_e32 v16, v4, v5
	v_min_u32_e32 v5, v4, v5
	v_max_u32_e32 v2, v20, v21
	v_min_u32_e32 v21, v20, v21
	v_max_u32_e32 v18, v6, v7
	v_min_u32_e32 v7, v6, v7
	v_max_u32_e32 v4, v22, v23
	v_min_u32_e32 v23, v22, v23
	v_max_u32_e32 v20, v8, v9
	v_min_u32_e32 v9, v8, v9
	v_max_u32_e32 v6, v24, v25
	v_min_u32_e32 v25, v24, v25
	v_max_u32_e32 v22, v10, v11
	v_min_u32_e32 v11, v10, v11
	v_max_u32_e32 v8, v26, v27
	v_min_u32_e32 v27, v26, v27
	v_max_u32_e32 v24, v12, v13
	v_min_u32_e32 v13, v12, v13
	v_max_u32_e32 v10, v28, v29
	v_min_u32_e32 v29, v28, v29
; __device__ __forceinline__ unsigned f2key(float f) { const unsigned u = __float_as_uint(f); return (u & 0x80000000u) ? ~u : (u | 0x80000000u); }
; __device__ void ph_peer(const float* __restrict__ SC, const bf16_t* __restrict__ H  , const float* __restrict__ gffn, const unsigned char* __restrict__ U, const unsigned char* __restrict__ V, float* X, const float* __restrict__ fgain) {
;     ...
;             unsigned k00[2], k01[2], k10[2], k11[2], top0[2], top1[2];
; #pragma unroll
;             for (int u = 0; u < 2; ++u) { const float* sc = SC + (size_t)tok * 2048 + (h + u) * 256;
;                 const float2 a0 = ((const float2*)sc)[lane], a1 = ((const float2*)(sc + 128))[lane];
;                 k00[u] = (f2key(a0.x) & ~127u) | (unsigned)(127 - 2 * lane); k01[u] = (f2key(a0.y) & ~127u) | (unsigned)(126 - 2 * lane);
;                 k10[u] = (f2key(a1.x) & ~127u) | (unsigned)(127 - 2 * lane); k11[u] = (f2key(a1.y) & ~127u) | (unsigned)(126 - 2 * lane);
;                 top0[u] = 0u; top1[u] = 0u; }
;             for (int it = 0; it < 16; ++it) {
; #pragma unroll
;                 for (int u = 0; u < 2; ++u) {
;                     const unsigned m0 = wave_max_u32(k00[u] > k01[u] ? k00[u] : k01[u]);
;                     const unsigned m1 = wave_max_u32(k10[u] > k11[u] ? k10[u] : k11[u]);
;                     if (lane == it) { top0[u] = m0; top1[u] = m1; }
;                     if (k00[u] == m0) k00[u] = 0u; if (k01[u] == m0) k01[u] = 0u;
;                     if (k10[u] == m1) k10[u] = 0u; if (k11[u] == m1) k11[u] = 0u; }
;             }
	v_max_u32_e32 v26, v14, v15
	v_min_u32_e32 v15, v14, v15
	v_max_u32_e32 v12, v30, v31
	v_min_u32_e32 v31, v30, v31
	v_max_u32_e32 v28, v215, v213
	v_min_u32_e32 v213, v215, v213
	v_max_u32_e32 v14, v214, v0
	v_min_u32_e32 v0, v214, v0
	v_max_u32_e32 v30, v1, v3
	v_min_u32_e32 v3, v1, v3
	v_max_u32_e32 v215, v17, v19
	v_min_u32_e32 v19, v17, v19
	v_max_u32_e32 v214, v16, v18
	v_min_u32_e32 v18, v16, v18
	v_max_u32_e32 v1, v2, v4
	v_min_u32_e32 v4, v2, v4
	v_max_u32_e32 v17, v5, v7
	v_min_u32_e32 v7, v5, v7
	v_max_u32_e32 v16, v21, v23
	v_min_u32_e32 v23, v21, v23
	v_max_u32_e32 v2, v20, v22
	v_min_u32_e32 v22, v20, v22
	v_max_u32_e32 v5, v6, v8
	v_min_u32_e32 v8, v6, v8
	v_max_u32_e32 v21, v9, v11
	v_min_u32_e32 v11, v9, v11
	v_max_u32_e32 v20, v25, v27
	v_min_u32_e32 v27, v25, v27
	v_max_u32_e32 v6, v24, v26
	v_min_u32_e32 v26, v24, v26
	v_max_u32_e32 v9, v10, v12
	v_min_u32_e32 v12, v10, v12
	v_max_u32_e32 v25, v13, v15
	v_min_u32_e32 v15, v13, v15
	v_max_u32_e32 v24, v29, v31
	v_min_u32_e32 v31, v29, v31
	v_max_u32_e32 v10, v30, v213
	v_min_u32_e32 v213, v30, v213
	v_max_u32_e32 v13, v215, v0
	v_min_u32_e32 v0, v215, v0
	v_max_u32_e32 v29, v17, v18
	v_min_u32_e32 v18, v17, v18
	v_max_u32_e32 v30, v16, v4
	v_min_u32_e32 v4, v16, v4
	v_max_u32_e32 v215, v21, v22
	v_min_u32_e32 v22, v21, v22
	v_max_u32_e32 v17, v20, v8
	v_min_u32_e32 v8, v20, v8
	v_max_u32_e32 v16, v25, v26
	v_min_u32_e32 v26, v25, v26
	v_max_u32_e32 v21, v24, v12
	v_min_u32_e32 v12, v24, v12
	v_max_u32_e32 v20, v28, v214
	v_min_u32_e32 v214, v28, v214
	v_max_u32_e32 v25, v14, v1
	v_min_u32_e32 v1, v14, v1
	v_max_u32_e32 v24, v10, v29
	v_min_u32_e32 v29, v10, v29
	v_max_u32_e32 v28, v13, v30
	v_min_u32_e32 v30, v13, v30
	v_max_u32_e32 v14, v213, v18
	v_min_u32_e32 v18, v213, v18
	v_max_u32_e32 v10, v0, v4
	v_min_u32_e32 v4, v0, v4
	v_max_u32_e32 v13, v3, v7
	v_min_u32_e32 v7, v3, v7
	v_max_u32_e32 v213, v19, v23
	v_min_u32_e32 v23, v19, v23
	v_max_u32_e32 v0, v2, v6
	v_min_u32_e32 v6, v2, v6
	v_max_u32_e32 v3, v5, v9
	v_min_u32_e32 v9, v5, v9
	v_max_u32_e32 v19, v215, v16
	v_min_u32_e32 v16, v215, v16
	v_max_u32_e32 v2, v17, v21
	v_min_u32_e32 v21, v17, v21
	v_max_u32_e32 v5, v22, v26
	v_min_u32_e32 v26, v22, v26
	v_max_u32_e32 v215, v8, v12
	v_min_u32_e32 v12, v8, v12
	v_max_u32_e32 v17, v11, v15
	v_min_u32_e32 v15, v11, v15
	v_max_u32_e32 v22, v27, v31
	v_min_u32_e32 v31, v27, v31
	v_max_u32_e32 v8, v14, v214
	v_min_u32_e32 v214, v14, v214
	v_max_u32_e32 v11, v10, v1
	v_min_u32_e32 v1, v10, v1
	v_max_u32_e32 v27, v13, v29
	v_min_u32_e32 v29, v13, v29
	v_max_u32_e32 v14, v213, v30
	v_min_u32_e32 v30, v213, v30
	v_max_u32_e32 v10, v5, v6
	v_min_u32_e32 v6, v5, v6
	v_max_u32_e32 v13, v215, v9
	v_min_u32_e32 v9, v215, v9
	v_max_u32_e32 v213, v17, v16
	v_min_u32_e32 v16, v17, v16
	v_max_u32_e32 v5, v22, v21
	v_min_u32_e32 v21, v22, v21
	v_max_u32_e32 v215, v24, v8
	v_min_u32_e32 v8, v24, v8
	v_max_u32_e32 v17, v28, v11
	v_min_u32_e32 v11, v28, v11
	v_max_u32_e32 v22, v27, v214
	v_min_u32_e32 v214, v27, v214
	v_max_u32_e32 v24, v14, v1
	v_min_u32_e32 v1, v14, v1
	v_max_u32_e32 v28, v29, v18
	v_min_u32_e32 v18, v29, v18
	v_max_u32_e32 v27, v30, v4
	v_min_u32_e32 v4, v30, v4
	v_max_u32_e32 v14, v19, v10
	v_min_u32_e32 v10, v19, v10
	v_max_u32_e32 v29, v2, v13
	v_min_u32_e32 v13, v2, v13
	v_max_u32_e32 v30, v213, v6
	v_min_u32_e32 v6, v213, v6
	v_max_u32_e32 v19, v5, v9
	v_min_u32_e32 v9, v5, v9
	v_max_u32_e32 v2, v16, v26
	v_min_u32_e32 v26, v16, v26
	v_max_u32_e32 v213, v21, v12
	v_min_u32_e32 v12, v21, v12
	v_max_u32_e32 v5, v20, v0
	v_min_u32_e32 v0, v20, v0
	v_max_u32_e32 v16, v25, v3
	v_min_u32_e32 v3, v25, v3
	v_max_u32_e32 v21, v215, v14
	v_min_u32_e32 v14, v215, v14
	v_max_u32_e32 v20, v17, v29
	v_min_u32_e32 v29, v17, v29
	v_max_u32_e32 v25, v8, v10
	v_min_u32_e32 v10, v8, v10
	v_max_u32_e32 v215, v11, v13
	v_min_u32_e32 v13, v11, v13
	v_max_u32_e32 v17, v22, v30
	v_min_u32_e32 v30, v22, v30
	v_max_u32_e32 v8, v24, v19
	v_min_u32_e32 v19, v24, v19
	v_max_u32_e32 v11, v214, v6
	v_min_u32_e32 v6, v214, v6
	v_max_u32_e32 v22, v1, v9
	v_min_u32_e32 v9, v1, v9
	v_max_u32_e32 v24, v28, v2
	v_min_u32_e32 v2, v28, v2
	v_max_u32_e32 v214, v27, v213
	v_min_u32_e32 v213, v27, v213
	v_max_u32_e32 v1, v18, v26
	v_min_u32_e32 v26, v18, v26
	v_max_u32_e32 v28, v4, v12
	v_min_u32_e32 v12, v4, v12
	v_max_u32_e32 v27, v7, v15
	v_min_u32_e32 v15, v7, v15
	v_max_u32_e32 v18, v23, v31
	v_min_u32_e32 v31, v23, v31
	v_max_u32_e32 v4, v11, v0
	v_min_u32_e32 v0, v11, v0
	v_max_u32_e32 v7, v22, v3
	v_min_u32_e32 v3, v22, v3
	v_max_u32_e32 v23, v24, v14
	v_min_u32_e32 v14, v24, v14
	v_max_u32_e32 v11, v214, v29
	v_min_u32_e32 v29, v214, v29
	v_max_u32_e32 v22, v1, v10
	v_min_u32_e32 v10, v1, v10
	v_max_u32_e32 v24, v28, v13
	v_min_u32_e32 v13, v28, v13
	v_max_u32_e32 v214, v27, v30
	v_min_u32_e32 v30, v27, v30
	v_max_u32_e32 v1, v18, v19
	v_min_u32_e32 v19, v18, v19
	v_max_u32_e32 v28, v25, v4
	v_min_u32_e32 v4, v25, v4
	v_max_u32_e32 v27, v215, v7
	v_min_u32_e32 v7, v215, v7
	v_max_u32_e32 v18, v17, v23
	v_min_u32_e32 v23, v17, v23
	v_max_u32_e32 v25, v8, v11
	v_min_u32_e32 v11, v8, v11
	v_max_u32_e32 v215, v22, v0
	v_min_u32_e32 v0, v22, v0
	v_max_u32_e32 v17, v24, v3
	v_min_u32_e32 v3, v24, v3
	v_max_u32_e32 v8, v214, v14
	v_min_u32_e32 v14, v214, v14
	v_max_u32_e32 v22, v1, v29
	v_min_u32_e32 v29, v1, v29
	v_max_u32_e32 v24, v10, v6
	v_min_u32_e32 v6, v10, v6
	v_max_u32_e32 v214, v13, v9
	v_min_u32_e32 v9, v13, v9
	v_max_u32_e32 v1, v30, v2
	v_min_u32_e32 v2, v30, v2
	v_max_u32_e32 v10, v19, v213
	v_min_u32_e32 v213, v19, v213
	v_max_u32_e32 v13, v21, v28
	v_min_u32_e32 v28, v21, v28
; __device__ __forceinline__ unsigned f2key(float f) { const unsigned u = __float_as_uint(f); return (u & 0x80000000u) ? ~u : (u | 0x80000000u); }
; __device__ void ph_peer(const float* __restrict__ SC, const bf16_t* __restrict__ H  , const float* __restrict__ gffn, const unsigned char* __restrict__ U, const unsigned char* __restrict__ V, float* X, const float* __restrict__ fgain) {
;     ...
;             unsigned k00[2], k01[2], k10[2], k11[2], top0[2], top1[2];
; #pragma unroll
;             for (int u = 0; u < 2; ++u) { const float* sc = SC + (size_t)tok * 2048 + (h + u) * 256;
;                 const float2 a0 = ((const float2*)sc)[lane], a1 = ((const float2*)(sc + 128))[lane];
;                 k00[u] = (f2key(a0.x) & ~127u) | (unsigned)(127 - 2 * lane); k01[u] = (f2key(a0.y) & ~127u) | (unsigned)(126 - 2 * lane);
;                 k10[u] = (f2key(a1.x) & ~127u) | (unsigned)(127 - 2 * lane); k11[u] = (f2key(a1.y) & ~127u) | (unsigned)(126 - 2 * lane);
;                 top0[u] = 0u; top1[u] = 0u; }
;             for (int it = 0; it < 16; ++it) {
; #pragma unroll
;                 for (int u = 0; u < 2; ++u) {
;                     const unsigned m0 = wave_max_u32(k00[u] > k01[u] ? k00[u] : k01[u]);
;                     const unsigned m1 = wave_max_u32(k10[u] > k11[u] ? k10[u] : k11[u]);
;                     if (lane == it) { top0[u] = m0; top1[u] = m1; }
;                     if (k00[u] == m0) k00[u] = 0u; if (k01[u] == m0) k01[u] = 0u;
;                     if (k10[u] == m1) k10[u] = 0u; if (k11[u] == m1) k11[u] = 0u; }
;             }
	v_max_u32_e32 v30, v20, v27
	v_min_u32_e32 v27, v20, v27
	v_max_u32_e32 v19, v18, v4
	v_min_u32_e32 v4, v18, v4
	v_max_u32_e32 v21, v25, v7
	v_min_u32_e32 v7, v25, v7
	v_max_u32_e32 v20, v23, v215
	v_min_u32_e32 v215, v23, v215
	v_max_u32_e32 v18, v11, v17
	v_min_u32_e32 v17, v11, v17
	v_max_u32_e32 v25, v8, v0
	v_min_u32_e32 v0, v8, v0
	v_max_u32_e32 v23, v22, v3
	v_min_u32_e32 v3, v22, v3
	v_max_u32_e32 v11, v14, v24
	v_min_u32_e32 v24, v14, v24
	v_max_u32_e32 v8, v29, v214
	v_min_u32_e32 v214, v29, v214
	v_max_u32_e32 v22, v1, v6
	v_min_u32_e32 v6, v1, v6
	v_max_u32_e32 v14, v10, v9
	v_min_u32_e32 v9, v10, v9
	v_max_u32_e32 v29, v2, v26
	v_min_u32_e32 v26, v2, v26
	v_max_u32_e32 v1, v213, v12
	v_min_u32_e32 v12, v213, v12
	v_max_u32_e32 v45, v42, v15
	v_max_u32_e32 v35, v32, v26
	v_max_u32_e32 v39, v37, v29
	v_max_u32_e32 v38, v48, v6
	v_max_u32_e32 v42, v43, v22
	v_max_u32_e32 v32, v41, v24
	v_max_u32_e32 v37, v46, v11
	v_max_u32_e32 v48, v49, v0
	v_max_u32_e32 v43, v47, v25
	v_max_u32_e32 v41, v44, v215
	v_max_u32_e32 v46, v34, v20
	v_max_u32_e32 v49, v36, v4
	v_max_u32_e32 v47, v50, v19
	v_max_u32_e32 v44, v33, v28
	v_max_u32_e32 v34, v51, v13
	v_max_u32_e32 v36, v40, v5
	v_max_u32_e32 v50, v45, v43
	v_min_u32_e32 v43, v45, v43
	v_max_u32_e32 v33, v35, v41
	v_min_u32_e32 v41, v35, v41
	v_max_u32_e32 v51, v39, v46
	v_min_u32_e32 v46, v39, v46
	v_max_u32_e32 v40, v38, v49
	v_min_u32_e32 v49, v38, v49
	v_max_u32_e32 v45, v42, v47
	v_min_u32_e32 v47, v42, v47
	v_max_u32_e32 v35, v32, v44
	v_min_u32_e32 v44, v32, v44
	v_max_u32_e32 v39, v37, v34
	v_min_u32_e32 v34, v37, v34
	v_max_u32_e32 v38, v48, v36
	v_min_u32_e32 v36, v48, v36
	v_max_u32_e32 v42, v50, v45
	v_min_u32_e32 v45, v50, v45
	v_max_u32_e32 v32, v33, v35
	v_min_u32_e32 v35, v33, v35
	v_max_u32_e32 v37, v51, v39
	v_min_u32_e32 v39, v51, v39
	v_max_u32_e32 v48, v40, v38
	v_min_u32_e32 v38, v40, v38
	v_max_u32_e32 v50, v43, v47
	v_min_u32_e32 v47, v43, v47
	v_max_u32_e32 v33, v41, v44
	v_min_u32_e32 v44, v41, v44
	v_max_u32_e32 v51, v46, v34
	v_min_u32_e32 v34, v46, v34
	v_max_u32_e32 v40, v49, v36
	v_min_u32_e32 v36, v49, v36
	v_max_u32_e32 v43, v42, v37
	v_min_u32_e32 v37, v42, v37
	v_max_u32_e32 v41, v32, v48
	v_min_u32_e32 v48, v32, v48
	v_max_u32_e32 v46, v45, v39
	v_min_u32_e32 v39, v45, v39
	v_max_u32_e32 v49, v35, v38
	v_min_u32_e32 v38, v35, v38
	v_max_u32_e32 v42, v50, v51
	v_min_u32_e32 v51, v50, v51
	v_max_u32_e32 v32, v33, v40
	v_min_u32_e32 v40, v33, v40
	v_max_u32_e32 v45, v47, v34
	v_min_u32_e32 v34, v47, v34
	v_max_u32_e32 v35, v44, v36
	v_min_u32_e32 v36, v44, v36
	v_max_u32_e32 v50, v43, v41
	v_min_u32_e32 v41, v43, v41
	v_max_u32_e32 v33, v37, v48
	v_min_u32_e32 v48, v37, v48
	v_max_u32_e32 v47, v46, v49
	v_min_u32_e32 v49, v46, v49
	v_max_u32_e32 v44, v39, v38
	v_min_u32_e32 v38, v39, v38
	v_max_u32_e32 v43, v42, v32
	v_min_u32_e32 v32, v42, v32
	v_max_u32_e32 v37, v51, v40
	v_min_u32_e32 v40, v51, v40
	v_max_u32_e32 v46, v45, v35
	v_min_u32_e32 v35, v45, v35
	v_max_u32_e32 v39, v34, v36
	v_min_u32_e32 v36, v34, v36
	v_max_u32_e32 v42, v50, v31
	v_max_u32_e32 v51, v41, v12
	v_max_u32_e32 v45, v33, v1
	v_max_u32_e32 v34, v48, v9
	v_max_u32_e32 v50, v47, v14
	v_max_u32_e32 v41, v49, v214
	v_max_u32_e32 v33, v44, v8
	v_max_u32_e32 v48, v38, v3
	v_max_u32_e32 v47, v43, v23
	v_max_u32_e32 v49, v32, v17
	v_max_u32_e32 v44, v37, v18
	v_max_u32_e32 v38, v40, v7
	v_max_u32_e32 v43, v46, v21
	v_max_u32_e32 v32, v35, v27
	v_max_u32_e32 v37, v39, v30
	v_max_u32_e32 v40, v36, v16
	v_max_u32_e32 v46, v42, v47
	v_min_u32_e32 v47, v42, v47
	v_max_u32_e32 v35, v51, v49
	v_min_u32_e32 v49, v51, v49
	v_max_u32_e32 v39, v45, v44
	v_min_u32_e32 v44, v45, v44
	v_max_u32_e32 v36, v34, v38
	v_min_u32_e32 v38, v34, v38
	v_max_u32_e32 v42, v50, v43
	v_min_u32_e32 v43, v50, v43
	v_max_u32_e32 v51, v41, v32
	v_min_u32_e32 v32, v41, v32
	v_max_u32_e32 v45, v33, v37
	v_min_u32_e32 v37, v33, v37
	v_max_u32_e32 v34, v48, v40
	v_min_u32_e32 v40, v48, v40
	v_max_u32_e32 v50, v46, v42
	v_min_u32_e32 v42, v46, v42
	v_max_u32_e32 v41, v35, v51
	v_min_u32_e32 v51, v35, v51
	v_max_u32_e32 v33, v39, v45
	v_min_u32_e32 v45, v39, v45
	v_max_u32_e32 v48, v36, v34
	v_min_u32_e32 v34, v36, v34
	v_max_u32_e32 v46, v47, v43
	v_min_u32_e32 v43, v47, v43
	v_max_u32_e32 v35, v49, v32
	v_min_u32_e32 v32, v49, v32
	v_max_u32_e32 v39, v44, v37
	v_min_u32_e32 v37, v44, v37
	v_max_u32_e32 v36, v38, v40
	v_min_u32_e32 v40, v38, v40
	v_max_u32_e32 v47, v50, v33
	v_min_u32_e32 v33, v50, v33
	v_max_u32_e32 v49, v41, v48
	v_min_u32_e32 v48, v41, v48
	v_max_u32_e32 v44, v42, v45
	v_min_u32_e32 v45, v42, v45
	v_max_u32_e32 v38, v51, v34
	v_min_u32_e32 v34, v51, v34
	v_max_u32_e32 v50, v46, v39
	v_min_u32_e32 v39, v46, v39
	v_max_u32_e32 v41, v35, v36
	v_min_u32_e32 v36, v35, v36
	v_max_u32_e32 v42, v43, v37
	v_min_u32_e32 v37, v43, v37
	v_max_u32_e32 v51, v32, v40
	v_min_u32_e32 v40, v32, v40
	v_max_u32_e32 v46, v47, v49
	v_min_u32_e32 v49, v47, v49
	v_max_u32_e32 v35, v33, v48
	v_min_u32_e32 v48, v33, v48
	v_max_u32_e32 v43, v44, v38
	v_min_u32_e32 v38, v44, v38
	v_max_u32_e32 v32, v45, v34
	v_min_u32_e32 v34, v45, v34
	v_max_u32_e32 v47, v50, v41
	v_min_u32_e32 v41, v50, v41
	v_max_u32_e32 v33, v39, v36
	v_min_u32_e32 v36, v39, v36
	v_max_u32_e32 v44, v42, v51
	v_min_u32_e32 v51, v42, v51
	v_max_u32_e32 v45, v37, v40
	v_min_u32_e32 v40, v37, v40
	v_mov_b32_e32 v217, v216
	global_load_dwordx4 v[180:183], v217, s[28:29] offset:512
	v_add_u32_e32 v157, s36, v217
	global_load_dwordx4 v[184:187], v157, s[28:29] offset:512
	v_add_u32_e32 v217, s36, v157
	global_load_dwordx4 v[188:191], v217, s[28:29] offset:512
	v_add_u32_e32 v157, s36, v217
	global_load_dwordx4 v[192:195], v157, s[28:29] offset:512
	v_add_u32_e32 v217, s36, v157
	global_load_dwordx4 v[196:199], v217, s[28:29] offset:512
	v_add_u32_e32 v157, s36, v217
	global_load_dwordx4 v[200:203], v157, s[28:29] offset:512
	v_add_u32_e32 v217, s36, v157
	global_load_dwordx4 v[204:207], v217, s[28:29] offset:512
	v_add_u32_e32 v157, s36, v217
	global_load_dwordx4 v[208:211], v157, s[28:29] offset:512
	s_waitcnt vmcnt(8)
; __device__ __forceinline__ unsigned f2key(float f) { const unsigned u = __float_as_uint(f); return (u & 0x80000000u) ? ~u : (u | 0x80000000u); }
; __device__ void ph_peer(const float* __restrict__ SC, const bf16_t* __restrict__ H  , const float* __restrict__ gffn, const unsigned char* __restrict__ U, const unsigned char* __restrict__ V, float* X, const float* __restrict__ fgain) {
;     ...
;             unsigned k00[2], k01[2], k10[2], k11[2], top0[2], top1[2];
; #pragma unroll
;             for (int u = 0; u < 2; ++u) { const float* sc = SC + (size_t)tok * 2048 + (h + u) * 256;
;                 const float2 a0 = ((const float2*)sc)[lane], a1 = ((const float2*)(sc + 128))[lane];
;                 k00[u] = (f2key(a0.x) & ~127u) | (unsigned)(127 - 2 * lane); k01[u] = (f2key(a0.y) & ~127u) | (unsigned)(126 - 2 * lane);
;                 k10[u] = (f2key(a1.x) & ~127u) | (unsigned)(127 - 2 * lane); k11[u] = (f2key(a1.y) & ~127u) | (unsigned)(126 - 2 * lane);
;                 top0[u] = 0u; top1[u] = 0u; }
;             for (int it = 0; it < 16; ++it) {
; #pragma unroll
;                 for (int u = 0; u < 2; ++u) {
;                     const unsigned m0 = wave_max_u32(k00[u] > k01[u] ? k00[u] : k01[u]);
;                     const unsigned m1 = wave_max_u32(k10[u] > k11[u] ? k10[u] : k11[u]);
;                     if (lane == it) { top0[u] = m0; top1[u] = m1; }
;                     if (k00[u] == m0) k00[u] = 0u; if (k01[u] == m0) k01[u] = 0u;
;                     if (k10[u] == m1) k10[u] = 0u; if (k11[u] == m1) k11[u] = 0u; }
;             }
	ds_write_b128 v144, v[52:55] offset:0
	ds_write_b128 v144, v[56:59] offset:1152
	ds_write_b128 v144, v[60:63] offset:2304
	ds_write_b128 v144, v[112:115] offset:3456
	ds_write_b128 v144, v[116:119] offset:4608
	ds_write_b128 v144, v[120:123] offset:5760
	ds_write_b128 v144, v[124:127] offset:6912
	ds_write_b128 v144, v[158:161] offset:8064
	ds_read_b128 v[0:3], v145 offset:0
	ds_read_b128 v[4:7], v145 offset:16
	ds_read_b128 v[8:11], v145 offset:32
	ds_read_b128 v[12:15], v145 offset:48
	ds_read_b128 v[16:19], v145 offset:64
	ds_read_b128 v[20:23], v145 offset:80
	ds_read_b128 v[24:27], v145 offset:96
	ds_read_b128 v[28:31], v145 offset:112
	s_waitcnt lgkmcnt(0)
	v_ashrrev_i32_e32 v212, 31, v0
	v_or_b32_e32 v212, 0x80000000, v212
	v_xor_b32_e32 v0, v0, v212
	v_and_or_b32 v0, v0, s30, 31
	v_ashrrev_i32_e32 v212, 31, v1
	v_or_b32_e32 v212, 0x80000000, v212
	v_xor_b32_e32 v1, v1, v212
	v_and_or_b32 v1, v1, s30, 30
	v_ashrrev_i32_e32 v212, 31, v2
	v_or_b32_e32 v212, 0x80000000, v212
	v_xor_b32_e32 v2, v2, v212
	v_and_or_b32 v2, v2, s30, 29
	v_ashrrev_i32_e32 v212, 31, v3
	v_or_b32_e32 v212, 0x80000000, v212
	v_xor_b32_e32 v3, v3, v212
	v_and_or_b32 v3, v3, s30, 28
	v_ashrrev_i32_e32 v212, 31, v4
	v_or_b32_e32 v212, 0x80000000, v212
	v_xor_b32_e32 v4, v4, v212
	v_and_or_b32 v4, v4, s30, 27
	v_ashrrev_i32_e32 v212, 31, v5
	v_or_b32_e32 v212, 0x80000000, v212
	v_xor_b32_e32 v5, v5, v212
	v_and_or_b32 v5, v5, s30, 26
	v_ashrrev_i32_e32 v212, 31, v6
	v_or_b32_e32 v212, 0x80000000, v212
	v_xor_b32_e32 v6, v6, v212
	v_and_or_b32 v6, v6, s30, 25
	v_ashrrev_i32_e32 v212, 31, v7
	v_or_b32_e32 v212, 0x80000000, v212
	v_xor_b32_e32 v7, v7, v212
	v_and_or_b32 v7, v7, s30, 24
	v_ashrrev_i32_e32 v212, 31, v8
	v_or_b32_e32 v212, 0x80000000, v212
	v_xor_b32_e32 v8, v8, v212
	v_and_or_b32 v8, v8, s30, 23
	v_ashrrev_i32_e32 v212, 31, v9
	v_or_b32_e32 v212, 0x80000000, v212
	v_xor_b32_e32 v9, v9, v212
	v_and_or_b32 v9, v9, s30, 22
	v_ashrrev_i32_e32 v212, 31, v10
	v_or_b32_e32 v212, 0x80000000, v212
	v_xor_b32_e32 v10, v10, v212
	v_and_or_b32 v10, v10, s30, 21
	v_ashrrev_i32_e32 v212, 31, v11
	v_or_b32_e32 v212, 0x80000000, v212
	v_xor_b32_e32 v11, v11, v212
	v_and_or_b32 v11, v11, s30, 20
	v_ashrrev_i32_e32 v212, 31, v12
	v_or_b32_e32 v212, 0x80000000, v212
	v_xor_b32_e32 v12, v12, v212
	v_and_or_b32 v12, v12, s30, 19
	v_ashrrev_i32_e32 v212, 31, v13
	v_or_b32_e32 v212, 0x80000000, v212
	v_xor_b32_e32 v13, v13, v212
	v_and_or_b32 v13, v13, s30, 18
	v_ashrrev_i32_e32 v212, 31, v14
	v_or_b32_e32 v212, 0x80000000, v212
	v_xor_b32_e32 v14, v14, v212
	v_and_or_b32 v14, v14, s30, 17
	v_ashrrev_i32_e32 v212, 31, v15
	v_or_b32_e32 v212, 0x80000000, v212
	v_xor_b32_e32 v15, v15, v212
	v_and_or_b32 v15, v15, s30, 16
	v_ashrrev_i32_e32 v212, 31, v16
	v_or_b32_e32 v212, 0x80000000, v212
	v_xor_b32_e32 v16, v16, v212
	v_and_or_b32 v16, v16, s30, 15
	v_ashrrev_i32_e32 v212, 31, v17
	v_or_b32_e32 v212, 0x80000000, v212
	v_xor_b32_e32 v17, v17, v212
	v_and_or_b32 v17, v17, s30, 14
	v_ashrrev_i32_e32 v212, 31, v18
	v_or_b32_e32 v212, 0x80000000, v212
	v_xor_b32_e32 v18, v18, v212
	v_and_or_b32 v18, v18, s30, 13
	v_ashrrev_i32_e32 v212, 31, v19
	v_or_b32_e32 v212, 0x80000000, v212
	v_xor_b32_e32 v19, v19, v212
	v_and_or_b32 v19, v19, s30, 12
	v_ashrrev_i32_e32 v212, 31, v20
	v_or_b32_e32 v212, 0x80000000, v212
	v_xor_b32_e32 v20, v20, v212
	v_and_or_b32 v20, v20, s30, 11
	v_ashrrev_i32_e32 v212, 31, v21
	v_or_b32_e32 v212, 0x80000000, v212
	v_xor_b32_e32 v21, v21, v212
	v_and_or_b32 v21, v21, s30, 10
	v_ashrrev_i32_e32 v212, 31, v22
	v_or_b32_e32 v212, 0x80000000, v212
	v_xor_b32_e32 v22, v22, v212
	v_and_or_b32 v22, v22, s30, 9
	v_ashrrev_i32_e32 v212, 31, v23
	v_or_b32_e32 v212, 0x80000000, v212
	v_xor_b32_e32 v23, v23, v212
	v_and_or_b32 v23, v23, s30, 8
	v_ashrrev_i32_e32 v212, 31, v24
	v_or_b32_e32 v212, 0x80000000, v212
	v_xor_b32_e32 v24, v24, v212
	v_and_or_b32 v24, v24, s30, 7
	v_ashrrev_i32_e32 v212, 31, v25
	v_or_b32_e32 v212, 0x80000000, v212
	v_xor_b32_e32 v25, v25, v212
	v_and_or_b32 v25, v25, s30, 6
	v_ashrrev_i32_e32 v212, 31, v26
	v_or_b32_e32 v212, 0x80000000, v212
	v_xor_b32_e32 v26, v26, v212
	v_and_or_b32 v26, v26, s30, 5
	v_ashrrev_i32_e32 v212, 31, v27
	v_or_b32_e32 v212, 0x80000000, v212
	v_xor_b32_e32 v27, v27, v212
	v_and_or_b32 v27, v27, s30, 4
	v_ashrrev_i32_e32 v212, 31, v28
	v_or_b32_e32 v212, 0x80000000, v212
	v_xor_b32_e32 v28, v28, v212
	v_and_or_b32 v28, v28, s30, 3
	v_ashrrev_i32_e32 v212, 31, v29
	v_or_b32_e32 v212, 0x80000000, v212
	v_xor_b32_e32 v29, v29, v212
	v_and_or_b32 v29, v29, s30, 2
	v_ashrrev_i32_e32 v212, 31, v30
	v_or_b32_e32 v212, 0x80000000, v212
	v_xor_b32_e32 v30, v30, v212
	v_and_or_b32 v30, v30, s30, 1
	v_ashrrev_i32_e32 v212, 31, v31
	v_or_b32_e32 v212, 0x80000000, v212
	v_xor_b32_e32 v31, v31, v212
	v_and_or_b32 v31, v31, s30, 0
	v_max_u32_e32 v215, v0, v1
	v_min_u32_e32 v1, v0, v1
	v_max_u32_e32 v214, v16, v17
	v_min_u32_e32 v17, v16, v17
	v_max_u32_e32 v213, v2, v3
	v_min_u32_e32 v3, v2, v3
	v_max_u32_e32 v0, v18, v19
	v_min_u32_e32 v19, v18, v19
	v_max_u32_e32 v16, v4, v5
	v_min_u32_e32 v5, v4, v5
	v_max_u32_e32 v2, v20, v21
	v_min_u32_e32 v21, v20, v21
	v_max_u32_e32 v18, v6, v7
	v_min_u32_e32 v7, v6, v7
	v_max_u32_e32 v4, v22, v23
	v_min_u32_e32 v23, v22, v23
	v_max_u32_e32 v20, v8, v9
	v_min_u32_e32 v9, v8, v9
	v_max_u32_e32 v6, v24, v25
	v_min_u32_e32 v25, v24, v25
	v_max_u32_e32 v22, v10, v11
	v_min_u32_e32 v11, v10, v11
	v_max_u32_e32 v8, v26, v27
	v_min_u32_e32 v27, v26, v27
	v_max_u32_e32 v24, v12, v13
	v_min_u32_e32 v13, v12, v13
	v_max_u32_e32 v10, v28, v29
	v_min_u32_e32 v29, v28, v29
	v_max_u32_e32 v26, v14, v15
; __device__ __forceinline__ unsigned f2key(float f) { const unsigned u = __float_as_uint(f); return (u & 0x80000000u) ? ~u : (u | 0x80000000u); }
; __device__ void ph_peer(const float* __restrict__ SC, const bf16_t* __restrict__ H  , const float* __restrict__ gffn, const unsigned char* __restrict__ U, const unsigned char* __restrict__ V, float* X, const float* __restrict__ fgain) {
;     ...
;             unsigned k00[2], k01[2], k10[2], k11[2], top0[2], top1[2];
; #pragma unroll
;             for (int u = 0; u < 2; ++u) { const float* sc = SC + (size_t)tok * 2048 + (h + u) * 256;
;                 const float2 a0 = ((const float2*)sc)[lane], a1 = ((const float2*)(sc + 128))[lane];
;                 k00[u] = (f2key(a0.x) & ~127u) | (unsigned)(127 - 2 * lane); k01[u] = (f2key(a0.y) & ~127u) | (unsigned)(126 - 2 * lane);
;                 k10[u] = (f2key(a1.x) & ~127u) | (unsigned)(127 - 2 * lane); k11[u] = (f2key(a1.y) & ~127u) | (unsigned)(126 - 2 * lane);
;                 top0[u] = 0u; top1[u] = 0u; }
;             for (int it = 0; it < 16; ++it) {
; #pragma unroll
;                 for (int u = 0; u < 2; ++u) {
;                     const unsigned m0 = wave_max_u32(k00[u] > k01[u] ? k00[u] : k01[u]);
;                     const unsigned m1 = wave_max_u32(k10[u] > k11[u] ? k10[u] : k11[u]);
;                     if (lane == it) { top0[u] = m0; top1[u] = m1; }
;                     if (k00[u] == m0) k00[u] = 0u; if (k01[u] == m0) k01[u] = 0u;
;                     if (k10[u] == m1) k10[u] = 0u; if (k11[u] == m1) k11[u] = 0u; }
;             }
	v_min_u32_e32 v15, v14, v15
	v_max_u32_e32 v12, v30, v31
	v_min_u32_e32 v31, v30, v31
	v_max_u32_e32 v28, v215, v213
	v_min_u32_e32 v213, v215, v213
	v_max_u32_e32 v14, v214, v0
	v_min_u32_e32 v0, v214, v0
	v_max_u32_e32 v30, v1, v3
	v_min_u32_e32 v3, v1, v3
	v_max_u32_e32 v215, v17, v19
	v_min_u32_e32 v19, v17, v19
	v_max_u32_e32 v214, v16, v18
	v_min_u32_e32 v18, v16, v18
	v_max_u32_e32 v1, v2, v4
	v_min_u32_e32 v4, v2, v4
	v_max_u32_e32 v17, v5, v7
	v_min_u32_e32 v7, v5, v7
	v_max_u32_e32 v16, v21, v23
	v_min_u32_e32 v23, v21, v23
	v_max_u32_e32 v2, v20, v22
	v_min_u32_e32 v22, v20, v22
	v_max_u32_e32 v5, v6, v8
	v_min_u32_e32 v8, v6, v8
	v_max_u32_e32 v21, v9, v11
	v_min_u32_e32 v11, v9, v11
	v_max_u32_e32 v20, v25, v27
	v_min_u32_e32 v27, v25, v27
	v_max_u32_e32 v6, v24, v26
	v_min_u32_e32 v26, v24, v26
	v_max_u32_e32 v9, v10, v12
	v_min_u32_e32 v12, v10, v12
	v_max_u32_e32 v25, v13, v15
	v_min_u32_e32 v15, v13, v15
	v_max_u32_e32 v24, v29, v31
	v_min_u32_e32 v31, v29, v31
	v_max_u32_e32 v10, v30, v213
	v_min_u32_e32 v213, v30, v213
	v_max_u32_e32 v13, v215, v0
	v_min_u32_e32 v0, v215, v0
	v_max_u32_e32 v29, v17, v18
	v_min_u32_e32 v18, v17, v18
	v_max_u32_e32 v30, v16, v4
	v_min_u32_e32 v4, v16, v4
	v_max_u32_e32 v215, v21, v22
	v_min_u32_e32 v22, v21, v22
	v_max_u32_e32 v17, v20, v8
	v_min_u32_e32 v8, v20, v8
	v_max_u32_e32 v16, v25, v26
	v_min_u32_e32 v26, v25, v26
	v_max_u32_e32 v21, v24, v12
	v_min_u32_e32 v12, v24, v12
	v_max_u32_e32 v20, v28, v214
	v_min_u32_e32 v214, v28, v214
	v_max_u32_e32 v25, v14, v1
	v_min_u32_e32 v1, v14, v1
	v_max_u32_e32 v24, v10, v29
	v_min_u32_e32 v29, v10, v29
	v_max_u32_e32 v28, v13, v30
	v_min_u32_e32 v30, v13, v30
	v_max_u32_e32 v14, v213, v18
	v_min_u32_e32 v18, v213, v18
	v_max_u32_e32 v10, v0, v4
	v_min_u32_e32 v4, v0, v4
	v_max_u32_e32 v13, v3, v7
	v_min_u32_e32 v7, v3, v7
	v_max_u32_e32 v213, v19, v23
	v_min_u32_e32 v23, v19, v23
	v_max_u32_e32 v0, v2, v6
	v_min_u32_e32 v6, v2, v6
	v_max_u32_e32 v3, v5, v9
	v_min_u32_e32 v9, v5, v9
	v_max_u32_e32 v19, v215, v16
	v_min_u32_e32 v16, v215, v16
	v_max_u32_e32 v2, v17, v21
	v_min_u32_e32 v21, v17, v21
	v_max_u32_e32 v5, v22, v26
	v_min_u32_e32 v26, v22, v26
	v_max_u32_e32 v215, v8, v12
	v_min_u32_e32 v12, v8, v12
	v_max_u32_e32 v17, v11, v15
	v_min_u32_e32 v15, v11, v15
	v_max_u32_e32 v22, v27, v31
	v_min_u32_e32 v31, v27, v31
	v_max_u32_e32 v8, v14, v214
	v_min_u32_e32 v214, v14, v214
	v_max_u32_e32 v11, v10, v1
	v_min_u32_e32 v1, v10, v1
	v_max_u32_e32 v27, v13, v29
	v_min_u32_e32 v29, v13, v29
	v_max_u32_e32 v14, v213, v30
	v_min_u32_e32 v30, v213, v30
	v_max_u32_e32 v10, v5, v6
	v_min_u32_e32 v6, v5, v6
	v_max_u32_e32 v13, v215, v9
	v_min_u32_e32 v9, v215, v9
	v_max_u32_e32 v213, v17, v16
	v_min_u32_e32 v16, v17, v16
	v_max_u32_e32 v5, v22, v21
	v_min_u32_e32 v21, v22, v21
	v_max_u32_e32 v215, v24, v8
	v_min_u32_e32 v8, v24, v8
	v_max_u32_e32 v17, v28, v11
	v_min_u32_e32 v11, v28, v11
	v_max_u32_e32 v22, v27, v214
	v_min_u32_e32 v214, v27, v214
	v_max_u32_e32 v24, v14, v1
	v_min_u32_e32 v1, v14, v1
	v_max_u32_e32 v28, v29, v18
	v_min_u32_e32 v18, v29, v18
	v_max_u32_e32 v27, v30, v4
	v_min_u32_e32 v4, v30, v4
	v_max_u32_e32 v14, v19, v10
	v_min_u32_e32 v10, v19, v10
	v_max_u32_e32 v29, v2, v13
	v_min_u32_e32 v13, v2, v13
	v_max_u32_e32 v30, v213, v6
	v_min_u32_e32 v6, v213, v6
	v_max_u32_e32 v19, v5, v9
	v_min_u32_e32 v9, v5, v9
	v_max_u32_e32 v2, v16, v26
	v_min_u32_e32 v26, v16, v26
	v_max_u32_e32 v213, v21, v12
	v_min_u32_e32 v12, v21, v12
	v_max_u32_e32 v5, v20, v0
	v_min_u32_e32 v0, v20, v0
	v_max_u32_e32 v16, v25, v3
	v_min_u32_e32 v3, v25, v3
	v_max_u32_e32 v21, v215, v14
	v_min_u32_e32 v14, v215, v14
	v_max_u32_e32 v20, v17, v29
	v_min_u32_e32 v29, v17, v29
	v_max_u32_e32 v25, v8, v10
	v_min_u32_e32 v10, v8, v10
	v_max_u32_e32 v215, v11, v13
	v_min_u32_e32 v13, v11, v13
	v_max_u32_e32 v17, v22, v30
	v_min_u32_e32 v30, v22, v30
	v_max_u32_e32 v8, v24, v19
	v_min_u32_e32 v19, v24, v19
	v_max_u32_e32 v11, v214, v6
	v_min_u32_e32 v6, v214, v6
	v_max_u32_e32 v22, v1, v9
	v_min_u32_e32 v9, v1, v9
	v_max_u32_e32 v24, v28, v2
	v_min_u32_e32 v2, v28, v2
	v_max_u32_e32 v214, v27, v213
	v_min_u32_e32 v213, v27, v213
	v_max_u32_e32 v1, v18, v26
	v_min_u32_e32 v26, v18, v26
	v_max_u32_e32 v28, v4, v12
	v_min_u32_e32 v12, v4, v12
	v_max_u32_e32 v27, v7, v15
	v_min_u32_e32 v15, v7, v15
	v_max_u32_e32 v18, v23, v31
	v_min_u32_e32 v31, v23, v31
	v_max_u32_e32 v4, v11, v0
	v_min_u32_e32 v0, v11, v0
	v_max_u32_e32 v7, v22, v3
	v_min_u32_e32 v3, v22, v3
	v_max_u32_e32 v23, v24, v14
	v_min_u32_e32 v14, v24, v14
	v_max_u32_e32 v11, v214, v29
	v_min_u32_e32 v29, v214, v29
	v_max_u32_e32 v22, v1, v10
	v_min_u32_e32 v10, v1, v10
	v_max_u32_e32 v24, v28, v13
	v_min_u32_e32 v13, v28, v13
	v_max_u32_e32 v214, v27, v30
	v_min_u32_e32 v30, v27, v30
	v_max_u32_e32 v1, v18, v19
	v_min_u32_e32 v19, v18, v19
	v_max_u32_e32 v28, v25, v4
	v_min_u32_e32 v4, v25, v4
	v_max_u32_e32 v27, v215, v7
	v_min_u32_e32 v7, v215, v7
	v_max_u32_e32 v18, v17, v23
	v_min_u32_e32 v23, v17, v23
	v_max_u32_e32 v25, v8, v11
	v_min_u32_e32 v11, v8, v11
	v_max_u32_e32 v215, v22, v0
	v_min_u32_e32 v0, v22, v0
	v_max_u32_e32 v17, v24, v3
	v_min_u32_e32 v3, v24, v3
	v_max_u32_e32 v8, v214, v14
	v_min_u32_e32 v14, v214, v14
	v_max_u32_e32 v22, v1, v29
	v_min_u32_e32 v29, v1, v29
	v_max_u32_e32 v24, v10, v6
	v_min_u32_e32 v6, v10, v6
	v_max_u32_e32 v214, v13, v9
	v_min_u32_e32 v9, v13, v9
	v_max_u32_e32 v1, v30, v2
	v_min_u32_e32 v2, v30, v2
	v_max_u32_e32 v10, v19, v213
	v_min_u32_e32 v213, v19, v213
	v_max_u32_e32 v13, v21, v28
	v_min_u32_e32 v28, v21, v28
	v_max_u32_e32 v30, v20, v27
; __device__ void ph_peer(const float* __restrict__ SC, const bf16_t* __restrict__ H  , const float* __restrict__ gffn, const unsigned char* __restrict__ U, const unsigned char* __restrict__ V, float* X, const float* __restrict__ fgain) {
;     ...
;             for (int it = 0; it < 16; ++it) {
; #pragma unroll
;                 for (int u = 0; u < 2; ++u) {
;                     const unsigned m0 = wave_max_u32(k00[u] > k01[u] ? k00[u] : k01[u]);
;                     const unsigned m1 = wave_max_u32(k10[u] > k11[u] ? k10[u] : k11[u]);
;                     if (lane == it) { top0[u] = m0; top1[u] = m1; }
;                     if (k00[u] == m0) k00[u] = 0u; if (k01[u] == m0) k01[u] = 0u;
;                     if (k10[u] == m1) k10[u] = 0u; if (k11[u] == m1) k11[u] = 0u; }
;             }
	v_min_u32_e32 v27, v20, v27
	v_max_u32_e32 v19, v18, v4
	v_min_u32_e32 v4, v18, v4
	v_max_u32_e32 v21, v25, v7
	v_min_u32_e32 v7, v25, v7
	v_max_u32_e32 v20, v23, v215
	v_min_u32_e32 v215, v23, v215
	v_max_u32_e32 v18, v11, v17
	v_min_u32_e32 v17, v11, v17
	v_max_u32_e32 v25, v8, v0
	v_min_u32_e32 v0, v8, v0
	v_max_u32_e32 v23, v22, v3
	v_min_u32_e32 v3, v22, v3
	v_max_u32_e32 v11, v14, v24
	v_min_u32_e32 v24, v14, v24
	v_max_u32_e32 v8, v29, v214
	v_min_u32_e32 v214, v29, v214
	v_max_u32_e32 v22, v1, v6
	v_min_u32_e32 v6, v1, v6
	v_max_u32_e32 v14, v10, v9
	v_min_u32_e32 v9, v10, v9
	v_max_u32_e32 v29, v2, v26
	v_min_u32_e32 v26, v2, v26
	v_max_u32_e32 v1, v213, v12
	v_min_u32_e32 v12, v213, v12
	v_max_u32_e32 v50, v46, v15
	v_max_u32_e32 v39, v49, v26
	v_max_u32_e32 v42, v35, v29
	v_max_u32_e32 v37, v48, v6
	v_max_u32_e32 v46, v43, v22
	v_max_u32_e32 v49, v38, v24
	v_max_u32_e32 v35, v32, v11
	v_max_u32_e32 v48, v34, v0
	v_max_u32_e32 v43, v47, v25
	v_max_u32_e32 v38, v41, v215
	v_max_u32_e32 v32, v33, v20
	v_max_u32_e32 v34, v36, v4
	v_max_u32_e32 v47, v44, v19
	v_max_u32_e32 v41, v51, v28
	v_max_u32_e32 v33, v45, v13
	v_max_u32_e32 v36, v40, v5
	v_max_u32_e32 v44, v50, v43
	v_min_u32_e32 v43, v50, v43
	v_max_u32_e32 v51, v39, v38
	v_min_u32_e32 v38, v39, v38
	v_max_u32_e32 v45, v42, v32
	v_min_u32_e32 v32, v42, v32
	v_max_u32_e32 v40, v37, v34
	v_min_u32_e32 v34, v37, v34
	v_max_u32_e32 v50, v46, v47
	v_min_u32_e32 v47, v46, v47
	v_max_u32_e32 v39, v49, v41
	v_min_u32_e32 v41, v49, v41
	v_max_u32_e32 v42, v35, v33
	v_min_u32_e32 v33, v35, v33
	v_max_u32_e32 v37, v48, v36
	v_min_u32_e32 v36, v48, v36
	v_max_u32_e32 v46, v44, v50
	v_min_u32_e32 v50, v44, v50
	v_max_u32_e32 v49, v51, v39
	v_min_u32_e32 v39, v51, v39
	v_max_u32_e32 v35, v45, v42
	v_min_u32_e32 v42, v45, v42
	v_max_u32_e32 v48, v40, v37
	v_min_u32_e32 v37, v40, v37
	v_max_u32_e32 v44, v43, v47
	v_min_u32_e32 v47, v43, v47
	v_max_u32_e32 v51, v38, v41
	v_min_u32_e32 v41, v38, v41
	v_max_u32_e32 v45, v32, v33
	v_min_u32_e32 v33, v32, v33
	v_max_u32_e32 v40, v34, v36
	v_min_u32_e32 v36, v34, v36
	v_max_u32_e32 v43, v46, v35
	v_min_u32_e32 v35, v46, v35
	v_max_u32_e32 v38, v49, v48
	v_min_u32_e32 v48, v49, v48
	v_max_u32_e32 v32, v50, v42
	v_min_u32_e32 v42, v50, v42
	v_max_u32_e32 v34, v39, v37
	v_min_u32_e32 v37, v39, v37
	v_max_u32_e32 v46, v44, v45
	v_min_u32_e32 v45, v44, v45
	v_max_u32_e32 v49, v51, v40
	v_min_u32_e32 v40, v51, v40
	v_max_u32_e32 v50, v47, v33
	v_min_u32_e32 v33, v47, v33
	v_max_u32_e32 v39, v41, v36
	v_min_u32_e32 v36, v41, v36
	v_max_u32_e32 v44, v43, v38
	v_min_u32_e32 v38, v43, v38
	v_max_u32_e32 v51, v35, v48
	v_min_u32_e32 v48, v35, v48
	v_max_u32_e32 v47, v32, v34
	v_min_u32_e32 v34, v32, v34
	v_max_u32_e32 v41, v42, v37
	v_min_u32_e32 v37, v42, v37
	v_max_u32_e32 v43, v46, v49
	v_min_u32_e32 v49, v46, v49
	v_max_u32_e32 v35, v45, v40
	v_min_u32_e32 v40, v45, v40
	v_max_u32_e32 v32, v50, v39
	v_min_u32_e32 v39, v50, v39
	v_max_u32_e32 v42, v33, v36
	v_min_u32_e32 v36, v33, v36
	v_max_u32_e32 v46, v44, v31
	v_max_u32_e32 v45, v38, v12
	v_max_u32_e32 v50, v51, v1
	v_max_u32_e32 v33, v48, v9
	v_max_u32_e32 v44, v47, v14
	v_max_u32_e32 v38, v34, v214
	v_max_u32_e32 v51, v41, v8
	v_max_u32_e32 v48, v37, v3
	v_max_u32_e32 v47, v43, v23
	v_max_u32_e32 v34, v49, v17
	v_max_u32_e32 v41, v35, v18
	v_max_u32_e32 v37, v40, v7
	v_max_u32_e32 v43, v32, v21
	v_max_u32_e32 v49, v39, v27
	v_max_u32_e32 v35, v42, v30
	v_max_u32_e32 v40, v36, v16
	v_max_u32_e32 v32, v46, v47
	v_min_u32_e32 v47, v46, v47
	v_max_u32_e32 v39, v45, v34
	v_min_u32_e32 v34, v45, v34
	v_max_u32_e32 v42, v50, v41
	v_min_u32_e32 v41, v50, v41
	v_max_u32_e32 v36, v33, v37
	v_min_u32_e32 v37, v33, v37
	v_max_u32_e32 v46, v44, v43
	v_min_u32_e32 v43, v44, v43
	v_max_u32_e32 v45, v38, v49
	v_min_u32_e32 v49, v38, v49
	v_max_u32_e32 v50, v51, v35
	v_min_u32_e32 v35, v51, v35
	v_max_u32_e32 v33, v48, v40
	v_min_u32_e32 v40, v48, v40
	v_max_u32_e32 v44, v32, v46
	v_min_u32_e32 v46, v32, v46
	v_max_u32_e32 v38, v39, v45
	v_min_u32_e32 v45, v39, v45
	v_max_u32_e32 v51, v42, v50
	v_min_u32_e32 v50, v42, v50
	v_max_u32_e32 v48, v36, v33
	v_min_u32_e32 v33, v36, v33
	v_max_u32_e32 v32, v47, v43
	v_min_u32_e32 v43, v47, v43
	v_max_u32_e32 v39, v34, v49
	v_min_u32_e32 v49, v34, v49
	v_max_u32_e32 v42, v41, v35
	v_min_u32_e32 v35, v41, v35
	v_max_u32_e32 v36, v37, v40
	v_min_u32_e32 v40, v37, v40
	v_max_u32_e32 v47, v44, v51
	v_min_u32_e32 v51, v44, v51
	v_max_u32_e32 v34, v38, v48
	v_min_u32_e32 v48, v38, v48
	v_max_u32_e32 v41, v46, v50
	v_min_u32_e32 v50, v46, v50
	v_max_u32_e32 v37, v45, v33
	v_min_u32_e32 v33, v45, v33
	v_max_u32_e32 v44, v32, v42
	v_min_u32_e32 v42, v32, v42
	v_max_u32_e32 v38, v39, v36
	v_min_u32_e32 v36, v39, v36
	v_max_u32_e32 v46, v43, v35
	v_min_u32_e32 v35, v43, v35
	v_max_u32_e32 v45, v49, v40
	v_min_u32_e32 v40, v49, v40
	v_max_u32_e32 v32, v47, v34
	v_min_u32_e32 v34, v47, v34
	v_max_u32_e32 v39, v51, v48
	v_min_u32_e32 v48, v51, v48
	v_max_u32_e32 v43, v41, v37
	v_min_u32_e32 v37, v41, v37
	v_max_u32_e32 v49, v50, v33
	v_min_u32_e32 v33, v50, v33
	v_max_u32_e32 v47, v44, v38
	v_min_u32_e32 v38, v44, v38
	v_max_u32_e32 v51, v42, v36
	v_min_u32_e32 v36, v42, v36
	v_max_u32_e32 v41, v46, v45
	v_min_u32_e32 v45, v46, v45
	v_max_u32_e32 v50, v35, v40
	v_min_u32_e32 v40, v35, v40
	ds_write_b8 v156, v32 offset:0
	ds_write_b8 v156, v34 offset:1
	ds_write_b8 v156, v39 offset:2
	ds_write_b8 v156, v48 offset:3
	ds_write_b8 v156, v43 offset:4
	ds_write_b8 v156, v37 offset:5
	ds_write_b8 v156, v49 offset:6
	ds_write_b8 v156, v33 offset:7
	ds_write_b8 v156, v47 offset:8
; __device__ __forceinline__ unsigned f2key(float f) { const unsigned u = __float_as_uint(f); return (u & 0x80000000u) ? ~u : (u | 0x80000000u); }
; __device__ __forceinline__ float key2f(unsigned k) { return __uint_as_float((k & 0x80000000u) ? (k & 0x7fffffffu) : ~k); }
; __device__ void ph_peer(const float* __restrict__ SC, const bf16_t* __restrict__ H  , const float* __restrict__ gffn, const unsigned char* __restrict__ U, const unsigned char* __restrict__ V, float* X, const float* __restrict__ fgain) {
;     ...
;             for (int u = 0; u < 2; ++u) { const float* sc = SC + (size_t)tok * 2048 + (h + u) * 256;
;                 const float2 a0 = ((const float2*)sc)[lane], a1 = ((const float2*)(sc + 128))[lane];
;                 k00[u] = (f2key(a0.x) & ~127u) | (unsigned)(127 - 2 * lane); k01[u] = (f2key(a0.y) & ~127u) | (unsigned)(126 - 2 * lane);
;                 k10[u] = (f2key(a1.x) & ~127u) | (unsigned)(127 - 2 * lane); k11[u] = (f2key(a1.y) & ~127u) | (unsigned)(126 - 2 * lane);
;                 top0[u] = 0u; top1[u] = 0u; }
;             for (int it = 0; it < 16; ++it) {
; #pragma unroll
;                 for (int u = 0; u < 2; ++u) {
;                     const unsigned m0 = wave_max_u32(k00[u] > k01[u] ? k00[u] : k01[u]);
;                     const unsigned m1 = wave_max_u32(k10[u] > k11[u] ? k10[u] : k11[u]);
;                     if (lane == it) { top0[u] = m0; top1[u] = m1; }
;                     if (k00[u] == m0) k00[u] = 0u; if (k01[u] == m0) k01[u] = 0u;
;                     if (k10[u] == m1) k10[u] = 0u; if (k11[u] == m1) k11[u] = 0u; }
;             }
;             const int ci = lane >> 2, cj0 = (lane & 3) * 4;
;             unsigned ck[2][4], best[2]; int n0[2], n1[2];
; #pragma unroll
;             for (int u = 0; u < 2; ++u) {
;                 const float s0 = key2f(top0[u] & ~127u), s1 = key2f(top1[u] & ~127u);
;                 n0[u] = 127 - (int)(top0[u] & 127u); n1[u] = 127 - (int)(top1[u] & 127u);
;                 const float si = __shfl(s0, ci);
	ds_write_b8 v156, v38 offset:9
	ds_write_b8 v156, v51 offset:10
	ds_write_b8 v156, v36 offset:11
	ds_write_b8 v156, v41 offset:12
	ds_write_b8 v156, v45 offset:13
	ds_write_b8 v156, v50 offset:14
	ds_write_b8 v156, v40 offset:15
	v_and_b32_e32 v96, s30, v32
	v_ashrrev_i32_e32 v212, 31, v96
	v_lshrrev_b32_e32 v212, 1, v212
	v_xnor_b32_e32 v96, v96, v212
	v_and_b32_e32 v97, s30, v34
	v_ashrrev_i32_e32 v212, 31, v97
	v_lshrrev_b32_e32 v212, 1, v212
	v_xnor_b32_e32 v97, v97, v212
	v_and_b32_e32 v98, s30, v39
	v_ashrrev_i32_e32 v212, 31, v98
	v_lshrrev_b32_e32 v212, 1, v212
	v_xnor_b32_e32 v98, v98, v212
	v_and_b32_e32 v99, s30, v48
	v_ashrrev_i32_e32 v212, 31, v99
	v_lshrrev_b32_e32 v212, 1, v212
	v_xnor_b32_e32 v99, v99, v212
	v_and_b32_e32 v100, s30, v43
	v_ashrrev_i32_e32 v212, 31, v100
	v_lshrrev_b32_e32 v212, 1, v212
	v_xnor_b32_e32 v100, v100, v212
	v_and_b32_e32 v101, s30, v37
	v_ashrrev_i32_e32 v212, 31, v101
	v_lshrrev_b32_e32 v212, 1, v212
	v_xnor_b32_e32 v101, v101, v212
	v_and_b32_e32 v102, s30, v49
	v_ashrrev_i32_e32 v212, 31, v102
	v_lshrrev_b32_e32 v212, 1, v212
	v_xnor_b32_e32 v102, v102, v212
	v_and_b32_e32 v103, s30, v33
	v_ashrrev_i32_e32 v212, 31, v103
	v_lshrrev_b32_e32 v212, 1, v212
	v_xnor_b32_e32 v103, v103, v212
	v_and_b32_e32 v104, s30, v47
	v_ashrrev_i32_e32 v212, 31, v104
	v_lshrrev_b32_e32 v212, 1, v212
	v_xnor_b32_e32 v104, v104, v212
	v_and_b32_e32 v105, s30, v38
	v_ashrrev_i32_e32 v212, 31, v105
	v_lshrrev_b32_e32 v212, 1, v212
	v_xnor_b32_e32 v105, v105, v212
	v_and_b32_e32 v106, s30, v51
	v_ashrrev_i32_e32 v212, 31, v106
	v_lshrrev_b32_e32 v212, 1, v212
	v_xnor_b32_e32 v106, v106, v212
	v_and_b32_e32 v107, s30, v36
	v_ashrrev_i32_e32 v212, 31, v107
	v_lshrrev_b32_e32 v212, 1, v212
	v_xnor_b32_e32 v107, v107, v212
	v_and_b32_e32 v108, s30, v41
	v_ashrrev_i32_e32 v212, 31, v108
	v_lshrrev_b32_e32 v212, 1, v212
	v_xnor_b32_e32 v108, v108, v212
	v_and_b32_e32 v109, s30, v45
	v_ashrrev_i32_e32 v212, 31, v109
	v_lshrrev_b32_e32 v212, 1, v212
	v_xnor_b32_e32 v109, v109, v212
	v_and_b32_e32 v110, s30, v50
	v_ashrrev_i32_e32 v212, 31, v110
	v_lshrrev_b32_e32 v212, 1, v212
	v_xnor_b32_e32 v110, v110, v212
	v_and_b32_e32 v111, s30, v40
	v_ashrrev_i32_e32 v212, 31, v111
	v_lshrrev_b32_e32 v212, 1, v212
	v_xnor_b32_e32 v111, v111, v212
	v_mov_b32_e32 v217, v216
	global_load_dwordx4 v[52:55], v217, s[28:29] offset:640
	v_add_u32_e32 v157, s36, v217
	global_load_dwordx4 v[56:59], v157, s[28:29] offset:640
	v_add_u32_e32 v217, s36, v157
	global_load_dwordx4 v[60:63], v217, s[28:29] offset:640
	v_add_u32_e32 v157, s36, v217
	global_load_dwordx4 v[112:115], v157, s[28:29] offset:640
	v_add_u32_e32 v217, s36, v157
	global_load_dwordx4 v[116:119], v217, s[28:29] offset:640
	v_add_u32_e32 v157, s36, v217
	global_load_dwordx4 v[120:123], v157, s[28:29] offset:640
	v_add_u32_e32 v217, s36, v157
	global_load_dwordx4 v[124:127], v217, s[28:29] offset:640
	v_add_u32_e32 v157, s36, v217
	global_load_dwordx4 v[158:161], v157, s[28:29] offset:640
	s_waitcnt vmcnt(8)
	ds_write_b128 v144, v[180:183] offset:0
	ds_write_b128 v144, v[184:187] offset:1152
	ds_write_b128 v144, v[188:191] offset:2304
	ds_write_b128 v144, v[192:195] offset:3456
	ds_write_b128 v144, v[196:199] offset:4608
	ds_write_b128 v144, v[200:203] offset:5760
	ds_write_b128 v144, v[204:207] offset:6912
	ds_write_b128 v144, v[208:211] offset:8064
	ds_read_b128 v[0:3], v145 offset:0
	ds_read_b128 v[4:7], v145 offset:16
	ds_read_b128 v[8:11], v145 offset:32
	ds_read_b128 v[12:15], v145 offset:48
	ds_read_b128 v[16:19], v145 offset:64
	ds_read_b128 v[20:23], v145 offset:80
	ds_read_b128 v[24:27], v145 offset:96
	ds_read_b128 v[28:31], v145 offset:112
	s_waitcnt lgkmcnt(0)
	v_ashrrev_i32_e32 v212, 31, v0
	v_or_b32_e32 v212, 0x80000000, v212
	v_xor_b32_e32 v0, v0, v212
	v_and_b32_e32 v0, s30, v0
	v_or_b32_e32 v0, 0x7f, v0
	v_ashrrev_i32_e32 v212, 31, v1
	v_or_b32_e32 v212, 0x80000000, v212
	v_xor_b32_e32 v1, v1, v212
	v_and_b32_e32 v1, s30, v1
	v_or_b32_e32 v1, 0x7e, v1
	v_ashrrev_i32_e32 v212, 31, v2
	v_or_b32_e32 v212, 0x80000000, v212
	v_xor_b32_e32 v2, v2, v212
	v_and_b32_e32 v2, s30, v2
	v_or_b32_e32 v2, 0x7d, v2
	v_ashrrev_i32_e32 v212, 31, v3
	v_or_b32_e32 v212, 0x80000000, v212
	v_xor_b32_e32 v3, v3, v212
	v_and_b32_e32 v3, s30, v3
	v_or_b32_e32 v3, 0x7c, v3
	v_ashrrev_i32_e32 v212, 31, v4
	v_or_b32_e32 v212, 0x80000000, v212
	v_xor_b32_e32 v4, v4, v212
	v_and_b32_e32 v4, s30, v4
	v_or_b32_e32 v4, 0x7b, v4
	v_ashrrev_i32_e32 v212, 31, v5
	v_or_b32_e32 v212, 0x80000000, v212
	v_xor_b32_e32 v5, v5, v212
	v_and_b32_e32 v5, s30, v5
	v_or_b32_e32 v5, 0x7a, v5
	v_ashrrev_i32_e32 v212, 31, v6
	v_or_b32_e32 v212, 0x80000000, v212
	v_xor_b32_e32 v6, v6, v212
	v_and_b32_e32 v6, s30, v6
	v_or_b32_e32 v6, 0x79, v6
	v_ashrrev_i32_e32 v212, 31, v7
	v_or_b32_e32 v212, 0x80000000, v212
	v_xor_b32_e32 v7, v7, v212
	v_and_b32_e32 v7, s30, v7
	v_or_b32_e32 v7, 0x78, v7
	v_ashrrev_i32_e32 v212, 31, v8
	v_or_b32_e32 v212, 0x80000000, v212
	v_xor_b32_e32 v8, v8, v212
	v_and_b32_e32 v8, s30, v8
	v_or_b32_e32 v8, 0x77, v8
	v_ashrrev_i32_e32 v212, 31, v9
	v_or_b32_e32 v212, 0x80000000, v212
	v_xor_b32_e32 v9, v9, v212
	v_and_b32_e32 v9, s30, v9
	v_or_b32_e32 v9, 0x76, v9
	v_ashrrev_i32_e32 v212, 31, v10
	v_or_b32_e32 v212, 0x80000000, v212
	v_xor_b32_e32 v10, v10, v212
	v_and_b32_e32 v10, s30, v10
	v_or_b32_e32 v10, 0x75, v10
	v_ashrrev_i32_e32 v212, 31, v11
	v_or_b32_e32 v212, 0x80000000, v212
	v_xor_b32_e32 v11, v11, v212
	v_and_b32_e32 v11, s30, v11
	v_or_b32_e32 v11, 0x74, v11
	v_ashrrev_i32_e32 v212, 31, v12
	v_or_b32_e32 v212, 0x80000000, v212
	v_xor_b32_e32 v12, v12, v212
; __device__ __forceinline__ unsigned f2key(float f) { const unsigned u = __float_as_uint(f); return (u & 0x80000000u) ? ~u : (u | 0x80000000u); }
; __device__ void ph_peer(const float* __restrict__ SC, const bf16_t* __restrict__ H  , const float* __restrict__ gffn, const unsigned char* __restrict__ U, const unsigned char* __restrict__ V, float* X, const float* __restrict__ fgain) {
;     ...
;             for (int u = 0; u < 2; ++u) { const float* sc = SC + (size_t)tok * 2048 + (h + u) * 256;
;                 const float2 a0 = ((const float2*)sc)[lane], a1 = ((const float2*)(sc + 128))[lane];
;                 k00[u] = (f2key(a0.x) & ~127u) | (unsigned)(127 - 2 * lane); k01[u] = (f2key(a0.y) & ~127u) | (unsigned)(126 - 2 * lane);
;                 k10[u] = (f2key(a1.x) & ~127u) | (unsigned)(127 - 2 * lane); k11[u] = (f2key(a1.y) & ~127u) | (unsigned)(126 - 2 * lane);
;                 top0[u] = 0u; top1[u] = 0u; }
;             for (int it = 0; it < 16; ++it) {
; #pragma unroll
;                 for (int u = 0; u < 2; ++u) {
;                     const unsigned m0 = wave_max_u32(k00[u] > k01[u] ? k00[u] : k01[u]);
;                     const unsigned m1 = wave_max_u32(k10[u] > k11[u] ? k10[u] : k11[u]);
;                     if (lane == it) { top0[u] = m0; top1[u] = m1; }
;                     if (k00[u] == m0) k00[u] = 0u; if (k01[u] == m0) k01[u] = 0u;
;                     if (k10[u] == m1) k10[u] = 0u; if (k11[u] == m1) k11[u] = 0u; }
;             }
	v_and_b32_e32 v12, s30, v12
	v_or_b32_e32 v12, 0x73, v12
	v_ashrrev_i32_e32 v212, 31, v13
	v_or_b32_e32 v212, 0x80000000, v212
	v_xor_b32_e32 v13, v13, v212
	v_and_b32_e32 v13, s30, v13
	v_or_b32_e32 v13, 0x72, v13
	v_ashrrev_i32_e32 v212, 31, v14
	v_or_b32_e32 v212, 0x80000000, v212
	v_xor_b32_e32 v14, v14, v212
	v_and_b32_e32 v14, s30, v14
	v_or_b32_e32 v14, 0x71, v14
	v_ashrrev_i32_e32 v212, 31, v15
	v_or_b32_e32 v212, 0x80000000, v212
	v_xor_b32_e32 v15, v15, v212
	v_and_b32_e32 v15, s30, v15
	v_or_b32_e32 v15, 0x70, v15
	v_ashrrev_i32_e32 v212, 31, v16
	v_or_b32_e32 v212, 0x80000000, v212
	v_xor_b32_e32 v16, v16, v212
	v_and_b32_e32 v16, s30, v16
	v_or_b32_e32 v16, 0x6f, v16
	v_ashrrev_i32_e32 v212, 31, v17
	v_or_b32_e32 v212, 0x80000000, v212
	v_xor_b32_e32 v17, v17, v212
	v_and_b32_e32 v17, s30, v17
	v_or_b32_e32 v17, 0x6e, v17
	v_ashrrev_i32_e32 v212, 31, v18
	v_or_b32_e32 v212, 0x80000000, v212
	v_xor_b32_e32 v18, v18, v212
	v_and_b32_e32 v18, s30, v18
	v_or_b32_e32 v18, 0x6d, v18
	v_ashrrev_i32_e32 v212, 31, v19
	v_or_b32_e32 v212, 0x80000000, v212
	v_xor_b32_e32 v19, v19, v212
	v_and_b32_e32 v19, s30, v19
	v_or_b32_e32 v19, 0x6c, v19
	v_ashrrev_i32_e32 v212, 31, v20
	v_or_b32_e32 v212, 0x80000000, v212
	v_xor_b32_e32 v20, v20, v212
	v_and_b32_e32 v20, s30, v20
	v_or_b32_e32 v20, 0x6b, v20
	v_ashrrev_i32_e32 v212, 31, v21
	v_or_b32_e32 v212, 0x80000000, v212
	v_xor_b32_e32 v21, v21, v212
	v_and_b32_e32 v21, s30, v21
	v_or_b32_e32 v21, 0x6a, v21
	v_ashrrev_i32_e32 v212, 31, v22
	v_or_b32_e32 v212, 0x80000000, v212
	v_xor_b32_e32 v22, v22, v212
	v_and_b32_e32 v22, s30, v22
	v_or_b32_e32 v22, 0x69, v22
	v_ashrrev_i32_e32 v212, 31, v23
	v_or_b32_e32 v212, 0x80000000, v212
	v_xor_b32_e32 v23, v23, v212
	v_and_b32_e32 v23, s30, v23
	v_or_b32_e32 v23, 0x68, v23
	v_ashrrev_i32_e32 v212, 31, v24
	v_or_b32_e32 v212, 0x80000000, v212
	v_xor_b32_e32 v24, v24, v212
	v_and_b32_e32 v24, s30, v24
	v_or_b32_e32 v24, 0x67, v24
	v_ashrrev_i32_e32 v212, 31, v25
	v_or_b32_e32 v212, 0x80000000, v212
	v_xor_b32_e32 v25, v25, v212
	v_and_b32_e32 v25, s30, v25
	v_or_b32_e32 v25, 0x66, v25
	v_ashrrev_i32_e32 v212, 31, v26
	v_or_b32_e32 v212, 0x80000000, v212
	v_xor_b32_e32 v26, v26, v212
	v_and_b32_e32 v26, s30, v26
	v_or_b32_e32 v26, 0x65, v26
	v_ashrrev_i32_e32 v212, 31, v27
	v_or_b32_e32 v212, 0x80000000, v212
	v_xor_b32_e32 v27, v27, v212
	v_and_b32_e32 v27, s30, v27
	v_or_b32_e32 v27, 0x64, v27
	v_ashrrev_i32_e32 v212, 31, v28
	v_or_b32_e32 v212, 0x80000000, v212
	v_xor_b32_e32 v28, v28, v212
	v_and_b32_e32 v28, s30, v28
	v_or_b32_e32 v28, 0x63, v28
	v_ashrrev_i32_e32 v212, 31, v29
	v_or_b32_e32 v212, 0x80000000, v212
	v_xor_b32_e32 v29, v29, v212
	v_and_b32_e32 v29, s30, v29
	v_or_b32_e32 v29, 0x62, v29
	v_ashrrev_i32_e32 v212, 31, v30
	v_or_b32_e32 v212, 0x80000000, v212
	v_xor_b32_e32 v30, v30, v212
	v_and_b32_e32 v30, s30, v30
	v_or_b32_e32 v30, 0x61, v30
	v_ashrrev_i32_e32 v212, 31, v31
	v_or_b32_e32 v212, 0x80000000, v212
	v_xor_b32_e32 v31, v31, v212
	v_and_b32_e32 v31, s30, v31
	v_or_b32_e32 v31, 0x60, v31
	v_max_u32_e32 v215, v0, v1
	v_min_u32_e32 v1, v0, v1
	v_max_u32_e32 v214, v16, v17
	v_min_u32_e32 v17, v16, v17
	v_max_u32_e32 v213, v2, v3
	v_min_u32_e32 v3, v2, v3
	v_max_u32_e32 v0, v18, v19
	v_min_u32_e32 v19, v18, v19
	v_max_u32_e32 v16, v4, v5
	v_min_u32_e32 v5, v4, v5
	v_max_u32_e32 v2, v20, v21
	v_min_u32_e32 v21, v20, v21
	v_max_u32_e32 v18, v6, v7
	v_min_u32_e32 v7, v6, v7
	v_max_u32_e32 v4, v22, v23
	v_min_u32_e32 v23, v22, v23
	v_max_u32_e32 v20, v8, v9
	v_min_u32_e32 v9, v8, v9
	v_max_u32_e32 v6, v24, v25
	v_min_u32_e32 v25, v24, v25
	v_max_u32_e32 v22, v10, v11
	v_min_u32_e32 v11, v10, v11
	v_max_u32_e32 v8, v26, v27
	v_min_u32_e32 v27, v26, v27
	v_max_u32_e32 v24, v12, v13
	v_min_u32_e32 v13, v12, v13
	v_max_u32_e32 v10, v28, v29
	v_min_u32_e32 v29, v28, v29
	v_max_u32_e32 v26, v14, v15
	v_min_u32_e32 v15, v14, v15
	v_max_u32_e32 v12, v30, v31
	v_min_u32_e32 v31, v30, v31
	v_max_u32_e32 v28, v215, v213
	v_min_u32_e32 v213, v215, v213
	v_max_u32_e32 v14, v214, v0
	v_min_u32_e32 v0, v214, v0
	v_max_u32_e32 v30, v1, v3
	v_min_u32_e32 v3, v1, v3
	v_max_u32_e32 v215, v17, v19
	v_min_u32_e32 v19, v17, v19
	v_max_u32_e32 v214, v16, v18
	v_min_u32_e32 v18, v16, v18
	v_max_u32_e32 v1, v2, v4
	v_min_u32_e32 v4, v2, v4
	v_max_u32_e32 v17, v5, v7
	v_min_u32_e32 v7, v5, v7
	v_max_u32_e32 v16, v21, v23
	v_min_u32_e32 v23, v21, v23
	v_max_u32_e32 v2, v20, v22
	v_min_u32_e32 v22, v20, v22
	v_max_u32_e32 v5, v6, v8
	v_min_u32_e32 v8, v6, v8
	v_max_u32_e32 v21, v9, v11
	v_min_u32_e32 v11, v9, v11
	v_max_u32_e32 v20, v25, v27
	v_min_u32_e32 v27, v25, v27
	v_max_u32_e32 v6, v24, v26
	v_min_u32_e32 v26, v24, v26
	v_max_u32_e32 v9, v10, v12
	v_min_u32_e32 v12, v10, v12
	v_max_u32_e32 v25, v13, v15
	v_min_u32_e32 v15, v13, v15
	v_max_u32_e32 v24, v29, v31
	v_min_u32_e32 v31, v29, v31
	v_max_u32_e32 v10, v30, v213
	v_min_u32_e32 v213, v30, v213
	v_max_u32_e32 v13, v215, v0
	v_min_u32_e32 v0, v215, v0
	v_max_u32_e32 v29, v17, v18
	v_min_u32_e32 v18, v17, v18
	v_max_u32_e32 v30, v16, v4
	v_min_u32_e32 v4, v16, v4
	v_max_u32_e32 v215, v21, v22
	v_min_u32_e32 v22, v21, v22
	v_max_u32_e32 v17, v20, v8
	v_min_u32_e32 v8, v20, v8
	v_max_u32_e32 v16, v25, v26
	v_min_u32_e32 v26, v25, v26
	v_max_u32_e32 v21, v24, v12
	v_min_u32_e32 v12, v24, v12
	v_max_u32_e32 v20, v28, v214
	v_min_u32_e32 v214, v28, v214
	v_max_u32_e32 v25, v14, v1
	v_min_u32_e32 v1, v14, v1
	v_max_u32_e32 v24, v10, v29
	v_min_u32_e32 v29, v10, v29
	v_max_u32_e32 v28, v13, v30
	v_min_u32_e32 v30, v13, v30
	v_max_u32_e32 v14, v213, v18
	v_min_u32_e32 v18, v213, v18
	v_max_u32_e32 v10, v0, v4
; __device__ void ph_peer(const float* __restrict__ SC, const bf16_t* __restrict__ H  , const float* __restrict__ gffn, const unsigned char* __restrict__ U, const unsigned char* __restrict__ V, float* X, const float* __restrict__ fgain) {
;     ...
;             for (int it = 0; it < 16; ++it) {
; #pragma unroll
;                 for (int u = 0; u < 2; ++u) {
;                     const unsigned m0 = wave_max_u32(k00[u] > k01[u] ? k00[u] : k01[u]);
;                     const unsigned m1 = wave_max_u32(k10[u] > k11[u] ? k10[u] : k11[u]);
;                     if (lane == it) { top0[u] = m0; top1[u] = m1; }
;                     if (k00[u] == m0) k00[u] = 0u; if (k01[u] == m0) k01[u] = 0u;
;                     if (k10[u] == m1) k10[u] = 0u; if (k11[u] == m1) k11[u] = 0u; }
;             }
	v_min_u32_e32 v4, v0, v4
	v_max_u32_e32 v13, v3, v7
	v_min_u32_e32 v7, v3, v7
	v_max_u32_e32 v213, v19, v23
	v_min_u32_e32 v23, v19, v23
	v_max_u32_e32 v0, v2, v6
	v_min_u32_e32 v6, v2, v6
	v_max_u32_e32 v3, v5, v9
	v_min_u32_e32 v9, v5, v9
	v_max_u32_e32 v19, v215, v16
	v_min_u32_e32 v16, v215, v16
	v_max_u32_e32 v2, v17, v21
	v_min_u32_e32 v21, v17, v21
	v_max_u32_e32 v5, v22, v26
	v_min_u32_e32 v26, v22, v26
	v_max_u32_e32 v215, v8, v12
	v_min_u32_e32 v12, v8, v12
	v_max_u32_e32 v17, v11, v15
	v_min_u32_e32 v15, v11, v15
	v_max_u32_e32 v22, v27, v31
	v_min_u32_e32 v31, v27, v31
	v_max_u32_e32 v8, v14, v214
	v_min_u32_e32 v214, v14, v214
	v_max_u32_e32 v11, v10, v1
	v_min_u32_e32 v1, v10, v1
	v_max_u32_e32 v27, v13, v29
	v_min_u32_e32 v29, v13, v29
	v_max_u32_e32 v14, v213, v30
	v_min_u32_e32 v30, v213, v30
	v_max_u32_e32 v10, v5, v6
	v_min_u32_e32 v6, v5, v6
	v_max_u32_e32 v13, v215, v9
	v_min_u32_e32 v9, v215, v9
	v_max_u32_e32 v213, v17, v16
	v_min_u32_e32 v16, v17, v16
	v_max_u32_e32 v5, v22, v21
	v_min_u32_e32 v21, v22, v21
	v_max_u32_e32 v215, v24, v8
	v_min_u32_e32 v8, v24, v8
	v_max_u32_e32 v17, v28, v11
	v_min_u32_e32 v11, v28, v11
	v_max_u32_e32 v22, v27, v214
	v_min_u32_e32 v214, v27, v214
	v_max_u32_e32 v24, v14, v1
	v_min_u32_e32 v1, v14, v1
	v_max_u32_e32 v28, v29, v18
	v_min_u32_e32 v18, v29, v18
	v_max_u32_e32 v27, v30, v4
	v_min_u32_e32 v4, v30, v4
	v_max_u32_e32 v14, v19, v10
	v_min_u32_e32 v10, v19, v10
	v_max_u32_e32 v29, v2, v13
	v_min_u32_e32 v13, v2, v13
	v_max_u32_e32 v30, v213, v6
	v_min_u32_e32 v6, v213, v6
	v_max_u32_e32 v19, v5, v9
	v_min_u32_e32 v9, v5, v9
	v_max_u32_e32 v2, v16, v26
	v_min_u32_e32 v26, v16, v26
	v_max_u32_e32 v213, v21, v12
	v_min_u32_e32 v12, v21, v12
	v_max_u32_e32 v5, v20, v0
	v_min_u32_e32 v0, v20, v0
	v_max_u32_e32 v16, v25, v3
	v_min_u32_e32 v3, v25, v3
	v_max_u32_e32 v21, v215, v14
	v_min_u32_e32 v14, v215, v14
	v_max_u32_e32 v20, v17, v29
	v_min_u32_e32 v29, v17, v29
	v_max_u32_e32 v25, v8, v10
	v_min_u32_e32 v10, v8, v10
	v_max_u32_e32 v215, v11, v13
	v_min_u32_e32 v13, v11, v13
	v_max_u32_e32 v17, v22, v30
	v_min_u32_e32 v30, v22, v30
	v_max_u32_e32 v8, v24, v19
	v_min_u32_e32 v19, v24, v19
	v_max_u32_e32 v11, v214, v6
	v_min_u32_e32 v6, v214, v6
	v_max_u32_e32 v22, v1, v9
	v_min_u32_e32 v9, v1, v9
	v_max_u32_e32 v24, v28, v2
	v_min_u32_e32 v2, v28, v2
	v_max_u32_e32 v214, v27, v213
	v_min_u32_e32 v213, v27, v213
	v_max_u32_e32 v1, v18, v26
	v_min_u32_e32 v26, v18, v26
	v_max_u32_e32 v28, v4, v12
	v_min_u32_e32 v12, v4, v12
	v_max_u32_e32 v27, v7, v15
	v_min_u32_e32 v15, v7, v15
	v_max_u32_e32 v18, v23, v31
	v_min_u32_e32 v31, v23, v31
	v_max_u32_e32 v4, v11, v0
	v_min_u32_e32 v0, v11, v0
	v_max_u32_e32 v7, v22, v3
	v_min_u32_e32 v3, v22, v3
	v_max_u32_e32 v23, v24, v14
	v_min_u32_e32 v14, v24, v14
	v_max_u32_e32 v11, v214, v29
	v_min_u32_e32 v29, v214, v29
	v_max_u32_e32 v22, v1, v10
	v_min_u32_e32 v10, v1, v10
	v_max_u32_e32 v24, v28, v13
	v_min_u32_e32 v13, v28, v13
	v_max_u32_e32 v214, v27, v30
	v_min_u32_e32 v30, v27, v30
	v_max_u32_e32 v1, v18, v19
	v_min_u32_e32 v19, v18, v19
	v_max_u32_e32 v28, v25, v4
	v_min_u32_e32 v4, v25, v4
	v_max_u32_e32 v27, v215, v7
	v_min_u32_e32 v7, v215, v7
	v_max_u32_e32 v18, v17, v23
	v_min_u32_e32 v23, v17, v23
	v_max_u32_e32 v25, v8, v11
	v_min_u32_e32 v11, v8, v11
	v_max_u32_e32 v215, v22, v0
	v_min_u32_e32 v0, v22, v0
	v_max_u32_e32 v17, v24, v3
	v_min_u32_e32 v3, v24, v3
	v_max_u32_e32 v8, v214, v14
	v_min_u32_e32 v14, v214, v14
	v_max_u32_e32 v22, v1, v29
	v_min_u32_e32 v29, v1, v29
	v_max_u32_e32 v24, v10, v6
	v_min_u32_e32 v6, v10, v6
	v_max_u32_e32 v214, v13, v9
	v_min_u32_e32 v9, v13, v9
	v_max_u32_e32 v1, v30, v2
	v_min_u32_e32 v2, v30, v2
	v_max_u32_e32 v10, v19, v213
	v_min_u32_e32 v213, v19, v213
	v_max_u32_e32 v13, v21, v28
	v_min_u32_e32 v28, v21, v28
	v_max_u32_e32 v30, v20, v27
	v_min_u32_e32 v27, v20, v27
	v_max_u32_e32 v19, v18, v4
	v_min_u32_e32 v4, v18, v4
	v_max_u32_e32 v21, v25, v7
	v_min_u32_e32 v7, v25, v7
	v_max_u32_e32 v20, v23, v215
	v_min_u32_e32 v215, v23, v215
	v_max_u32_e32 v18, v11, v17
	v_min_u32_e32 v17, v11, v17
	v_max_u32_e32 v25, v8, v0
	v_min_u32_e32 v0, v8, v0
	v_max_u32_e32 v23, v22, v3
	v_min_u32_e32 v3, v22, v3
	v_max_u32_e32 v11, v14, v24
	v_min_u32_e32 v24, v14, v24
	v_max_u32_e32 v8, v29, v214
	v_min_u32_e32 v214, v29, v214
	v_max_u32_e32 v22, v1, v6
	v_min_u32_e32 v6, v1, v6
	v_max_u32_e32 v14, v10, v9
	v_min_u32_e32 v9, v10, v9
	v_max_u32_e32 v29, v2, v26
	v_min_u32_e32 v26, v2, v26
	v_max_u32_e32 v1, v213, v12
	v_min_u32_e32 v12, v213, v12
	v_mov_b32_e32 v51, v5
	v_mov_b32_e32 v50, v13
	v_mov_b32_e32 v49, v28
	v_mov_b32_e32 v48, v19
	v_mov_b32_e32 v47, v4
	v_mov_b32_e32 v46, v20
	v_mov_b32_e32 v45, v215
	v_mov_b32_e32 v44, v25
	v_mov_b32_e32 v43, v0
	v_mov_b32_e32 v42, v11
	v_mov_b32_e32 v41, v24
	v_mov_b32_e32 v40, v22
	v_mov_b32_e32 v39, v6
	v_mov_b32_e32 v38, v29
	v_mov_b32_e32 v37, v26
	v_mov_b32_e32 v36, v15
	v_max_u32_e32 v35, v51, v31
	v_max_u32_e32 v34, v50, v12
	v_max_u32_e32 v33, v49, v1
	v_max_u32_e32 v32, v48, v9
	v_max_u32_e32 v51, v47, v14
	v_max_u32_e32 v50, v46, v214
	v_max_u32_e32 v49, v45, v8
	v_max_u32_e32 v48, v44, v3
	v_max_u32_e32 v47, v43, v23
	v_max_u32_e32 v46, v42, v17
	v_max_u32_e32 v45, v41, v18
	v_max_u32_e32 v44, v40, v7
	v_max_u32_e32 v43, v39, v21
	v_max_u32_e32 v42, v38, v27
	v_max_u32_e32 v41, v37, v30
	v_max_u32_e32 v40, v36, v16
	v_max_u32_e32 v39, v35, v47
	v_min_u32_e32 v47, v35, v47
	v_max_u32_e32 v38, v34, v46
	v_min_u32_e32 v46, v34, v46
	v_max_u32_e32 v37, v33, v45
	v_min_u32_e32 v45, v33, v45
	v_max_u32_e32 v36, v32, v44
	v_min_u32_e32 v44, v32, v44
; __device__ __forceinline__ unsigned f2key(float f) { const unsigned u = __float_as_uint(f); return (u & 0x80000000u) ? ~u : (u | 0x80000000u); }
; __device__ void ph_peer(const float* __restrict__ SC, const bf16_t* __restrict__ H  , const float* __restrict__ gffn, const unsigned char* __restrict__ U, const unsigned char* __restrict__ V, float* X, const float* __restrict__ fgain) {
;     ...
;             for (int u = 0; u < 2; ++u) { const float* sc = SC + (size_t)tok * 2048 + (h + u) * 256;
;                 const float2 a0 = ((const float2*)sc)[lane], a1 = ((const float2*)(sc + 128))[lane];
;                 k00[u] = (f2key(a0.x) & ~127u) | (unsigned)(127 - 2 * lane); k01[u] = (f2key(a0.y) & ~127u) | (unsigned)(126 - 2 * lane);
;                 k10[u] = (f2key(a1.x) & ~127u) | (unsigned)(127 - 2 * lane); k11[u] = (f2key(a1.y) & ~127u) | (unsigned)(126 - 2 * lane);
;                 top0[u] = 0u; top1[u] = 0u; }
;             for (int it = 0; it < 16; ++it) {
; #pragma unroll
;                 for (int u = 0; u < 2; ++u) {
;                     const unsigned m0 = wave_max_u32(k00[u] > k01[u] ? k00[u] : k01[u]);
;                     const unsigned m1 = wave_max_u32(k10[u] > k11[u] ? k10[u] : k11[u]);
;                     if (lane == it) { top0[u] = m0; top1[u] = m1; }
;                     if (k00[u] == m0) k00[u] = 0u; if (k01[u] == m0) k01[u] = 0u;
;                     if (k10[u] == m1) k10[u] = 0u; if (k11[u] == m1) k11[u] = 0u; }
;             }
	v_max_u32_e32 v35, v51, v43
	v_min_u32_e32 v43, v51, v43
	v_max_u32_e32 v34, v50, v42
	v_min_u32_e32 v42, v50, v42
	v_max_u32_e32 v33, v49, v41
	v_min_u32_e32 v41, v49, v41
	v_max_u32_e32 v32, v48, v40
	v_min_u32_e32 v40, v48, v40
	v_max_u32_e32 v51, v39, v35
	v_min_u32_e32 v35, v39, v35
	v_max_u32_e32 v50, v38, v34
	v_min_u32_e32 v34, v38, v34
	v_max_u32_e32 v49, v37, v33
	v_min_u32_e32 v33, v37, v33
	v_max_u32_e32 v48, v36, v32
	v_min_u32_e32 v32, v36, v32
	v_max_u32_e32 v39, v47, v43
	v_min_u32_e32 v43, v47, v43
	v_max_u32_e32 v38, v46, v42
	v_min_u32_e32 v42, v46, v42
	v_max_u32_e32 v37, v45, v41
	v_min_u32_e32 v41, v45, v41
	v_max_u32_e32 v36, v44, v40
	v_min_u32_e32 v40, v44, v40
	v_max_u32_e32 v47, v51, v49
	v_min_u32_e32 v49, v51, v49
	v_max_u32_e32 v46, v50, v48
	v_min_u32_e32 v48, v50, v48
	v_max_u32_e32 v45, v35, v33
	v_min_u32_e32 v33, v35, v33
	v_max_u32_e32 v44, v34, v32
	v_min_u32_e32 v32, v34, v32
	v_max_u32_e32 v51, v39, v37
	v_min_u32_e32 v37, v39, v37
	v_max_u32_e32 v50, v38, v36
	v_min_u32_e32 v36, v38, v36
	v_max_u32_e32 v35, v43, v41
	v_min_u32_e32 v41, v43, v41
	v_max_u32_e32 v34, v42, v40
	v_min_u32_e32 v40, v42, v40
	v_max_u32_e32 v39, v47, v46
	v_min_u32_e32 v46, v47, v46
	v_max_u32_e32 v38, v49, v48
	v_min_u32_e32 v48, v49, v48
	v_max_u32_e32 v43, v45, v44
	v_min_u32_e32 v44, v45, v44
	v_max_u32_e32 v42, v33, v32
	v_min_u32_e32 v32, v33, v32
	v_max_u32_e32 v47, v51, v50
	v_min_u32_e32 v50, v51, v50
	v_max_u32_e32 v49, v37, v36
	v_min_u32_e32 v36, v37, v36
	v_max_u32_e32 v45, v35, v34
	v_min_u32_e32 v34, v35, v34
	v_max_u32_e32 v33, v41, v40
	v_min_u32_e32 v40, v41, v40
	v_mov_b32_e32 v217, v216
	global_load_dwordx4 v[180:183], v217, s[28:29] offset:768
	v_add_u32_e32 v157, s36, v217
	global_load_dwordx4 v[184:187], v157, s[28:29] offset:768
	v_add_u32_e32 v217, s36, v157
	global_load_dwordx4 v[188:191], v217, s[28:29] offset:768
	v_add_u32_e32 v157, s36, v217
	global_load_dwordx4 v[192:195], v157, s[28:29] offset:768
	v_add_u32_e32 v217, s36, v157
	global_load_dwordx4 v[196:199], v217, s[28:29] offset:768
	v_add_u32_e32 v157, s36, v217
	global_load_dwordx4 v[200:203], v157, s[28:29] offset:768
	v_add_u32_e32 v217, s36, v157
	global_load_dwordx4 v[204:207], v217, s[28:29] offset:768
	v_add_u32_e32 v157, s36, v217
	global_load_dwordx4 v[208:211], v157, s[28:29] offset:768
	s_waitcnt vmcnt(8)
	ds_write_b128 v144, v[52:55] offset:0
	ds_write_b128 v144, v[56:59] offset:1152
	ds_write_b128 v144, v[60:63] offset:2304
	ds_write_b128 v144, v[112:115] offset:3456
	ds_write_b128 v144, v[116:119] offset:4608
	ds_write_b128 v144, v[120:123] offset:5760
	ds_write_b128 v144, v[124:127] offset:6912
	ds_write_b128 v144, v[158:161] offset:8064
	ds_read_b128 v[0:3], v145 offset:0
	ds_read_b128 v[4:7], v145 offset:16
	ds_read_b128 v[8:11], v145 offset:32
	ds_read_b128 v[12:15], v145 offset:48
	ds_read_b128 v[16:19], v145 offset:64
	ds_read_b128 v[20:23], v145 offset:80
	ds_read_b128 v[24:27], v145 offset:96
	ds_read_b128 v[28:31], v145 offset:112
	s_waitcnt lgkmcnt(0)
	v_ashrrev_i32_e32 v212, 31, v0
	v_or_b32_e32 v212, 0x80000000, v212
	v_xor_b32_e32 v0, v0, v212
	v_and_b32_e32 v0, s30, v0
	v_or_b32_e32 v0, 0x5f, v0
	v_ashrrev_i32_e32 v212, 31, v1
	v_or_b32_e32 v212, 0x80000000, v212
	v_xor_b32_e32 v1, v1, v212
	v_and_b32_e32 v1, s30, v1
	v_or_b32_e32 v1, 0x5e, v1
	v_ashrrev_i32_e32 v212, 31, v2
	v_or_b32_e32 v212, 0x80000000, v212
	v_xor_b32_e32 v2, v2, v212
	v_and_b32_e32 v2, s30, v2
	v_or_b32_e32 v2, 0x5d, v2
	v_ashrrev_i32_e32 v212, 31, v3
	v_or_b32_e32 v212, 0x80000000, v212
	v_xor_b32_e32 v3, v3, v212
	v_and_b32_e32 v3, s30, v3
	v_or_b32_e32 v3, 0x5c, v3
	v_ashrrev_i32_e32 v212, 31, v4
	v_or_b32_e32 v212, 0x80000000, v212
	v_xor_b32_e32 v4, v4, v212
	v_and_b32_e32 v4, s30, v4
	v_or_b32_e32 v4, 0x5b, v4
	v_ashrrev_i32_e32 v212, 31, v5
	v_or_b32_e32 v212, 0x80000000, v212
	v_xor_b32_e32 v5, v5, v212
	v_and_b32_e32 v5, s30, v5
	v_or_b32_e32 v5, 0x5a, v5
	v_ashrrev_i32_e32 v212, 31, v6
	v_or_b32_e32 v212, 0x80000000, v212
	v_xor_b32_e32 v6, v6, v212
	v_and_b32_e32 v6, s30, v6
	v_or_b32_e32 v6, 0x59, v6
	v_ashrrev_i32_e32 v212, 31, v7
	v_or_b32_e32 v212, 0x80000000, v212
	v_xor_b32_e32 v7, v7, v212
	v_and_b32_e32 v7, s30, v7
	v_or_b32_e32 v7, 0x58, v7
	v_ashrrev_i32_e32 v212, 31, v8
	v_or_b32_e32 v212, 0x80000000, v212
	v_xor_b32_e32 v8, v8, v212
	v_and_b32_e32 v8, s30, v8
	v_or_b32_e32 v8, 0x57, v8
	v_ashrrev_i32_e32 v212, 31, v9
	v_or_b32_e32 v212, 0x80000000, v212
	v_xor_b32_e32 v9, v9, v212
	v_and_b32_e32 v9, s30, v9
	v_or_b32_e32 v9, 0x56, v9
	v_ashrrev_i32_e32 v212, 31, v10
	v_or_b32_e32 v212, 0x80000000, v212
	v_xor_b32_e32 v10, v10, v212
	v_and_b32_e32 v10, s30, v10
	v_or_b32_e32 v10, 0x55, v10
	v_ashrrev_i32_e32 v212, 31, v11
	v_or_b32_e32 v212, 0x80000000, v212
	v_xor_b32_e32 v11, v11, v212
	v_and_b32_e32 v11, s30, v11
	v_or_b32_e32 v11, 0x54, v11
	v_ashrrev_i32_e32 v212, 31, v12
	v_or_b32_e32 v212, 0x80000000, v212
	v_xor_b32_e32 v12, v12, v212
	v_and_b32_e32 v12, s30, v12
	v_or_b32_e32 v12, 0x53, v12
	v_ashrrev_i32_e32 v212, 31, v13
	v_or_b32_e32 v212, 0x80000000, v212
	v_xor_b32_e32 v13, v13, v212
	v_and_b32_e32 v13, s30, v13
	v_or_b32_e32 v13, 0x52, v13
	v_ashrrev_i32_e32 v212, 31, v14
	v_or_b32_e32 v212, 0x80000000, v212
	v_xor_b32_e32 v14, v14, v212
	v_and_b32_e32 v14, s30, v14
	v_or_b32_e32 v14, 0x51, v14
	v_ashrrev_i32_e32 v212, 31, v15
	v_or_b32_e32 v212, 0x80000000, v212
	v_xor_b32_e32 v15, v15, v212
	v_and_b32_e32 v15, s30, v15
	v_or_b32_e32 v15, 0x50, v15
	v_ashrrev_i32_e32 v212, 31, v16
	v_or_b32_e32 v212, 0x80000000, v212
	v_xor_b32_e32 v16, v16, v212
	v_and_b32_e32 v16, s30, v16
	v_or_b32_e32 v16, 0x4f, v16
; __device__ __forceinline__ unsigned f2key(float f) { const unsigned u = __float_as_uint(f); return (u & 0x80000000u) ? ~u : (u | 0x80000000u); }
; __device__ void ph_peer(const float* __restrict__ SC, const bf16_t* __restrict__ H  , const float* __restrict__ gffn, const unsigned char* __restrict__ U, const unsigned char* __restrict__ V, float* X, const float* __restrict__ fgain) {
;     ...
;             for (int u = 0; u < 2; ++u) { const float* sc = SC + (size_t)tok * 2048 + (h + u) * 256;
;                 const float2 a0 = ((const float2*)sc)[lane], a1 = ((const float2*)(sc + 128))[lane];
;                 k00[u] = (f2key(a0.x) & ~127u) | (unsigned)(127 - 2 * lane); k01[u] = (f2key(a0.y) & ~127u) | (unsigned)(126 - 2 * lane);
;                 k10[u] = (f2key(a1.x) & ~127u) | (unsigned)(127 - 2 * lane); k11[u] = (f2key(a1.y) & ~127u) | (unsigned)(126 - 2 * lane);
;                 top0[u] = 0u; top1[u] = 0u; }
;             for (int it = 0; it < 16; ++it) {
; #pragma unroll
;                 for (int u = 0; u < 2; ++u) {
;                     const unsigned m0 = wave_max_u32(k00[u] > k01[u] ? k00[u] : k01[u]);
;                     const unsigned m1 = wave_max_u32(k10[u] > k11[u] ? k10[u] : k11[u]);
;                     if (lane == it) { top0[u] = m0; top1[u] = m1; }
;                     if (k00[u] == m0) k00[u] = 0u; if (k01[u] == m0) k01[u] = 0u;
;                     if (k10[u] == m1) k10[u] = 0u; if (k11[u] == m1) k11[u] = 0u; }
;             }
	v_ashrrev_i32_e32 v212, 31, v17
	v_or_b32_e32 v212, 0x80000000, v212
	v_xor_b32_e32 v17, v17, v212
	v_and_b32_e32 v17, s30, v17
	v_or_b32_e32 v17, 0x4e, v17
	v_ashrrev_i32_e32 v212, 31, v18
	v_or_b32_e32 v212, 0x80000000, v212
	v_xor_b32_e32 v18, v18, v212
	v_and_b32_e32 v18, s30, v18
	v_or_b32_e32 v18, 0x4d, v18
	v_ashrrev_i32_e32 v212, 31, v19
	v_or_b32_e32 v212, 0x80000000, v212
	v_xor_b32_e32 v19, v19, v212
	v_and_b32_e32 v19, s30, v19
	v_or_b32_e32 v19, 0x4c, v19
	v_ashrrev_i32_e32 v212, 31, v20
	v_or_b32_e32 v212, 0x80000000, v212
	v_xor_b32_e32 v20, v20, v212
	v_and_b32_e32 v20, s30, v20
	v_or_b32_e32 v20, 0x4b, v20
	v_ashrrev_i32_e32 v212, 31, v21
	v_or_b32_e32 v212, 0x80000000, v212
	v_xor_b32_e32 v21, v21, v212
	v_and_b32_e32 v21, s30, v21
	v_or_b32_e32 v21, 0x4a, v21
	v_ashrrev_i32_e32 v212, 31, v22
	v_or_b32_e32 v212, 0x80000000, v212
	v_xor_b32_e32 v22, v22, v212
	v_and_b32_e32 v22, s30, v22
	v_or_b32_e32 v22, 0x49, v22
	v_ashrrev_i32_e32 v212, 31, v23
	v_or_b32_e32 v212, 0x80000000, v212
	v_xor_b32_e32 v23, v23, v212
	v_and_b32_e32 v23, s30, v23
	v_or_b32_e32 v23, 0x48, v23
	v_ashrrev_i32_e32 v212, 31, v24
	v_or_b32_e32 v212, 0x80000000, v212
	v_xor_b32_e32 v24, v24, v212
	v_and_b32_e32 v24, s30, v24
	v_or_b32_e32 v24, 0x47, v24
	v_ashrrev_i32_e32 v212, 31, v25
	v_or_b32_e32 v212, 0x80000000, v212
	v_xor_b32_e32 v25, v25, v212
	v_and_b32_e32 v25, s30, v25
	v_or_b32_e32 v25, 0x46, v25
	v_ashrrev_i32_e32 v212, 31, v26
	v_or_b32_e32 v212, 0x80000000, v212
	v_xor_b32_e32 v26, v26, v212
	v_and_b32_e32 v26, s30, v26
	v_or_b32_e32 v26, 0x45, v26
	v_ashrrev_i32_e32 v212, 31, v27
	v_or_b32_e32 v212, 0x80000000, v212
	v_xor_b32_e32 v27, v27, v212
	v_and_b32_e32 v27, s30, v27
	v_or_b32_e32 v27, 0x44, v27
	v_ashrrev_i32_e32 v212, 31, v28
	v_or_b32_e32 v212, 0x80000000, v212
	v_xor_b32_e32 v28, v28, v212
	v_and_b32_e32 v28, s30, v28
	v_or_b32_e32 v28, 0x43, v28
	v_ashrrev_i32_e32 v212, 31, v29
	v_or_b32_e32 v212, 0x80000000, v212
	v_xor_b32_e32 v29, v29, v212
	v_and_b32_e32 v29, s30, v29
	v_or_b32_e32 v29, 0x42, v29
	v_ashrrev_i32_e32 v212, 31, v30
	v_or_b32_e32 v212, 0x80000000, v212
	v_xor_b32_e32 v30, v30, v212
	v_and_b32_e32 v30, s30, v30
	v_or_b32_e32 v30, 0x41, v30
	v_ashrrev_i32_e32 v212, 31, v31
	v_or_b32_e32 v212, 0x80000000, v212
	v_xor_b32_e32 v31, v31, v212
	v_and_or_b32 v31, v31, s30, 64
	v_max_u32_e32 v215, v0, v1
	v_min_u32_e32 v1, v0, v1
	v_max_u32_e32 v214, v16, v17
	v_min_u32_e32 v17, v16, v17
	v_max_u32_e32 v213, v2, v3
	v_min_u32_e32 v3, v2, v3
	v_max_u32_e32 v0, v18, v19
	v_min_u32_e32 v19, v18, v19
	v_max_u32_e32 v16, v4, v5
	v_min_u32_e32 v5, v4, v5
	v_max_u32_e32 v2, v20, v21
	v_min_u32_e32 v21, v20, v21
	v_max_u32_e32 v18, v6, v7
	v_min_u32_e32 v7, v6, v7
	v_max_u32_e32 v4, v22, v23
	v_min_u32_e32 v23, v22, v23
	v_max_u32_e32 v20, v8, v9
	v_min_u32_e32 v9, v8, v9
	v_max_u32_e32 v6, v24, v25
	v_min_u32_e32 v25, v24, v25
	v_max_u32_e32 v22, v10, v11
	v_min_u32_e32 v11, v10, v11
	v_max_u32_e32 v8, v26, v27
	v_min_u32_e32 v27, v26, v27
	v_max_u32_e32 v24, v12, v13
	v_min_u32_e32 v13, v12, v13
	v_max_u32_e32 v10, v28, v29
	v_min_u32_e32 v29, v28, v29
	v_max_u32_e32 v26, v14, v15
	v_min_u32_e32 v15, v14, v15
	v_max_u32_e32 v12, v30, v31
	v_min_u32_e32 v31, v30, v31
	v_max_u32_e32 v28, v215, v213
	v_min_u32_e32 v213, v215, v213
	v_max_u32_e32 v14, v214, v0
	v_min_u32_e32 v0, v214, v0
	v_max_u32_e32 v30, v1, v3
	v_min_u32_e32 v3, v1, v3
	v_max_u32_e32 v215, v17, v19
	v_min_u32_e32 v19, v17, v19
	v_max_u32_e32 v214, v16, v18
	v_min_u32_e32 v18, v16, v18
	v_max_u32_e32 v1, v2, v4
	v_min_u32_e32 v4, v2, v4
	v_max_u32_e32 v17, v5, v7
	v_min_u32_e32 v7, v5, v7
	v_max_u32_e32 v16, v21, v23
	v_min_u32_e32 v23, v21, v23
	v_max_u32_e32 v2, v20, v22
	v_min_u32_e32 v22, v20, v22
	v_max_u32_e32 v5, v6, v8
	v_min_u32_e32 v8, v6, v8
	v_max_u32_e32 v21, v9, v11
	v_min_u32_e32 v11, v9, v11
	v_max_u32_e32 v20, v25, v27
	v_min_u32_e32 v27, v25, v27
	v_max_u32_e32 v6, v24, v26
	v_min_u32_e32 v26, v24, v26
	v_max_u32_e32 v9, v10, v12
	v_min_u32_e32 v12, v10, v12
	v_max_u32_e32 v25, v13, v15
	v_min_u32_e32 v15, v13, v15
	v_max_u32_e32 v24, v29, v31
	v_min_u32_e32 v31, v29, v31
	v_max_u32_e32 v10, v30, v213
	v_min_u32_e32 v213, v30, v213
	v_max_u32_e32 v13, v215, v0
	v_min_u32_e32 v0, v215, v0
	v_max_u32_e32 v29, v17, v18
	v_min_u32_e32 v18, v17, v18
	v_max_u32_e32 v30, v16, v4
	v_min_u32_e32 v4, v16, v4
	v_max_u32_e32 v215, v21, v22
	v_min_u32_e32 v22, v21, v22
	v_max_u32_e32 v17, v20, v8
	v_min_u32_e32 v8, v20, v8
	v_max_u32_e32 v16, v25, v26
	v_min_u32_e32 v26, v25, v26
	v_max_u32_e32 v21, v24, v12
	v_min_u32_e32 v12, v24, v12
	v_max_u32_e32 v20, v28, v214
	v_min_u32_e32 v214, v28, v214
	v_max_u32_e32 v25, v14, v1
	v_min_u32_e32 v1, v14, v1
	v_max_u32_e32 v24, v10, v29
	v_min_u32_e32 v29, v10, v29
	v_max_u32_e32 v28, v13, v30
	v_min_u32_e32 v30, v13, v30
	v_max_u32_e32 v14, v213, v18
	v_min_u32_e32 v18, v213, v18
	v_max_u32_e32 v10, v0, v4
	v_min_u32_e32 v4, v0, v4
	v_max_u32_e32 v13, v3, v7
	v_min_u32_e32 v7, v3, v7
	v_max_u32_e32 v213, v19, v23
	v_min_u32_e32 v23, v19, v23
	v_max_u32_e32 v0, v2, v6
	v_min_u32_e32 v6, v2, v6
	v_max_u32_e32 v3, v5, v9
	v_min_u32_e32 v9, v5, v9
	v_max_u32_e32 v19, v215, v16
	v_min_u32_e32 v16, v215, v16
	v_max_u32_e32 v2, v17, v21
	v_min_u32_e32 v21, v17, v21
	v_max_u32_e32 v5, v22, v26
	v_min_u32_e32 v26, v22, v26
	v_max_u32_e32 v215, v8, v12
	v_min_u32_e32 v12, v8, v12
	v_max_u32_e32 v17, v11, v15
	v_min_u32_e32 v15, v11, v15
	v_max_u32_e32 v22, v27, v31
	v_min_u32_e32 v31, v27, v31
	v_max_u32_e32 v8, v14, v214
	v_min_u32_e32 v214, v14, v214
	v_max_u32_e32 v11, v10, v1
	v_min_u32_e32 v1, v10, v1
; __device__ void ph_peer(const float* __restrict__ SC, const bf16_t* __restrict__ H  , const float* __restrict__ gffn, const unsigned char* __restrict__ U, const unsigned char* __restrict__ V, float* X, const float* __restrict__ fgain) {
;     ...
;             for (int it = 0; it < 16; ++it) {
; #pragma unroll
;                 for (int u = 0; u < 2; ++u) {
;                     const unsigned m0 = wave_max_u32(k00[u] > k01[u] ? k00[u] : k01[u]);
;                     const unsigned m1 = wave_max_u32(k10[u] > k11[u] ? k10[u] : k11[u]);
;                     if (lane == it) { top0[u] = m0; top1[u] = m1; }
;                     if (k00[u] == m0) k00[u] = 0u; if (k01[u] == m0) k01[u] = 0u;
;                     if (k10[u] == m1) k10[u] = 0u; if (k11[u] == m1) k11[u] = 0u; }
;             }
	v_max_u32_e32 v27, v13, v29
	v_min_u32_e32 v29, v13, v29
	v_max_u32_e32 v14, v213, v30
	v_min_u32_e32 v30, v213, v30
	v_max_u32_e32 v10, v5, v6
	v_min_u32_e32 v6, v5, v6
	v_max_u32_e32 v13, v215, v9
	v_min_u32_e32 v9, v215, v9
	v_max_u32_e32 v213, v17, v16
	v_min_u32_e32 v16, v17, v16
	v_max_u32_e32 v5, v22, v21
	v_min_u32_e32 v21, v22, v21
	v_max_u32_e32 v215, v24, v8
	v_min_u32_e32 v8, v24, v8
	v_max_u32_e32 v17, v28, v11
	v_min_u32_e32 v11, v28, v11
	v_max_u32_e32 v22, v27, v214
	v_min_u32_e32 v214, v27, v214
	v_max_u32_e32 v24, v14, v1
	v_min_u32_e32 v1, v14, v1
	v_max_u32_e32 v28, v29, v18
	v_min_u32_e32 v18, v29, v18
	v_max_u32_e32 v27, v30, v4
	v_min_u32_e32 v4, v30, v4
	v_max_u32_e32 v14, v19, v10
	v_min_u32_e32 v10, v19, v10
	v_max_u32_e32 v29, v2, v13
	v_min_u32_e32 v13, v2, v13
	v_max_u32_e32 v30, v213, v6
	v_min_u32_e32 v6, v213, v6
	v_max_u32_e32 v19, v5, v9
	v_min_u32_e32 v9, v5, v9
	v_max_u32_e32 v2, v16, v26
	v_min_u32_e32 v26, v16, v26
	v_max_u32_e32 v213, v21, v12
	v_min_u32_e32 v12, v21, v12
	v_max_u32_e32 v5, v20, v0
	v_min_u32_e32 v0, v20, v0
	v_max_u32_e32 v16, v25, v3
	v_min_u32_e32 v3, v25, v3
	v_max_u32_e32 v21, v215, v14
	v_min_u32_e32 v14, v215, v14
	v_max_u32_e32 v20, v17, v29
	v_min_u32_e32 v29, v17, v29
	v_max_u32_e32 v25, v8, v10
	v_min_u32_e32 v10, v8, v10
	v_max_u32_e32 v215, v11, v13
	v_min_u32_e32 v13, v11, v13
	v_max_u32_e32 v17, v22, v30
	v_min_u32_e32 v30, v22, v30
	v_max_u32_e32 v8, v24, v19
	v_min_u32_e32 v19, v24, v19
	v_max_u32_e32 v11, v214, v6
	v_min_u32_e32 v6, v214, v6
	v_max_u32_e32 v22, v1, v9
	v_min_u32_e32 v9, v1, v9
	v_max_u32_e32 v24, v28, v2
	v_min_u32_e32 v2, v28, v2
	v_max_u32_e32 v214, v27, v213
	v_min_u32_e32 v213, v27, v213
	v_max_u32_e32 v1, v18, v26
	v_min_u32_e32 v26, v18, v26
	v_max_u32_e32 v28, v4, v12
	v_min_u32_e32 v12, v4, v12
	v_max_u32_e32 v27, v7, v15
	v_min_u32_e32 v15, v7, v15
	v_max_u32_e32 v18, v23, v31
	v_min_u32_e32 v31, v23, v31
	v_max_u32_e32 v4, v11, v0
	v_min_u32_e32 v0, v11, v0
	v_max_u32_e32 v7, v22, v3
	v_min_u32_e32 v3, v22, v3
	v_max_u32_e32 v23, v24, v14
	v_min_u32_e32 v14, v24, v14
	v_max_u32_e32 v11, v214, v29
	v_min_u32_e32 v29, v214, v29
	v_max_u32_e32 v22, v1, v10
	v_min_u32_e32 v10, v1, v10
	v_max_u32_e32 v24, v28, v13
	v_min_u32_e32 v13, v28, v13
	v_max_u32_e32 v214, v27, v30
	v_min_u32_e32 v30, v27, v30
	v_max_u32_e32 v1, v18, v19
	v_min_u32_e32 v19, v18, v19
	v_max_u32_e32 v28, v25, v4
	v_min_u32_e32 v4, v25, v4
	v_max_u32_e32 v27, v215, v7
	v_min_u32_e32 v7, v215, v7
	v_max_u32_e32 v18, v17, v23
	v_min_u32_e32 v23, v17, v23
	v_max_u32_e32 v25, v8, v11
	v_min_u32_e32 v11, v8, v11
	v_max_u32_e32 v215, v22, v0
	v_min_u32_e32 v0, v22, v0
	v_max_u32_e32 v17, v24, v3
	v_min_u32_e32 v3, v24, v3
	v_max_u32_e32 v8, v214, v14
	v_min_u32_e32 v14, v214, v14
	v_max_u32_e32 v22, v1, v29
	v_min_u32_e32 v29, v1, v29
	v_max_u32_e32 v24, v10, v6
	v_min_u32_e32 v6, v10, v6
	v_max_u32_e32 v214, v13, v9
	v_min_u32_e32 v9, v13, v9
	v_max_u32_e32 v1, v30, v2
	v_min_u32_e32 v2, v30, v2
	v_max_u32_e32 v10, v19, v213
	v_min_u32_e32 v213, v19, v213
	v_max_u32_e32 v13, v21, v28
	v_min_u32_e32 v28, v21, v28
	v_max_u32_e32 v30, v20, v27
	v_min_u32_e32 v27, v20, v27
	v_max_u32_e32 v19, v18, v4
	v_min_u32_e32 v4, v18, v4
	v_max_u32_e32 v21, v25, v7
	v_min_u32_e32 v7, v25, v7
	v_max_u32_e32 v20, v23, v215
	v_min_u32_e32 v215, v23, v215
	v_max_u32_e32 v18, v11, v17
	v_min_u32_e32 v17, v11, v17
	v_max_u32_e32 v25, v8, v0
	v_min_u32_e32 v0, v8, v0
	v_max_u32_e32 v23, v22, v3
	v_min_u32_e32 v3, v22, v3
	v_max_u32_e32 v11, v14, v24
	v_min_u32_e32 v24, v14, v24
	v_max_u32_e32 v8, v29, v214
	v_min_u32_e32 v214, v29, v214
	v_max_u32_e32 v22, v1, v6
	v_min_u32_e32 v6, v1, v6
	v_max_u32_e32 v14, v10, v9
	v_min_u32_e32 v9, v10, v9
	v_max_u32_e32 v29, v2, v26
	v_min_u32_e32 v26, v2, v26
	v_max_u32_e32 v1, v213, v12
	v_min_u32_e32 v12, v213, v12
	v_max_u32_e32 v51, v39, v15
	v_max_u32_e32 v37, v46, v26
	v_max_u32_e32 v35, v38, v29
	v_max_u32_e32 v41, v48, v6
	v_max_u32_e32 v39, v43, v22
	v_max_u32_e32 v46, v44, v24
	v_max_u32_e32 v38, v42, v11
	v_max_u32_e32 v48, v32, v0
	v_max_u32_e32 v43, v47, v25
	v_max_u32_e32 v44, v50, v215
	v_max_u32_e32 v42, v49, v20
	v_max_u32_e32 v32, v36, v4
	v_max_u32_e32 v47, v45, v19
	v_max_u32_e32 v50, v34, v28
	v_max_u32_e32 v49, v33, v13
	v_max_u32_e32 v36, v40, v5
	v_max_u32_e32 v45, v51, v43
	v_min_u32_e32 v43, v51, v43
	v_max_u32_e32 v34, v37, v44
	v_min_u32_e32 v44, v37, v44
	v_max_u32_e32 v33, v35, v42
	v_min_u32_e32 v42, v35, v42
	v_max_u32_e32 v40, v41, v32
	v_min_u32_e32 v32, v41, v32
	v_max_u32_e32 v51, v39, v47
	v_min_u32_e32 v47, v39, v47
	v_max_u32_e32 v37, v46, v50
	v_min_u32_e32 v50, v46, v50
	v_max_u32_e32 v35, v38, v49
	v_min_u32_e32 v49, v38, v49
	v_max_u32_e32 v41, v48, v36
	v_min_u32_e32 v36, v48, v36
	v_max_u32_e32 v39, v45, v51
	v_min_u32_e32 v51, v45, v51
	v_max_u32_e32 v46, v34, v37
	v_min_u32_e32 v37, v34, v37
	v_max_u32_e32 v38, v33, v35
	v_min_u32_e32 v35, v33, v35
	v_max_u32_e32 v48, v40, v41
	v_min_u32_e32 v41, v40, v41
	v_max_u32_e32 v45, v43, v47
	v_min_u32_e32 v47, v43, v47
	v_max_u32_e32 v34, v44, v50
	v_min_u32_e32 v50, v44, v50
	v_max_u32_e32 v33, v42, v49
	v_min_u32_e32 v49, v42, v49
	v_max_u32_e32 v40, v32, v36
	v_min_u32_e32 v36, v32, v36
	v_max_u32_e32 v43, v39, v38
	v_min_u32_e32 v38, v39, v38
	v_max_u32_e32 v44, v46, v48
	v_min_u32_e32 v48, v46, v48
	v_max_u32_e32 v42, v51, v35
	v_min_u32_e32 v35, v51, v35
	v_max_u32_e32 v32, v37, v41
	v_min_u32_e32 v41, v37, v41
	v_max_u32_e32 v39, v45, v33
	v_min_u32_e32 v33, v45, v33
	v_max_u32_e32 v46, v34, v40
	v_min_u32_e32 v40, v34, v40
	v_max_u32_e32 v51, v47, v49
; __device__ __forceinline__ unsigned f2key(float f) { const unsigned u = __float_as_uint(f); return (u & 0x80000000u) ? ~u : (u | 0x80000000u); }
; __device__ void ph_peer(const float* __restrict__ SC, const bf16_t* __restrict__ H  , const float* __restrict__ gffn, const unsigned char* __restrict__ U, const unsigned char* __restrict__ V, float* X, const float* __restrict__ fgain) {
;     ...
;             for (int u = 0; u < 2; ++u) { const float* sc = SC + (size_t)tok * 2048 + (h + u) * 256;
;                 const float2 a0 = ((const float2*)sc)[lane], a1 = ((const float2*)(sc + 128))[lane];
;                 k00[u] = (f2key(a0.x) & ~127u) | (unsigned)(127 - 2 * lane); k01[u] = (f2key(a0.y) & ~127u) | (unsigned)(126 - 2 * lane);
;                 k10[u] = (f2key(a1.x) & ~127u) | (unsigned)(127 - 2 * lane); k11[u] = (f2key(a1.y) & ~127u) | (unsigned)(126 - 2 * lane);
;                 top0[u] = 0u; top1[u] = 0u; }
;             for (int it = 0; it < 16; ++it) {
; #pragma unroll
;                 for (int u = 0; u < 2; ++u) {
;                     const unsigned m0 = wave_max_u32(k00[u] > k01[u] ? k00[u] : k01[u]);
;                     const unsigned m1 = wave_max_u32(k10[u] > k11[u] ? k10[u] : k11[u]);
;                     if (lane == it) { top0[u] = m0; top1[u] = m1; }
;                     if (k00[u] == m0) k00[u] = 0u; if (k01[u] == m0) k01[u] = 0u;
;                     if (k10[u] == m1) k10[u] = 0u; if (k11[u] == m1) k11[u] = 0u; }
;             }
	v_min_u32_e32 v49, v47, v49
	v_max_u32_e32 v37, v50, v36
	v_min_u32_e32 v36, v50, v36
	v_max_u32_e32 v45, v43, v44
	v_min_u32_e32 v44, v43, v44
	v_max_u32_e32 v34, v38, v48
	v_min_u32_e32 v48, v38, v48
	v_max_u32_e32 v47, v42, v32
	v_min_u32_e32 v32, v42, v32
	v_max_u32_e32 v50, v35, v41
	v_min_u32_e32 v41, v35, v41
	v_max_u32_e32 v43, v39, v46
	v_min_u32_e32 v46, v39, v46
	v_max_u32_e32 v38, v33, v40
	v_min_u32_e32 v40, v33, v40
	v_max_u32_e32 v42, v51, v37
	v_min_u32_e32 v37, v51, v37
	v_max_u32_e32 v35, v49, v36
	v_min_u32_e32 v36, v49, v36
	v_max_u32_e32 v39, v45, v31
	v_max_u32_e32 v33, v44, v12
	v_max_u32_e32 v51, v34, v1
	v_max_u32_e32 v49, v48, v9
	v_max_u32_e32 v45, v47, v14
	v_max_u32_e32 v44, v32, v214
	v_max_u32_e32 v34, v50, v8
	v_max_u32_e32 v48, v41, v3
	v_max_u32_e32 v47, v43, v23
	v_max_u32_e32 v32, v46, v17
	v_max_u32_e32 v50, v38, v18
	v_max_u32_e32 v41, v40, v7
	v_max_u32_e32 v43, v42, v21
	v_max_u32_e32 v46, v37, v27
	v_max_u32_e32 v38, v35, v30
	v_max_u32_e32 v40, v36, v16
	v_max_u32_e32 v42, v39, v47
	v_min_u32_e32 v47, v39, v47
	v_max_u32_e32 v37, v33, v32
	v_min_u32_e32 v32, v33, v32
	v_max_u32_e32 v35, v51, v50
	v_min_u32_e32 v50, v51, v50
	v_max_u32_e32 v36, v49, v41
	v_min_u32_e32 v41, v49, v41
	v_max_u32_e32 v39, v45, v43
	v_min_u32_e32 v43, v45, v43
	v_max_u32_e32 v33, v44, v46
	v_min_u32_e32 v46, v44, v46
	v_max_u32_e32 v51, v34, v38
	v_min_u32_e32 v38, v34, v38
	v_max_u32_e32 v49, v48, v40
	v_min_u32_e32 v40, v48, v40
	v_max_u32_e32 v45, v42, v39
	v_min_u32_e32 v39, v42, v39
	v_max_u32_e32 v44, v37, v33
	v_min_u32_e32 v33, v37, v33
	v_max_u32_e32 v34, v35, v51
	v_min_u32_e32 v51, v35, v51
	v_max_u32_e32 v48, v36, v49
	v_min_u32_e32 v49, v36, v49
	v_max_u32_e32 v42, v47, v43
	v_min_u32_e32 v43, v47, v43
	v_max_u32_e32 v37, v32, v46
	v_min_u32_e32 v46, v32, v46
	v_max_u32_e32 v35, v50, v38
	v_min_u32_e32 v38, v50, v38
	v_max_u32_e32 v36, v41, v40
	v_min_u32_e32 v40, v41, v40
	v_max_u32_e32 v47, v45, v34
	v_min_u32_e32 v34, v45, v34
	v_max_u32_e32 v32, v44, v48
	v_min_u32_e32 v48, v44, v48
	v_max_u32_e32 v50, v39, v51
	v_min_u32_e32 v51, v39, v51
	v_max_u32_e32 v41, v33, v49
	v_min_u32_e32 v49, v33, v49
	v_max_u32_e32 v45, v42, v35
	v_min_u32_e32 v35, v42, v35
	v_max_u32_e32 v44, v37, v36
	v_min_u32_e32 v36, v37, v36
	v_max_u32_e32 v39, v43, v38
	v_min_u32_e32 v38, v43, v38
	v_max_u32_e32 v33, v46, v40
	v_min_u32_e32 v40, v46, v40
	v_max_u32_e32 v42, v47, v32
	v_min_u32_e32 v32, v47, v32
	v_max_u32_e32 v37, v34, v48
	v_min_u32_e32 v48, v34, v48
	v_max_u32_e32 v43, v50, v41
	v_min_u32_e32 v41, v50, v41
	v_max_u32_e32 v46, v51, v49
	v_min_u32_e32 v49, v51, v49
	v_max_u32_e32 v47, v45, v44
	v_min_u32_e32 v44, v45, v44
	v_max_u32_e32 v34, v35, v36
	v_min_u32_e32 v36, v35, v36
	v_max_u32_e32 v50, v39, v33
	v_min_u32_e32 v33, v39, v33
	v_max_u32_e32 v51, v38, v40
	v_min_u32_e32 v40, v38, v40
	v_mov_b32_e32 v217, v216
	global_load_dwordx4 v[52:55], v217, s[28:29] offset:896
	v_add_u32_e32 v157, s36, v217
	global_load_dwordx4 v[56:59], v157, s[28:29] offset:896
	v_add_u32_e32 v217, s36, v157
	global_load_dwordx4 v[60:63], v217, s[28:29] offset:896
	v_add_u32_e32 v157, s36, v217
	global_load_dwordx4 v[112:115], v157, s[28:29] offset:896
	v_add_u32_e32 v217, s36, v157
	global_load_dwordx4 v[116:119], v217, s[28:29] offset:896
	v_add_u32_e32 v157, s36, v217
	global_load_dwordx4 v[120:123], v157, s[28:29] offset:896
	v_add_u32_e32 v217, s36, v157
	global_load_dwordx4 v[124:127], v217, s[28:29] offset:896
	v_add_u32_e32 v157, s36, v217
	global_load_dwordx4 v[158:161], v157, s[28:29] offset:896
	s_waitcnt vmcnt(8)
	ds_write_b128 v144, v[180:183] offset:0
	ds_write_b128 v144, v[184:187] offset:1152
	ds_write_b128 v144, v[188:191] offset:2304
	ds_write_b128 v144, v[192:195] offset:3456
	ds_write_b128 v144, v[196:199] offset:4608
	ds_write_b128 v144, v[200:203] offset:5760
	ds_write_b128 v144, v[204:207] offset:6912
	ds_write_b128 v144, v[208:211] offset:8064
	ds_read_b128 v[0:3], v145 offset:0
	ds_read_b128 v[4:7], v145 offset:16
	ds_read_b128 v[8:11], v145 offset:32
	ds_read_b128 v[12:15], v145 offset:48
	ds_read_b128 v[16:19], v145 offset:64
	ds_read_b128 v[20:23], v145 offset:80
	ds_read_b128 v[24:27], v145 offset:96
	ds_read_b128 v[28:31], v145 offset:112
	s_waitcnt lgkmcnt(0)
; __device__ __forceinline__ unsigned f2key(float f) { const unsigned u = __float_as_uint(f); return (u & 0x80000000u) ? ~u : (u | 0x80000000u); }
; __device__ void ph_peer(const float* __restrict__ SC, const bf16_t* __restrict__ H  , const float* __restrict__ gffn, const unsigned char* __restrict__ U, const unsigned char* __restrict__ V, float* X, const float* __restrict__ fgain) {
;     ...
;             for (int u = 0; u < 2; ++u) { const float* sc = SC + (size_t)tok * 2048 + (h + u) * 256;
;                 const float2 a0 = ((const float2*)sc)[lane], a1 = ((const float2*)(sc + 128))[lane];
;                 k00[u] = (f2key(a0.x) & ~127u) | (unsigned)(127 - 2 * lane); k01[u] = (f2key(a0.y) & ~127u) | (unsigned)(126 - 2 * lane);
;                 k10[u] = (f2key(a1.x) & ~127u) | (unsigned)(127 - 2 * lane); k11[u] = (f2key(a1.y) & ~127u) | (unsigned)(126 - 2 * lane);
;                 top0[u] = 0u; top1[u] = 0u; }
;             for (int it = 0; it < 16; ++it) {
; #pragma unroll
;                 for (int u = 0; u < 2; ++u) {
;                     const unsigned m0 = wave_max_u32(k00[u] > k01[u] ? k00[u] : k01[u]);
;                     const unsigned m1 = wave_max_u32(k10[u] > k11[u] ? k10[u] : k11[u]);
;                     if (lane == it) { top0[u] = m0; top1[u] = m1; }
;                     if (k00[u] == m0) k00[u] = 0u; if (k01[u] == m0) k01[u] = 0u;
;                     if (k10[u] == m1) k10[u] = 0u; if (k11[u] == m1) k11[u] = 0u; }
;             }
	v_ashrrev_i32_e32 v212, 31, v0
	v_or_b32_e32 v212, 0x80000000, v212
	v_xor_b32_e32 v0, v0, v212
	v_and_or_b32 v0, v0, s30, 63
	v_ashrrev_i32_e32 v212, 31, v1
	v_or_b32_e32 v212, 0x80000000, v212
	v_xor_b32_e32 v1, v1, v212
	v_and_or_b32 v1, v1, s30, 62
	v_ashrrev_i32_e32 v212, 31, v2
	v_or_b32_e32 v212, 0x80000000, v212
	v_xor_b32_e32 v2, v2, v212
	v_and_or_b32 v2, v2, s30, 61
	v_ashrrev_i32_e32 v212, 31, v3
	v_or_b32_e32 v212, 0x80000000, v212
	v_xor_b32_e32 v3, v3, v212
	v_and_or_b32 v3, v3, s30, 60
	v_ashrrev_i32_e32 v212, 31, v4
	v_or_b32_e32 v212, 0x80000000, v212
	v_xor_b32_e32 v4, v4, v212
	v_and_or_b32 v4, v4, s30, 59
	v_ashrrev_i32_e32 v212, 31, v5
	v_or_b32_e32 v212, 0x80000000, v212
	v_xor_b32_e32 v5, v5, v212
	v_and_or_b32 v5, v5, s30, 58
	v_ashrrev_i32_e32 v212, 31, v6
	v_or_b32_e32 v212, 0x80000000, v212
	v_xor_b32_e32 v6, v6, v212
	v_and_or_b32 v6, v6, s30, 57
	v_ashrrev_i32_e32 v212, 31, v7
	v_or_b32_e32 v212, 0x80000000, v212
	v_xor_b32_e32 v7, v7, v212
	v_and_or_b32 v7, v7, s30, 56
	v_ashrrev_i32_e32 v212, 31, v8
	v_or_b32_e32 v212, 0x80000000, v212
	v_xor_b32_e32 v8, v8, v212
	v_and_or_b32 v8, v8, s30, 55
	v_ashrrev_i32_e32 v212, 31, v9
	v_or_b32_e32 v212, 0x80000000, v212
	v_xor_b32_e32 v9, v9, v212
	v_and_or_b32 v9, v9, s30, 54
	v_ashrrev_i32_e32 v212, 31, v10
	v_or_b32_e32 v212, 0x80000000, v212
	v_xor_b32_e32 v10, v10, v212
	v_and_or_b32 v10, v10, s30, 53
	v_ashrrev_i32_e32 v212, 31, v11
	v_or_b32_e32 v212, 0x80000000, v212
	v_xor_b32_e32 v11, v11, v212
	v_and_or_b32 v11, v11, s30, 52
	v_ashrrev_i32_e32 v212, 31, v12
	v_or_b32_e32 v212, 0x80000000, v212
	v_xor_b32_e32 v12, v12, v212
	v_and_or_b32 v12, v12, s30, 51
	v_ashrrev_i32_e32 v212, 31, v13
	v_or_b32_e32 v212, 0x80000000, v212
	v_xor_b32_e32 v13, v13, v212
	v_and_or_b32 v13, v13, s30, 50
	v_ashrrev_i32_e32 v212, 31, v14
	v_or_b32_e32 v212, 0x80000000, v212
	v_xor_b32_e32 v14, v14, v212
	v_and_or_b32 v14, v14, s30, 49
	v_ashrrev_i32_e32 v212, 31, v15
	v_or_b32_e32 v212, 0x80000000, v212
	v_xor_b32_e32 v15, v15, v212
	v_and_or_b32 v15, v15, s30, 48
	v_ashrrev_i32_e32 v212, 31, v16
	v_or_b32_e32 v212, 0x80000000, v212
	v_xor_b32_e32 v16, v16, v212
	v_and_or_b32 v16, v16, s30, 47
	v_ashrrev_i32_e32 v212, 31, v17
	v_or_b32_e32 v212, 0x80000000, v212
	v_xor_b32_e32 v17, v17, v212
	v_and_or_b32 v17, v17, s30, 46
	v_ashrrev_i32_e32 v212, 31, v18
	v_or_b32_e32 v212, 0x80000000, v212
	v_xor_b32_e32 v18, v18, v212
	v_and_or_b32 v18, v18, s30, 45
	v_ashrrev_i32_e32 v212, 31, v19
	v_or_b32_e32 v212, 0x80000000, v212
	v_xor_b32_e32 v19, v19, v212
	v_and_or_b32 v19, v19, s30, 44
	v_ashrrev_i32_e32 v212, 31, v20
	v_or_b32_e32 v212, 0x80000000, v212
	v_xor_b32_e32 v20, v20, v212
	v_and_or_b32 v20, v20, s30, 43
	v_ashrrev_i32_e32 v212, 31, v21
	v_or_b32_e32 v212, 0x80000000, v212
	v_xor_b32_e32 v21, v21, v212
	v_and_or_b32 v21, v21, s30, 42
	v_ashrrev_i32_e32 v212, 31, v22
	v_or_b32_e32 v212, 0x80000000, v212
	v_xor_b32_e32 v22, v22, v212
	v_and_or_b32 v22, v22, s30, 41
	v_ashrrev_i32_e32 v212, 31, v23
	v_or_b32_e32 v212, 0x80000000, v212
	v_xor_b32_e32 v23, v23, v212
	v_and_or_b32 v23, v23, s30, 40
	v_ashrrev_i32_e32 v212, 31, v24
	v_or_b32_e32 v212, 0x80000000, v212
	v_xor_b32_e32 v24, v24, v212
	v_and_or_b32 v24, v24, s30, 39
	v_ashrrev_i32_e32 v212, 31, v25
	v_or_b32_e32 v212, 0x80000000, v212
	v_xor_b32_e32 v25, v25, v212
	v_and_or_b32 v25, v25, s30, 38
	v_ashrrev_i32_e32 v212, 31, v26
	v_or_b32_e32 v212, 0x80000000, v212
	v_xor_b32_e32 v26, v26, v212
	v_and_or_b32 v26, v26, s30, 37
	v_ashrrev_i32_e32 v212, 31, v27
	v_or_b32_e32 v212, 0x80000000, v212
	v_xor_b32_e32 v27, v27, v212
	v_and_or_b32 v27, v27, s30, 36
	v_ashrrev_i32_e32 v212, 31, v28
	v_or_b32_e32 v212, 0x80000000, v212
	v_xor_b32_e32 v28, v28, v212
	v_and_or_b32 v28, v28, s30, 35
	v_ashrrev_i32_e32 v212, 31, v29
	v_or_b32_e32 v212, 0x80000000, v212
	v_xor_b32_e32 v29, v29, v212
	v_and_or_b32 v29, v29, s30, 34
	v_ashrrev_i32_e32 v212, 31, v30
	v_or_b32_e32 v212, 0x80000000, v212
	v_xor_b32_e32 v30, v30, v212
	v_and_or_b32 v30, v30, s30, 33
	v_ashrrev_i32_e32 v212, 31, v31
	v_or_b32_e32 v212, 0x80000000, v212
	v_xor_b32_e32 v31, v31, v212
	v_and_or_b32 v31, v31, s30, 32
	v_max_u32_e32 v215, v0, v1
	v_min_u32_e32 v1, v0, v1
	v_max_u32_e32 v214, v16, v17
	v_min_u32_e32 v17, v16, v17
	v_max_u32_e32 v213, v2, v3
	v_min_u32_e32 v3, v2, v3
	v_max_u32_e32 v0, v18, v19
	v_min_u32_e32 v19, v18, v19
	v_max_u32_e32 v16, v4, v5
	v_min_u32_e32 v5, v4, v5
	v_max_u32_e32 v2, v20, v21
	v_min_u32_e32 v21, v20, v21
	v_max_u32_e32 v18, v6, v7
	v_min_u32_e32 v7, v6, v7
	v_max_u32_e32 v4, v22, v23
	v_min_u32_e32 v23, v22, v23
	v_max_u32_e32 v20, v8, v9
	v_min_u32_e32 v9, v8, v9
	v_max_u32_e32 v6, v24, v25
	v_min_u32_e32 v25, v24, v25
	v_max_u32_e32 v22, v10, v11
	v_min_u32_e32 v11, v10, v11
	v_max_u32_e32 v8, v26, v27
	v_min_u32_e32 v27, v26, v27
	v_max_u32_e32 v24, v12, v13
	v_min_u32_e32 v13, v12, v13
	v_max_u32_e32 v10, v28, v29
	v_min_u32_e32 v29, v28, v29
	v_max_u32_e32 v26, v14, v15
	v_min_u32_e32 v15, v14, v15
	v_max_u32_e32 v12, v30, v31
	v_min_u32_e32 v31, v30, v31
	v_max_u32_e32 v28, v215, v213
	v_min_u32_e32 v213, v215, v213
	v_max_u32_e32 v14, v214, v0
	v_min_u32_e32 v0, v214, v0
	v_max_u32_e32 v30, v1, v3
	v_min_u32_e32 v3, v1, v3
	v_max_u32_e32 v215, v17, v19
	v_min_u32_e32 v19, v17, v19
	v_max_u32_e32 v214, v16, v18
	v_min_u32_e32 v18, v16, v18
	v_max_u32_e32 v1, v2, v4
	v_min_u32_e32 v4, v2, v4
	v_max_u32_e32 v17, v5, v7
	v_min_u32_e32 v7, v5, v7
	v_max_u32_e32 v16, v21, v23
	v_min_u32_e32 v23, v21, v23
	v_max_u32_e32 v2, v20, v22
	v_min_u32_e32 v22, v20, v22
	v_max_u32_e32 v5, v6, v8
	v_min_u32_e32 v8, v6, v8
; __device__ void ph_peer(const float* __restrict__ SC, const bf16_t* __restrict__ H  , const float* __restrict__ gffn, const unsigned char* __restrict__ U, const unsigned char* __restrict__ V, float* X, const float* __restrict__ fgain) {
;     ...
;             for (int it = 0; it < 16; ++it) {
; #pragma unroll
;                 for (int u = 0; u < 2; ++u) {
;                     const unsigned m0 = wave_max_u32(k00[u] > k01[u] ? k00[u] : k01[u]);
;                     const unsigned m1 = wave_max_u32(k10[u] > k11[u] ? k10[u] : k11[u]);
;                     if (lane == it) { top0[u] = m0; top1[u] = m1; }
;                     if (k00[u] == m0) k00[u] = 0u; if (k01[u] == m0) k01[u] = 0u;
;                     if (k10[u] == m1) k10[u] = 0u; if (k11[u] == m1) k11[u] = 0u; }
;             }
	v_max_u32_e32 v21, v9, v11
	v_min_u32_e32 v11, v9, v11
	v_max_u32_e32 v20, v25, v27
	v_min_u32_e32 v27, v25, v27
	v_max_u32_e32 v6, v24, v26
	v_min_u32_e32 v26, v24, v26
	v_max_u32_e32 v9, v10, v12
	v_min_u32_e32 v12, v10, v12
	v_max_u32_e32 v25, v13, v15
	v_min_u32_e32 v15, v13, v15
	v_max_u32_e32 v24, v29, v31
	v_min_u32_e32 v31, v29, v31
	v_max_u32_e32 v10, v30, v213
	v_min_u32_e32 v213, v30, v213
	v_max_u32_e32 v13, v215, v0
	v_min_u32_e32 v0, v215, v0
	v_max_u32_e32 v29, v17, v18
	v_min_u32_e32 v18, v17, v18
	v_max_u32_e32 v30, v16, v4
	v_min_u32_e32 v4, v16, v4
	v_max_u32_e32 v215, v21, v22
	v_min_u32_e32 v22, v21, v22
	v_max_u32_e32 v17, v20, v8
	v_min_u32_e32 v8, v20, v8
	v_max_u32_e32 v16, v25, v26
	v_min_u32_e32 v26, v25, v26
	v_max_u32_e32 v21, v24, v12
	v_min_u32_e32 v12, v24, v12
	v_max_u32_e32 v20, v28, v214
	v_min_u32_e32 v214, v28, v214
	v_max_u32_e32 v25, v14, v1
	v_min_u32_e32 v1, v14, v1
	v_max_u32_e32 v24, v10, v29
	v_min_u32_e32 v29, v10, v29
	v_max_u32_e32 v28, v13, v30
	v_min_u32_e32 v30, v13, v30
	v_max_u32_e32 v14, v213, v18
	v_min_u32_e32 v18, v213, v18
	v_max_u32_e32 v10, v0, v4
	v_min_u32_e32 v4, v0, v4
	v_max_u32_e32 v13, v3, v7
	v_min_u32_e32 v7, v3, v7
	v_max_u32_e32 v213, v19, v23
	v_min_u32_e32 v23, v19, v23
	v_max_u32_e32 v0, v2, v6
	v_min_u32_e32 v6, v2, v6
	v_max_u32_e32 v3, v5, v9
	v_min_u32_e32 v9, v5, v9
	v_max_u32_e32 v19, v215, v16
	v_min_u32_e32 v16, v215, v16
	v_max_u32_e32 v2, v17, v21
	v_min_u32_e32 v21, v17, v21
	v_max_u32_e32 v5, v22, v26
	v_min_u32_e32 v26, v22, v26
	v_max_u32_e32 v215, v8, v12
	v_min_u32_e32 v12, v8, v12
	v_max_u32_e32 v17, v11, v15
	v_min_u32_e32 v15, v11, v15
	v_max_u32_e32 v22, v27, v31
	v_min_u32_e32 v31, v27, v31
	v_max_u32_e32 v8, v14, v214
	v_min_u32_e32 v214, v14, v214
	v_max_u32_e32 v11, v10, v1
	v_min_u32_e32 v1, v10, v1
	v_max_u32_e32 v27, v13, v29
	v_min_u32_e32 v29, v13, v29
	v_max_u32_e32 v14, v213, v30
	v_min_u32_e32 v30, v213, v30
	v_max_u32_e32 v10, v5, v6
	v_min_u32_e32 v6, v5, v6
	v_max_u32_e32 v13, v215, v9
	v_min_u32_e32 v9, v215, v9
	v_max_u32_e32 v213, v17, v16
	v_min_u32_e32 v16, v17, v16
	v_max_u32_e32 v5, v22, v21
	v_min_u32_e32 v21, v22, v21
	v_max_u32_e32 v215, v24, v8
	v_min_u32_e32 v8, v24, v8
	v_max_u32_e32 v17, v28, v11
	v_min_u32_e32 v11, v28, v11
	v_max_u32_e32 v22, v27, v214
	v_min_u32_e32 v214, v27, v214
	v_max_u32_e32 v24, v14, v1
	v_min_u32_e32 v1, v14, v1
	v_max_u32_e32 v28, v29, v18
	v_min_u32_e32 v18, v29, v18
	v_max_u32_e32 v27, v30, v4
	v_min_u32_e32 v4, v30, v4
	v_max_u32_e32 v14, v19, v10
	v_min_u32_e32 v10, v19, v10
	v_max_u32_e32 v29, v2, v13
	v_min_u32_e32 v13, v2, v13
	v_max_u32_e32 v30, v213, v6
	v_min_u32_e32 v6, v213, v6
	v_max_u32_e32 v19, v5, v9
	v_min_u32_e32 v9, v5, v9
	v_max_u32_e32 v2, v16, v26
	v_min_u32_e32 v26, v16, v26
	v_max_u32_e32 v213, v21, v12
	v_min_u32_e32 v12, v21, v12
	v_max_u32_e32 v5, v20, v0
	v_min_u32_e32 v0, v20, v0
	v_max_u32_e32 v16, v25, v3
	v_min_u32_e32 v3, v25, v3
	v_max_u32_e32 v21, v215, v14
	v_min_u32_e32 v14, v215, v14
	v_max_u32_e32 v20, v17, v29
	v_min_u32_e32 v29, v17, v29
	v_max_u32_e32 v25, v8, v10
	v_min_u32_e32 v10, v8, v10
	v_max_u32_e32 v215, v11, v13
	v_min_u32_e32 v13, v11, v13
	v_max_u32_e32 v17, v22, v30
	v_min_u32_e32 v30, v22, v30
	v_max_u32_e32 v8, v24, v19
	v_min_u32_e32 v19, v24, v19
	v_max_u32_e32 v11, v214, v6
	v_min_u32_e32 v6, v214, v6
	v_max_u32_e32 v22, v1, v9
	v_min_u32_e32 v9, v1, v9
	v_max_u32_e32 v24, v28, v2
	v_min_u32_e32 v2, v28, v2
	v_max_u32_e32 v214, v27, v213
	v_min_u32_e32 v213, v27, v213
	v_max_u32_e32 v1, v18, v26
	v_min_u32_e32 v26, v18, v26
	v_max_u32_e32 v28, v4, v12
	v_min_u32_e32 v12, v4, v12
	v_max_u32_e32 v27, v7, v15
	v_min_u32_e32 v15, v7, v15
	v_max_u32_e32 v18, v23, v31
	v_min_u32_e32 v31, v23, v31
	v_max_u32_e32 v4, v11, v0
	v_min_u32_e32 v0, v11, v0
	v_max_u32_e32 v7, v22, v3
	v_min_u32_e32 v3, v22, v3
	v_max_u32_e32 v23, v24, v14
	v_min_u32_e32 v14, v24, v14
	v_max_u32_e32 v11, v214, v29
	v_min_u32_e32 v29, v214, v29
	v_max_u32_e32 v22, v1, v10
	v_min_u32_e32 v10, v1, v10
	v_max_u32_e32 v24, v28, v13
	v_min_u32_e32 v13, v28, v13
	v_max_u32_e32 v214, v27, v30
	v_min_u32_e32 v30, v27, v30
	v_max_u32_e32 v1, v18, v19
	v_min_u32_e32 v19, v18, v19
	v_max_u32_e32 v28, v25, v4
	v_min_u32_e32 v4, v25, v4
	v_max_u32_e32 v27, v215, v7
	v_min_u32_e32 v7, v215, v7
	v_max_u32_e32 v18, v17, v23
	v_min_u32_e32 v23, v17, v23
	v_max_u32_e32 v25, v8, v11
	v_min_u32_e32 v11, v8, v11
	v_max_u32_e32 v215, v22, v0
	v_min_u32_e32 v0, v22, v0
	v_max_u32_e32 v17, v24, v3
	v_min_u32_e32 v3, v24, v3
	v_max_u32_e32 v8, v214, v14
	v_min_u32_e32 v14, v214, v14
	v_max_u32_e32 v22, v1, v29
	v_min_u32_e32 v29, v1, v29
	v_max_u32_e32 v24, v10, v6
	v_min_u32_e32 v6, v10, v6
	v_max_u32_e32 v214, v13, v9
	v_min_u32_e32 v9, v13, v9
	v_max_u32_e32 v1, v30, v2
	v_min_u32_e32 v2, v30, v2
	v_max_u32_e32 v10, v19, v213
	v_min_u32_e32 v213, v19, v213
	v_max_u32_e32 v13, v21, v28
	v_min_u32_e32 v28, v21, v28
	v_max_u32_e32 v30, v20, v27
	v_min_u32_e32 v27, v20, v27
	v_max_u32_e32 v19, v18, v4
	v_min_u32_e32 v4, v18, v4
	v_max_u32_e32 v21, v25, v7
	v_min_u32_e32 v7, v25, v7
	v_max_u32_e32 v20, v23, v215
	v_min_u32_e32 v215, v23, v215
	v_max_u32_e32 v18, v11, v17
	v_min_u32_e32 v17, v11, v17
	v_max_u32_e32 v25, v8, v0
	v_min_u32_e32 v0, v8, v0
	v_max_u32_e32 v23, v22, v3
	v_min_u32_e32 v3, v22, v3
	v_max_u32_e32 v11, v14, v24
	v_min_u32_e32 v24, v14, v24
	v_max_u32_e32 v8, v29, v214
	v_min_u32_e32 v214, v29, v214
	v_max_u32_e32 v22, v1, v6
	v_min_u32_e32 v6, v1, v6
	v_max_u32_e32 v14, v10, v9
	v_min_u32_e32 v9, v10, v9
	v_max_u32_e32 v29, v2, v26
	v_min_u32_e32 v26, v2, v26
; __device__ __forceinline__ unsigned f2key(float f) { const unsigned u = __float_as_uint(f); return (u & 0x80000000u) ? ~u : (u | 0x80000000u); }
; __device__ void ph_peer(const float* __restrict__ SC, const bf16_t* __restrict__ H  , const float* __restrict__ gffn, const unsigned char* __restrict__ U, const unsigned char* __restrict__ V, float* X, const float* __restrict__ fgain) {
;     ...
;             for (int u = 0; u < 2; ++u) { const float* sc = SC + (size_t)tok * 2048 + (h + u) * 256;
;                 const float2 a0 = ((const float2*)sc)[lane], a1 = ((const float2*)(sc + 128))[lane];
;                 k00[u] = (f2key(a0.x) & ~127u) | (unsigned)(127 - 2 * lane); k01[u] = (f2key(a0.y) & ~127u) | (unsigned)(126 - 2 * lane);
;                 k10[u] = (f2key(a1.x) & ~127u) | (unsigned)(127 - 2 * lane); k11[u] = (f2key(a1.y) & ~127u) | (unsigned)(126 - 2 * lane);
;                 top0[u] = 0u; top1[u] = 0u; }
;             for (int it = 0; it < 16; ++it) {
; #pragma unroll
;                 for (int u = 0; u < 2; ++u) {
;                     const unsigned m0 = wave_max_u32(k00[u] > k01[u] ? k00[u] : k01[u]);
;                     const unsigned m1 = wave_max_u32(k10[u] > k11[u] ? k10[u] : k11[u]);
;                     if (lane == it) { top0[u] = m0; top1[u] = m1; }
;                     if (k00[u] == m0) k00[u] = 0u; if (k01[u] == m0) k01[u] = 0u;
;                     if (k10[u] == m1) k10[u] = 0u; if (k11[u] == m1) k11[u] = 0u; }
;             }
	v_max_u32_e32 v1, v213, v12
	v_min_u32_e32 v12, v213, v12
	v_max_u32_e32 v45, v42, v15
	v_max_u32_e32 v35, v32, v26
	v_max_u32_e32 v39, v37, v29
	v_max_u32_e32 v38, v48, v6
	v_max_u32_e32 v42, v43, v22
	v_max_u32_e32 v32, v41, v24
	v_max_u32_e32 v37, v46, v11
	v_max_u32_e32 v48, v49, v0
	v_max_u32_e32 v43, v47, v25
	v_max_u32_e32 v41, v44, v215
	v_max_u32_e32 v46, v34, v20
	v_max_u32_e32 v49, v36, v4
	v_max_u32_e32 v47, v50, v19
	v_max_u32_e32 v44, v33, v28
	v_max_u32_e32 v34, v51, v13
	v_max_u32_e32 v36, v40, v5
	v_max_u32_e32 v50, v45, v43
	v_min_u32_e32 v43, v45, v43
	v_max_u32_e32 v33, v35, v41
	v_min_u32_e32 v41, v35, v41
	v_max_u32_e32 v51, v39, v46
	v_min_u32_e32 v46, v39, v46
	v_max_u32_e32 v40, v38, v49
	v_min_u32_e32 v49, v38, v49
	v_max_u32_e32 v45, v42, v47
	v_min_u32_e32 v47, v42, v47
	v_max_u32_e32 v35, v32, v44
	v_min_u32_e32 v44, v32, v44
	v_max_u32_e32 v39, v37, v34
	v_min_u32_e32 v34, v37, v34
	v_max_u32_e32 v38, v48, v36
	v_min_u32_e32 v36, v48, v36
	v_max_u32_e32 v42, v50, v45
	v_min_u32_e32 v45, v50, v45
	v_max_u32_e32 v32, v33, v35
	v_min_u32_e32 v35, v33, v35
	v_max_u32_e32 v37, v51, v39
	v_min_u32_e32 v39, v51, v39
	v_max_u32_e32 v48, v40, v38
	v_min_u32_e32 v38, v40, v38
	v_max_u32_e32 v50, v43, v47
	v_min_u32_e32 v47, v43, v47
	v_max_u32_e32 v33, v41, v44
	v_min_u32_e32 v44, v41, v44
	v_max_u32_e32 v51, v46, v34
	v_min_u32_e32 v34, v46, v34
	v_max_u32_e32 v40, v49, v36
	v_min_u32_e32 v36, v49, v36
	v_max_u32_e32 v43, v42, v37
	v_min_u32_e32 v37, v42, v37
	v_max_u32_e32 v41, v32, v48
	v_min_u32_e32 v48, v32, v48
	v_max_u32_e32 v46, v45, v39
	v_min_u32_e32 v39, v45, v39
	v_max_u32_e32 v49, v35, v38
	v_min_u32_e32 v38, v35, v38
	v_max_u32_e32 v42, v50, v51
	v_min_u32_e32 v51, v50, v51
	v_max_u32_e32 v32, v33, v40
	v_min_u32_e32 v40, v33, v40
	v_max_u32_e32 v45, v47, v34
	v_min_u32_e32 v34, v47, v34
	v_max_u32_e32 v35, v44, v36
	v_min_u32_e32 v36, v44, v36
	v_max_u32_e32 v50, v43, v41
	v_min_u32_e32 v41, v43, v41
	v_max_u32_e32 v33, v37, v48
	v_min_u32_e32 v48, v37, v48
	v_max_u32_e32 v47, v46, v49
	v_min_u32_e32 v49, v46, v49
	v_max_u32_e32 v44, v39, v38
	v_min_u32_e32 v38, v39, v38
	v_max_u32_e32 v43, v42, v32
	v_min_u32_e32 v32, v42, v32
	v_max_u32_e32 v37, v51, v40
	v_min_u32_e32 v40, v51, v40
	v_max_u32_e32 v46, v45, v35
	v_min_u32_e32 v35, v45, v35
	v_max_u32_e32 v39, v34, v36
	v_min_u32_e32 v36, v34, v36
	v_max_u32_e32 v42, v50, v31
	v_max_u32_e32 v51, v41, v12
	v_max_u32_e32 v45, v33, v1
	v_max_u32_e32 v34, v48, v9
	v_max_u32_e32 v50, v47, v14
	v_max_u32_e32 v41, v49, v214
	v_max_u32_e32 v33, v44, v8
	v_max_u32_e32 v48, v38, v3
	v_max_u32_e32 v47, v43, v23
	v_max_u32_e32 v49, v32, v17
	v_max_u32_e32 v44, v37, v18
	v_max_u32_e32 v38, v40, v7
	v_max_u32_e32 v43, v46, v21
	v_max_u32_e32 v32, v35, v27
	v_max_u32_e32 v37, v39, v30
	v_max_u32_e32 v40, v36, v16
	v_max_u32_e32 v46, v42, v47
	v_min_u32_e32 v47, v42, v47
	v_max_u32_e32 v35, v51, v49
	v_min_u32_e32 v49, v51, v49
	v_max_u32_e32 v39, v45, v44
	v_min_u32_e32 v44, v45, v44
	v_max_u32_e32 v36, v34, v38
	v_min_u32_e32 v38, v34, v38
	v_max_u32_e32 v42, v50, v43
	v_min_u32_e32 v43, v50, v43
	v_max_u32_e32 v51, v41, v32
	v_min_u32_e32 v32, v41, v32
	v_max_u32_e32 v45, v33, v37
	v_min_u32_e32 v37, v33, v37
	v_max_u32_e32 v34, v48, v40
	v_min_u32_e32 v40, v48, v40
	v_max_u32_e32 v50, v46, v42
	v_min_u32_e32 v42, v46, v42
	v_max_u32_e32 v41, v35, v51
	v_min_u32_e32 v51, v35, v51
	v_max_u32_e32 v33, v39, v45
	v_min_u32_e32 v45, v39, v45
	v_max_u32_e32 v48, v36, v34
	v_min_u32_e32 v34, v36, v34
	v_max_u32_e32 v46, v47, v43
	v_min_u32_e32 v43, v47, v43
	v_max_u32_e32 v35, v49, v32
	v_min_u32_e32 v32, v49, v32
	v_max_u32_e32 v39, v44, v37
	v_min_u32_e32 v37, v44, v37
	v_max_u32_e32 v36, v38, v40
	v_min_u32_e32 v40, v38, v40
	v_max_u32_e32 v47, v50, v33
	v_min_u32_e32 v33, v50, v33
	v_max_u32_e32 v49, v41, v48
	v_min_u32_e32 v48, v41, v48
	v_max_u32_e32 v44, v42, v45
	v_min_u32_e32 v45, v42, v45
	v_max_u32_e32 v38, v51, v34
	v_min_u32_e32 v34, v51, v34
	v_max_u32_e32 v50, v46, v39
	v_min_u32_e32 v39, v46, v39
	v_max_u32_e32 v41, v35, v36
	v_min_u32_e32 v36, v35, v36
	v_max_u32_e32 v42, v43, v37
	v_min_u32_e32 v37, v43, v37
	v_max_u32_e32 v51, v32, v40
	v_min_u32_e32 v40, v32, v40
	v_max_u32_e32 v46, v47, v49
	v_min_u32_e32 v49, v47, v49
	v_max_u32_e32 v35, v33, v48
	v_min_u32_e32 v48, v33, v48
	v_max_u32_e32 v43, v44, v38
	v_min_u32_e32 v38, v44, v38
	v_max_u32_e32 v32, v45, v34
	v_min_u32_e32 v34, v45, v34
	v_max_u32_e32 v47, v50, v41
	v_min_u32_e32 v41, v50, v41
	v_max_u32_e32 v33, v39, v36
	v_min_u32_e32 v36, v39, v36
	v_max_u32_e32 v44, v42, v51
	v_min_u32_e32 v51, v42, v51
	v_max_u32_e32 v45, v37, v40
	v_min_u32_e32 v40, v37, v40
	s_waitcnt vmcnt(0)
	ds_write_b128 v144, v[52:55] offset:0
	ds_write_b128 v144, v[56:59] offset:1152
	ds_write_b128 v144, v[60:63] offset:2304
	ds_write_b128 v144, v[112:115] offset:3456
	ds_write_b128 v144, v[116:119] offset:4608
	ds_write_b128 v144, v[120:123] offset:5760
	ds_write_b128 v144, v[124:127] offset:6912
	ds_write_b128 v144, v[158:161] offset:8064
	ds_read_b128 v[0:3], v145 offset:0
	ds_read_b128 v[4:7], v145 offset:16
	ds_read_b128 v[8:11], v145 offset:32
	ds_read_b128 v[12:15], v145 offset:48
	ds_read_b128 v[16:19], v145 offset:64
	ds_read_b128 v[20:23], v145 offset:80
	ds_read_b128 v[24:27], v145 offset:96
	ds_read_b128 v[28:31], v145 offset:112
	s_waitcnt lgkmcnt(0)
; __device__ __forceinline__ unsigned f2key(float f) { const unsigned u = __float_as_uint(f); return (u & 0x80000000u) ? ~u : (u | 0x80000000u); }
; __device__ void ph_peer(const float* __restrict__ SC, const bf16_t* __restrict__ H  , const float* __restrict__ gffn, const unsigned char* __restrict__ U, const unsigned char* __restrict__ V, float* X, const float* __restrict__ fgain) {
;     ...
;             for (int u = 0; u < 2; ++u) { const float* sc = SC + (size_t)tok * 2048 + (h + u) * 256;
;                 const float2 a0 = ((const float2*)sc)[lane], a1 = ((const float2*)(sc + 128))[lane];
;                 k00[u] = (f2key(a0.x) & ~127u) | (unsigned)(127 - 2 * lane); k01[u] = (f2key(a0.y) & ~127u) | (unsigned)(126 - 2 * lane);
;                 k10[u] = (f2key(a1.x) & ~127u) | (unsigned)(127 - 2 * lane); k11[u] = (f2key(a1.y) & ~127u) | (unsigned)(126 - 2 * lane);
;                 top0[u] = 0u; top1[u] = 0u; }
;             for (int it = 0; it < 16; ++it) {
; #pragma unroll
;                 for (int u = 0; u < 2; ++u) {
;                     const unsigned m0 = wave_max_u32(k00[u] > k01[u] ? k00[u] : k01[u]);
;                     const unsigned m1 = wave_max_u32(k10[u] > k11[u] ? k10[u] : k11[u]);
;                     if (lane == it) { top0[u] = m0; top1[u] = m1; }
;                     if (k00[u] == m0) k00[u] = 0u; if (k01[u] == m0) k01[u] = 0u;
;                     if (k10[u] == m1) k10[u] = 0u; if (k11[u] == m1) k11[u] = 0u; }
;             }
	v_ashrrev_i32_e32 v212, 31, v0
	v_or_b32_e32 v212, 0x80000000, v212
	v_xor_b32_e32 v0, v0, v212
	v_and_or_b32 v0, v0, s30, 31
	v_ashrrev_i32_e32 v212, 31, v1
	v_or_b32_e32 v212, 0x80000000, v212
	v_xor_b32_e32 v1, v1, v212
	v_and_or_b32 v1, v1, s30, 30
	v_ashrrev_i32_e32 v212, 31, v2
	v_or_b32_e32 v212, 0x80000000, v212
	v_xor_b32_e32 v2, v2, v212
	v_and_or_b32 v2, v2, s30, 29
	v_ashrrev_i32_e32 v212, 31, v3
	v_or_b32_e32 v212, 0x80000000, v212
	v_xor_b32_e32 v3, v3, v212
	v_and_or_b32 v3, v3, s30, 28
	v_ashrrev_i32_e32 v212, 31, v4
	v_or_b32_e32 v212, 0x80000000, v212
	v_xor_b32_e32 v4, v4, v212
	v_and_or_b32 v4, v4, s30, 27
	v_ashrrev_i32_e32 v212, 31, v5
	v_or_b32_e32 v212, 0x80000000, v212
	v_xor_b32_e32 v5, v5, v212
	v_and_or_b32 v5, v5, s30, 26
	v_ashrrev_i32_e32 v212, 31, v6
	v_or_b32_e32 v212, 0x80000000, v212
	v_xor_b32_e32 v6, v6, v212
	v_and_or_b32 v6, v6, s30, 25
	v_ashrrev_i32_e32 v212, 31, v7
	v_or_b32_e32 v212, 0x80000000, v212
	v_xor_b32_e32 v7, v7, v212
	v_and_or_b32 v7, v7, s30, 24
	v_ashrrev_i32_e32 v212, 31, v8
	v_or_b32_e32 v212, 0x80000000, v212
	v_xor_b32_e32 v8, v8, v212
	v_and_or_b32 v8, v8, s30, 23
	v_ashrrev_i32_e32 v212, 31, v9
	v_or_b32_e32 v212, 0x80000000, v212
	v_xor_b32_e32 v9, v9, v212
	v_and_or_b32 v9, v9, s30, 22
	v_ashrrev_i32_e32 v212, 31, v10
	v_or_b32_e32 v212, 0x80000000, v212
	v_xor_b32_e32 v10, v10, v212
	v_and_or_b32 v10, v10, s30, 21
	v_ashrrev_i32_e32 v212, 31, v11
	v_or_b32_e32 v212, 0x80000000, v212
	v_xor_b32_e32 v11, v11, v212
	v_and_or_b32 v11, v11, s30, 20
	v_ashrrev_i32_e32 v212, 31, v12
	v_or_b32_e32 v212, 0x80000000, v212
	v_xor_b32_e32 v12, v12, v212
	v_and_or_b32 v12, v12, s30, 19
	v_ashrrev_i32_e32 v212, 31, v13
	v_or_b32_e32 v212, 0x80000000, v212
	v_xor_b32_e32 v13, v13, v212
	v_and_or_b32 v13, v13, s30, 18
	v_ashrrev_i32_e32 v212, 31, v14
	v_or_b32_e32 v212, 0x80000000, v212
	v_xor_b32_e32 v14, v14, v212
	v_and_or_b32 v14, v14, s30, 17
	v_ashrrev_i32_e32 v212, 31, v15
	v_or_b32_e32 v212, 0x80000000, v212
	v_xor_b32_e32 v15, v15, v212
	v_and_or_b32 v15, v15, s30, 16
	v_ashrrev_i32_e32 v212, 31, v16
	v_or_b32_e32 v212, 0x80000000, v212
	v_xor_b32_e32 v16, v16, v212
	v_and_or_b32 v16, v16, s30, 15
	v_ashrrev_i32_e32 v212, 31, v17
	v_or_b32_e32 v212, 0x80000000, v212
	v_xor_b32_e32 v17, v17, v212
	v_and_or_b32 v17, v17, s30, 14
	v_ashrrev_i32_e32 v212, 31, v18
	v_or_b32_e32 v212, 0x80000000, v212
	v_xor_b32_e32 v18, v18, v212
	v_and_or_b32 v18, v18, s30, 13
	v_ashrrev_i32_e32 v212, 31, v19
	v_or_b32_e32 v212, 0x80000000, v212
	v_xor_b32_e32 v19, v19, v212
	v_and_or_b32 v19, v19, s30, 12
	v_ashrrev_i32_e32 v212, 31, v20
	v_or_b32_e32 v212, 0x80000000, v212
	v_xor_b32_e32 v20, v20, v212
	v_and_or_b32 v20, v20, s30, 11
	v_ashrrev_i32_e32 v212, 31, v21
	v_or_b32_e32 v212, 0x80000000, v212
	v_xor_b32_e32 v21, v21, v212
	v_and_or_b32 v21, v21, s30, 10
	v_ashrrev_i32_e32 v212, 31, v22
	v_or_b32_e32 v212, 0x80000000, v212
	v_xor_b32_e32 v22, v22, v212
	v_and_or_b32 v22, v22, s30, 9
	v_ashrrev_i32_e32 v212, 31, v23
	v_or_b32_e32 v212, 0x80000000, v212
	v_xor_b32_e32 v23, v23, v212
	v_and_or_b32 v23, v23, s30, 8
	v_ashrrev_i32_e32 v212, 31, v24
	v_or_b32_e32 v212, 0x80000000, v212
	v_xor_b32_e32 v24, v24, v212
	v_and_or_b32 v24, v24, s30, 7
	v_ashrrev_i32_e32 v212, 31, v25
	v_or_b32_e32 v212, 0x80000000, v212
	v_xor_b32_e32 v25, v25, v212
	v_and_or_b32 v25, v25, s30, 6
	v_ashrrev_i32_e32 v212, 31, v26
	v_or_b32_e32 v212, 0x80000000, v212
	v_xor_b32_e32 v26, v26, v212
	v_and_or_b32 v26, v26, s30, 5
	v_ashrrev_i32_e32 v212, 31, v27
	v_or_b32_e32 v212, 0x80000000, v212
	v_xor_b32_e32 v27, v27, v212
	v_and_or_b32 v27, v27, s30, 4
	v_ashrrev_i32_e32 v212, 31, v28
	v_or_b32_e32 v212, 0x80000000, v212
	v_xor_b32_e32 v28, v28, v212
	v_and_or_b32 v28, v28, s30, 3
	v_ashrrev_i32_e32 v212, 31, v29
	v_or_b32_e32 v212, 0x80000000, v212
	v_xor_b32_e32 v29, v29, v212
	v_and_or_b32 v29, v29, s30, 2
	v_ashrrev_i32_e32 v212, 31, v30
	v_or_b32_e32 v212, 0x80000000, v212
	v_xor_b32_e32 v30, v30, v212
	v_and_or_b32 v30, v30, s30, 1
	v_ashrrev_i32_e32 v212, 31, v31
	v_or_b32_e32 v212, 0x80000000, v212
	v_xor_b32_e32 v31, v31, v212
	v_and_or_b32 v31, v31, s30, 0
	v_max_u32_e32 v215, v0, v1
	v_min_u32_e32 v1, v0, v1
	v_max_u32_e32 v214, v16, v17
	v_min_u32_e32 v17, v16, v17
	v_max_u32_e32 v213, v2, v3
	v_min_u32_e32 v3, v2, v3
	v_max_u32_e32 v0, v18, v19
	v_min_u32_e32 v19, v18, v19
	v_max_u32_e32 v16, v4, v5
	v_min_u32_e32 v5, v4, v5
	v_max_u32_e32 v2, v20, v21
	v_min_u32_e32 v21, v20, v21
	v_max_u32_e32 v18, v6, v7
	v_min_u32_e32 v7, v6, v7
	v_max_u32_e32 v4, v22, v23
	v_min_u32_e32 v23, v22, v23
	v_max_u32_e32 v20, v8, v9
	v_min_u32_e32 v9, v8, v9
	v_max_u32_e32 v6, v24, v25
	v_min_u32_e32 v25, v24, v25
	v_max_u32_e32 v22, v10, v11
	v_min_u32_e32 v11, v10, v11
	v_max_u32_e32 v8, v26, v27
	v_min_u32_e32 v27, v26, v27
	v_max_u32_e32 v24, v12, v13
	v_min_u32_e32 v13, v12, v13
	v_max_u32_e32 v10, v28, v29
	v_min_u32_e32 v29, v28, v29
	v_max_u32_e32 v26, v14, v15
	v_min_u32_e32 v15, v14, v15
	v_max_u32_e32 v12, v30, v31
	v_min_u32_e32 v31, v30, v31
	v_max_u32_e32 v28, v215, v213
	v_min_u32_e32 v213, v215, v213
	v_max_u32_e32 v14, v214, v0
	v_min_u32_e32 v0, v214, v0
	v_max_u32_e32 v30, v1, v3
	v_min_u32_e32 v3, v1, v3
	v_max_u32_e32 v215, v17, v19
	v_min_u32_e32 v19, v17, v19
	v_max_u32_e32 v214, v16, v18
	v_min_u32_e32 v18, v16, v18
	v_max_u32_e32 v1, v2, v4
	v_min_u32_e32 v4, v2, v4
	v_max_u32_e32 v17, v5, v7
	v_min_u32_e32 v7, v5, v7
	v_max_u32_e32 v16, v21, v23
	v_min_u32_e32 v23, v21, v23
	v_max_u32_e32 v2, v20, v22
	v_min_u32_e32 v22, v20, v22
	v_max_u32_e32 v5, v6, v8
	v_min_u32_e32 v8, v6, v8
; __device__ void ph_peer(const float* __restrict__ SC, const bf16_t* __restrict__ H  , const float* __restrict__ gffn, const unsigned char* __restrict__ U, const unsigned char* __restrict__ V, float* X, const float* __restrict__ fgain) {
;     ...
;             for (int it = 0; it < 16; ++it) {
; #pragma unroll
;                 for (int u = 0; u < 2; ++u) {
;                     const unsigned m0 = wave_max_u32(k00[u] > k01[u] ? k00[u] : k01[u]);
;                     const unsigned m1 = wave_max_u32(k10[u] > k11[u] ? k10[u] : k11[u]);
;                     if (lane == it) { top0[u] = m0; top1[u] = m1; }
;                     if (k00[u] == m0) k00[u] = 0u; if (k01[u] == m0) k01[u] = 0u;
;                     if (k10[u] == m1) k10[u] = 0u; if (k11[u] == m1) k11[u] = 0u; }
;             }
	v_max_u32_e32 v21, v9, v11
	v_min_u32_e32 v11, v9, v11
	v_max_u32_e32 v20, v25, v27
	v_min_u32_e32 v27, v25, v27
	v_max_u32_e32 v6, v24, v26
	v_min_u32_e32 v26, v24, v26
	v_max_u32_e32 v9, v10, v12
	v_min_u32_e32 v12, v10, v12
	v_max_u32_e32 v25, v13, v15
	v_min_u32_e32 v15, v13, v15
	v_max_u32_e32 v24, v29, v31
	v_min_u32_e32 v31, v29, v31
	v_max_u32_e32 v10, v30, v213
	v_min_u32_e32 v213, v30, v213
	v_max_u32_e32 v13, v215, v0
	v_min_u32_e32 v0, v215, v0
	v_max_u32_e32 v29, v17, v18
	v_min_u32_e32 v18, v17, v18
	v_max_u32_e32 v30, v16, v4
	v_min_u32_e32 v4, v16, v4
	v_max_u32_e32 v215, v21, v22
	v_min_u32_e32 v22, v21, v22
	v_max_u32_e32 v17, v20, v8
	v_min_u32_e32 v8, v20, v8
	v_max_u32_e32 v16, v25, v26
	v_min_u32_e32 v26, v25, v26
	v_max_u32_e32 v21, v24, v12
	v_min_u32_e32 v12, v24, v12
	v_max_u32_e32 v20, v28, v214
	v_min_u32_e32 v214, v28, v214
	v_max_u32_e32 v25, v14, v1
	v_min_u32_e32 v1, v14, v1
	v_max_u32_e32 v24, v10, v29
	v_min_u32_e32 v29, v10, v29
	v_max_u32_e32 v28, v13, v30
	v_min_u32_e32 v30, v13, v30
	v_max_u32_e32 v14, v213, v18
	v_min_u32_e32 v18, v213, v18
	v_max_u32_e32 v10, v0, v4
	v_min_u32_e32 v4, v0, v4
	v_max_u32_e32 v13, v3, v7
	v_min_u32_e32 v7, v3, v7
	v_max_u32_e32 v213, v19, v23
	v_min_u32_e32 v23, v19, v23
	v_max_u32_e32 v0, v2, v6
	v_min_u32_e32 v6, v2, v6
	v_max_u32_e32 v3, v5, v9
	v_min_u32_e32 v9, v5, v9
	v_max_u32_e32 v19, v215, v16
	v_min_u32_e32 v16, v215, v16
	v_max_u32_e32 v2, v17, v21
	v_min_u32_e32 v21, v17, v21
	v_max_u32_e32 v5, v22, v26
	v_min_u32_e32 v26, v22, v26
	v_max_u32_e32 v215, v8, v12
	v_min_u32_e32 v12, v8, v12
	v_max_u32_e32 v17, v11, v15
	v_min_u32_e32 v15, v11, v15
	v_max_u32_e32 v22, v27, v31
	v_min_u32_e32 v31, v27, v31
	v_max_u32_e32 v8, v14, v214
	v_min_u32_e32 v214, v14, v214
	v_max_u32_e32 v11, v10, v1
	v_min_u32_e32 v1, v10, v1
	v_max_u32_e32 v27, v13, v29
	v_min_u32_e32 v29, v13, v29
	v_max_u32_e32 v14, v213, v30
	v_min_u32_e32 v30, v213, v30
	v_max_u32_e32 v10, v5, v6
	v_min_u32_e32 v6, v5, v6
	v_max_u32_e32 v13, v215, v9
	v_min_u32_e32 v9, v215, v9
	v_max_u32_e32 v213, v17, v16
	v_min_u32_e32 v16, v17, v16
	v_max_u32_e32 v5, v22, v21
	v_min_u32_e32 v21, v22, v21
	v_max_u32_e32 v215, v24, v8
	v_min_u32_e32 v8, v24, v8
	v_max_u32_e32 v17, v28, v11
	v_min_u32_e32 v11, v28, v11
	v_max_u32_e32 v22, v27, v214
	v_min_u32_e32 v214, v27, v214
	v_max_u32_e32 v24, v14, v1
	v_min_u32_e32 v1, v14, v1
	v_max_u32_e32 v28, v29, v18
	v_min_u32_e32 v18, v29, v18
	v_max_u32_e32 v27, v30, v4
	v_min_u32_e32 v4, v30, v4
	v_max_u32_e32 v14, v19, v10
	v_min_u32_e32 v10, v19, v10
	v_max_u32_e32 v29, v2, v13
	v_min_u32_e32 v13, v2, v13
	v_max_u32_e32 v30, v213, v6
	v_min_u32_e32 v6, v213, v6
	v_max_u32_e32 v19, v5, v9
	v_min_u32_e32 v9, v5, v9
	v_max_u32_e32 v2, v16, v26
	v_min_u32_e32 v26, v16, v26
	v_max_u32_e32 v213, v21, v12
	v_min_u32_e32 v12, v21, v12
	v_max_u32_e32 v5, v20, v0
	v_min_u32_e32 v0, v20, v0
	v_max_u32_e32 v16, v25, v3
	v_min_u32_e32 v3, v25, v3
	v_max_u32_e32 v21, v215, v14
	v_min_u32_e32 v14, v215, v14
	v_max_u32_e32 v20, v17, v29
	v_min_u32_e32 v29, v17, v29
	v_max_u32_e32 v25, v8, v10
	v_min_u32_e32 v10, v8, v10
	v_max_u32_e32 v215, v11, v13
	v_min_u32_e32 v13, v11, v13
	v_max_u32_e32 v17, v22, v30
	v_min_u32_e32 v30, v22, v30
	v_max_u32_e32 v8, v24, v19
	v_min_u32_e32 v19, v24, v19
	v_max_u32_e32 v11, v214, v6
	v_min_u32_e32 v6, v214, v6
	v_max_u32_e32 v22, v1, v9
	v_min_u32_e32 v9, v1, v9
	v_max_u32_e32 v24, v28, v2
	v_min_u32_e32 v2, v28, v2
	v_max_u32_e32 v214, v27, v213
	v_min_u32_e32 v213, v27, v213
	v_max_u32_e32 v1, v18, v26
	v_min_u32_e32 v26, v18, v26
	v_max_u32_e32 v28, v4, v12
	v_min_u32_e32 v12, v4, v12
	v_max_u32_e32 v27, v7, v15
	v_min_u32_e32 v15, v7, v15
	v_max_u32_e32 v18, v23, v31
	v_min_u32_e32 v31, v23, v31
	v_max_u32_e32 v4, v11, v0
	v_min_u32_e32 v0, v11, v0
	v_max_u32_e32 v7, v22, v3
	v_min_u32_e32 v3, v22, v3
	v_max_u32_e32 v23, v24, v14
	v_min_u32_e32 v14, v24, v14
	v_max_u32_e32 v11, v214, v29
	v_min_u32_e32 v29, v214, v29
	v_max_u32_e32 v22, v1, v10
	v_min_u32_e32 v10, v1, v10
	v_max_u32_e32 v24, v28, v13
	v_min_u32_e32 v13, v28, v13
	v_max_u32_e32 v214, v27, v30
	v_min_u32_e32 v30, v27, v30
	v_max_u32_e32 v1, v18, v19
	v_min_u32_e32 v19, v18, v19
	v_max_u32_e32 v28, v25, v4
	v_min_u32_e32 v4, v25, v4
	v_max_u32_e32 v27, v215, v7
	v_min_u32_e32 v7, v215, v7
	v_max_u32_e32 v18, v17, v23
	v_min_u32_e32 v23, v17, v23
	v_max_u32_e32 v25, v8, v11
	v_min_u32_e32 v11, v8, v11
	v_max_u32_e32 v215, v22, v0
	v_min_u32_e32 v0, v22, v0
	v_max_u32_e32 v17, v24, v3
	v_min_u32_e32 v3, v24, v3
	v_max_u32_e32 v8, v214, v14
	v_min_u32_e32 v14, v214, v14
	v_max_u32_e32 v22, v1, v29
	v_min_u32_e32 v29, v1, v29
	v_max_u32_e32 v24, v10, v6
	v_min_u32_e32 v6, v10, v6
	v_max_u32_e32 v214, v13, v9
	v_min_u32_e32 v9, v13, v9
	v_max_u32_e32 v1, v30, v2
	v_min_u32_e32 v2, v30, v2
	v_max_u32_e32 v10, v19, v213
	v_min_u32_e32 v213, v19, v213
	v_max_u32_e32 v13, v21, v28
	v_min_u32_e32 v28, v21, v28
	v_max_u32_e32 v30, v20, v27
	v_min_u32_e32 v27, v20, v27
	v_max_u32_e32 v19, v18, v4
	v_min_u32_e32 v4, v18, v4
	v_max_u32_e32 v21, v25, v7
	v_min_u32_e32 v7, v25, v7
	v_max_u32_e32 v20, v23, v215
	v_min_u32_e32 v215, v23, v215
	v_max_u32_e32 v18, v11, v17
	v_min_u32_e32 v17, v11, v17
	v_max_u32_e32 v25, v8, v0
	v_min_u32_e32 v0, v8, v0
	v_max_u32_e32 v23, v22, v3
	v_min_u32_e32 v3, v22, v3
	v_max_u32_e32 v11, v14, v24
	v_min_u32_e32 v24, v14, v24
	v_max_u32_e32 v8, v29, v214
	v_min_u32_e32 v214, v29, v214
	v_max_u32_e32 v22, v1, v6
	v_min_u32_e32 v6, v1, v6
	v_max_u32_e32 v14, v10, v9
	v_min_u32_e32 v9, v10, v9
	v_max_u32_e32 v29, v2, v26
	v_min_u32_e32 v26, v2, v26
; __device__ __forceinline__ float key2f(unsigned k) { return __uint_as_float((k & 0x80000000u) ? (k & 0x7fffffffu) : ~k); }
; __device__ void ph_peer(const float* __restrict__ SC, const bf16_t* __restrict__ H  , const float* __restrict__ gffn, const unsigned char* __restrict__ U, const unsigned char* __restrict__ V, float* X, const float* __restrict__ fgain) {
;     ...
;             for (int it = 0; it < 16; ++it) {
; #pragma unroll
;                 for (int u = 0; u < 2; ++u) {
;                     const unsigned m0 = wave_max_u32(k00[u] > k01[u] ? k00[u] : k01[u]);
;                     const unsigned m1 = wave_max_u32(k10[u] > k11[u] ? k10[u] : k11[u]);
;                     if (lane == it) { top0[u] = m0; top1[u] = m1; }
;                     if (k00[u] == m0) k00[u] = 0u; if (k01[u] == m0) k01[u] = 0u;
;                     if (k10[u] == m1) k10[u] = 0u; if (k11[u] == m1) k11[u] = 0u; }
;             }
;             const int ci = lane >> 2, cj0 = (lane & 3) * 4;
;             unsigned ck[2][4], best[2]; int n0[2], n1[2];
; #pragma unroll
;             for (int u = 0; u < 2; ++u) {
;                 const float s0 = key2f(top0[u] & ~127u), s1 = key2f(top1[u] & ~127u);
;                 n0[u] = 127 - (int)(top0[u] & 127u); n1[u] = 127 - (int)(top1[u] & 127u);
;                 const float si = __shfl(s0, ci);
	v_max_u32_e32 v1, v213, v12
	v_min_u32_e32 v12, v213, v12
	v_max_u32_e32 v50, v46, v15
	v_max_u32_e32 v39, v49, v26
	v_max_u32_e32 v42, v35, v29
	v_max_u32_e32 v37, v48, v6
	v_max_u32_e32 v46, v43, v22
	v_max_u32_e32 v49, v38, v24
	v_max_u32_e32 v35, v32, v11
	v_max_u32_e32 v48, v34, v0
	v_max_u32_e32 v43, v47, v25
	v_max_u32_e32 v38, v41, v215
	v_max_u32_e32 v32, v33, v20
	v_max_u32_e32 v34, v36, v4
	v_max_u32_e32 v47, v44, v19
	v_max_u32_e32 v41, v51, v28
	v_max_u32_e32 v33, v45, v13
	v_max_u32_e32 v36, v40, v5
	v_max_u32_e32 v44, v50, v43
	v_min_u32_e32 v43, v50, v43
	v_max_u32_e32 v51, v39, v38
	v_min_u32_e32 v38, v39, v38
	v_max_u32_e32 v45, v42, v32
	v_min_u32_e32 v32, v42, v32
	v_max_u32_e32 v40, v37, v34
	v_min_u32_e32 v34, v37, v34
	v_max_u32_e32 v50, v46, v47
	v_min_u32_e32 v47, v46, v47
	v_max_u32_e32 v39, v49, v41
	v_min_u32_e32 v41, v49, v41
	v_max_u32_e32 v42, v35, v33
	v_min_u32_e32 v33, v35, v33
	v_max_u32_e32 v37, v48, v36
	v_min_u32_e32 v36, v48, v36
	v_max_u32_e32 v46, v44, v50
	v_min_u32_e32 v50, v44, v50
	v_max_u32_e32 v49, v51, v39
	v_min_u32_e32 v39, v51, v39
	v_max_u32_e32 v35, v45, v42
	v_min_u32_e32 v42, v45, v42
	v_max_u32_e32 v48, v40, v37
	v_min_u32_e32 v37, v40, v37
	v_max_u32_e32 v44, v43, v47
	v_min_u32_e32 v47, v43, v47
	v_max_u32_e32 v51, v38, v41
	v_min_u32_e32 v41, v38, v41
	v_max_u32_e32 v45, v32, v33
	v_min_u32_e32 v33, v32, v33
	v_max_u32_e32 v40, v34, v36
	v_min_u32_e32 v36, v34, v36
	v_max_u32_e32 v43, v46, v35
	v_min_u32_e32 v35, v46, v35
	v_max_u32_e32 v38, v49, v48
	v_min_u32_e32 v48, v49, v48
	v_max_u32_e32 v32, v50, v42
	v_min_u32_e32 v42, v50, v42
	v_max_u32_e32 v34, v39, v37
	v_min_u32_e32 v37, v39, v37
	v_max_u32_e32 v46, v44, v45
	v_min_u32_e32 v45, v44, v45
	v_max_u32_e32 v49, v51, v40
	v_min_u32_e32 v40, v51, v40
	v_max_u32_e32 v50, v47, v33
	v_min_u32_e32 v33, v47, v33
	v_max_u32_e32 v39, v41, v36
	v_min_u32_e32 v36, v41, v36
	v_max_u32_e32 v44, v43, v38
	v_min_u32_e32 v38, v43, v38
	v_max_u32_e32 v51, v35, v48
	v_min_u32_e32 v48, v35, v48
	v_max_u32_e32 v47, v32, v34
	v_min_u32_e32 v34, v32, v34
	v_max_u32_e32 v41, v42, v37
	v_min_u32_e32 v37, v42, v37
	v_max_u32_e32 v43, v46, v49
	v_min_u32_e32 v49, v46, v49
	v_max_u32_e32 v35, v45, v40
	v_min_u32_e32 v40, v45, v40
	v_max_u32_e32 v32, v50, v39
	v_min_u32_e32 v39, v50, v39
	v_max_u32_e32 v42, v33, v36
	v_min_u32_e32 v36, v33, v36
	v_max_u32_e32 v46, v44, v31
	v_max_u32_e32 v45, v38, v12
	v_max_u32_e32 v50, v51, v1
	v_max_u32_e32 v33, v48, v9
	v_max_u32_e32 v44, v47, v14
	v_max_u32_e32 v38, v34, v214
	v_max_u32_e32 v51, v41, v8
	v_max_u32_e32 v48, v37, v3
	v_max_u32_e32 v47, v43, v23
	v_max_u32_e32 v34, v49, v17
	v_max_u32_e32 v41, v35, v18
	v_max_u32_e32 v37, v40, v7
	v_max_u32_e32 v43, v32, v21
	v_max_u32_e32 v49, v39, v27
	v_max_u32_e32 v35, v42, v30
	v_max_u32_e32 v40, v36, v16
	v_max_u32_e32 v32, v46, v47
	v_min_u32_e32 v47, v46, v47
	v_max_u32_e32 v39, v45, v34
	v_min_u32_e32 v34, v45, v34
	v_max_u32_e32 v42, v50, v41
	v_min_u32_e32 v41, v50, v41
	v_max_u32_e32 v36, v33, v37
	v_min_u32_e32 v37, v33, v37
	v_max_u32_e32 v46, v44, v43
	v_min_u32_e32 v43, v44, v43
	v_max_u32_e32 v45, v38, v49
	v_min_u32_e32 v49, v38, v49
	v_max_u32_e32 v50, v51, v35
	v_min_u32_e32 v35, v51, v35
	v_max_u32_e32 v33, v48, v40
	v_min_u32_e32 v40, v48, v40
	v_max_u32_e32 v44, v32, v46
	v_min_u32_e32 v46, v32, v46
	v_max_u32_e32 v38, v39, v45
	v_min_u32_e32 v45, v39, v45
	v_max_u32_e32 v51, v42, v50
	v_min_u32_e32 v50, v42, v50
	v_max_u32_e32 v48, v36, v33
	v_min_u32_e32 v33, v36, v33
	v_max_u32_e32 v32, v47, v43
	v_min_u32_e32 v43, v47, v43
	v_max_u32_e32 v39, v34, v49
	v_min_u32_e32 v49, v34, v49
	v_max_u32_e32 v42, v41, v35
	v_min_u32_e32 v35, v41, v35
	v_max_u32_e32 v36, v37, v40
	v_min_u32_e32 v40, v37, v40
	v_max_u32_e32 v47, v44, v51
	v_min_u32_e32 v51, v44, v51
	v_max_u32_e32 v34, v38, v48
	v_min_u32_e32 v48, v38, v48
	v_max_u32_e32 v41, v46, v50
	v_min_u32_e32 v50, v46, v50
	v_max_u32_e32 v37, v45, v33
	v_min_u32_e32 v33, v45, v33
	v_max_u32_e32 v44, v32, v42
	v_min_u32_e32 v42, v32, v42
	v_max_u32_e32 v38, v39, v36
	v_min_u32_e32 v36, v39, v36
	v_max_u32_e32 v46, v43, v35
	v_min_u32_e32 v35, v43, v35
	v_max_u32_e32 v45, v49, v40
	v_min_u32_e32 v40, v49, v40
	v_max_u32_e32 v32, v47, v34
	v_min_u32_e32 v34, v47, v34
	v_max_u32_e32 v39, v51, v48
	v_min_u32_e32 v48, v51, v48
	v_max_u32_e32 v43, v41, v37
	v_min_u32_e32 v37, v41, v37
	v_max_u32_e32 v49, v50, v33
	v_min_u32_e32 v33, v50, v33
	v_max_u32_e32 v47, v44, v38
	v_min_u32_e32 v38, v44, v38
	v_max_u32_e32 v51, v42, v36
	v_min_u32_e32 v36, v42, v36
	v_max_u32_e32 v41, v46, v45
	v_min_u32_e32 v45, v46, v45
	v_max_u32_e32 v50, v35, v40
	v_min_u32_e32 v40, v35, v40
	ds_write_b8 v156, v32 offset:16
	ds_write_b8 v156, v34 offset:17
	ds_write_b8 v156, v39 offset:18
	ds_write_b8 v156, v48 offset:19
	ds_write_b8 v156, v43 offset:20
	ds_write_b8 v156, v37 offset:21
	ds_write_b8 v156, v49 offset:22
	ds_write_b8 v156, v33 offset:23
	ds_write_b8 v156, v47 offset:24
	ds_write_b8 v156, v38 offset:25
	ds_write_b8 v156, v51 offset:26
	ds_write_b8 v156, v36 offset:27
	ds_write_b8 v156, v41 offset:28
	ds_write_b8 v156, v45 offset:29
	ds_write_b8 v156, v50 offset:30
	ds_write_b8 v156, v40 offset:31
	v_and_b32_e32 v112, s30, v32
	v_ashrrev_i32_e32 v212, 31, v112
	v_lshrrev_b32_e32 v212, 1, v212
	v_xnor_b32_e32 v112, v112, v212
	v_and_b32_e32 v113, s30, v34
	v_ashrrev_i32_e32 v212, 31, v113
	v_lshrrev_b32_e32 v212, 1, v212
	v_xnor_b32_e32 v113, v113, v212
	v_and_b32_e32 v114, s30, v39
	v_ashrrev_i32_e32 v212, 31, v114
	v_lshrrev_b32_e32 v212, 1, v212
	v_xnor_b32_e32 v114, v114, v212
	v_and_b32_e32 v115, s30, v48
; __device__ __forceinline__ unsigned f2key(float f) { const unsigned u = __float_as_uint(f); return (u & 0x80000000u) ? ~u : (u | 0x80000000u); }
; __device__ __forceinline__ float key2f(unsigned k) { return __uint_as_float((k & 0x80000000u) ? (k & 0x7fffffffu) : ~k); }
; __device__ void ph_peer(const float* __restrict__ SC, const bf16_t* __restrict__ H  , const float* __restrict__ gffn, const unsigned char* __restrict__ U, const unsigned char* __restrict__ V, float* X, const float* __restrict__ fgain) {
;     ...
;             const int ci = lane >> 2, cj0 = (lane & 3) * 4;
;             unsigned ck[2][4], best[2]; int n0[2], n1[2];
; #pragma unroll
;             for (int u = 0; u < 2; ++u) {
;                 const float s0 = key2f(top0[u] & ~127u), s1 = key2f(top1[u] & ~127u);
;                 n0[u] = 127 - (int)(top0[u] & 127u); n1[u] = 127 - (int)(top1[u] & 127u);
;                 const float si = __shfl(s0, ci);
; #pragma unroll
;                 for (int jj = 0; jj < 4; ++jj) { const float sj = __shfl(s1, cj0 + jj); ck[u][jj] = (f2key(si + sj) & ~255u) | (unsigned)(255 - (ci * 16 + cj0 + jj)); }
	v_ashrrev_i32_e32 v212, 31, v115
	v_lshrrev_b32_e32 v212, 1, v212
	v_xnor_b32_e32 v115, v115, v212
	v_and_b32_e32 v116, s30, v43
	v_ashrrev_i32_e32 v212, 31, v116
	v_lshrrev_b32_e32 v212, 1, v212
	v_xnor_b32_e32 v116, v116, v212
	v_and_b32_e32 v117, s30, v37
	v_ashrrev_i32_e32 v212, 31, v117
	v_lshrrev_b32_e32 v212, 1, v212
	v_xnor_b32_e32 v117, v117, v212
	v_and_b32_e32 v118, s30, v49
	v_ashrrev_i32_e32 v212, 31, v118
	v_lshrrev_b32_e32 v212, 1, v212
	v_xnor_b32_e32 v118, v118, v212
	v_and_b32_e32 v119, s30, v33
	v_ashrrev_i32_e32 v212, 31, v119
	v_lshrrev_b32_e32 v212, 1, v212
	v_xnor_b32_e32 v119, v119, v212
	v_and_b32_e32 v120, s30, v47
	v_ashrrev_i32_e32 v212, 31, v120
	v_lshrrev_b32_e32 v212, 1, v212
	v_xnor_b32_e32 v120, v120, v212
	v_and_b32_e32 v121, s30, v38
	v_ashrrev_i32_e32 v212, 31, v121
	v_lshrrev_b32_e32 v212, 1, v212
	v_xnor_b32_e32 v121, v121, v212
	v_and_b32_e32 v122, s30, v51
	v_ashrrev_i32_e32 v212, 31, v122
	v_lshrrev_b32_e32 v212, 1, v212
	v_xnor_b32_e32 v122, v122, v212
	v_and_b32_e32 v123, s30, v36
	v_ashrrev_i32_e32 v212, 31, v123
	v_lshrrev_b32_e32 v212, 1, v212
	v_xnor_b32_e32 v123, v123, v212
	v_and_b32_e32 v124, s30, v41
	v_ashrrev_i32_e32 v212, 31, v124
	v_lshrrev_b32_e32 v212, 1, v212
	v_xnor_b32_e32 v124, v124, v212
	v_and_b32_e32 v125, s30, v45
	v_ashrrev_i32_e32 v212, 31, v125
	v_lshrrev_b32_e32 v212, 1, v212
	v_xnor_b32_e32 v125, v125, v212
	v_and_b32_e32 v126, s30, v50
	v_ashrrev_i32_e32 v212, 31, v126
	v_lshrrev_b32_e32 v212, 1, v212
	v_xnor_b32_e32 v126, v126, v212
	v_and_b32_e32 v127, s30, v40
	v_ashrrev_i32_e32 v212, 31, v127
	v_lshrrev_b32_e32 v212, 1, v212
	v_xnor_b32_e32 v127, v127, v212
	v_add_f32_e32 v0, v96, v112
	v_add_f32_e32 v1, v96, v113
	v_add_f32_e32 v2, v96, v114
	v_add_f32_e32 v3, v96, v115
	v_add_f32_e32 v4, v96, v116
	v_add_f32_e32 v5, v96, v117
	v_add_f32_e32 v6, v96, v118
	v_add_f32_e32 v7, v96, v119
	v_add_f32_e32 v8, v96, v120
	v_add_f32_e32 v9, v96, v121
	v_add_f32_e32 v10, v96, v122
	v_add_f32_e32 v11, v96, v123
	v_add_f32_e32 v12, v96, v124
	v_add_f32_e32 v13, v96, v125
	v_add_f32_e32 v14, v96, v126
	v_add_f32_e32 v15, v96, v127
	v_add_f32_e32 v16, v97, v112
	v_add_f32_e32 v17, v97, v113
	v_add_f32_e32 v18, v97, v114
	v_add_f32_e32 v19, v97, v115
	v_add_f32_e32 v20, v97, v116
	v_add_f32_e32 v21, v97, v117
	v_add_f32_e32 v22, v97, v118
	v_add_f32_e32 v23, v97, v119
	v_add_f32_e32 v24, v98, v112
	v_add_f32_e32 v25, v98, v113
	v_add_f32_e32 v26, v98, v114
	v_add_f32_e32 v27, v98, v115
	v_add_f32_e32 v28, v98, v116
	v_add_f32_e32 v29, v99, v112
	v_add_f32_e32 v30, v99, v113
	v_add_f32_e32 v31, v99, v114
	v_add_f32_e32 v180, v99, v115
	v_add_f32_e32 v181, v100, v112
	v_add_f32_e32 v182, v100, v113
	v_add_f32_e32 v183, v100, v114
	v_add_f32_e32 v184, v101, v112
	v_add_f32_e32 v185, v101, v113
	v_add_f32_e32 v186, v102, v112
	v_add_f32_e32 v187, v102, v113
	v_add_f32_e32 v188, v103, v112
	v_add_f32_e32 v189, v103, v113
	v_add_f32_e32 v190, v104, v112
	v_add_f32_e32 v191, v105, v112
	v_add_f32_e32 v192, v106, v112
	v_add_f32_e32 v193, v107, v112
	v_add_f32_e32 v194, v108, v112
	v_add_f32_e32 v195, v109, v112
	v_add_f32_e32 v196, v110, v112
	v_add_f32_e32 v197, v111, v112
	v_ashrrev_i32_e32 v212, 31, v0
	v_or_b32_e32 v212, 0x80000000, v212
	v_xor_b32_e32 v0, v0, v212
	v_and_b32_e32 v0, s31, v0
	v_or_b32_e32 v0, 0xff, v0
	v_ashrrev_i32_e32 v212, 31, v1
	v_or_b32_e32 v212, 0x80000000, v212
	v_xor_b32_e32 v1, v1, v212
	v_and_b32_e32 v1, s31, v1
	v_or_b32_e32 v1, 0xfe, v1
	v_ashrrev_i32_e32 v212, 31, v2
	v_or_b32_e32 v212, 0x80000000, v212
	v_xor_b32_e32 v2, v2, v212
	v_and_b32_e32 v2, s31, v2
	v_or_b32_e32 v2, 0xfd, v2
	v_ashrrev_i32_e32 v212, 31, v3
	v_or_b32_e32 v212, 0x80000000, v212
	v_xor_b32_e32 v3, v3, v212
	v_and_b32_e32 v3, s31, v3
	v_or_b32_e32 v3, 0xfc, v3
	v_ashrrev_i32_e32 v212, 31, v4
	v_or_b32_e32 v212, 0x80000000, v212
	v_xor_b32_e32 v4, v4, v212
	v_and_b32_e32 v4, s31, v4
	v_or_b32_e32 v4, 0xfb, v4
	v_ashrrev_i32_e32 v212, 31, v5
	v_or_b32_e32 v212, 0x80000000, v212
	v_xor_b32_e32 v5, v5, v212
	v_and_b32_e32 v5, s31, v5
	v_or_b32_e32 v5, 0xfa, v5
	v_ashrrev_i32_e32 v212, 31, v6
	v_or_b32_e32 v212, 0x80000000, v212
	v_xor_b32_e32 v6, v6, v212
	v_and_b32_e32 v6, s31, v6
	v_or_b32_e32 v6, 0xf9, v6
	v_ashrrev_i32_e32 v212, 31, v7
	v_or_b32_e32 v212, 0x80000000, v212
	v_xor_b32_e32 v7, v7, v212
	v_and_b32_e32 v7, s31, v7
	v_or_b32_e32 v7, 0xf8, v7
	v_ashrrev_i32_e32 v212, 31, v8
	v_or_b32_e32 v212, 0x80000000, v212
	v_xor_b32_e32 v8, v8, v212
	v_and_b32_e32 v8, s31, v8
	v_or_b32_e32 v8, 0xf7, v8
	v_ashrrev_i32_e32 v212, 31, v9
	v_or_b32_e32 v212, 0x80000000, v212
	v_xor_b32_e32 v9, v9, v212
	v_and_b32_e32 v9, s31, v9
	v_or_b32_e32 v9, 0xf6, v9
	v_ashrrev_i32_e32 v212, 31, v10
	v_or_b32_e32 v212, 0x80000000, v212
	v_xor_b32_e32 v10, v10, v212
	v_and_b32_e32 v10, s31, v10
	v_or_b32_e32 v10, 0xf5, v10
	v_ashrrev_i32_e32 v212, 31, v11
	v_or_b32_e32 v212, 0x80000000, v212
	v_xor_b32_e32 v11, v11, v212
	v_and_b32_e32 v11, s31, v11
	v_or_b32_e32 v11, 0xf4, v11
	v_ashrrev_i32_e32 v212, 31, v12
	v_or_b32_e32 v212, 0x80000000, v212
	v_xor_b32_e32 v12, v12, v212
	v_and_b32_e32 v12, s31, v12
	v_or_b32_e32 v12, 0xf3, v12
	v_ashrrev_i32_e32 v212, 31, v13
	v_or_b32_e32 v212, 0x80000000, v212
	v_xor_b32_e32 v13, v13, v212
	v_and_b32_e32 v13, s31, v13
	v_or_b32_e32 v13, 0xf2, v13
	v_ashrrev_i32_e32 v212, 31, v14
	v_or_b32_e32 v212, 0x80000000, v212
	v_xor_b32_e32 v14, v14, v212
	v_and_b32_e32 v14, s31, v14
	v_or_b32_e32 v14, 0xf1, v14
	v_ashrrev_i32_e32 v212, 31, v15
	v_or_b32_e32 v212, 0x80000000, v212
	v_xor_b32_e32 v15, v15, v212
	v_and_b32_e32 v15, s31, v15
	v_or_b32_e32 v15, 0xf0, v15
; __device__ __forceinline__ unsigned f2key(float f) { const unsigned u = __float_as_uint(f); return (u & 0x80000000u) ? ~u : (u | 0x80000000u); }
; __device__ __forceinline__ float key2f(unsigned k) { return __uint_as_float((k & 0x80000000u) ? (k & 0x7fffffffu) : ~k); }
; __device__ void ph_peer(const float* __restrict__ SC, const bf16_t* __restrict__ H  , const float* __restrict__ gffn, const unsigned char* __restrict__ U, const unsigned char* __restrict__ V, float* X, const float* __restrict__ fgain) {
;     ...
;             const int ci = lane >> 2, cj0 = (lane & 3) * 4;
;             unsigned ck[2][4], best[2]; int n0[2], n1[2];
; #pragma unroll
;             for (int u = 0; u < 2; ++u) {
;                 const float s0 = key2f(top0[u] & ~127u), s1 = key2f(top1[u] & ~127u);
;                 n0[u] = 127 - (int)(top0[u] & 127u); n1[u] = 127 - (int)(top1[u] & 127u);
;                 const float si = __shfl(s0, ci);
; #pragma unroll
;                 for (int jj = 0; jj < 4; ++jj) { const float sj = __shfl(s1, cj0 + jj); ck[u][jj] = (f2key(si + sj) & ~255u) | (unsigned)(255 - (ci * 16 + cj0 + jj)); }
;                 best[u] = 0u; }
;             for (int it = 0; it < 16; ++it) {
; #pragma unroll
;                 for (int u = 0; u < 2; ++u) {
;                     const unsigned a = ck[u][0] > ck[u][1] ? ck[u][0] : ck[u][1], b = ck[u][2] > ck[u][3] ? ck[u][2] : ck[u][3];
;                     const unsigned mx = wave_max_u32(a > b ? a : b);
;                     if (lane == it) best[u] = mx;
; #pragma unroll
;                     for (int jj = 0; jj < 4; ++jj) if (ck[u][jj] == mx) ck[u][jj] = 0u; }
;             }
	v_ashrrev_i32_e32 v212, 31, v16
	v_or_b32_e32 v212, 0x80000000, v212
	v_xor_b32_e32 v16, v16, v212
	v_and_b32_e32 v16, s31, v16
	v_or_b32_e32 v16, 0xef, v16
	v_ashrrev_i32_e32 v212, 31, v17
	v_or_b32_e32 v212, 0x80000000, v212
	v_xor_b32_e32 v17, v17, v212
	v_and_b32_e32 v17, s31, v17
	v_or_b32_e32 v17, 0xee, v17
	v_ashrrev_i32_e32 v212, 31, v18
	v_or_b32_e32 v212, 0x80000000, v212
	v_xor_b32_e32 v18, v18, v212
	v_and_b32_e32 v18, s31, v18
	v_or_b32_e32 v18, 0xed, v18
	v_ashrrev_i32_e32 v212, 31, v19
	v_or_b32_e32 v212, 0x80000000, v212
	v_xor_b32_e32 v19, v19, v212
	v_and_b32_e32 v19, s31, v19
	v_or_b32_e32 v19, 0xec, v19
	v_ashrrev_i32_e32 v212, 31, v20
	v_or_b32_e32 v212, 0x80000000, v212
	v_xor_b32_e32 v20, v20, v212
	v_and_b32_e32 v20, s31, v20
	v_or_b32_e32 v20, 0xeb, v20
	v_ashrrev_i32_e32 v212, 31, v21
	v_or_b32_e32 v212, 0x80000000, v212
	v_xor_b32_e32 v21, v21, v212
	v_and_b32_e32 v21, s31, v21
	v_or_b32_e32 v21, 0xea, v21
	v_ashrrev_i32_e32 v212, 31, v22
	v_or_b32_e32 v212, 0x80000000, v212
	v_xor_b32_e32 v22, v22, v212
	v_and_b32_e32 v22, s31, v22
	v_or_b32_e32 v22, 0xe9, v22
	v_ashrrev_i32_e32 v212, 31, v23
	v_or_b32_e32 v212, 0x80000000, v212
	v_xor_b32_e32 v23, v23, v212
	v_and_b32_e32 v23, s31, v23
	v_or_b32_e32 v23, 0xe8, v23
	v_ashrrev_i32_e32 v212, 31, v24
	v_or_b32_e32 v212, 0x80000000, v212
	v_xor_b32_e32 v24, v24, v212
	v_and_b32_e32 v24, s31, v24
	v_or_b32_e32 v24, 0xdf, v24
	v_ashrrev_i32_e32 v212, 31, v25
	v_or_b32_e32 v212, 0x80000000, v212
	v_xor_b32_e32 v25, v25, v212
	v_and_b32_e32 v25, s31, v25
	v_or_b32_e32 v25, 0xde, v25
	v_ashrrev_i32_e32 v212, 31, v26
	v_or_b32_e32 v212, 0x80000000, v212
	v_xor_b32_e32 v26, v26, v212
	v_and_b32_e32 v26, s31, v26
	v_or_b32_e32 v26, 0xdd, v26
	v_ashrrev_i32_e32 v212, 31, v27
	v_or_b32_e32 v212, 0x80000000, v212
	v_xor_b32_e32 v27, v27, v212
	v_and_b32_e32 v27, s31, v27
	v_or_b32_e32 v27, 0xdc, v27
	v_ashrrev_i32_e32 v212, 31, v28
	v_or_b32_e32 v212, 0x80000000, v212
	v_xor_b32_e32 v28, v28, v212
	v_and_b32_e32 v28, s31, v28
	v_or_b32_e32 v28, 0xdb, v28
	v_ashrrev_i32_e32 v212, 31, v29
	v_or_b32_e32 v212, 0x80000000, v212
	v_xor_b32_e32 v29, v29, v212
	v_and_b32_e32 v29, s31, v29
	v_or_b32_e32 v29, 0xcf, v29
	v_ashrrev_i32_e32 v212, 31, v30
	v_or_b32_e32 v212, 0x80000000, v212
	v_xor_b32_e32 v30, v30, v212
	v_and_b32_e32 v30, s31, v30
	v_or_b32_e32 v30, 0xce, v30
	v_ashrrev_i32_e32 v212, 31, v31
	v_or_b32_e32 v212, 0x80000000, v212
	v_xor_b32_e32 v31, v31, v212
	v_and_b32_e32 v31, s31, v31
	v_or_b32_e32 v31, 0xcd, v31
	v_ashrrev_i32_e32 v212, 31, v180
	v_or_b32_e32 v212, 0x80000000, v212
	v_xor_b32_e32 v180, v180, v212
	v_and_b32_e32 v180, s31, v180
	v_or_b32_e32 v180, 0xcc, v180
	v_ashrrev_i32_e32 v212, 31, v181
	v_or_b32_e32 v212, 0x80000000, v212
	v_xor_b32_e32 v181, v181, v212
	v_and_b32_e32 v181, s31, v181
	v_or_b32_e32 v181, 0xbf, v181
	v_ashrrev_i32_e32 v212, 31, v182
	v_or_b32_e32 v212, 0x80000000, v212
	v_xor_b32_e32 v182, v182, v212
	v_and_b32_e32 v182, s31, v182
	v_or_b32_e32 v182, 0xbe, v182
	v_ashrrev_i32_e32 v212, 31, v183
	v_or_b32_e32 v212, 0x80000000, v212
	v_xor_b32_e32 v183, v183, v212
	v_and_b32_e32 v183, s31, v183
	v_or_b32_e32 v183, 0xbd, v183
	v_ashrrev_i32_e32 v212, 31, v184
	v_or_b32_e32 v212, 0x80000000, v212
	v_xor_b32_e32 v184, v184, v212
	v_and_b32_e32 v184, s31, v184
	v_or_b32_e32 v184, 0xaf, v184
	v_ashrrev_i32_e32 v212, 31, v185
	v_or_b32_e32 v212, 0x80000000, v212
	v_xor_b32_e32 v185, v185, v212
	v_and_b32_e32 v185, s31, v185
	v_or_b32_e32 v185, 0xae, v185
	v_ashrrev_i32_e32 v212, 31, v186
	v_or_b32_e32 v212, 0x80000000, v212
	v_xor_b32_e32 v186, v186, v212
	v_and_b32_e32 v186, s31, v186
	v_or_b32_e32 v186, 0x9f, v186
	v_ashrrev_i32_e32 v212, 31, v187
	v_or_b32_e32 v212, 0x80000000, v212
	v_xor_b32_e32 v187, v187, v212
	v_and_b32_e32 v187, s31, v187
	v_or_b32_e32 v187, 0x9e, v187
	v_ashrrev_i32_e32 v212, 31, v188
	v_or_b32_e32 v212, 0x80000000, v212
	v_xor_b32_e32 v188, v188, v212
	v_and_b32_e32 v188, s31, v188
	v_or_b32_e32 v188, 0x8f, v188
	v_ashrrev_i32_e32 v212, 31, v189
	v_or_b32_e32 v212, 0x80000000, v212
	v_xor_b32_e32 v189, v189, v212
	v_and_b32_e32 v189, s31, v189
	v_or_b32_e32 v189, 0x8e, v189
	v_ashrrev_i32_e32 v212, 31, v190
	v_or_b32_e32 v212, 0x80000000, v212
	v_xor_b32_e32 v190, v190, v212
	v_and_b32_e32 v190, s31, v190
	v_or_b32_e32 v190, 0x7f, v190
	v_ashrrev_i32_e32 v212, 31, v191
	v_or_b32_e32 v212, 0x80000000, v212
	v_xor_b32_e32 v191, v191, v212
	v_and_b32_e32 v191, s31, v191
	v_or_b32_e32 v191, 0x6f, v191
	v_ashrrev_i32_e32 v212, 31, v192
	v_or_b32_e32 v212, 0x80000000, v212
	v_xor_b32_e32 v192, v192, v212
	v_and_b32_e32 v192, s31, v192
	v_or_b32_e32 v192, 0x5f, v192
	v_ashrrev_i32_e32 v212, 31, v193
	v_or_b32_e32 v212, 0x80000000, v212
	v_xor_b32_e32 v193, v193, v212
	v_and_b32_e32 v193, s31, v193
	v_or_b32_e32 v193, 0x4f, v193
	v_ashrrev_i32_e32 v212, 31, v194
	v_or_b32_e32 v212, 0x80000000, v212
	v_xor_b32_e32 v194, v194, v212
	v_and_or_b32 v194, v194, s31, 63
	v_ashrrev_i32_e32 v212, 31, v195
	v_or_b32_e32 v212, 0x80000000, v212
	v_xor_b32_e32 v195, v195, v212
	v_and_or_b32 v195, v195, s31, 47
	v_ashrrev_i32_e32 v212, 31, v196
	v_or_b32_e32 v212, 0x80000000, v212
	v_xor_b32_e32 v196, v196, v212
	v_and_or_b32 v196, v196, s31, 31
	v_ashrrev_i32_e32 v212, 31, v197
	v_or_b32_e32 v212, 0x80000000, v212
	v_xor_b32_e32 v197, v197, v212
	v_and_or_b32 v197, v197, s31, 15
	v_max_u32_e32 v51, v0, v1
	v_min_u32_e32 v1, v0, v1
	v_max_u32_e32 v50, v2, v3
	v_min_u32_e32 v3, v2, v3
	v_max_u32_e32 v49, v4, v5
	v_min_u32_e32 v5, v4, v5
	v_max_u32_e32 v48, v6, v7
	v_min_u32_e32 v7, v6, v7
	v_max_u32_e32 v47, v8, v9
	v_min_u32_e32 v9, v8, v9
; __device__ void ph_peer(const float* __restrict__ SC, const bf16_t* __restrict__ H  , const float* __restrict__ gffn, const unsigned char* __restrict__ U, const unsigned char* __restrict__ V, float* X, const float* __restrict__ fgain) {
;     ...
;             for (int it = 0; it < 16; ++it) {
; #pragma unroll
;                 for (int u = 0; u < 2; ++u) {
;                     const unsigned a = ck[u][0] > ck[u][1] ? ck[u][0] : ck[u][1], b = ck[u][2] > ck[u][3] ? ck[u][2] : ck[u][3];
;                     const unsigned mx = wave_max_u32(a > b ? a : b);
;                     if (lane == it) best[u] = mx;
; #pragma unroll
;                     for (int jj = 0; jj < 4; ++jj) if (ck[u][jj] == mx) ck[u][jj] = 0u; }
;             }
	v_max_u32_e32 v46, v10, v11
	v_min_u32_e32 v11, v10, v11
	v_max_u32_e32 v45, v12, v13
	v_min_u32_e32 v13, v12, v13
	v_max_u32_e32 v44, v14, v15
	v_min_u32_e32 v15, v14, v15
	v_max_u32_e32 v43, v51, v50
	v_min_u32_e32 v50, v51, v50
	v_max_u32_e32 v42, v1, v3
	v_min_u32_e32 v3, v1, v3
	v_max_u32_e32 v41, v49, v48
	v_min_u32_e32 v48, v49, v48
	v_max_u32_e32 v40, v5, v7
	v_min_u32_e32 v7, v5, v7
	v_max_u32_e32 v39, v47, v46
	v_min_u32_e32 v46, v47, v46
	v_max_u32_e32 v38, v9, v11
	v_min_u32_e32 v11, v9, v11
	v_max_u32_e32 v37, v45, v44
	v_min_u32_e32 v44, v45, v44
	v_max_u32_e32 v36, v13, v15
	v_min_u32_e32 v15, v13, v15
	v_max_u32_e32 v35, v42, v50
	v_min_u32_e32 v50, v42, v50
	v_max_u32_e32 v34, v40, v48
	v_min_u32_e32 v48, v40, v48
	v_max_u32_e32 v33, v38, v46
	v_min_u32_e32 v46, v38, v46
	v_max_u32_e32 v32, v36, v44
	v_min_u32_e32 v44, v36, v44
	v_max_u32_e32 v0, v43, v41
	v_min_u32_e32 v41, v43, v41
	v_max_u32_e32 v2, v35, v34
	v_min_u32_e32 v34, v35, v34
	v_max_u32_e32 v4, v50, v48
	v_min_u32_e32 v48, v50, v48
	v_max_u32_e32 v6, v3, v7
	v_min_u32_e32 v7, v3, v7
	v_max_u32_e32 v8, v39, v37
	v_min_u32_e32 v37, v39, v37
	v_max_u32_e32 v10, v33, v32
	v_min_u32_e32 v32, v33, v32
	v_max_u32_e32 v12, v46, v44
	v_min_u32_e32 v44, v46, v44
	v_max_u32_e32 v14, v11, v15
	v_min_u32_e32 v15, v11, v15
	v_max_u32_e32 v51, v4, v41
	v_min_u32_e32 v41, v4, v41
	v_max_u32_e32 v1, v6, v34
	v_min_u32_e32 v34, v6, v34
	v_max_u32_e32 v49, v12, v37
	v_min_u32_e32 v37, v12, v37
	v_max_u32_e32 v5, v14, v32
	v_min_u32_e32 v32, v14, v32
	v_max_u32_e32 v47, v2, v51
	v_min_u32_e32 v51, v2, v51
	v_max_u32_e32 v9, v1, v41
	v_min_u32_e32 v41, v1, v41
	v_max_u32_e32 v45, v34, v48
	v_min_u32_e32 v48, v34, v48
	v_max_u32_e32 v13, v10, v49
	v_min_u32_e32 v49, v10, v49
	v_max_u32_e32 v42, v5, v37
	v_min_u32_e32 v37, v5, v37
	v_max_u32_e32 v40, v32, v44
	v_min_u32_e32 v44, v32, v44
	v_max_u32_e32 v38, v0, v8
	v_min_u32_e32 v8, v0, v8
	v_max_u32_e32 v36, v47, v13
	v_min_u32_e32 v13, v47, v13
	v_max_u32_e32 v43, v51, v49
	v_min_u32_e32 v49, v51, v49
	v_max_u32_e32 v35, v9, v42
	v_min_u32_e32 v42, v9, v42
	v_max_u32_e32 v50, v41, v37
	v_min_u32_e32 v37, v41, v37
	v_max_u32_e32 v3, v45, v40
	v_min_u32_e32 v40, v45, v40
	v_max_u32_e32 v39, v48, v44
	v_min_u32_e32 v44, v48, v44
	v_max_u32_e32 v33, v7, v15
	v_min_u32_e32 v15, v7, v15
	v_max_u32_e32 v46, v50, v8
	v_min_u32_e32 v8, v50, v8
	v_max_u32_e32 v11, v3, v13
	v_min_u32_e32 v13, v3, v13
	v_max_u32_e32 v4, v39, v49
	v_min_u32_e32 v49, v39, v49
	v_max_u32_e32 v6, v33, v42
	v_min_u32_e32 v42, v33, v42
	v_max_u32_e32 v12, v43, v46
	v_min_u32_e32 v46, v43, v46
	v_max_u32_e32 v14, v35, v11
	v_min_u32_e32 v11, v35, v11
	v_max_u32_e32 v2, v4, v8
	v_min_u32_e32 v8, v4, v8
	v_max_u32_e32 v1, v6, v13
	v_min_u32_e32 v13, v6, v13
	v_max_u32_e32 v34, v49, v37
	v_min_u32_e32 v37, v49, v37
	v_max_u32_e32 v10, v42, v40
	v_min_u32_e32 v40, v42, v40
	v_max_u32_e32 v5, v36, v12
	v_min_u32_e32 v12, v36, v12
	v_max_u32_e32 v32, v14, v46
	v_min_u32_e32 v46, v14, v46
	v_max_u32_e32 v0, v11, v2
	v_min_u32_e32 v2, v11, v2
	v_max_u32_e32 v47, v1, v8
	v_min_u32_e32 v8, v1, v8
	v_max_u32_e32 v51, v13, v34
	v_min_u32_e32 v34, v13, v34
	v_max_u32_e32 v9, v10, v37
	v_min_u32_e32 v37, v10, v37
	v_max_u32_e32 v41, v40, v44
	v_min_u32_e32 v44, v40, v44
	v_max_u32_e32 v45, v16, v17
	v_min_u32_e32 v17, v16, v17
	v_max_u32_e32 v48, v18, v19
	v_min_u32_e32 v19, v18, v19
	v_max_u32_e32 v7, v20, v21
	v_min_u32_e32 v21, v20, v21
	v_max_u32_e32 v50, v22, v23
	v_min_u32_e32 v23, v22, v23
	v_max_u32_e32 v3, v24, v25
	v_min_u32_e32 v25, v24, v25
	v_max_u32_e32 v39, v26, v27
	v_min_u32_e32 v27, v26, v27
	v_max_u32_e32 v33, v28, v29
	v_min_u32_e32 v29, v28, v29
	v_max_u32_e32 v43, v30, v31
	v_min_u32_e32 v31, v30, v31
	v_max_u32_e32 v35, v45, v48
	v_min_u32_e32 v48, v45, v48
	v_max_u32_e32 v4, v17, v19
	v_min_u32_e32 v19, v17, v19
	v_max_u32_e32 v6, v7, v50
	v_min_u32_e32 v50, v7, v50
	v_max_u32_e32 v49, v21, v23
	v_min_u32_e32 v23, v21, v23
	v_max_u32_e32 v42, v3, v39
	v_min_u32_e32 v39, v3, v39
	v_max_u32_e32 v36, v25, v27
	v_min_u32_e32 v27, v25, v27
	v_max_u32_e32 v14, v33, v43
	v_min_u32_e32 v43, v33, v43
	v_max_u32_e32 v11, v29, v31
	v_min_u32_e32 v31, v29, v31
	v_max_u32_e32 v1, v4, v48
	v_min_u32_e32 v48, v4, v48
	v_max_u32_e32 v13, v49, v50
	v_min_u32_e32 v50, v49, v50
	v_max_u32_e32 v10, v36, v39
	v_min_u32_e32 v39, v36, v39
	v_max_u32_e32 v40, v11, v43
	v_min_u32_e32 v43, v11, v43
	v_max_u32_e32 v16, v35, v6
	v_min_u32_e32 v6, v35, v6
	v_max_u32_e32 v18, v1, v13
	v_min_u32_e32 v13, v1, v13
	v_max_u32_e32 v20, v48, v50
	v_min_u32_e32 v50, v48, v50
	v_max_u32_e32 v22, v19, v23
	v_min_u32_e32 v23, v19, v23
	v_max_u32_e32 v24, v42, v14
	v_min_u32_e32 v14, v42, v14
	v_max_u32_e32 v26, v10, v40
	v_min_u32_e32 v40, v10, v40
	v_max_u32_e32 v28, v39, v43
	v_min_u32_e32 v43, v39, v43
	v_max_u32_e32 v30, v27, v31
	v_min_u32_e32 v31, v27, v31
	v_max_u32_e32 v45, v20, v6
	v_min_u32_e32 v6, v20, v6
	v_max_u32_e32 v17, v22, v13
	v_min_u32_e32 v13, v22, v13
	v_max_u32_e32 v7, v28, v14
	v_min_u32_e32 v14, v28, v14
	v_max_u32_e32 v21, v30, v40
	v_min_u32_e32 v40, v30, v40
	v_max_u32_e32 v3, v18, v45
	v_min_u32_e32 v45, v18, v45
	v_max_u32_e32 v25, v17, v6
	v_min_u32_e32 v6, v17, v6
	v_max_u32_e32 v33, v13, v50
	v_min_u32_e32 v50, v13, v50
	v_max_u32_e32 v29, v26, v7
	v_min_u32_e32 v7, v26, v7
	v_max_u32_e32 v4, v21, v14
	v_min_u32_e32 v14, v21, v14
	v_max_u32_e32 v49, v40, v43
	v_min_u32_e32 v43, v40, v43
	v_max_u32_e32 v36, v16, v24
	v_min_u32_e32 v24, v16, v24
	v_max_u32_e32 v11, v3, v29
	v_min_u32_e32 v29, v3, v29
	v_max_u32_e32 v35, v45, v7
	v_min_u32_e32 v7, v45, v7
; __device__ void ph_peer(const float* __restrict__ SC, const bf16_t* __restrict__ H  , const float* __restrict__ gffn, const unsigned char* __restrict__ U, const unsigned char* __restrict__ V, float* X, const float* __restrict__ fgain) {
;     ...
;             for (int it = 0; it < 16; ++it) {
; #pragma unroll
;                 for (int u = 0; u < 2; ++u) {
;                     const unsigned a = ck[u][0] > ck[u][1] ? ck[u][0] : ck[u][1], b = ck[u][2] > ck[u][3] ? ck[u][2] : ck[u][3];
;                     const unsigned mx = wave_max_u32(a > b ? a : b);
;                     if (lane == it) best[u] = mx;
; #pragma unroll
;                     for (int jj = 0; jj < 4; ++jj) if (ck[u][jj] == mx) ck[u][jj] = 0u; }
;             }
	v_max_u32_e32 v1, v25, v4
	v_min_u32_e32 v4, v25, v4
	v_max_u32_e32 v48, v6, v14
	v_min_u32_e32 v14, v6, v14
	v_max_u32_e32 v19, v33, v49
	v_min_u32_e32 v49, v33, v49
	v_max_u32_e32 v42, v50, v43
	v_min_u32_e32 v43, v50, v43
	v_max_u32_e32 v10, v23, v31
	v_min_u32_e32 v31, v23, v31
	v_max_u32_e32 v39, v48, v24
	v_min_u32_e32 v24, v48, v24
	v_max_u32_e32 v27, v19, v29
	v_min_u32_e32 v29, v19, v29
	v_max_u32_e32 v20, v42, v7
	v_min_u32_e32 v7, v42, v7
	v_max_u32_e32 v22, v10, v4
	v_min_u32_e32 v4, v10, v4
	v_max_u32_e32 v28, v35, v39
	v_min_u32_e32 v39, v35, v39
	v_max_u32_e32 v30, v1, v27
	v_min_u32_e32 v27, v1, v27
	v_max_u32_e32 v18, v20, v24
	v_min_u32_e32 v24, v20, v24
	v_max_u32_e32 v17, v22, v29
	v_min_u32_e32 v29, v22, v29
	v_max_u32_e32 v13, v7, v14
	v_min_u32_e32 v14, v7, v14
	v_max_u32_e32 v26, v4, v49
	v_min_u32_e32 v49, v4, v49
	v_max_u32_e32 v21, v11, v28
	v_min_u32_e32 v28, v11, v28
	v_max_u32_e32 v40, v30, v39
	v_min_u32_e32 v39, v30, v39
	v_max_u32_e32 v16, v27, v18
	v_min_u32_e32 v18, v27, v18
	v_max_u32_e32 v3, v17, v24
	v_min_u32_e32 v24, v17, v24
	v_max_u32_e32 v45, v29, v13
	v_min_u32_e32 v13, v29, v13
	v_max_u32_e32 v25, v26, v14
	v_min_u32_e32 v14, v26, v14
	v_max_u32_e32 v6, v49, v43
	v_min_u32_e32 v43, v49, v43
	v_max_u32_e32 v33, v180, v181
	v_min_u32_e32 v181, v180, v181
	v_max_u32_e32 v50, v182, v183
	v_min_u32_e32 v183, v182, v183
	v_max_u32_e32 v23, v184, v185
	v_min_u32_e32 v185, v184, v185
	v_max_u32_e32 v48, v186, v187
	v_min_u32_e32 v187, v186, v187
	v_max_u32_e32 v19, v188, v189
	v_min_u32_e32 v189, v188, v189
	v_max_u32_e32 v42, v190, v191
	v_min_u32_e32 v191, v190, v191
	v_max_u32_e32 v10, v192, v193
	v_min_u32_e32 v193, v192, v193
	v_max_u32_e32 v35, v194, v195
	v_min_u32_e32 v195, v194, v195
	v_max_u32_e32 v1, v33, v50
	v_min_u32_e32 v50, v33, v50
	v_max_u32_e32 v20, v181, v183
	v_min_u32_e32 v183, v181, v183
	v_max_u32_e32 v22, v23, v48
	v_min_u32_e32 v48, v23, v48
	v_max_u32_e32 v7, v185, v187
	v_min_u32_e32 v187, v185, v187
	v_max_u32_e32 v4, v19, v42
	v_min_u32_e32 v42, v19, v42
	v_max_u32_e32 v11, v189, v191
	v_min_u32_e32 v191, v189, v191
	v_max_u32_e32 v30, v10, v35
	v_min_u32_e32 v35, v10, v35
	v_max_u32_e32 v27, v193, v195
	v_min_u32_e32 v195, v193, v195
	v_max_u32_e32 v17, v20, v50
	v_min_u32_e32 v50, v20, v50
	v_max_u32_e32 v29, v7, v48
	v_min_u32_e32 v48, v7, v48
	v_max_u32_e32 v26, v11, v42
	v_min_u32_e32 v42, v11, v42
	v_max_u32_e32 v49, v27, v35
	v_min_u32_e32 v35, v27, v35
	v_max_u32_e32 v180, v1, v22
	v_min_u32_e32 v22, v1, v22
	v_max_u32_e32 v182, v17, v29
	v_min_u32_e32 v29, v17, v29
	v_max_u32_e32 v184, v50, v48
	v_min_u32_e32 v48, v50, v48
	v_max_u32_e32 v186, v183, v187
	v_min_u32_e32 v187, v183, v187
	v_max_u32_e32 v188, v4, v30
	v_min_u32_e32 v30, v4, v30
	v_max_u32_e32 v190, v26, v49
	v_min_u32_e32 v49, v26, v49
	v_max_u32_e32 v192, v42, v35
	v_min_u32_e32 v35, v42, v35
	v_max_u32_e32 v194, v191, v195
	v_min_u32_e32 v195, v191, v195
	v_max_u32_e32 v33, v184, v22
	v_min_u32_e32 v22, v184, v22
	v_max_u32_e32 v181, v186, v29
	v_min_u32_e32 v29, v186, v29
	v_max_u32_e32 v23, v192, v30
	v_min_u32_e32 v30, v192, v30
	v_max_u32_e32 v185, v194, v49
	v_min_u32_e32 v49, v194, v49
	v_max_u32_e32 v19, v182, v33
	v_min_u32_e32 v33, v182, v33
	v_max_u32_e32 v189, v181, v22
	v_min_u32_e32 v22, v181, v22
	v_max_u32_e32 v10, v29, v48
	v_min_u32_e32 v48, v29, v48
	v_max_u32_e32 v193, v190, v23
	v_min_u32_e32 v23, v190, v23
	v_max_u32_e32 v20, v185, v30
	v_min_u32_e32 v30, v185, v30
	v_max_u32_e32 v7, v49, v35
	v_min_u32_e32 v35, v49, v35
	v_max_u32_e32 v11, v180, v188
	v_min_u32_e32 v188, v180, v188
	v_max_u32_e32 v27, v19, v193
	v_min_u32_e32 v193, v19, v193
	v_max_u32_e32 v1, v33, v23
	v_min_u32_e32 v23, v33, v23
	v_max_u32_e32 v17, v189, v20
	v_min_u32_e32 v20, v189, v20
	v_max_u32_e32 v50, v22, v30
	v_min_u32_e32 v30, v22, v30
	v_max_u32_e32 v183, v10, v7
	v_min_u32_e32 v7, v10, v7
	v_max_u32_e32 v4, v48, v35
	v_min_u32_e32 v35, v48, v35
	v_max_u32_e32 v26, v187, v195
	v_min_u32_e32 v195, v187, v195
	v_max_u32_e32 v42, v50, v188
	v_min_u32_e32 v188, v50, v188
	v_max_u32_e32 v191, v183, v193
	v_min_u32_e32 v193, v183, v193
	v_max_u32_e32 v184, v4, v23
	v_min_u32_e32 v23, v4, v23
	v_max_u32_e32 v186, v26, v20
	v_min_u32_e32 v20, v26, v20
	v_max_u32_e32 v192, v1, v42
	v_min_u32_e32 v42, v1, v42
	v_max_u32_e32 v194, v17, v191
	v_min_u32_e32 v191, v17, v191
	v_max_u32_e32 v182, v184, v188
	v_min_u32_e32 v188, v184, v188
	v_max_u32_e32 v181, v186, v193
	v_min_u32_e32 v193, v186, v193
	v_max_u32_e32 v29, v23, v30
	v_min_u32_e32 v30, v23, v30
	v_max_u32_e32 v190, v20, v7
	v_min_u32_e32 v7, v20, v7
	v_max_u32_e32 v185, v27, v192
	v_min_u32_e32 v192, v27, v192
	v_max_u32_e32 v49, v194, v42
	v_min_u32_e32 v42, v194, v42
	v_max_u32_e32 v180, v191, v182
	v_min_u32_e32 v182, v191, v182
	v_max_u32_e32 v19, v181, v188
	v_min_u32_e32 v188, v181, v188
	v_max_u32_e32 v33, v193, v29
	v_min_u32_e32 v29, v193, v29
	v_max_u32_e32 v189, v190, v30
	v_min_u32_e32 v30, v190, v30
	v_max_u32_e32 v22, v7, v35
	v_min_u32_e32 v35, v7, v35
	v_max_u32_e32 v10, v196, v197
	v_min_u32_e32 v197, v196, v197
	v_max_u32_e32 v48, v38, v31
	v_max_u32_e32 v187, v5, v43
	v_max_u32_e32 v50, v12, v6
	v_max_u32_e32 v183, v32, v14
	v_max_u32_e32 v4, v46, v25
	v_max_u32_e32 v26, v0, v13
	v_max_u32_e32 v1, v2, v45
	v_max_u32_e32 v17, v47, v24
	v_max_u32_e32 v184, v8, v3
	v_max_u32_e32 v186, v51, v18
	v_max_u32_e32 v23, v34, v16
	v_max_u32_e32 v20, v9, v39
	v_max_u32_e32 v27, v37, v40
	v_max_u32_e32 v194, v41, v28
	v_max_u32_e32 v191, v44, v21
	v_max_u32_e32 v181, v15, v36
	v_max_u32_e32 v193, v48, v184
	v_min_u32_e32 v184, v48, v184
; __device__ void ph_peer(const float* __restrict__ SC, const bf16_t* __restrict__ H  , const float* __restrict__ gffn, const unsigned char* __restrict__ U, const unsigned char* __restrict__ V, float* X, const float* __restrict__ fgain) {
;     ...
;             for (int it = 0; it < 16; ++it) {
; #pragma unroll
;                 for (int u = 0; u < 2; ++u) {
;                     const unsigned a = ck[u][0] > ck[u][1] ? ck[u][0] : ck[u][1], b = ck[u][2] > ck[u][3] ? ck[u][2] : ck[u][3];
;                     const unsigned mx = wave_max_u32(a > b ? a : b);
;                     if (lane == it) best[u] = mx;
; #pragma unroll
;                     for (int jj = 0; jj < 4; ++jj) if (ck[u][jj] == mx) ck[u][jj] = 0u; }
;             }
	v_max_u32_e32 v190, v187, v186
	v_min_u32_e32 v186, v187, v186
	v_max_u32_e32 v7, v50, v23
	v_min_u32_e32 v23, v50, v23
	v_max_u32_e32 v196, v183, v20
	v_min_u32_e32 v20, v183, v20
	v_max_u32_e32 v38, v4, v27
	v_min_u32_e32 v27, v4, v27
	v_max_u32_e32 v5, v26, v194
	v_min_u32_e32 v194, v26, v194
	v_max_u32_e32 v12, v1, v191
	v_min_u32_e32 v191, v1, v191
	v_max_u32_e32 v32, v17, v181
	v_min_u32_e32 v181, v17, v181
	v_max_u32_e32 v46, v193, v38
	v_min_u32_e32 v38, v193, v38
	v_max_u32_e32 v0, v190, v5
	v_min_u32_e32 v5, v190, v5
	v_max_u32_e32 v2, v7, v12
	v_min_u32_e32 v12, v7, v12
	v_max_u32_e32 v47, v196, v32
	v_min_u32_e32 v32, v196, v32
	v_max_u32_e32 v8, v184, v27
	v_min_u32_e32 v27, v184, v27
	v_max_u32_e32 v51, v186, v194
	v_min_u32_e32 v194, v186, v194
	v_max_u32_e32 v34, v23, v191
	v_min_u32_e32 v191, v23, v191
	v_max_u32_e32 v9, v20, v181
	v_min_u32_e32 v181, v20, v181
	v_max_u32_e32 v37, v46, v2
	v_min_u32_e32 v2, v46, v2
	v_max_u32_e32 v41, v0, v47
	v_min_u32_e32 v47, v0, v47
	v_max_u32_e32 v44, v38, v12
	v_min_u32_e32 v12, v38, v12
	v_max_u32_e32 v15, v5, v32
	v_min_u32_e32 v32, v5, v32
	v_max_u32_e32 v48, v8, v34
	v_min_u32_e32 v34, v8, v34
	v_max_u32_e32 v187, v51, v9
	v_min_u32_e32 v9, v51, v9
	v_max_u32_e32 v50, v27, v191
	v_min_u32_e32 v191, v27, v191
	v_max_u32_e32 v183, v194, v181
	v_min_u32_e32 v181, v194, v181
	v_max_u32_e32 v4, v37, v41
	v_min_u32_e32 v41, v37, v41
	v_max_u32_e32 v26, v2, v47
	v_min_u32_e32 v47, v2, v47
	v_max_u32_e32 v1, v44, v15
	v_min_u32_e32 v15, v44, v15
	v_max_u32_e32 v17, v12, v32
	v_min_u32_e32 v32, v12, v32
	v_max_u32_e32 v193, v48, v187
	v_min_u32_e32 v187, v48, v187
	v_max_u32_e32 v190, v34, v9
	v_min_u32_e32 v9, v34, v9
	v_max_u32_e32 v7, v50, v183
	v_min_u32_e32 v183, v50, v183
	v_max_u32_e32 v196, v191, v181
	v_min_u32_e32 v181, v191, v181
	v_max_u32_e32 v184, v35, v197
	v_max_u32_e32 v186, v195, v10
	v_max_u32_e32 v23, v11, v188
	v_min_u32_e32 v188, v11, v188
	v_max_u32_e32 v20, v185, v33
	v_min_u32_e32 v33, v185, v33
	v_max_u32_e32 v46, v192, v29
	v_min_u32_e32 v29, v192, v29
	v_max_u32_e32 v0, v49, v189
	v_min_u32_e32 v189, v49, v189
	v_max_u32_e32 v38, v42, v30
	v_min_u32_e32 v30, v42, v30
	v_max_u32_e32 v5, v180, v22
	v_min_u32_e32 v22, v180, v22
	v_max_u32_e32 v8, v182, v184
	v_min_u32_e32 v184, v182, v184
	v_max_u32_e32 v51, v19, v186
	v_min_u32_e32 v186, v19, v186
	v_max_u32_e32 v27, v23, v38
	v_min_u32_e32 v38, v23, v38
	v_max_u32_e32 v194, v20, v5
	v_min_u32_e32 v5, v20, v5
	v_max_u32_e32 v37, v46, v8
	v_min_u32_e32 v8, v46, v8
	v_max_u32_e32 v2, v0, v51
	v_min_u32_e32 v51, v0, v51
	v_max_u32_e32 v44, v188, v30
	v_min_u32_e32 v30, v188, v30
	v_max_u32_e32 v12, v33, v22
	v_min_u32_e32 v22, v33, v22
	v_max_u32_e32 v48, v29, v184
	v_min_u32_e32 v184, v29, v184
	v_max_u32_e32 v34, v189, v186
	v_min_u32_e32 v186, v189, v186
	v_max_u32_e32 v50, v27, v37
	v_min_u32_e32 v37, v27, v37
	v_max_u32_e32 v191, v194, v2
	v_min_u32_e32 v2, v194, v2
	v_max_u32_e32 v35, v38, v8
	v_min_u32_e32 v8, v38, v8
	v_max_u32_e32 v195, v5, v51
	v_min_u32_e32 v51, v5, v51
	v_max_u32_e32 v11, v44, v48
	v_min_u32_e32 v48, v44, v48
	v_max_u32_e32 v185, v12, v34
	v_min_u32_e32 v34, v12, v34
	v_max_u32_e32 v192, v30, v184
	v_min_u32_e32 v184, v30, v184
	v_max_u32_e32 v49, v22, v186
	v_min_u32_e32 v186, v22, v186
	v_max_u32_e32 v42, v50, v191
	v_min_u32_e32 v191, v50, v191
	v_max_u32_e32 v180, v37, v2
	v_min_u32_e32 v2, v37, v2
	v_max_u32_e32 v182, v35, v195
	v_min_u32_e32 v195, v35, v195
	v_max_u32_e32 v19, v8, v51
	v_min_u32_e32 v51, v8, v51
	v_max_u32_e32 v23, v11, v185
	v_min_u32_e32 v185, v11, v185
	v_max_u32_e32 v20, v48, v34
	v_min_u32_e32 v34, v48, v34
	v_max_u32_e32 v46, v192, v49
	v_min_u32_e32 v49, v192, v49
	v_max_u32_e32 v0, v184, v186
	v_min_u32_e32 v186, v184, v186
	v_max_u32_e32 v188, v4, v186
	v_max_u32_e32 v33, v41, v0
	v_max_u32_e32 v29, v26, v49
	v_max_u32_e32 v189, v47, v46
	v_max_u32_e32 v27, v1, v34
	v_max_u32_e32 v194, v15, v20
	v_max_u32_e32 v38, v17, v185
	v_max_u32_e32 v5, v32, v23
	v_max_u32_e32 v44, v193, v51
	v_max_u32_e32 v12, v187, v19
	v_max_u32_e32 v30, v190, v195
	v_max_u32_e32 v22, v9, v182
	v_max_u32_e32 v50, v7, v2
	v_max_u32_e32 v37, v183, v180
	v_max_u32_e32 v35, v196, v191
	v_max_u32_e32 v8, v181, v42
	v_max_u32_e32 v11, v188, v44
	v_min_u32_e32 v44, v188, v44
	v_max_u32_e32 v48, v33, v12
	v_min_u32_e32 v12, v33, v12
	v_max_u32_e32 v192, v29, v30
	v_min_u32_e32 v30, v29, v30
	v_max_u32_e32 v184, v189, v22
; __device__ __forceinline__ float key2f(unsigned k) { return __uint_as_float((k & 0x80000000u) ? (k & 0x7fffffffu) : ~k); }
; __device__ void ph_peer(const float* __restrict__ SC, const bf16_t* __restrict__ H  , const float* __restrict__ gffn, const unsigned char* __restrict__ U, const unsigned char* __restrict__ V, float* X, const float* __restrict__ fgain) {
;     ...
;             for (int it = 0; it < 16; ++it) {
; #pragma unroll
;                 for (int u = 0; u < 2; ++u) {
;                     const unsigned a = ck[u][0] > ck[u][1] ? ck[u][0] : ck[u][1], b = ck[u][2] > ck[u][3] ? ck[u][2] : ck[u][3];
;                     const unsigned mx = wave_max_u32(a > b ? a : b);
;                     if (lane == it) best[u] = mx;
; #pragma unroll
;                     for (int jj = 0; jj < 4; ++jj) if (ck[u][jj] == mx) ck[u][jj] = 0u; }
;             }
; #pragma unroll
;             for (int u = 0; u < 2; ++u) {
;                 const float bs = key2f(best[u] & ~255u);
;                 const int pos = 255 - (int)(best[u] & 255u);
;                 const int e0 = __shfl(n0[u], (pos >> 4) & 15), e1 = __shfl(n1[u], pos & 15);
;                 const float mxs = __shfl(bs, 0);
;                 float e = lane < 16 ? __expf((bs - mxs) * rstd) : 0.f;
;                 const float den = row16_sum(e);
;                 const int iv = __shfl(e0 * 128 + e1, lane & 15); const float gv = __shfl(e / den, lane & 15);
;                 const int hh = h + u;
;                 if (grp == (hh & 3)) { if (hh < 4) { idx_lo = iv; g_lo = gv; } else { idx_hi = iv; g_hi = gv; } } }
	v_min_u32_e32 v22, v189, v22
	v_max_u32_e32 v4, v27, v50
	v_min_u32_e32 v50, v27, v50
	v_max_u32_e32 v41, v194, v37
	v_min_u32_e32 v37, v194, v37
	v_max_u32_e32 v26, v38, v35
	v_min_u32_e32 v35, v38, v35
	v_max_u32_e32 v47, v5, v8
	v_min_u32_e32 v8, v5, v8
	v_max_u32_e32 v1, v11, v4
	v_min_u32_e32 v4, v11, v4
	v_max_u32_e32 v15, v48, v41
	v_min_u32_e32 v41, v48, v41
	v_max_u32_e32 v17, v192, v26
	v_min_u32_e32 v26, v192, v26
	v_max_u32_e32 v32, v184, v47
	v_min_u32_e32 v47, v184, v47
	v_max_u32_e32 v193, v44, v50
	v_min_u32_e32 v50, v44, v50
	v_max_u32_e32 v187, v12, v37
	v_min_u32_e32 v37, v12, v37
	v_max_u32_e32 v190, v30, v35
	v_min_u32_e32 v35, v30, v35
	v_max_u32_e32 v9, v22, v8
	v_min_u32_e32 v8, v22, v8
	v_max_u32_e32 v7, v1, v17
	v_min_u32_e32 v17, v1, v17
	v_max_u32_e32 v183, v15, v32
	v_min_u32_e32 v32, v15, v32
	v_max_u32_e32 v196, v4, v26
	v_min_u32_e32 v26, v4, v26
	v_max_u32_e32 v181, v41, v47
	v_min_u32_e32 v47, v41, v47
	v_max_u32_e32 v188, v193, v190
	v_min_u32_e32 v190, v193, v190
	v_max_u32_e32 v33, v187, v9
	v_min_u32_e32 v9, v187, v9
	v_max_u32_e32 v29, v50, v35
	v_min_u32_e32 v35, v50, v35
	v_max_u32_e32 v189, v37, v8
	v_min_u32_e32 v8, v37, v8
	v_max_u32_e32 v27, v7, v183
	v_min_u32_e32 v183, v7, v183
	v_max_u32_e32 v194, v17, v32
	v_min_u32_e32 v32, v17, v32
	v_max_u32_e32 v38, v196, v181
	v_min_u32_e32 v181, v196, v181
	v_max_u32_e32 v5, v26, v47
	v_min_u32_e32 v47, v26, v47
	v_max_u32_e32 v11, v188, v33
	v_min_u32_e32 v33, v188, v33
	v_max_u32_e32 v48, v190, v9
	v_min_u32_e32 v9, v190, v9
	v_max_u32_e32 v192, v29, v189
	v_min_u32_e32 v189, v29, v189
	v_max_u32_e32 v184, v35, v8
	v_min_u32_e32 v8, v35, v8
	ds_write_b8 v156, v27 offset:96
	ds_write_b8 v156, v183 offset:97
	ds_write_b8 v156, v194 offset:98
	ds_write_b8 v156, v32 offset:99
	ds_write_b8 v156, v38 offset:100
	ds_write_b8 v156, v181 offset:101
	ds_write_b8 v156, v5 offset:102
	ds_write_b8 v156, v47 offset:103
	ds_write_b8 v156, v11 offset:104
	ds_write_b8 v156, v33 offset:105
	ds_write_b8 v156, v48 offset:106
	ds_write_b8 v156, v9 offset:107
	ds_write_b8 v156, v192 offset:108
	ds_write_b8 v156, v189 offset:109
	ds_write_b8 v156, v184 offset:110
	ds_write_b8 v156, v8 offset:111
	v_and_b32_e32 v96, s31, v27
	v_ashrrev_i32_e32 v212, 31, v96
	v_lshrrev_b32_e32 v212, 1, v212
	v_xnor_b32_e32 v96, v96, v212
	v_and_b32_e32 v97, s31, v183
	v_ashrrev_i32_e32 v212, 31, v97
	v_lshrrev_b32_e32 v212, 1, v212
	v_xnor_b32_e32 v97, v97, v212
	v_and_b32_e32 v98, s31, v194
	v_ashrrev_i32_e32 v212, 31, v98
	v_lshrrev_b32_e32 v212, 1, v212
	v_xnor_b32_e32 v98, v98, v212
	v_and_b32_e32 v99, s31, v32
	v_ashrrev_i32_e32 v212, 31, v99
	v_lshrrev_b32_e32 v212, 1, v212
	v_xnor_b32_e32 v99, v99, v212
	v_and_b32_e32 v100, s31, v38
	v_ashrrev_i32_e32 v212, 31, v100
	v_lshrrev_b32_e32 v212, 1, v212
	v_xnor_b32_e32 v100, v100, v212
	v_and_b32_e32 v101, s31, v181
	v_ashrrev_i32_e32 v212, 31, v101
	v_lshrrev_b32_e32 v212, 1, v212
	v_xnor_b32_e32 v101, v101, v212
	v_and_b32_e32 v102, s31, v5
	v_ashrrev_i32_e32 v212, 31, v102
	v_lshrrev_b32_e32 v212, 1, v212
	v_xnor_b32_e32 v102, v102, v212
	v_and_b32_e32 v103, s31, v47
	v_ashrrev_i32_e32 v212, 31, v103
	v_lshrrev_b32_e32 v212, 1, v212
	v_xnor_b32_e32 v103, v103, v212
	v_and_b32_e32 v104, s31, v11
	v_ashrrev_i32_e32 v212, 31, v104
	v_lshrrev_b32_e32 v212, 1, v212
	v_xnor_b32_e32 v104, v104, v212
	v_and_b32_e32 v105, s31, v33
	v_ashrrev_i32_e32 v212, 31, v105
	v_lshrrev_b32_e32 v212, 1, v212
	v_xnor_b32_e32 v105, v105, v212
	v_and_b32_e32 v106, s31, v48
	v_ashrrev_i32_e32 v212, 31, v106
	v_lshrrev_b32_e32 v212, 1, v212
	v_xnor_b32_e32 v106, v106, v212
	v_and_b32_e32 v107, s31, v9
	v_ashrrev_i32_e32 v212, 31, v107
	v_lshrrev_b32_e32 v212, 1, v212
	v_xnor_b32_e32 v107, v107, v212
	v_and_b32_e32 v108, s31, v192
	v_ashrrev_i32_e32 v212, 31, v108
	v_lshrrev_b32_e32 v212, 1, v212
	v_xnor_b32_e32 v108, v108, v212
	v_and_b32_e32 v109, s31, v189
	v_ashrrev_i32_e32 v212, 31, v109
	v_lshrrev_b32_e32 v212, 1, v212
	v_xnor_b32_e32 v109, v109, v212
	v_and_b32_e32 v110, s31, v184
	v_ashrrev_i32_e32 v212, 31, v110
	v_lshrrev_b32_e32 v212, 1, v212
	v_xnor_b32_e32 v110, v110, v212
	v_and_b32_e32 v111, s31, v8
	v_ashrrev_i32_e32 v212, 31, v111
	v_lshrrev_b32_e32 v212, 1, v212
	v_xnor_b32_e32 v111, v111, v212
	ds_write_b128 v156, v[96:99] offset:32
	ds_write_b128 v156, v[100:103] offset:48
	ds_write_b128 v156, v[104:107] offset:64
	ds_write_b128 v156, v[108:111] offset:80
	s_branch .LBB0_221

; __device__ __forceinline__ float dot2pb(__bf16 x0, __bf16 x1, unsigned h, float c) { bf2_t x; x[0] = x0; x[1] = x1; bf2_t y; __builtin_memcpy(&y, &h, 4); return __builtin_amdgcn_fdot2_f32_bf16(x, y, c, false); }
; __device__ void ph_peer(const float* __restrict__ SC, const bf16_t* __restrict__ H  , const float* __restrict__ gffn, const unsigned char* __restrict__ U, const unsigned char* __restrict__ V, float* X, const float* __restrict__ fgain) {
;     ...
;         for (int it = 0; it < 32; ++it) {
;             const int src = (it * 4 + grp) & 63;
;             const int e = __shfl(it < 16 ? idx_lo : idx_hi, src);
;             const float gt = __shfl(it < 16 ? g_lo : g_hi, src);
;             const u32x4* up = (const u32x4*)(U + (size_t)e * 768 + 48 * sub);
;             const u32x4 u0 = up[0], u1 = up[1], u2 = up[2];
;             u32x2 vw[2][3];
; #pragma unroll
;             for (int r = 0; r < 2; ++r) { const int ea = __builtin_amdgcn_readlane(e, 32 * r), eb = __builtin_amdgcn_readlane(e, 32 * r + 16);
;                 const u32x2* vp = (const u32x2*)(V + (size_t)(half ? eb : ea) * 768 + 24 * c32); vw[r][0] = vp[0]; vw[r][1] = vp[1]; vw[r][2] = vp[2]; }
;             float d0 = 0.f, d1 = 0.f, d2 = 0.f, d3 = 0.f;
;             {   const v6u_t p0 = (v6u_t){u0.x, u0.y, u0.z, u0.w, u1.x, u1.y};
;                 const v32bf_t r0 = __builtin_amdgcn_cvt_scalef32_pk32_bf16_fp6(p0, 1.0f);
; #pragma unroll
;                 for (int k = 0; k < 16; k += 4) { d0 = dot2pb(r0[2 * k], r0[2 * k + 1], hf2[k], d0); d1 = dot2pb(r0[2 * k + 2], r0[2 * k + 3], hf2[k + 1], d1);
;                     d2 = dot2pb(r0[2 * k + 4], r0[2 * k + 5], hf2[k + 2], d2); d3 = dot2pb(r0[2 * k + 6], r0[2 * k + 7], hf2[k + 3], d3); } }
;             {   const v6u_t p1 = (v6u_t){u1.z, u1.w, u2.x, u2.y, u2.z, u2.w};
;                 const v32bf_t r1 = __builtin_amdgcn_cvt_scalef32_pk32_bf16_fp6(p1, 1.0f);
; #pragma unroll
;                 for (int k = 0; k < 16; k += 4) { d0 = dot2pb(r1[2 * k], r1[2 * k + 1], hf2[16 + k], d0); d1 = dot2pb(r1[2 * k + 2], r1[2 * k + 3], hf2[16 + k + 1], d1);
;                     d2 = dot2pb(r1[2 * k + 4], r1[2 * k + 5], hf2[16 + k + 2], d2); d3 = dot2pb(r1[2 * k + 6], r1[2 * k + 7], hf2[16 + k + 3], d3); } }
;             const float d = row16_sum((d0 + d1) + (d2 + d3)) * FP6_INV;
.Lpeer_uloop:
	ds_read_b32 v58, v61 offset:1520
	ds_read_b32 v59, v61 offset:2032
	s_waitcnt lgkmcnt(1)
	v_mad_u32_u24 v0, v58, s14, v92
	global_load_dwordx4 v[44:47], v0, s[46:47]
	global_load_dwordx4 v[48:51], v0, s[46:47] offset:16
	global_load_dwordx4 v[52:55], v0, s[46:47] offset:32
	s_waitcnt vmcnt(3)
	v_cvt_scalef32_pk32_bf16_fp6 v[0:15], v[32:37], 1.0
	v_dot2_f32_bf16 v23, v0, v95, 0
	v_dot2_f32_bf16 v25, v1, v159, 0
	v_dot2_f32_bf16 v22, v2, v160, 0
	v_dot2_f32_bf16 v24, v3, v161, 0
	v_dot2c_f32_bf16_e32 v23, v4, v180
	v_dot2c_f32_bf16_e32 v25, v5, v181
	v_dot2c_f32_bf16_e32 v22, v6, v182
	v_dot2c_f32_bf16_e32 v24, v7, v183
	v_dot2c_f32_bf16_e32 v23, v8, v184
	v_dot2c_f32_bf16_e32 v25, v9, v185
	v_dot2c_f32_bf16_e32 v22, v10, v186
	v_dot2c_f32_bf16_e32 v24, v11, v187
	v_dot2c_f32_bf16_e32 v23, v12, v188
	v_dot2c_f32_bf16_e32 v25, v13, v189
	v_dot2c_f32_bf16_e32 v22, v14, v190
	v_dot2c_f32_bf16_e32 v24, v15, v191
	v_cvt_scalef32_pk32_bf16_fp6 v[0:15], v[38:43], 1.0
	v_dot2c_f32_bf16_e32 v23, v0, v192
	v_dot2c_f32_bf16_e32 v25, v1, v193
	v_dot2c_f32_bf16_e32 v22, v2, v194
	v_dot2c_f32_bf16_e32 v24, v3, v195
	v_dot2c_f32_bf16_e32 v23, v4, v196
	v_dot2c_f32_bf16_e32 v25, v5, v197
	v_dot2c_f32_bf16_e32 v22, v6, v198
	v_dot2c_f32_bf16_e32 v24, v7, v199
	v_dot2c_f32_bf16_e32 v23, v8, v200
	v_dot2c_f32_bf16_e32 v25, v9, v201
	v_dot2c_f32_bf16_e32 v22, v10, v202
	v_dot2c_f32_bf16_e32 v24, v11, v203
	v_dot2c_f32_bf16_e32 v23, v12, v204
	v_dot2c_f32_bf16_e32 v25, v13, v205
	v_dot2c_f32_bf16_e32 v22, v14, v206
	v_dot2c_f32_bf16_e32 v24, v15, v207
	s_nop 2
	v_pk_add_f32 v[0:1], v[24:25], v[22:23]
	s_nop 0
	v_add_f32_e32 v246, v0, v1
	s_waitcnt lgkmcnt(0)
	v_cndmask_b32_e64 v209, v209, v57, s[50:51]
	ds_read_b32 v56, v61
	ds_read_b32 v57, v61 offset:512
	v_add_u32_e32 v61, 16, v61
	s_add_i32 s1, s1, 1
	s_waitcnt lgkmcnt(1)
	v_mad_u32_u24 v0, v56, s14, v92
	global_load_dwordx4 v[32:35], v0, s[46:47]
	global_load_dwordx4 v[36:39], v0, s[46:47] offset:16
	global_load_dwordx4 v[40:43], v0, s[46:47] offset:32
	s_waitcnt vmcnt(3)
	v_cvt_scalef32_pk32_bf16_fp6 v[0:15], v[44:49], 1.0
	v_dot2_f32_bf16 v23, v0, v212, 0
	v_dot2_f32_bf16 v25, v1, v213, 0
	v_dot2_f32_bf16 v22, v2, v214, 0
	v_dot2_f32_bf16 v24, v3, v215, 0
	v_dot2c_f32_bf16_e32 v23, v4, v218
	v_dot2c_f32_bf16_e32 v25, v5, v219
	v_dot2c_f32_bf16_e32 v22, v6, v220
	v_dot2c_f32_bf16_e32 v24, v7, v221
	v_dot2c_f32_bf16_e32 v23, v8, v222
	v_dot2c_f32_bf16_e32 v25, v9, v223
	v_dot2c_f32_bf16_e32 v22, v10, v224
	v_dot2c_f32_bf16_e32 v24, v11, v225
	v_dot2c_f32_bf16_e32 v23, v12, v226
	v_dot2c_f32_bf16_e32 v25, v13, v227
	v_dot2c_f32_bf16_e32 v22, v14, v228
	v_dot2c_f32_bf16_e32 v24, v15, v229
	v_cvt_scalef32_pk32_bf16_fp6 v[0:15], v[50:55], 1.0
	v_dot2c_f32_bf16_e32 v23, v0, v230
	v_dot2c_f32_bf16_e32 v25, v1, v231
	v_dot2c_f32_bf16_e32 v22, v2, v232
	v_dot2c_f32_bf16_e32 v24, v3, v233
	v_dot2c_f32_bf16_e32 v23, v4, v234
	v_dot2c_f32_bf16_e32 v25, v5, v235
	v_dot2c_f32_bf16_e32 v22, v6, v236
	v_dot2c_f32_bf16_e32 v24, v7, v237
	v_dot2c_f32_bf16_e32 v23, v8, v238
	v_dot2c_f32_bf16_e32 v25, v9, v239
	v_dot2c_f32_bf16_e32 v22, v10, v240
	v_dot2c_f32_bf16_e32 v24, v11, v241
	v_dot2c_f32_bf16_e32 v23, v12, v242
	v_dot2c_f32_bf16_e32 v25, v13, v243
	v_dot2c_f32_bf16_e32 v22, v14, v244
	v_dot2c_f32_bf16_e32 v24, v15, v245
	s_nop 2
	v_pk_add_f32 v[0:1], v[24:25], v[22:23]
	s_nop 0
	v_add_f32_e32 v250, v0, v1
	s_waitcnt lgkmcnt(0)
	v_cndmask_b32_e64 v211, v211, v59, s[50:51]
	ds_read_b32 v58, v61 offset:1520
	ds_read_b32 v59, v61 offset:2032
	s_waitcnt lgkmcnt(1)
	v_mad_u32_u24 v0, v58, s14, v92
	global_load_dwordx4 v[44:47], v0, s[46:47]
	global_load_dwordx4 v[48:51], v0, s[46:47] offset:16
	global_load_dwordx4 v[52:55], v0, s[46:47] offset:32
	s_waitcnt vmcnt(3)
	v_cvt_scalef32_pk32_bf16_fp6 v[0:15], v[32:37], 1.0
	v_dot2_f32_bf16 v23, v0, v95, 0
	v_dot2_f32_bf16 v25, v1, v159, 0
	v_dot2_f32_bf16 v22, v2, v160, 0
	v_dot2_f32_bf16 v24, v3, v161, 0
	v_dot2c_f32_bf16_e32 v23, v4, v180
	v_dot2c_f32_bf16_e32 v25, v5, v181
	v_dot2c_f32_bf16_e32 v22, v6, v182
	v_dot2c_f32_bf16_e32 v24, v7, v183
	v_dot2c_f32_bf16_e32 v23, v8, v184
	v_dot2c_f32_bf16_e32 v25, v9, v185
	v_dot2c_f32_bf16_e32 v22, v10, v186
	v_dot2c_f32_bf16_e32 v24, v11, v187
	v_dot2c_f32_bf16_e32 v23, v12, v188
	v_dot2c_f32_bf16_e32 v25, v13, v189
	v_dot2c_f32_bf16_e32 v22, v14, v190
	v_dot2c_f32_bf16_e32 v24, v15, v191
	v_cvt_scalef32_pk32_bf16_fp6 v[0:15], v[38:43], 1.0
	v_dot2c_f32_bf16_e32 v23, v0, v192
	v_dot2c_f32_bf16_e32 v25, v1, v193
	v_dot2c_f32_bf16_e32 v22, v2, v194
	v_dot2c_f32_bf16_e32 v24, v3, v195
	v_dot2c_f32_bf16_e32 v23, v4, v196
	v_dot2c_f32_bf16_e32 v25, v5, v197
	v_dot2c_f32_bf16_e32 v22, v6, v198
	v_dot2c_f32_bf16_e32 v24, v7, v199
	v_dot2c_f32_bf16_e32 v23, v8, v200
	v_dot2c_f32_bf16_e32 v25, v9, v201
	v_dot2c_f32_bf16_e32 v22, v10, v202
	v_dot2c_f32_bf16_e32 v24, v11, v203
	v_dot2c_f32_bf16_e32 v23, v12, v204
	v_dot2c_f32_bf16_e32 v25, v13, v205
	v_dot2c_f32_bf16_e32 v22, v14, v206
	v_dot2c_f32_bf16_e32 v24, v15, v207
	s_nop 2
	v_pk_add_f32 v[0:1], v[24:25], v[22:23]
	s_nop 0
	v_add_f32_e32 v247, v0, v1
	s_waitcnt lgkmcnt(0)
	v_cndmask_b32_e64 v209, v209, v57, s[52:53]
	ds_read_b32 v56, v61
	ds_read_b32 v57, v61 offset:512
	v_add_u32_e32 v61, 16, v61
	s_add_i32 s1, s1, 1
	s_waitcnt lgkmcnt(1)
	v_mad_u32_u24 v0, v56, s14, v92
	global_load_dwordx4 v[32:35], v0, s[46:47]
	global_load_dwordx4 v[36:39], v0, s[46:47] offset:16
	global_load_dwordx4 v[40:43], v0, s[46:47] offset:32
	s_waitcnt vmcnt(3)
; __device__ __forceinline__ float dot2pb(__bf16 x0, __bf16 x1, unsigned h, float c) { bf2_t x; x[0] = x0; x[1] = x1; bf2_t y; __builtin_memcpy(&y, &h, 4); return __builtin_amdgcn_fdot2_f32_bf16(x, y, c, false); }
; __device__ void ph_peer(const float* __restrict__ SC, const bf16_t* __restrict__ H  , const float* __restrict__ gffn, const unsigned char* __restrict__ U, const unsigned char* __restrict__ V, float* X, const float* __restrict__ fgain) {
;     ...
;         for (int it = 0; it < 32; ++it) {
;             const int src = (it * 4 + grp) & 63;
;             const int e = __shfl(it < 16 ? idx_lo : idx_hi, src);
;             const float gt = __shfl(it < 16 ? g_lo : g_hi, src);
;             const u32x4* up = (const u32x4*)(U + (size_t)e * 768 + 48 * sub);
;             const u32x4 u0 = up[0], u1 = up[1], u2 = up[2];
;             u32x2 vw[2][3];
; #pragma unroll
;             for (int r = 0; r < 2; ++r) { const int ea = __builtin_amdgcn_readlane(e, 32 * r), eb = __builtin_amdgcn_readlane(e, 32 * r + 16);
;                 const u32x2* vp = (const u32x2*)(V + (size_t)(half ? eb : ea) * 768 + 24 * c32); vw[r][0] = vp[0]; vw[r][1] = vp[1]; vw[r][2] = vp[2]; }
;             float d0 = 0.f, d1 = 0.f, d2 = 0.f, d3 = 0.f;
;             {   const v6u_t p0 = (v6u_t){u0.x, u0.y, u0.z, u0.w, u1.x, u1.y};
;                 const v32bf_t r0 = __builtin_amdgcn_cvt_scalef32_pk32_bf16_fp6(p0, 1.0f);
; #pragma unroll
;                 for (int k = 0; k < 16; k += 4) { d0 = dot2pb(r0[2 * k], r0[2 * k + 1], hf2[k], d0); d1 = dot2pb(r0[2 * k + 2], r0[2 * k + 3], hf2[k + 1], d1);
;                     d2 = dot2pb(r0[2 * k + 4], r0[2 * k + 5], hf2[k + 2], d2); d3 = dot2pb(r0[2 * k + 6], r0[2 * k + 7], hf2[k + 3], d3); } }
;             {   const v6u_t p1 = (v6u_t){u1.z, u1.w, u2.x, u2.y, u2.z, u2.w};
;                 const v32bf_t r1 = __builtin_amdgcn_cvt_scalef32_pk32_bf16_fp6(p1, 1.0f);
; #pragma unroll
;                 for (int k = 0; k < 16; k += 4) { d0 = dot2pb(r1[2 * k], r1[2 * k + 1], hf2[16 + k], d0); d1 = dot2pb(r1[2 * k + 2], r1[2 * k + 3], hf2[16 + k + 1], d1);
;                     d2 = dot2pb(r1[2 * k + 4], r1[2 * k + 5], hf2[16 + k + 2], d2); d3 = dot2pb(r1[2 * k + 6], r1[2 * k + 7], hf2[16 + k + 3], d3); } }
;             const float d = row16_sum((d0 + d1) + (d2 + d3)) * FP6_INV;
	v_cvt_scalef32_pk32_bf16_fp6 v[0:15], v[44:49], 1.0
	v_dot2_f32_bf16 v23, v0, v212, 0
	v_dot2_f32_bf16 v25, v1, v213, 0
	v_dot2_f32_bf16 v22, v2, v214, 0
	v_dot2_f32_bf16 v24, v3, v215, 0
	v_dot2c_f32_bf16_e32 v23, v4, v218
	v_dot2c_f32_bf16_e32 v25, v5, v219
	v_dot2c_f32_bf16_e32 v22, v6, v220
	v_dot2c_f32_bf16_e32 v24, v7, v221
	v_dot2c_f32_bf16_e32 v23, v8, v222
	v_dot2c_f32_bf16_e32 v25, v9, v223
	v_dot2c_f32_bf16_e32 v22, v10, v224
	v_dot2c_f32_bf16_e32 v24, v11, v225
	v_dot2c_f32_bf16_e32 v23, v12, v226
	v_dot2c_f32_bf16_e32 v25, v13, v227
	v_dot2c_f32_bf16_e32 v22, v14, v228
	v_dot2c_f32_bf16_e32 v24, v15, v229
	v_cvt_scalef32_pk32_bf16_fp6 v[0:15], v[50:55], 1.0
	v_dot2c_f32_bf16_e32 v23, v0, v230
	v_dot2c_f32_bf16_e32 v25, v1, v231
	v_dot2c_f32_bf16_e32 v22, v2, v232
	v_dot2c_f32_bf16_e32 v24, v3, v233
	v_dot2c_f32_bf16_e32 v23, v4, v234
	v_dot2c_f32_bf16_e32 v25, v5, v235
	v_dot2c_f32_bf16_e32 v22, v6, v236
	v_dot2c_f32_bf16_e32 v24, v7, v237
	v_dot2c_f32_bf16_e32 v23, v8, v238
	v_dot2c_f32_bf16_e32 v25, v9, v239
	v_dot2c_f32_bf16_e32 v22, v10, v240
	v_dot2c_f32_bf16_e32 v24, v11, v241
	v_dot2c_f32_bf16_e32 v23, v12, v242
	v_dot2c_f32_bf16_e32 v25, v13, v243
	v_dot2c_f32_bf16_e32 v22, v14, v244
	v_dot2c_f32_bf16_e32 v24, v15, v245
	s_nop 2
	v_pk_add_f32 v[0:1], v[24:25], v[22:23]
	s_nop 0
	v_add_f32_e32 v216, v0, v1
	s_waitcnt lgkmcnt(0)
	v_cndmask_b32_e64 v211, v211, v59, s[52:53]
	ds_read_b32 v58, v61 offset:1520
	ds_read_b32 v59, v61 offset:2032
	s_waitcnt lgkmcnt(1)
	v_mad_u32_u24 v0, v58, s14, v92
	global_load_dwordx4 v[44:47], v0, s[46:47]
	global_load_dwordx4 v[48:51], v0, s[46:47] offset:16
	global_load_dwordx4 v[52:55], v0, s[46:47] offset:32
	s_waitcnt vmcnt(3)
	v_cvt_scalef32_pk32_bf16_fp6 v[0:15], v[32:37], 1.0
	v_dot2_f32_bf16 v23, v0, v95, 0
	v_dot2_f32_bf16 v25, v1, v159, 0
	v_dot2_f32_bf16 v22, v2, v160, 0
	v_dot2_f32_bf16 v24, v3, v161, 0
	v_dot2c_f32_bf16_e32 v23, v4, v180
	v_dot2c_f32_bf16_e32 v25, v5, v181
	v_dot2c_f32_bf16_e32 v22, v6, v182
	v_dot2c_f32_bf16_e32 v24, v7, v183
	v_dot2c_f32_bf16_e32 v23, v8, v184
	v_dot2c_f32_bf16_e32 v25, v9, v185
	v_dot2c_f32_bf16_e32 v22, v10, v186
	v_dot2c_f32_bf16_e32 v24, v11, v187
	v_dot2c_f32_bf16_e32 v23, v12, v188
	v_dot2c_f32_bf16_e32 v25, v13, v189
	v_dot2c_f32_bf16_e32 v22, v14, v190
	v_dot2c_f32_bf16_e32 v24, v15, v191
	v_cvt_scalef32_pk32_bf16_fp6 v[0:15], v[38:43], 1.0
	v_dot2c_f32_bf16_e32 v23, v0, v192
	v_dot2c_f32_bf16_e32 v25, v1, v193
	v_dot2c_f32_bf16_e32 v22, v2, v194
	v_dot2c_f32_bf16_e32 v24, v3, v195
	v_dot2c_f32_bf16_e32 v23, v4, v196
	v_dot2c_f32_bf16_e32 v25, v5, v197
	v_dot2c_f32_bf16_e32 v22, v6, v198
	v_dot2c_f32_bf16_e32 v24, v7, v199
	v_dot2c_f32_bf16_e32 v23, v8, v200
	v_dot2c_f32_bf16_e32 v25, v9, v201
	v_dot2c_f32_bf16_e32 v22, v10, v202
	v_dot2c_f32_bf16_e32 v24, v11, v203
	v_dot2c_f32_bf16_e32 v23, v12, v204
	v_dot2c_f32_bf16_e32 v25, v13, v205
	v_dot2c_f32_bf16_e32 v22, v14, v206
	v_dot2c_f32_bf16_e32 v24, v15, v207
	s_nop 2
	v_pk_add_f32 v[0:1], v[24:25], v[22:23]
	s_nop 0
	v_add_f32_e32 v248, v0, v1
	s_waitcnt lgkmcnt(0)
	v_cndmask_b32_e64 v209, v209, v57, s[54:55]
	ds_read_b32 v56, v61
	ds_read_b32 v57, v61 offset:512
	v_add_u32_e32 v61, 16, v61
	s_add_i32 s1, s1, 1
	s_waitcnt lgkmcnt(1)
	v_mad_u32_u24 v0, v56, s14, v92
	global_load_dwordx4 v[32:35], v0, s[46:47]
	global_load_dwordx4 v[36:39], v0, s[46:47] offset:16
	global_load_dwordx4 v[40:43], v0, s[46:47] offset:32
	s_waitcnt vmcnt(3)
	v_cvt_scalef32_pk32_bf16_fp6 v[0:15], v[44:49], 1.0
	v_dot2_f32_bf16 v23, v0, v212, 0
	v_dot2_f32_bf16 v25, v1, v213, 0
	v_dot2_f32_bf16 v22, v2, v214, 0
	v_dot2_f32_bf16 v24, v3, v215, 0
	v_dot2c_f32_bf16_e32 v23, v4, v218
	v_dot2c_f32_bf16_e32 v25, v5, v219
	v_dot2c_f32_bf16_e32 v22, v6, v220
	v_dot2c_f32_bf16_e32 v24, v7, v221
	v_dot2c_f32_bf16_e32 v23, v8, v222
	v_dot2c_f32_bf16_e32 v25, v9, v223
	v_dot2c_f32_bf16_e32 v22, v10, v224
	v_dot2c_f32_bf16_e32 v24, v11, v225
	v_dot2c_f32_bf16_e32 v23, v12, v226
	v_dot2c_f32_bf16_e32 v25, v13, v227
	v_dot2c_f32_bf16_e32 v22, v14, v228
	v_dot2c_f32_bf16_e32 v24, v15, v229
	v_cvt_scalef32_pk32_bf16_fp6 v[0:15], v[50:55], 1.0
	v_dot2c_f32_bf16_e32 v23, v0, v230
	v_dot2c_f32_bf16_e32 v25, v1, v231
	v_dot2c_f32_bf16_e32 v22, v2, v232
	v_dot2c_f32_bf16_e32 v24, v3, v233
	v_dot2c_f32_bf16_e32 v23, v4, v234
	v_dot2c_f32_bf16_e32 v25, v5, v235
	v_dot2c_f32_bf16_e32 v22, v6, v236
	v_dot2c_f32_bf16_e32 v24, v7, v237
	v_dot2c_f32_bf16_e32 v23, v8, v238
	v_dot2c_f32_bf16_e32 v25, v9, v239
	v_dot2c_f32_bf16_e32 v22, v10, v240
	v_dot2c_f32_bf16_e32 v24, v11, v241
	v_dot2c_f32_bf16_e32 v23, v12, v242
	v_dot2c_f32_bf16_e32 v25, v13, v243
	v_dot2c_f32_bf16_e32 v22, v14, v244
	v_dot2c_f32_bf16_e32 v24, v15, v245
	s_nop 2
	v_pk_add_f32 v[0:1], v[24:25], v[22:23]
	s_nop 0
	v_add_f32_e32 v217, v0, v1
	s_waitcnt lgkmcnt(0)
	v_cndmask_b32_e64 v211, v211, v59, s[54:55]
	ds_read_b32 v58, v61 offset:1520
	ds_read_b32 v59, v61 offset:2032
	s_waitcnt lgkmcnt(1)
	v_mad_u32_u24 v0, v58, s14, v92
	global_load_dwordx4 v[44:47], v0, s[46:47]
	global_load_dwordx4 v[48:51], v0, s[46:47] offset:16
	global_load_dwordx4 v[52:55], v0, s[46:47] offset:32
	s_waitcnt vmcnt(3)
; __device__ __forceinline__ float gelu1(float v) { const f32x2 r = gelu_pk((f32x2){v, v}); return r.x; }
; __device__ __forceinline__ float dot2pb(__bf16 x0, __bf16 x1, unsigned h, float c) { bf2_t x; x[0] = x0; x[1] = x1; bf2_t y; __builtin_memcpy(&y, &h, 4); return __builtin_amdgcn_fdot2_f32_bf16(x, y, c, false); }
; __device__ void ph_peer(const float* __restrict__ SC, const bf16_t* __restrict__ H  , const float* __restrict__ gffn, const unsigned char* __restrict__ U, const unsigned char* __restrict__ V, float* X, const float* __restrict__ fgain) {
;     ...
;             const u32x4* up = (const u32x4*)(U + (size_t)e * 768 + 48 * sub);
;             const u32x4 u0 = up[0], u1 = up[1], u2 = up[2];
;             u32x2 vw[2][3];
; #pragma unroll
;             for (int r = 0; r < 2; ++r) { const int ea = __builtin_amdgcn_readlane(e, 32 * r), eb = __builtin_amdgcn_readlane(e, 32 * r + 16);
;                 const u32x2* vp = (const u32x2*)(V + (size_t)(half ? eb : ea) * 768 + 24 * c32); vw[r][0] = vp[0]; vw[r][1] = vp[1]; vw[r][2] = vp[2]; }
;             float d0 = 0.f, d1 = 0.f, d2 = 0.f, d3 = 0.f;
;             {   const v6u_t p0 = (v6u_t){u0.x, u0.y, u0.z, u0.w, u1.x, u1.y};
;                 const v32bf_t r0 = __builtin_amdgcn_cvt_scalef32_pk32_bf16_fp6(p0, 1.0f);
; #pragma unroll
;                 for (int k = 0; k < 16; k += 4) { d0 = dot2pb(r0[2 * k], r0[2 * k + 1], hf2[k], d0); d1 = dot2pb(r0[2 * k + 2], r0[2 * k + 3], hf2[k + 1], d1);
;                     d2 = dot2pb(r0[2 * k + 4], r0[2 * k + 5], hf2[k + 2], d2); d3 = dot2pb(r0[2 * k + 6], r0[2 * k + 7], hf2[k + 3], d3); } }
;             {   const v6u_t p1 = (v6u_t){u1.z, u1.w, u2.x, u2.y, u2.z, u2.w};
;                 const v32bf_t r1 = __builtin_amdgcn_cvt_scalef32_pk32_bf16_fp6(p1, 1.0f);
; #pragma unroll
;                 for (int k = 0; k < 16; k += 4) { d0 = dot2pb(r1[2 * k], r1[2 * k + 1], hf2[16 + k], d0); d1 = dot2pb(r1[2 * k + 2], r1[2 * k + 3], hf2[16 + k + 1], d1);
;                     d2 = dot2pb(r1[2 * k + 4], r1[2 * k + 5], hf2[16 + k + 2], d2); d3 = dot2pb(r1[2 * k + 6], r1[2 * k + 7], hf2[16 + k + 3], d3); } }
;             const float d = row16_sum((d0 + d1) + (d2 + d3)) * FP6_INV;
;             const float a = gt * gelu1(d) * FP6_INV;
	v_cvt_scalef32_pk32_bf16_fp6 v[0:15], v[32:37], 1.0
	v_dot2_f32_bf16 v23, v0, v95, 0
	v_dot2_f32_bf16 v25, v1, v159, 0
	v_dot2_f32_bf16 v22, v2, v160, 0
	v_dot2_f32_bf16 v24, v3, v161, 0
	v_dot2c_f32_bf16_e32 v23, v4, v180
	v_dot2c_f32_bf16_e32 v25, v5, v181
	v_dot2c_f32_bf16_e32 v22, v6, v182
	v_dot2c_f32_bf16_e32 v24, v7, v183
	v_dot2c_f32_bf16_e32 v23, v8, v184
	v_dot2c_f32_bf16_e32 v25, v9, v185
	v_dot2c_f32_bf16_e32 v22, v10, v186
	v_dot2c_f32_bf16_e32 v24, v11, v187
	v_dot2c_f32_bf16_e32 v23, v12, v188
	v_dot2c_f32_bf16_e32 v25, v13, v189
	v_dot2c_f32_bf16_e32 v22, v14, v190
	v_dot2c_f32_bf16_e32 v24, v15, v191
	v_cvt_scalef32_pk32_bf16_fp6 v[0:15], v[38:43], 1.0
	v_dot2c_f32_bf16_e32 v23, v0, v192
	v_dot2c_f32_bf16_e32 v25, v1, v193
	v_dot2c_f32_bf16_e32 v22, v2, v194
	v_dot2c_f32_bf16_e32 v24, v3, v195
	v_dot2c_f32_bf16_e32 v23, v4, v196
	v_dot2c_f32_bf16_e32 v25, v5, v197
	v_dot2c_f32_bf16_e32 v22, v6, v198
	v_dot2c_f32_bf16_e32 v24, v7, v199
	v_dot2c_f32_bf16_e32 v23, v8, v200
	v_dot2c_f32_bf16_e32 v25, v9, v201
	v_dot2c_f32_bf16_e32 v22, v10, v202
	v_dot2c_f32_bf16_e32 v24, v11, v203
	v_dot2c_f32_bf16_e32 v23, v12, v204
	v_dot2c_f32_bf16_e32 v25, v13, v205
	v_dot2c_f32_bf16_e32 v22, v14, v206
	v_dot2c_f32_bf16_e32 v24, v15, v207
	s_nop 2
	v_pk_add_f32 v[0:1], v[24:25], v[22:23]
	s_nop 0
	v_add_f32_e32 v249, v0, v1
	s_waitcnt lgkmcnt(0)
	v_cndmask_b32_e64 v209, v209, v57, s[56:57]
	v_cndmask_b32_e64 v2, v247, v246, s[58:59]
	v_cndmask_b32_e64 v3, v246, v247, s[58:59]
	v_cndmask_b32_e64 v4, v249, v248, s[58:59]
	v_cndmask_b32_e64 v5, v248, v249, s[58:59]
	v_add_f32_dpp v3, v2, v3 quad_perm:[1,0,3,2] row_mask:0xf bank_mask:0xf bound_ctrl:1
	v_add_f32_dpp v5, v4, v5 quad_perm:[1,0,3,2] row_mask:0xf bank_mask:0xf bound_ctrl:1
	v_cndmask_b32_e64 v2, v5, v3, s[60:61]
	v_cndmask_b32_e64 v0, v3, v5, s[60:61]
	s_nop 0
	v_add_f32_dpp v0, v2, v0 quad_perm:[2,3,0,1] row_mask:0xf bank_mask:0xf bound_ctrl:1
	s_nop 1
	v_add_f32_dpp v0, v0, v0 row_ror:4 row_mask:0xf bank_mask:0xf bound_ctrl:1
	s_nop 1
	v_add_f32_dpp v0, v0, v0 row_ror:8 row_mask:0xf bank_mask:0xf bound_ctrl:1
	v_mul_f32_e32 v0, 0x3caaaaab, v0
	v_and_b32_e32 v2, 0x7fffffff, v0
	v_pk_fma_f32 v[2:3], v[2:3], s[16:17], 1.0 op_sel_hi:[0,0,0]
	v_rcp_f32_e32 v2, v2
	v_rcp_f32_e32 v3, v3
	v_mul_f32_e32 v1, v0, v0
	v_mul_f32_e32 v1, 0xbf38aa3b, v1
	v_cmp_gt_f32_e32 vcc, 0, v0
	v_pk_fma_f32 v[4:5], v[2:3], s[24:25], v[130:131] op_sel_hi:[1,0,0]
	s_nop 0
	v_pk_fma_f32 v[4:5], v[2:3], v[4:5], s[28:29] op_sel_hi:[1,1,0]
	s_nop 0
	v_pk_fma_f32 v[4:5], v[2:3], v[4:5], s[30:31] op_sel_hi:[1,1,0]
	s_nop 0
	v_pk_fma_f32 v[4:5], v[2:3], v[4:5], s[36:37] op_sel_hi:[1,1,0]
	s_nop 0
	v_pk_mul_f32 v[2:3], v[2:3], v[4:5]
	v_exp_f32_e32 v4, v1
	s_nop 0
	v_pk_mul_f32 v[2:3], v[4:5], v[2:3] op_sel_hi:[0,1]
	v_pk_fma_f32 v[4:5], v[0:1], v[2:3], v[0:1] op_sel_hi:[0,1,1] neg_lo:[1,0,0] neg_hi:[1,0,0]
	v_mul_f32_e32 v0, v0, v2
	v_cndmask_b32_e32 v0, v4, v0, vcc
	v_mul_f32_e32 v0, v0, v209
	v_mul_f32_e32 v60, 0x3caaaaab, v0
	v_add_u32_e32 v62, v61, v155
	ds_write_b32 v62, v60 offset:960
	ds_read_b32 v56, v61
	ds_read_b32 v57, v61 offset:512
	v_add_u32_e32 v61, 16, v61
	s_add_i32 s1, s1, 1
	s_waitcnt lgkmcnt(1)
	v_mad_u32_u24 v0, v56, s14, v92
	global_load_dwordx4 v[32:35], v0, s[46:47]
	global_load_dwordx4 v[36:39], v0, s[46:47] offset:16
	global_load_dwordx4 v[40:43], v0, s[46:47] offset:32
	s_waitcnt vmcnt(3)
	v_cvt_scalef32_pk32_bf16_fp6 v[0:15], v[44:49], 1.0
	v_dot2_f32_bf16 v23, v0, v212, 0
	v_dot2_f32_bf16 v25, v1, v213, 0
	v_dot2_f32_bf16 v22, v2, v214, 0
	v_dot2_f32_bf16 v24, v3, v215, 0
	v_dot2c_f32_bf16_e32 v23, v4, v218
	v_dot2c_f32_bf16_e32 v25, v5, v219
	v_dot2c_f32_bf16_e32 v22, v6, v220
	v_dot2c_f32_bf16_e32 v24, v7, v221
	v_dot2c_f32_bf16_e32 v23, v8, v222
	v_dot2c_f32_bf16_e32 v25, v9, v223
	v_dot2c_f32_bf16_e32 v22, v10, v224
	v_dot2c_f32_bf16_e32 v24, v11, v225
	v_dot2c_f32_bf16_e32 v23, v12, v226
	v_dot2c_f32_bf16_e32 v25, v13, v227
	v_dot2c_f32_bf16_e32 v22, v14, v228
	v_dot2c_f32_bf16_e32 v24, v15, v229
	v_cvt_scalef32_pk32_bf16_fp6 v[0:15], v[50:55], 1.0
	v_dot2c_f32_bf16_e32 v23, v0, v230
	v_dot2c_f32_bf16_e32 v25, v1, v231
	v_dot2c_f32_bf16_e32 v22, v2, v232
	v_dot2c_f32_bf16_e32 v24, v3, v233
	v_dot2c_f32_bf16_e32 v23, v4, v234
	v_dot2c_f32_bf16_e32 v25, v5, v235
	v_dot2c_f32_bf16_e32 v22, v6, v236
	v_dot2c_f32_bf16_e32 v24, v7, v237
	v_dot2c_f32_bf16_e32 v23, v8, v238
	v_dot2c_f32_bf16_e32 v25, v9, v239
	v_dot2c_f32_bf16_e32 v22, v10, v240
	v_dot2c_f32_bf16_e32 v24, v11, v241
	v_dot2c_f32_bf16_e32 v23, v12, v242
	v_dot2c_f32_bf16_e32 v25, v13, v243
	v_dot2c_f32_bf16_e32 v22, v14, v244
	v_dot2c_f32_bf16_e32 v24, v15, v245
	s_nop 2
	v_pk_add_f32 v[0:1], v[24:25], v[22:23]
	s_nop 0
	v_add_f32_e32 v63, v0, v1
	s_waitcnt lgkmcnt(0)
	v_cndmask_b32_e64 v211, v211, v59, s[56:57]
	v_cndmask_b32_e64 v2, v216, v250, s[58:59]
	v_cndmask_b32_e64 v3, v250, v216, s[58:59]
	v_cndmask_b32_e64 v4, v63, v217, s[58:59]
	v_cndmask_b32_e64 v5, v217, v63, s[58:59]
	v_add_f32_dpp v3, v2, v3 quad_perm:[1,0,3,2] row_mask:0xf bank_mask:0xf bound_ctrl:1
	v_add_f32_dpp v5, v4, v5 quad_perm:[1,0,3,2] row_mask:0xf bank_mask:0xf bound_ctrl:1
	v_cndmask_b32_e64 v2, v5, v3, s[60:61]
	v_cndmask_b32_e64 v0, v3, v5, s[60:61]
	s_nop 0
	v_add_f32_dpp v0, v2, v0 quad_perm:[2,3,0,1] row_mask:0xf bank_mask:0xf bound_ctrl:1
	s_nop 1
	v_add_f32_dpp v0, v0, v0 row_ror:4 row_mask:0xf bank_mask:0xf bound_ctrl:1
	s_nop 1
	v_add_f32_dpp v0, v0, v0 row_ror:8 row_mask:0xf bank_mask:0xf bound_ctrl:1
	v_mul_f32_e32 v0, 0x3caaaaab, v0
	v_and_b32_e32 v2, 0x7fffffff, v0
	v_pk_fma_f32 v[2:3], v[2:3], s[16:17], 1.0 op_sel_hi:[0,0,0]
	v_rcp_f32_e32 v2, v2
	v_rcp_f32_e32 v3, v3
	v_mul_f32_e32 v1, v0, v0
	v_mul_f32_e32 v1, 0xbf38aa3b, v1
	v_cmp_gt_f32_e32 vcc, 0, v0
	v_pk_fma_f32 v[4:5], v[2:3], s[24:25], v[130:131] op_sel_hi:[1,0,0]
	s_nop 0
	v_pk_fma_f32 v[4:5], v[2:3], v[4:5], s[28:29] op_sel_hi:[1,1,0]
	s_nop 0
	v_pk_fma_f32 v[4:5], v[2:3], v[4:5], s[30:31] op_sel_hi:[1,1,0]
	s_nop 0
	v_pk_fma_f32 v[4:5], v[2:3], v[4:5], s[36:37] op_sel_hi:[1,1,0]
	s_nop 0
	v_pk_mul_f32 v[2:3], v[2:3], v[4:5]
	v_exp_f32_e32 v4, v1
	s_nop 0
	v_pk_mul_f32 v[2:3], v[4:5], v[2:3] op_sel_hi:[0,1]
	v_pk_fma_f32 v[4:5], v[0:1], v[2:3], v[0:1] op_sel_hi:[0,1,1] neg_lo:[1,0,0] neg_hi:[1,0,0]
	v_mul_f32_e32 v0, v0, v2
	v_cndmask_b32_e32 v0, v4, v0, vcc
	v_mul_f32_e32 v0, v0, v211
	v_mul_f32_e32 v60, 0x3caaaaab, v0
	v_add_u32_e32 v62, v61, v155
	ds_write_b32 v62, v60 offset:2480
	s_cmp_lt_u32 s1, 29
	s_cbranch_scc1 .Lpeer_uloop
; __device__ __forceinline__ float dot2pb(__bf16 x0, __bf16 x1, unsigned h, float c) { bf2_t x; x[0] = x0; x[1] = x1; bf2_t y; __builtin_memcpy(&y, &h, 4); return __builtin_amdgcn_fdot2_f32_bf16(x, y, c, false); }
; __device__ void ph_peer(const float* __restrict__ SC, const bf16_t* __restrict__ H  , const float* __restrict__ gffn, const unsigned char* __restrict__ U, const unsigned char* __restrict__ V, float* X, const float* __restrict__ fgain) {
;     ...
;             const u32x4* up = (const u32x4*)(U + (size_t)e * 768 + 48 * sub);
;             const u32x4 u0 = up[0], u1 = up[1], u2 = up[2];
;             u32x2 vw[2][3];
; #pragma unroll
;             for (int r = 0; r < 2; ++r) { const int ea = __builtin_amdgcn_readlane(e, 32 * r), eb = __builtin_amdgcn_readlane(e, 32 * r + 16);
;                 const u32x2* vp = (const u32x2*)(V + (size_t)(half ? eb : ea) * 768 + 24 * c32); vw[r][0] = vp[0]; vw[r][1] = vp[1]; vw[r][2] = vp[2]; }
;             float d0 = 0.f, d1 = 0.f, d2 = 0.f, d3 = 0.f;
;             {   const v6u_t p0 = (v6u_t){u0.x, u0.y, u0.z, u0.w, u1.x, u1.y};
;                 const v32bf_t r0 = __builtin_amdgcn_cvt_scalef32_pk32_bf16_fp6(p0, 1.0f);
; #pragma unroll
;                 for (int k = 0; k < 16; k += 4) { d0 = dot2pb(r0[2 * k], r0[2 * k + 1], hf2[k], d0); d1 = dot2pb(r0[2 * k + 2], r0[2 * k + 3], hf2[k + 1], d1);
;                     d2 = dot2pb(r0[2 * k + 4], r0[2 * k + 5], hf2[k + 2], d2); d3 = dot2pb(r0[2 * k + 6], r0[2 * k + 7], hf2[k + 3], d3); } }
;             {   const v6u_t p1 = (v6u_t){u1.z, u1.w, u2.x, u2.y, u2.z, u2.w};
;                 const v32bf_t r1 = __builtin_amdgcn_cvt_scalef32_pk32_bf16_fp6(p1, 1.0f);
; #pragma unroll
;                 for (int k = 0; k < 16; k += 4) { d0 = dot2pb(r1[2 * k], r1[2 * k + 1], hf2[16 + k], d0); d1 = dot2pb(r1[2 * k + 2], r1[2 * k + 3], hf2[16 + k + 1], d1);
;                     d2 = dot2pb(r1[2 * k + 4], r1[2 * k + 5], hf2[16 + k + 2], d2); d3 = dot2pb(r1[2 * k + 6], r1[2 * k + 7], hf2[16 + k + 3], d3); } }
;             const float d = row16_sum((d0 + d1) + (d2 + d3)) * FP6_INV;
	ds_read_b32 v58, v61 offset:1520
	ds_read_b32 v59, v61 offset:2032
	s_waitcnt lgkmcnt(1)
	v_mad_u32_u24 v0, v58, s14, v92
	global_load_dwordx4 v[44:47], v0, s[46:47]
	global_load_dwordx4 v[48:51], v0, s[46:47] offset:16
	global_load_dwordx4 v[52:55], v0, s[46:47] offset:32
	s_waitcnt vmcnt(3)
	v_cvt_scalef32_pk32_bf16_fp6 v[0:15], v[32:37], 1.0
	v_dot2_f32_bf16 v23, v0, v95, 0
	v_dot2_f32_bf16 v25, v1, v159, 0
	v_dot2_f32_bf16 v22, v2, v160, 0
	v_dot2_f32_bf16 v24, v3, v161, 0
	v_dot2c_f32_bf16_e32 v23, v4, v180
	v_dot2c_f32_bf16_e32 v25, v5, v181
	v_dot2c_f32_bf16_e32 v22, v6, v182
	v_dot2c_f32_bf16_e32 v24, v7, v183
	v_dot2c_f32_bf16_e32 v23, v8, v184
	v_dot2c_f32_bf16_e32 v25, v9, v185
	v_dot2c_f32_bf16_e32 v22, v10, v186
	v_dot2c_f32_bf16_e32 v24, v11, v187
	v_dot2c_f32_bf16_e32 v23, v12, v188
	v_dot2c_f32_bf16_e32 v25, v13, v189
	v_dot2c_f32_bf16_e32 v22, v14, v190
	v_dot2c_f32_bf16_e32 v24, v15, v191
	v_cvt_scalef32_pk32_bf16_fp6 v[0:15], v[38:43], 1.0
	v_dot2c_f32_bf16_e32 v23, v0, v192
	v_dot2c_f32_bf16_e32 v25, v1, v193
	v_dot2c_f32_bf16_e32 v22, v2, v194
	v_dot2c_f32_bf16_e32 v24, v3, v195
	v_dot2c_f32_bf16_e32 v23, v4, v196
	v_dot2c_f32_bf16_e32 v25, v5, v197
	v_dot2c_f32_bf16_e32 v22, v6, v198
	v_dot2c_f32_bf16_e32 v24, v7, v199
	v_dot2c_f32_bf16_e32 v23, v8, v200
	v_dot2c_f32_bf16_e32 v25, v9, v201
	v_dot2c_f32_bf16_e32 v22, v10, v202
	v_dot2c_f32_bf16_e32 v24, v11, v203
	v_dot2c_f32_bf16_e32 v23, v12, v204
	v_dot2c_f32_bf16_e32 v25, v13, v205
	v_dot2c_f32_bf16_e32 v22, v14, v206
	v_dot2c_f32_bf16_e32 v24, v15, v207
	s_nop 2
	v_pk_add_f32 v[0:1], v[24:25], v[22:23]
	s_nop 0
	v_add_f32_e32 v246, v0, v1
	s_waitcnt lgkmcnt(0)
	v_cndmask_b32_e64 v209, v209, v57, s[50:51]
	ds_read_b32 v56, v61
	ds_read_b32 v57, v61 offset:512
	v_add_u32_e32 v61, 16, v61
	s_add_i32 s1, s1, 1
	s_waitcnt lgkmcnt(1)
	v_mad_u32_u24 v0, v56, s14, v92
	global_load_dwordx4 v[32:35], v0, s[46:47]
	global_load_dwordx4 v[36:39], v0, s[46:47] offset:16
	global_load_dwordx4 v[40:43], v0, s[46:47] offset:32
	s_waitcnt vmcnt(3)
	v_cvt_scalef32_pk32_bf16_fp6 v[0:15], v[44:49], 1.0
	v_dot2_f32_bf16 v23, v0, v212, 0
	v_dot2_f32_bf16 v25, v1, v213, 0
	v_dot2_f32_bf16 v22, v2, v214, 0
	v_dot2_f32_bf16 v24, v3, v215, 0
	v_dot2c_f32_bf16_e32 v23, v4, v218
	v_dot2c_f32_bf16_e32 v25, v5, v219
	v_dot2c_f32_bf16_e32 v22, v6, v220
	v_dot2c_f32_bf16_e32 v24, v7, v221
	v_dot2c_f32_bf16_e32 v23, v8, v222
	v_dot2c_f32_bf16_e32 v25, v9, v223
	v_dot2c_f32_bf16_e32 v22, v10, v224
	v_dot2c_f32_bf16_e32 v24, v11, v225
	v_dot2c_f32_bf16_e32 v23, v12, v226
	v_dot2c_f32_bf16_e32 v25, v13, v227
	v_dot2c_f32_bf16_e32 v22, v14, v228
	v_dot2c_f32_bf16_e32 v24, v15, v229
	v_cvt_scalef32_pk32_bf16_fp6 v[0:15], v[50:55], 1.0
	v_dot2c_f32_bf16_e32 v23, v0, v230
	v_dot2c_f32_bf16_e32 v25, v1, v231
	v_dot2c_f32_bf16_e32 v22, v2, v232
	v_dot2c_f32_bf16_e32 v24, v3, v233
	v_dot2c_f32_bf16_e32 v23, v4, v234
	v_dot2c_f32_bf16_e32 v25, v5, v235
	v_dot2c_f32_bf16_e32 v22, v6, v236
	v_dot2c_f32_bf16_e32 v24, v7, v237
	v_dot2c_f32_bf16_e32 v23, v8, v238
	v_dot2c_f32_bf16_e32 v25, v9, v239
	v_dot2c_f32_bf16_e32 v22, v10, v240
	v_dot2c_f32_bf16_e32 v24, v11, v241
	v_dot2c_f32_bf16_e32 v23, v12, v242
	v_dot2c_f32_bf16_e32 v25, v13, v243
	v_dot2c_f32_bf16_e32 v22, v14, v244
	v_dot2c_f32_bf16_e32 v24, v15, v245
	s_nop 2
	v_pk_add_f32 v[0:1], v[24:25], v[22:23]
	s_nop 0
	v_add_f32_e32 v250, v0, v1
	s_waitcnt lgkmcnt(0)
	v_cndmask_b32_e64 v211, v211, v59, s[50:51]
	ds_read_b32 v58, v61 offset:1520
	ds_read_b32 v59, v61 offset:2032
	s_waitcnt lgkmcnt(1)
	v_mad_u32_u24 v0, v58, s14, v92
	global_load_dwordx4 v[44:47], v0, s[46:47]
	global_load_dwordx4 v[48:51], v0, s[46:47] offset:16
	global_load_dwordx4 v[52:55], v0, s[46:47] offset:32
	s_waitcnt vmcnt(3)
	v_cvt_scalef32_pk32_bf16_fp6 v[0:15], v[32:37], 1.0
	v_dot2_f32_bf16 v23, v0, v95, 0
	v_dot2_f32_bf16 v25, v1, v159, 0
	v_dot2_f32_bf16 v22, v2, v160, 0
	v_dot2_f32_bf16 v24, v3, v161, 0
	v_dot2c_f32_bf16_e32 v23, v4, v180
	v_dot2c_f32_bf16_e32 v25, v5, v181
	v_dot2c_f32_bf16_e32 v22, v6, v182
	v_dot2c_f32_bf16_e32 v24, v7, v183
	v_dot2c_f32_bf16_e32 v23, v8, v184
	v_dot2c_f32_bf16_e32 v25, v9, v185
	v_dot2c_f32_bf16_e32 v22, v10, v186
	v_dot2c_f32_bf16_e32 v24, v11, v187
	v_dot2c_f32_bf16_e32 v23, v12, v188
	v_dot2c_f32_bf16_e32 v25, v13, v189
	v_dot2c_f32_bf16_e32 v22, v14, v190
	v_dot2c_f32_bf16_e32 v24, v15, v191
	v_cvt_scalef32_pk32_bf16_fp6 v[0:15], v[38:43], 1.0
	v_dot2c_f32_bf16_e32 v23, v0, v192
	v_dot2c_f32_bf16_e32 v25, v1, v193
	v_dot2c_f32_bf16_e32 v22, v2, v194
	v_dot2c_f32_bf16_e32 v24, v3, v195
	v_dot2c_f32_bf16_e32 v23, v4, v196
	v_dot2c_f32_bf16_e32 v25, v5, v197
	v_dot2c_f32_bf16_e32 v22, v6, v198
	v_dot2c_f32_bf16_e32 v24, v7, v199
	v_dot2c_f32_bf16_e32 v23, v8, v200
	v_dot2c_f32_bf16_e32 v25, v9, v201
	v_dot2c_f32_bf16_e32 v22, v10, v202
	v_dot2c_f32_bf16_e32 v24, v11, v203
	v_dot2c_f32_bf16_e32 v23, v12, v204
	v_dot2c_f32_bf16_e32 v25, v13, v205
	v_dot2c_f32_bf16_e32 v22, v14, v206
	v_dot2c_f32_bf16_e32 v24, v15, v207
	s_nop 2
	v_pk_add_f32 v[0:1], v[24:25], v[22:23]
	s_nop 0
	v_add_f32_e32 v247, v0, v1
	s_waitcnt lgkmcnt(0)
	v_cndmask_b32_e64 v209, v209, v57, s[52:53]
	ds_read_b32 v56, v61
	ds_read_b32 v57, v61 offset:512
	v_add_u32_e32 v61, 16, v61
	s_add_i32 s1, s1, 1
	s_waitcnt lgkmcnt(1)
	v_mad_u32_u24 v0, v56, s14, v92
	global_load_dwordx4 v[32:35], v0, s[46:47]
	global_load_dwordx4 v[36:39], v0, s[46:47] offset:16
	global_load_dwordx4 v[40:43], v0, s[46:47] offset:32
	s_waitcnt vmcnt(3)
; __device__ __forceinline__ float dot2pb(__bf16 x0, __bf16 x1, unsigned h, float c) { bf2_t x; x[0] = x0; x[1] = x1; bf2_t y; __builtin_memcpy(&y, &h, 4); return __builtin_amdgcn_fdot2_f32_bf16(x, y, c, false); }
; __device__ void ph_peer(const float* __restrict__ SC, const bf16_t* __restrict__ H  , const float* __restrict__ gffn, const unsigned char* __restrict__ U, const unsigned char* __restrict__ V, float* X, const float* __restrict__ fgain) {
;     ...
;             const u32x4* up = (const u32x4*)(U + (size_t)e * 768 + 48 * sub);
;             const u32x4 u0 = up[0], u1 = up[1], u2 = up[2];
;             u32x2 vw[2][3];
; #pragma unroll
;             for (int r = 0; r < 2; ++r) { const int ea = __builtin_amdgcn_readlane(e, 32 * r), eb = __builtin_amdgcn_readlane(e, 32 * r + 16);
;                 const u32x2* vp = (const u32x2*)(V + (size_t)(half ? eb : ea) * 768 + 24 * c32); vw[r][0] = vp[0]; vw[r][1] = vp[1]; vw[r][2] = vp[2]; }
;             float d0 = 0.f, d1 = 0.f, d2 = 0.f, d3 = 0.f;
;             {   const v6u_t p0 = (v6u_t){u0.x, u0.y, u0.z, u0.w, u1.x, u1.y};
;                 const v32bf_t r0 = __builtin_amdgcn_cvt_scalef32_pk32_bf16_fp6(p0, 1.0f);
; #pragma unroll
;                 for (int k = 0; k < 16; k += 4) { d0 = dot2pb(r0[2 * k], r0[2 * k + 1], hf2[k], d0); d1 = dot2pb(r0[2 * k + 2], r0[2 * k + 3], hf2[k + 1], d1);
;                     d2 = dot2pb(r0[2 * k + 4], r0[2 * k + 5], hf2[k + 2], d2); d3 = dot2pb(r0[2 * k + 6], r0[2 * k + 7], hf2[k + 3], d3); } }
;             {   const v6u_t p1 = (v6u_t){u1.z, u1.w, u2.x, u2.y, u2.z, u2.w};
;                 const v32bf_t r1 = __builtin_amdgcn_cvt_scalef32_pk32_bf16_fp6(p1, 1.0f);
; #pragma unroll
;                 for (int k = 0; k < 16; k += 4) { d0 = dot2pb(r1[2 * k], r1[2 * k + 1], hf2[16 + k], d0); d1 = dot2pb(r1[2 * k + 2], r1[2 * k + 3], hf2[16 + k + 1], d1);
;                     d2 = dot2pb(r1[2 * k + 4], r1[2 * k + 5], hf2[16 + k + 2], d2); d3 = dot2pb(r1[2 * k + 6], r1[2 * k + 7], hf2[16 + k + 3], d3); } }
;             const float d = row16_sum((d0 + d1) + (d2 + d3)) * FP6_INV;
	v_cvt_scalef32_pk32_bf16_fp6 v[0:15], v[44:49], 1.0
	v_dot2_f32_bf16 v23, v0, v212, 0
	v_dot2_f32_bf16 v25, v1, v213, 0
	v_dot2_f32_bf16 v22, v2, v214, 0
	v_dot2_f32_bf16 v24, v3, v215, 0
	v_dot2c_f32_bf16_e32 v23, v4, v218
	v_dot2c_f32_bf16_e32 v25, v5, v219
	v_dot2c_f32_bf16_e32 v22, v6, v220
	v_dot2c_f32_bf16_e32 v24, v7, v221
	v_dot2c_f32_bf16_e32 v23, v8, v222
	v_dot2c_f32_bf16_e32 v25, v9, v223
	v_dot2c_f32_bf16_e32 v22, v10, v224
	v_dot2c_f32_bf16_e32 v24, v11, v225
	v_dot2c_f32_bf16_e32 v23, v12, v226
	v_dot2c_f32_bf16_e32 v25, v13, v227
	v_dot2c_f32_bf16_e32 v22, v14, v228
	v_dot2c_f32_bf16_e32 v24, v15, v229
	v_cvt_scalef32_pk32_bf16_fp6 v[0:15], v[50:55], 1.0
	v_dot2c_f32_bf16_e32 v23, v0, v230
	v_dot2c_f32_bf16_e32 v25, v1, v231
	v_dot2c_f32_bf16_e32 v22, v2, v232
	v_dot2c_f32_bf16_e32 v24, v3, v233
	v_dot2c_f32_bf16_e32 v23, v4, v234
	v_dot2c_f32_bf16_e32 v25, v5, v235
	v_dot2c_f32_bf16_e32 v22, v6, v236
	v_dot2c_f32_bf16_e32 v24, v7, v237
	v_dot2c_f32_bf16_e32 v23, v8, v238
	v_dot2c_f32_bf16_e32 v25, v9, v239
	v_dot2c_f32_bf16_e32 v22, v10, v240
	v_dot2c_f32_bf16_e32 v24, v11, v241
	v_dot2c_f32_bf16_e32 v23, v12, v242
	v_dot2c_f32_bf16_e32 v25, v13, v243
	v_dot2c_f32_bf16_e32 v22, v14, v244
	v_dot2c_f32_bf16_e32 v24, v15, v245
	s_nop 2
	v_pk_add_f32 v[0:1], v[24:25], v[22:23]
	s_nop 0
	v_add_f32_e32 v216, v0, v1
	s_waitcnt lgkmcnt(0)
	v_cndmask_b32_e64 v211, v211, v59, s[52:53]
	ds_read_b32 v58, v61 offset:1520
	ds_read_b32 v59, v61 offset:2032
	s_waitcnt lgkmcnt(1)
	v_mad_u32_u24 v0, v58, s14, v92
	global_load_dwordx4 v[44:47], v0, s[46:47]
	global_load_dwordx4 v[48:51], v0, s[46:47] offset:16
	global_load_dwordx4 v[52:55], v0, s[46:47] offset:32
	s_waitcnt vmcnt(3)
	v_cvt_scalef32_pk32_bf16_fp6 v[0:15], v[32:37], 1.0
	v_dot2_f32_bf16 v23, v0, v95, 0
	v_dot2_f32_bf16 v25, v1, v159, 0
	v_dot2_f32_bf16 v22, v2, v160, 0
	v_dot2_f32_bf16 v24, v3, v161, 0
	v_dot2c_f32_bf16_e32 v23, v4, v180
	v_dot2c_f32_bf16_e32 v25, v5, v181
	v_dot2c_f32_bf16_e32 v22, v6, v182
	v_dot2c_f32_bf16_e32 v24, v7, v183
	v_dot2c_f32_bf16_e32 v23, v8, v184
	v_dot2c_f32_bf16_e32 v25, v9, v185
	v_dot2c_f32_bf16_e32 v22, v10, v186
	v_dot2c_f32_bf16_e32 v24, v11, v187
	v_dot2c_f32_bf16_e32 v23, v12, v188
	v_dot2c_f32_bf16_e32 v25, v13, v189
	v_dot2c_f32_bf16_e32 v22, v14, v190
	v_dot2c_f32_bf16_e32 v24, v15, v191
	v_cvt_scalef32_pk32_bf16_fp6 v[0:15], v[38:43], 1.0
	v_dot2c_f32_bf16_e32 v23, v0, v192
	v_dot2c_f32_bf16_e32 v25, v1, v193
	v_dot2c_f32_bf16_e32 v22, v2, v194
	v_dot2c_f32_bf16_e32 v24, v3, v195
	v_dot2c_f32_bf16_e32 v23, v4, v196
	v_dot2c_f32_bf16_e32 v25, v5, v197
	v_dot2c_f32_bf16_e32 v22, v6, v198
	v_dot2c_f32_bf16_e32 v24, v7, v199
	v_dot2c_f32_bf16_e32 v23, v8, v200
	v_dot2c_f32_bf16_e32 v25, v9, v201
	v_dot2c_f32_bf16_e32 v22, v10, v202
	v_dot2c_f32_bf16_e32 v24, v11, v203
	v_dot2c_f32_bf16_e32 v23, v12, v204
	v_dot2c_f32_bf16_e32 v25, v13, v205
	v_dot2c_f32_bf16_e32 v22, v14, v206
	v_dot2c_f32_bf16_e32 v24, v15, v207
	s_nop 2
	v_pk_add_f32 v[0:1], v[24:25], v[22:23]
	s_nop 0
	v_add_f32_e32 v248, v0, v1
	s_waitcnt lgkmcnt(0)
	v_cndmask_b32_e64 v209, v209, v57, s[54:55]
	ds_read_b32 v56, v61
	ds_read_b32 v57, v61 offset:512
	v_add_u32_e32 v61, 16, v61
	s_add_i32 s1, s1, 1
	s_waitcnt lgkmcnt(1)
	v_mad_u32_u24 v0, v56, s14, v92
	global_load_dwordx4 v[32:35], v0, s[46:47]
	global_load_dwordx4 v[36:39], v0, s[46:47] offset:16
	global_load_dwordx4 v[40:43], v0, s[46:47] offset:32
	s_waitcnt vmcnt(3)
	v_cvt_scalef32_pk32_bf16_fp6 v[0:15], v[44:49], 1.0
	v_dot2_f32_bf16 v23, v0, v212, 0
	v_dot2_f32_bf16 v25, v1, v213, 0
	v_dot2_f32_bf16 v22, v2, v214, 0
	v_dot2_f32_bf16 v24, v3, v215, 0
	v_dot2c_f32_bf16_e32 v23, v4, v218
	v_dot2c_f32_bf16_e32 v25, v5, v219
	v_dot2c_f32_bf16_e32 v22, v6, v220
	v_dot2c_f32_bf16_e32 v24, v7, v221
	v_dot2c_f32_bf16_e32 v23, v8, v222
	v_dot2c_f32_bf16_e32 v25, v9, v223
	v_dot2c_f32_bf16_e32 v22, v10, v224
	v_dot2c_f32_bf16_e32 v24, v11, v225
	v_dot2c_f32_bf16_e32 v23, v12, v226
	v_dot2c_f32_bf16_e32 v25, v13, v227
	v_dot2c_f32_bf16_e32 v22, v14, v228
	v_dot2c_f32_bf16_e32 v24, v15, v229
	v_cvt_scalef32_pk32_bf16_fp6 v[0:15], v[50:55], 1.0
	v_dot2c_f32_bf16_e32 v23, v0, v230
	v_dot2c_f32_bf16_e32 v25, v1, v231
	v_dot2c_f32_bf16_e32 v22, v2, v232
	v_dot2c_f32_bf16_e32 v24, v3, v233
	v_dot2c_f32_bf16_e32 v23, v4, v234
	v_dot2c_f32_bf16_e32 v25, v5, v235
	v_dot2c_f32_bf16_e32 v22, v6, v236
	v_dot2c_f32_bf16_e32 v24, v7, v237
	v_dot2c_f32_bf16_e32 v23, v8, v238
	v_dot2c_f32_bf16_e32 v25, v9, v239
	v_dot2c_f32_bf16_e32 v22, v10, v240
	v_dot2c_f32_bf16_e32 v24, v11, v241
	v_dot2c_f32_bf16_e32 v23, v12, v242
	v_dot2c_f32_bf16_e32 v25, v13, v243
	v_dot2c_f32_bf16_e32 v22, v14, v244
	v_dot2c_f32_bf16_e32 v24, v15, v245
	s_nop 2
	v_pk_add_f32 v[0:1], v[24:25], v[22:23]
	s_nop 0
	v_add_f32_e32 v217, v0, v1
	s_waitcnt lgkmcnt(0)
	v_cndmask_b32_e64 v211, v211, v59, s[54:55]
	ds_read_b32 v58, v61 offset:1520
	ds_read_b32 v59, v61 offset:2032
	s_waitcnt lgkmcnt(1)
	v_mad_u32_u24 v0, v58, s14, v92
	global_load_dwordx4 v[44:47], v0, s[46:47]
	global_load_dwordx4 v[48:51], v0, s[46:47] offset:16
	global_load_dwordx4 v[52:55], v0, s[46:47] offset:32
	s_waitcnt vmcnt(3)
; __device__ __forceinline__ float gelu1(float v) { const f32x2 r = gelu_pk((f32x2){v, v}); return r.x; }
; __device__ __forceinline__ float dot2pb(__bf16 x0, __bf16 x1, unsigned h, float c) { bf2_t x; x[0] = x0; x[1] = x1; bf2_t y; __builtin_memcpy(&y, &h, 4); return __builtin_amdgcn_fdot2_f32_bf16(x, y, c, false); }
; __device__ void ph_peer(const float* __restrict__ SC, const bf16_t* __restrict__ H  , const float* __restrict__ gffn, const unsigned char* __restrict__ U, const unsigned char* __restrict__ V, float* X, const float* __restrict__ fgain) {
;     ...
;             const u32x4* up = (const u32x4*)(U + (size_t)e * 768 + 48 * sub);
;             const u32x4 u0 = up[0], u1 = up[1], u2 = up[2];
;             u32x2 vw[2][3];
; #pragma unroll
;             for (int r = 0; r < 2; ++r) { const int ea = __builtin_amdgcn_readlane(e, 32 * r), eb = __builtin_amdgcn_readlane(e, 32 * r + 16);
;                 const u32x2* vp = (const u32x2*)(V + (size_t)(half ? eb : ea) * 768 + 24 * c32); vw[r][0] = vp[0]; vw[r][1] = vp[1]; vw[r][2] = vp[2]; }
;             float d0 = 0.f, d1 = 0.f, d2 = 0.f, d3 = 0.f;
;             {   const v6u_t p0 = (v6u_t){u0.x, u0.y, u0.z, u0.w, u1.x, u1.y};
;                 const v32bf_t r0 = __builtin_amdgcn_cvt_scalef32_pk32_bf16_fp6(p0, 1.0f);
; #pragma unroll
;                 for (int k = 0; k < 16; k += 4) { d0 = dot2pb(r0[2 * k], r0[2 * k + 1], hf2[k], d0); d1 = dot2pb(r0[2 * k + 2], r0[2 * k + 3], hf2[k + 1], d1);
;                     d2 = dot2pb(r0[2 * k + 4], r0[2 * k + 5], hf2[k + 2], d2); d3 = dot2pb(r0[2 * k + 6], r0[2 * k + 7], hf2[k + 3], d3); } }
;             {   const v6u_t p1 = (v6u_t){u1.z, u1.w, u2.x, u2.y, u2.z, u2.w};
;                 const v32bf_t r1 = __builtin_amdgcn_cvt_scalef32_pk32_bf16_fp6(p1, 1.0f);
; #pragma unroll
;                 for (int k = 0; k < 16; k += 4) { d0 = dot2pb(r1[2 * k], r1[2 * k + 1], hf2[16 + k], d0); d1 = dot2pb(r1[2 * k + 2], r1[2 * k + 3], hf2[16 + k + 1], d1);
;                     d2 = dot2pb(r1[2 * k + 4], r1[2 * k + 5], hf2[16 + k + 2], d2); d3 = dot2pb(r1[2 * k + 6], r1[2 * k + 7], hf2[16 + k + 3], d3); } }
;             const float d = row16_sum((d0 + d1) + (d2 + d3)) * FP6_INV;
;             const float a = gt * gelu1(d) * FP6_INV;
	v_cvt_scalef32_pk32_bf16_fp6 v[0:15], v[32:37], 1.0
	v_dot2_f32_bf16 v23, v0, v95, 0
	v_dot2_f32_bf16 v25, v1, v159, 0
	v_dot2_f32_bf16 v22, v2, v160, 0
	v_dot2_f32_bf16 v24, v3, v161, 0
	v_dot2c_f32_bf16_e32 v23, v4, v180
	v_dot2c_f32_bf16_e32 v25, v5, v181
	v_dot2c_f32_bf16_e32 v22, v6, v182
	v_dot2c_f32_bf16_e32 v24, v7, v183
	v_dot2c_f32_bf16_e32 v23, v8, v184
	v_dot2c_f32_bf16_e32 v25, v9, v185
	v_dot2c_f32_bf16_e32 v22, v10, v186
	v_dot2c_f32_bf16_e32 v24, v11, v187
	v_dot2c_f32_bf16_e32 v23, v12, v188
	v_dot2c_f32_bf16_e32 v25, v13, v189
	v_dot2c_f32_bf16_e32 v22, v14, v190
	v_dot2c_f32_bf16_e32 v24, v15, v191
	v_cvt_scalef32_pk32_bf16_fp6 v[0:15], v[38:43], 1.0
	v_dot2c_f32_bf16_e32 v23, v0, v192
	v_dot2c_f32_bf16_e32 v25, v1, v193
	v_dot2c_f32_bf16_e32 v22, v2, v194
	v_dot2c_f32_bf16_e32 v24, v3, v195
	v_dot2c_f32_bf16_e32 v23, v4, v196
	v_dot2c_f32_bf16_e32 v25, v5, v197
	v_dot2c_f32_bf16_e32 v22, v6, v198
	v_dot2c_f32_bf16_e32 v24, v7, v199
	v_dot2c_f32_bf16_e32 v23, v8, v200
	v_dot2c_f32_bf16_e32 v25, v9, v201
	v_dot2c_f32_bf16_e32 v22, v10, v202
	v_dot2c_f32_bf16_e32 v24, v11, v203
	v_dot2c_f32_bf16_e32 v23, v12, v204
	v_dot2c_f32_bf16_e32 v25, v13, v205
	v_dot2c_f32_bf16_e32 v22, v14, v206
	v_dot2c_f32_bf16_e32 v24, v15, v207
	s_nop 2
	v_pk_add_f32 v[0:1], v[24:25], v[22:23]
	s_nop 0
	v_add_f32_e32 v249, v0, v1
	s_waitcnt lgkmcnt(0)
	v_cndmask_b32_e64 v209, v209, v57, s[56:57]
	v_cndmask_b32_e64 v2, v247, v246, s[58:59]
	v_cndmask_b32_e64 v3, v246, v247, s[58:59]
	v_cndmask_b32_e64 v4, v249, v248, s[58:59]
	v_cndmask_b32_e64 v5, v248, v249, s[58:59]
	v_add_f32_dpp v3, v2, v3 quad_perm:[1,0,3,2] row_mask:0xf bank_mask:0xf bound_ctrl:1
	v_add_f32_dpp v5, v4, v5 quad_perm:[1,0,3,2] row_mask:0xf bank_mask:0xf bound_ctrl:1
	v_cndmask_b32_e64 v2, v5, v3, s[60:61]
	v_cndmask_b32_e64 v0, v3, v5, s[60:61]
	s_nop 0
	v_add_f32_dpp v0, v2, v0 quad_perm:[2,3,0,1] row_mask:0xf bank_mask:0xf bound_ctrl:1
	s_nop 1
	v_add_f32_dpp v0, v0, v0 row_ror:4 row_mask:0xf bank_mask:0xf bound_ctrl:1
	s_nop 1
	v_add_f32_dpp v0, v0, v0 row_ror:8 row_mask:0xf bank_mask:0xf bound_ctrl:1
	v_mul_f32_e32 v0, 0x3caaaaab, v0
	v_and_b32_e32 v2, 0x7fffffff, v0
	v_pk_fma_f32 v[2:3], v[2:3], s[16:17], 1.0 op_sel_hi:[0,0,0]
	v_rcp_f32_e32 v2, v2
	v_rcp_f32_e32 v3, v3
	v_mul_f32_e32 v1, v0, v0
	v_mul_f32_e32 v1, 0xbf38aa3b, v1
	v_cmp_gt_f32_e32 vcc, 0, v0
	v_pk_fma_f32 v[4:5], v[2:3], s[24:25], v[130:131] op_sel_hi:[1,0,0]
	s_nop 0
	v_pk_fma_f32 v[4:5], v[2:3], v[4:5], s[28:29] op_sel_hi:[1,1,0]
	s_nop 0
	v_pk_fma_f32 v[4:5], v[2:3], v[4:5], s[30:31] op_sel_hi:[1,1,0]
	s_nop 0
	v_pk_fma_f32 v[4:5], v[2:3], v[4:5], s[36:37] op_sel_hi:[1,1,0]
	s_nop 0
	v_pk_mul_f32 v[2:3], v[2:3], v[4:5]
	v_exp_f32_e32 v4, v1
	s_nop 0
	v_pk_mul_f32 v[2:3], v[4:5], v[2:3] op_sel_hi:[0,1]
	v_pk_fma_f32 v[4:5], v[0:1], v[2:3], v[0:1] op_sel_hi:[0,1,1] neg_lo:[1,0,0] neg_hi:[1,0,0]
	v_mul_f32_e32 v0, v0, v2
	v_cndmask_b32_e32 v0, v4, v0, vcc
	v_mul_f32_e32 v0, v0, v209
	v_mul_f32_e32 v60, 0x3caaaaab, v0
	v_add_u32_e32 v62, v61, v155
	ds_write_b32 v62, v60 offset:960
	s_waitcnt vmcnt(0)
	v_cvt_scalef32_pk32_bf16_fp6 v[0:15], v[44:49], 1.0
	v_dot2_f32_bf16 v23, v0, v212, 0
	v_dot2_f32_bf16 v25, v1, v213, 0
	v_dot2_f32_bf16 v22, v2, v214, 0
	v_dot2_f32_bf16 v24, v3, v215, 0
	v_dot2c_f32_bf16_e32 v23, v4, v218
	v_dot2c_f32_bf16_e32 v25, v5, v219
	v_dot2c_f32_bf16_e32 v22, v6, v220
	v_dot2c_f32_bf16_e32 v24, v7, v221
	v_dot2c_f32_bf16_e32 v23, v8, v222
	v_dot2c_f32_bf16_e32 v25, v9, v223
	v_dot2c_f32_bf16_e32 v22, v10, v224
	v_dot2c_f32_bf16_e32 v24, v11, v225
	v_dot2c_f32_bf16_e32 v23, v12, v226
	v_dot2c_f32_bf16_e32 v25, v13, v227
	v_dot2c_f32_bf16_e32 v22, v14, v228
	v_dot2c_f32_bf16_e32 v24, v15, v229
	v_cvt_scalef32_pk32_bf16_fp6 v[0:15], v[50:55], 1.0
	v_dot2c_f32_bf16_e32 v23, v0, v230
	v_dot2c_f32_bf16_e32 v25, v1, v231
	v_dot2c_f32_bf16_e32 v22, v2, v232
	v_dot2c_f32_bf16_e32 v24, v3, v233
	v_dot2c_f32_bf16_e32 v23, v4, v234
	v_dot2c_f32_bf16_e32 v25, v5, v235
	v_dot2c_f32_bf16_e32 v22, v6, v236
	v_dot2c_f32_bf16_e32 v24, v7, v237
	v_dot2c_f32_bf16_e32 v23, v8, v238
	v_dot2c_f32_bf16_e32 v25, v9, v239
	v_dot2c_f32_bf16_e32 v22, v10, v240
	v_dot2c_f32_bf16_e32 v24, v11, v241
	v_dot2c_f32_bf16_e32 v23, v12, v242
	v_dot2c_f32_bf16_e32 v25, v13, v243
	v_dot2c_f32_bf16_e32 v22, v14, v244
	v_dot2c_f32_bf16_e32 v24, v15, v245
	s_nop 2
	v_pk_add_f32 v[0:1], v[24:25], v[22:23]
	s_nop 0
	v_add_f32_e32 v63, v0, v1
	s_waitcnt lgkmcnt(0)
	v_cndmask_b32_e64 v211, v211, v59, s[56:57]
	v_cndmask_b32_e64 v2, v216, v250, s[58:59]
	v_cndmask_b32_e64 v3, v250, v216, s[58:59]
	v_cndmask_b32_e64 v4, v63, v217, s[58:59]
	v_cndmask_b32_e64 v5, v217, v63, s[58:59]
	v_add_f32_dpp v3, v2, v3 quad_perm:[1,0,3,2] row_mask:0xf bank_mask:0xf bound_ctrl:1
	v_add_f32_dpp v5, v4, v5 quad_perm:[1,0,3,2] row_mask:0xf bank_mask:0xf bound_ctrl:1
	v_cndmask_b32_e64 v2, v5, v3, s[60:61]
	v_cndmask_b32_e64 v0, v3, v5, s[60:61]
	s_nop 0
	v_add_f32_dpp v0, v2, v0 quad_perm:[2,3,0,1] row_mask:0xf bank_mask:0xf bound_ctrl:1
	s_nop 1
	v_add_f32_dpp v0, v0, v0 row_ror:4 row_mask:0xf bank_mask:0xf bound_ctrl:1
	s_nop 1
	v_add_f32_dpp v0, v0, v0 row_ror:8 row_mask:0xf bank_mask:0xf bound_ctrl:1
	v_mul_f32_e32 v0, 0x3caaaaab, v0
	v_and_b32_e32 v2, 0x7fffffff, v0
	v_pk_fma_f32 v[2:3], v[2:3], s[16:17], 1.0 op_sel_hi:[0,0,0]
	v_rcp_f32_e32 v2, v2
	v_rcp_f32_e32 v3, v3
	v_mul_f32_e32 v1, v0, v0
	v_mul_f32_e32 v1, 0xbf38aa3b, v1
	v_cmp_gt_f32_e32 vcc, 0, v0
	v_pk_fma_f32 v[4:5], v[2:3], s[24:25], v[130:131] op_sel_hi:[1,0,0]
	s_nop 0
	v_pk_fma_f32 v[4:5], v[2:3], v[4:5], s[28:29] op_sel_hi:[1,1,0]
	s_nop 0
	v_pk_fma_f32 v[4:5], v[2:3], v[4:5], s[30:31] op_sel_hi:[1,1,0]
	s_nop 0
	v_pk_fma_f32 v[4:5], v[2:3], v[4:5], s[36:37] op_sel_hi:[1,1,0]
	s_nop 0
	v_pk_mul_f32 v[2:3], v[2:3], v[4:5]
	v_exp_f32_e32 v4, v1
	s_nop 0
	v_pk_mul_f32 v[2:3], v[4:5], v[2:3] op_sel_hi:[0,1]
	v_pk_fma_f32 v[4:5], v[0:1], v[2:3], v[0:1] op_sel_hi:[0,1,1] neg_lo:[1,0,0] neg_hi:[1,0,0]
	v_mul_f32_e32 v0, v0, v2
	v_cndmask_b32_e32 v0, v4, v0, vcc
	v_mul_f32_e32 v0, v0, v211
	v_mul_f32_e32 v60, 0x3caaaaab, v0
	v_add_u32_e32 v62, v61, v155
	ds_write_b32 v62, v60 offset:2496
	v_mov_b32_e32 v180, 0
	v_mov_b32_e32 v181, 0
	v_mov_b32_e32 v182, 0
	v_mov_b32_e32 v183, 0
	v_mov_b32_e32 v184, 0
	v_mov_b32_e32 v185, 0
	v_mov_b32_e32 v186, 0
	v_mov_b32_e32 v187, 0
	v_mov_b32_e32 v188, 0
	v_mov_b32_e32 v189, 0
	v_mov_b32_e32 v190, 0
	v_mov_b32_e32 v191, 0
	v_mov_b32_e32 v192, 0
	v_mov_b32_e32 v193, 0
	v_mov_b32_e32 v194, 0
	v_mov_b32_e32 v195, 0
	v_mov_b32_e32 v196, 0
	v_mov_b32_e32 v197, 0
	v_mov_b32_e32 v198, 0
	v_mov_b32_e32 v199, 0
	v_mov_b32_e32 v200, 0
	v_mov_b32_e32 v201, 0
	v_mov_b32_e32 v202, 0
	v_mov_b32_e32 v203, 0
	v_mov_b32_e32 v204, 0
	v_mov_b32_e32 v205, 0
	v_mov_b32_e32 v206, 0
	v_mov_b32_e32 v207, 0
	v_mov_b32_e32 v208, 0
	v_mov_b32_e32 v209, 0
	v_mov_b32_e32 v210, 0
	v_mov_b32_e32 v211, 0
	s_barrier
; __device__ void ph_peer(const float* __restrict__ SC, const bf16_t* __restrict__ H  , const float* __restrict__ gffn, const unsigned char* __restrict__ U, const unsigned char* __restrict__ V, float* X, const float* __restrict__ fgain) {
;     ...
;         for (int it = 0; it < 32; ++it) {
;             const int src = (it * 4 + grp) & 63;
;             const int e = __shfl(it < 16 ? idx_lo : idx_hi, src);
;             const float gt = __shfl(it < 16 ? g_lo : g_hi, src);
;             const u32x4* up = (const u32x4*)(U + (size_t)e * 768 + 48 * sub);
;             const u32x4 u0 = up[0], u1 = up[1], u2 = up[2];
;             u32x2 vw[2][3];
; #pragma unroll
;             for (int r = 0; r < 2; ++r) { const int ea = __builtin_amdgcn_readlane(e, 32 * r), eb = __builtin_amdgcn_readlane(e, 32 * r + 16);
;                 const u32x2* vp = (const u32x2*)(V + (size_t)(half ? eb : ea) * 768 + 24 * c32); vw[r][0] = vp[0]; vw[r][1] = vp[1]; vw[r][2] = vp[2]; }
	v_lshrrev_b32_e32 v61, 6, v131
	v_lshrrev_b32_e32 v0, 5, v74
	v_mul_u32_u24_e32 v61, 0x2400, v61
	v_lshl_add_u32 v61, v0, 2, v61
	s_mov_b32 s1, 0
	ds_read_b32 v32, v61 offset:0
	ds_read_b32 v33, v61 offset:8
	ds_read_b32 v56, v61 offset:1024
	ds_read_b32 v58, v61 offset:1032
	v_add_u32_e32 v61, 16, v61
	s_add_i32 s1, s1, 1
	s_waitcnt lgkmcnt(2)
	v_mad_u32_u24 v0, v32, s14, v93
	v_mad_u32_u24 v1, v33, s14, v93
	global_load_dwordx4 v[44:47], v0, s[48:49]
	global_load_dwordx2 v[48:49], v0, s[48:49] offset:16
	global_load_dwordx4 v[50:53], v1, s[48:49]
	global_load_dwordx2 v[54:55], v1, s[48:49] offset:16
